# all flat loads/stores of global-memory pointers converted to global_* (no lgkmcnt coupling); LDS-generic sc0/sc1 accesses untouched
# speedup vs baseline: 1.0012x; 1.0012x over previous
.LBB0_5:
	s_or_b64 exec, exec, s[2:3]
	s_load_dwordx16 s[40:55], s[0:1], 0xc0
	s_mov_b64 s[10:11], s[88:89]
	s_mov_b64 s[2:3], s[86:87]
	v_mov_b32_e32 v3, v224
	s_nop 0
	v_or_b32_e32 v1, s70, v3
	v_cmp_eq_u32_e32 vcc, 0, v1
	s_and_saveexec_b64 s[2:3], vcc
	s_cbranch_execz .LBB0_7
	v_mov_b32_e32 v1, s10
	v_add_co_u32_e32 v4, vcc, 0x300ae000, v1
	v_mov_b32_e32 v1, s11
	s_nop 0
	v_addc_co_u32_e32 v5, vcc, 0, v1, vcc
	v_mov_b32_e32 v1, 0
	global_store_dword v[4:5], v1, off offset:1536

.LBB0_10:
	v_cmp_lt_i32_e32 vcc, s18, v2
	s_and_saveexec_b64 s[14:15], vcc
	s_xor_b64 s[14:15], exec, s[14:15]
	s_cbranch_execz .LBB0_12
	v_add_u32_e32 v4, 0xfffc0000, v2
	v_lshrrev_b32_e32 v3, 7, v4
	v_and_b32_e32 v9, 0x1fc00, v6
	v_add_lshl_u32 v3, v9, v3, 2
	s_waitcnt lgkmcnt(0)
	global_load_dword v3, v3, s[52:53]
	v_lshl_add_u64 v[10:11], v[4:5], 1, s[6:7]
	s_waitcnt vmcnt(0)
	v_cvt_pk_bf16_f32 v3, v3, v5
	global_store_short v[10:11], v3, off
.LBB0_12:
	s_andn2_saveexec_b64 s[14:15], s[14:15]
	s_cbranch_execz .LBB0_9
	s_waitcnt lgkmcnt(0)
	v_mov_b32_e32 v3, s51
	v_mov_b32_e32 v4, s47
	v_cmp_lt_i32_sdwa vcc, sext(v2), v7 src0_sel:WORD_1 src1_sel:DWORD
	s_nop 1
	v_cndmask_b32_e32 v11, v3, v4, vcc
	v_mov_b32_e32 v3, s50
	v_mov_b32_e32 v4, s46
	v_cndmask_b32_e32 v10, v3, v4, vcc
	v_lshlrev_b32_sdwa v3, v8, sext(v2) dst_sel:DWORD dst_unused:UNUSED_PAD src0_sel:DWORD src1_sel:WORD_1
	v_lshrrev_b32_e32 v4, 4, v2
	v_and_or_b32 v3, v3, 64, v1
	v_and_b32_e32 v4, 0xffc, v4
	v_lshl_or_b32 v4, v3, 12, v4
	v_lshl_add_u64 v[10:11], v[10:11], 0, v[4:5]
	v_ashrrev_i32_e32 v3, 31, v2
	global_load_dword v4, v[10:11], off
	v_lshl_add_u64 v[10:11], v[2:3], 1, s[4:5]
	s_waitcnt vmcnt(0)
	v_cvt_pk_bf16_f32 v4, v4, v5
	global_store_short v[10:11], v4, off
	s_branch .LBB0_9

.LBB0_20:
	s_cmpk_gt_u32 s22, 0x207
	s_cbranch_scc0 .LBB0_38
	s_cmpk_gt_u32 s22, 0xf07
	s_cbranch_scc0 .LBB0_31
	s_cmpk_gt_u32 s22, 0x1307
	s_cbranch_scc0 .LBB0_28
	s_cmpk_gt_u32 s22, 0x2907
	s_cbranch_scc0 .LBB0_25
	s_add_i32 s0, s22, 0xffffd6f8
	s_lshl_b32 s1, s0, 1
	s_lshl_b32 s0, s0, 6
	v_mov_b32_e32 v12, v224
	s_and_b32 s3, s0, 0x7c0
	v_readlane_b32 s60, v253, 32
	s_and_b32 s2, s1, 0x1ffc0
	v_lshlrev_b32_e32 v2, 4, v12
	s_lshl_b32 s0, s3, 2
	v_readlane_b32 s68, v253, 40
	v_ashrrev_i32_e32 v13, 4, v12
	v_and_b32_e32 v22, 0xf0, v2
	v_readlane_b32 s69, v253, 41
	s_add_u32 s0, s68, s0
	v_add_u32_e32 v2, s2, v13
	v_add_u32_e32 v8, 0x200, v12
	s_addc_u32 s1, s69, 0
	v_ashrrev_i32_e32 v3, 31, v2
	v_ashrrev_i32_e32 v16, 4, v8
	v_lshl_add_u64 v[6:7], s[0:1], 0, v[22:23]
	v_lshlrev_b64 v[2:3], 13, v[2:3]
	v_add_u32_e32 v8, s2, v16
	v_lshl_add_u64 v[2:3], v[6:7], 0, v[2:3]
	v_ashrrev_i32_e32 v9, 31, v8
	global_load_dwordx4 v[2:5], v[2:3], off
	v_lshlrev_b64 v[8:9], 13, v[8:9]
	v_lshl_add_u64 v[6:7], v[6:7], 0, v[8:9]
	global_load_dwordx4 v[6:9], v[6:7], off
	v_readlane_b32 s0, v253, 4
	v_readlane_b32 s1, v253, 5
	v_ashrrev_i32_e32 v14, 3, v12
	v_lshlrev_b32_e32 v12, 3, v12
	v_mov_b64_e32 v[10:11], s[0:1]
	v_and_b32_e32 v17, 56, v12
	v_lshlrev_b32_e32 v18, 2, v14
	v_add_u32_e32 v14, s3, v14
	v_add_u32_e32 v12, 16, v22
	s_movk_i32 s0, 0x2c00
	v_mul_u32_u24_e32 v19, 0x104, v17
	v_mad_i64_i32 v[10:11], s[0:1], v14, s0, v[10:11]
	v_mad_u64_u32 v[14:15], s[0:1], v13, s51, v[12:13]
	v_mad_u64_u32 v[12:13], s[0:1], v16, s51, v[12:13]
	v_add3_u32 v13, 16, v19, v18
	v_add_u32_e32 v15, 0x400, v13
	s_lshl_b32 s18, s2, 1
	v_lshl_add_u64 v[10:11], v[10:11], 0, s[18:19]
	v_lshlrev_b32_e32 v22, 1, v17
	v_lshl_add_u64 v[10:11], v[10:11], 0, v[22:23]
	v_readlane_b32 s61, v253, 33
	v_readlane_b32 s62, v253, 34
	v_readlane_b32 s63, v253, 35
	v_readlane_b32 s64, v253, 36
	v_readlane_b32 s65, v253, 37
	v_readlane_b32 s66, v253, 38
	v_readlane_b32 s67, v253, 39
	v_readlane_b32 s70, v253, 42
	v_readlane_b32 s71, v253, 43
	v_readlane_b32 s72, v253, 44
	v_readlane_b32 s73, v253, 45
	v_readlane_b32 s74, v253, 46
	v_readlane_b32 s75, v253, 47
	s_mov_b64 s[0:1], 0
	s_waitcnt vmcnt(0)
	ds_write2_b32 v14, v2, v3 offset1:1
	ds_write2_b32 v14, v4, v5 offset0:2 offset1:3
	ds_write2_b32 v12, v6, v7 offset1:1
	ds_write2_b32 v12, v8, v9 offset0:2 offset1:3
	s_waitcnt lgkmcnt(0)
	s_barrier
	ds_read2_b32 v[2:3], v13 offset1:65
	ds_read2_b32 v[4:5], v13 offset0:130 offset1:195
	ds_read2_b32 v[6:7], v15 offset0:4 offset1:69
	ds_read2_b32 v[8:9], v15 offset0:134 offset1:199
	s_waitcnt lgkmcnt(3)
	v_cvt_pk_bf16_f32 v2, v2, v3
	s_waitcnt lgkmcnt(2)
	v_cvt_pk_bf16_f32 v3, v4, v5
	s_waitcnt lgkmcnt(1)
	v_cvt_pk_bf16_f32 v4, v6, v7
	s_waitcnt lgkmcnt(0)
	v_cvt_pk_bf16_f32 v5, v8, v9
	global_store_dwordx4 v[10:11], v[2:5], off
	s_waitcnt lgkmcnt(0)
	s_barrier
.LBB0_25:
	s_andn2_b64 vcc, exec, s[0:1]
	s_cbranch_vccnz .LBB0_27
	s_add_i32 s0, s22, 0xecf8
	s_and_b32 s1, s0, 0xffff
	s_mul_i32 s1, s1, 0xba2f
	s_lshr_b32 s2, s1, 23
	s_mul_i32 s1, s2, 0xb0
	s_sub_i32 s0, s0, s1
	s_lshl_b32 s0, s0, 6
	s_and_b32 s4, s0, 0xffc0
	v_readlane_b32 s60, v253, 32
	v_mov_b32_e32 v10, v224
	s_lshl_b32 s3, s2, 6
	s_lshl_b32 s0, s4, 2
	v_readlane_b32 s64, v253, 36
	v_readlane_b32 s65, v253, 37
	v_lshlrev_b32_e32 v2, 4, v10
	s_add_u32 s0, s64, s0
	v_and_b32_e32 v22, 0xf0, v2
	s_addc_u32 s1, s65, 0
	v_ashrrev_i32_e32 v11, 4, v10
	v_lshl_add_u64 v[6:7], s[0:1], 0, v[22:23]
	v_add_u32_e32 v2, s3, v11
	s_mov_b32 s5, 0xb000
	v_add_u32_e32 v8, 0x200, v10
	v_mad_i64_i32 v[2:3], s[0:1], v2, s5, v[6:7]
	v_ashrrev_i32_e32 v14, 4, v8
	global_load_dwordx4 v[2:5], v[2:3], off
	v_add_u32_e32 v8, s3, v14
	v_mad_i64_i32 v[6:7], s[0:1], v8, s5, v[6:7]
	global_load_dwordx4 v[6:9], v[6:7], off
	v_ashrrev_i32_e32 v15, 3, v10
	v_lshlrev_b32_e32 v10, 3, v10
	v_and_b32_e32 v16, 56, v10
	v_add_u32_e32 v10, 16, v22
	v_lshlrev_b32_e32 v17, 2, v15
	v_mul_u32_u24_e32 v18, 0x104, v16
	v_mad_u64_u32 v[12:13], s[0:1], v11, s51, v[10:11]
	v_mad_u64_u32 v[10:11], s[0:1], v14, s51, v[10:11]
	v_add3_u32 v11, 16, v18, v17
	v_add_u32_e32 v14, s4, v15
	v_add_u32_e32 v13, 0x400, v11
	v_ashrrev_i32_e32 v15, 31, v14
	v_readlane_b32 s0, v253, 6
	v_lshlrev_b64 v[14:15], 12, v[14:15]
	v_readlane_b32 s1, v253, 7
	s_lshl_b32 s18, s2, 7
	v_lshlrev_b32_e32 v22, 1, v16
	v_lshl_add_u64 v[14:15], s[0:1], 0, v[14:15]
	v_lshl_add_u64 v[14:15], v[14:15], 0, s[18:19]
	v_readlane_b32 s61, v253, 33
	v_readlane_b32 s62, v253, 34
	v_readlane_b32 s63, v253, 35
	v_readlane_b32 s66, v253, 38
	v_readlane_b32 s67, v253, 39
	v_readlane_b32 s68, v253, 40
	v_readlane_b32 s69, v253, 41
	v_readlane_b32 s70, v253, 42
	v_readlane_b32 s71, v253, 43
	v_readlane_b32 s72, v253, 44
	v_readlane_b32 s73, v253, 45
	v_readlane_b32 s74, v253, 46
	v_readlane_b32 s75, v253, 47
	s_waitcnt vmcnt(0)
	ds_write2_b32 v12, v2, v3 offset1:1
	ds_write2_b32 v12, v4, v5 offset0:2 offset1:3
	ds_write2_b32 v10, v6, v7 offset1:1
	ds_write2_b32 v10, v8, v9 offset0:2 offset1:3
	s_waitcnt lgkmcnt(0)
	s_barrier
	ds_read2_b32 v[2:3], v11 offset1:65
	ds_read2_b32 v[4:5], v11 offset0:130 offset1:195
	ds_read2_b32 v[6:7], v13 offset0:4 offset1:69
	ds_read2_b32 v[8:9], v13 offset0:134 offset1:199
	v_lshl_add_u64 v[10:11], v[14:15], 0, v[22:23]
	s_waitcnt lgkmcnt(3)
	v_cvt_pk_bf16_f32 v2, v2, v3
	s_waitcnt lgkmcnt(2)
	v_cvt_pk_bf16_f32 v3, v4, v5
	s_waitcnt lgkmcnt(1)
	v_cvt_pk_bf16_f32 v4, v6, v7
	s_waitcnt lgkmcnt(0)
	v_cvt_pk_bf16_f32 v5, v8, v9
	global_store_dwordx4 v[10:11], v[2:5], off
	s_waitcnt lgkmcnt(0)
	s_barrier

.LBB0_28:
	s_andn2_b64 vcc, exec, s[0:1]
	s_cbranch_vccnz .LBB0_30
	s_add_i32 s0, s22, 0xfffff0f8
	s_lshl_b32 s1, s0, 1
	s_lshl_b32 s0, s0, 6
	v_mov_b32_e32 v10, v224
	s_and_b32 s3, s0, 0x7c0
	v_readlane_b32 s60, v253, 32
	s_and_b32 s2, s1, 0x1ffc0
	v_lshlrev_b32_e32 v2, 4, v10
	s_lshl_b32 s0, s3, 2
	v_readlane_b32 s74, v253, 46
	v_ashrrev_i32_e32 v13, 4, v10
	v_and_b32_e32 v22, 0xf0, v2
	v_readlane_b32 s75, v253, 47
	s_add_u32 s0, s74, s0
	v_add_u32_e32 v2, s2, v13
	v_add_u32_e32 v8, 0x200, v10
	s_addc_u32 s1, s75, 0
	v_ashrrev_i32_e32 v3, 31, v2
	v_ashrrev_i32_e32 v16, 4, v8
	v_lshl_add_u64 v[6:7], s[0:1], 0, v[22:23]
	v_lshlrev_b64 v[2:3], 13, v[2:3]
	v_add_u32_e32 v8, s2, v16
	v_lshl_add_u64 v[2:3], v[6:7], 0, v[2:3]
	v_ashrrev_i32_e32 v9, 31, v8
	global_load_dwordx4 v[2:5], v[2:3], off
	v_lshlrev_b64 v[8:9], 13, v[8:9]
	v_lshl_add_u64 v[6:7], v[6:7], 0, v[8:9]
	global_load_dwordx4 v[6:9], v[6:7], off
	v_ashrrev_i32_e32 v11, 3, v10
	v_lshlrev_b32_e32 v10, 3, v10
	v_and_b32_e32 v17, 56, v10
	v_add_u32_e32 v12, 16, v22
	v_lshlrev_b32_e32 v18, 2, v11
	v_mul_u32_u24_e32 v19, 0x104, v17
	v_mad_u64_u32 v[14:15], s[0:1], v13, s51, v[12:13]
	v_mad_u64_u32 v[12:13], s[0:1], v16, s51, v[12:13]
	v_add_u32_e32 v10, s3, v11
	v_add3_u32 v13, 16, v19, v18
	v_ashrrev_i32_e32 v11, 31, v10
	v_add_u32_e32 v15, 0x400, v13
	v_readlane_b32 s0, v253, 8
	v_lshlrev_b64 v[10:11], 12, v[10:11]
	v_readlane_b32 s1, v253, 9
	s_lshl_b32 s18, s2, 1
	v_lshlrev_b32_e32 v22, 1, v17
	v_lshl_add_u64 v[10:11], s[0:1], 0, v[10:11]
	v_lshl_add_u64 v[10:11], v[10:11], 0, s[18:19]
	v_lshl_add_u64 v[10:11], v[10:11], 0, v[22:23]
	v_readlane_b32 s61, v253, 33
	v_readlane_b32 s62, v253, 34
	v_readlane_b32 s63, v253, 35
	v_readlane_b32 s64, v253, 36
	v_readlane_b32 s65, v253, 37
	v_readlane_b32 s66, v253, 38
	v_readlane_b32 s67, v253, 39
	v_readlane_b32 s68, v253, 40
	v_readlane_b32 s69, v253, 41
	v_readlane_b32 s70, v253, 42
	v_readlane_b32 s71, v253, 43
	v_readlane_b32 s72, v253, 44
	v_readlane_b32 s73, v253, 45
	s_waitcnt vmcnt(0)
	ds_write2_b32 v14, v2, v3 offset1:1
	ds_write2_b32 v14, v4, v5 offset0:2 offset1:3
	ds_write2_b32 v12, v6, v7 offset1:1
	ds_write2_b32 v12, v8, v9 offset0:2 offset1:3
	s_waitcnt lgkmcnt(0)
	s_barrier
	ds_read2_b32 v[2:3], v13 offset1:65
	ds_read2_b32 v[4:5], v13 offset0:130 offset1:195
	ds_read2_b32 v[6:7], v15 offset0:4 offset1:69
	ds_read2_b32 v[8:9], v15 offset0:134 offset1:199
	s_waitcnt lgkmcnt(3)
	v_cvt_pk_bf16_f32 v2, v2, v3
	s_waitcnt lgkmcnt(2)
	v_cvt_pk_bf16_f32 v3, v4, v5
	s_waitcnt lgkmcnt(1)
	v_cvt_pk_bf16_f32 v4, v6, v7
	s_waitcnt lgkmcnt(0)
	v_cvt_pk_bf16_f32 v5, v8, v9
	global_store_dwordx4 v[10:11], v[2:5], off
	s_waitcnt lgkmcnt(0)
	s_barrier

.LBB0_36:
	v_mad_u64_u32 v[6:7], s[0:1], v6, s51, v[10:11]
	s_waitcnt vmcnt(0)
	ds_write2_b32 v6, v2, v3 offset1:1
	ds_write2_b32 v6, v4, v5 offset0:2 offset1:3
	v_lshlrev_b32_e32 v2, 3, v11
	v_ashrrev_i32_e32 v10, 3, v11
	v_and_b32_e32 v11, 56, v2
	v_mul_u32_u24_e32 v2, 0x104, v11
	v_lshlrev_b32_e32 v3, 2, v10
	v_add3_u32 v6, 16, v2, v3
	s_waitcnt lgkmcnt(0)
	s_barrier
	ds_read2_b32 v[2:3], v6 offset1:65
	ds_read2_b32 v[4:5], v6 offset0:130 offset1:195
	v_add_u32_e32 v8, 0x400, v6
	ds_read2_b32 v[6:7], v8 offset0:4 offset1:69
	ds_read2_b32 v[8:9], v8 offset0:134 offset1:199
	s_lshl_b32 s3, s3, 6
	s_and_b32 s0, 0xffff, s3
	s_waitcnt lgkmcnt(3)
	v_cvt_pk_bf16_f32 v2, v2, v3
	s_waitcnt lgkmcnt(2)
	v_cvt_pk_bf16_f32 v3, v4, v5
	s_waitcnt lgkmcnt(1)
	v_cvt_pk_bf16_f32 v4, v6, v7
	v_add_u32_e32 v6, s0, v10
	v_ashrrev_i32_e32 v7, 31, v6
	v_lshlrev_b64 v[6:7], 12, v[6:7]
	v_lshl_add_u64 v[6:7], s[10:11], 0, v[6:7]
	s_lshl_b32 s18, s2, 1
	v_lshl_add_u64 v[6:7], v[6:7], 0, s[18:19]
	v_lshlrev_b32_e32 v22, 1, v11
	v_lshl_add_u64 v[6:7], v[6:7], 0, v[22:23]
	s_waitcnt lgkmcnt(0)
	v_cvt_pk_bf16_f32 v5, v8, v9
	global_store_dwordx4 v[6:7], v[2:5], off
	s_waitcnt lgkmcnt(0)
	s_barrier

.LBB0_46:
	v_lshl_add_u64 v[82:83], v[28:29], 0, s[2:3]
	v_add_co_u32_e32 v84, vcc, s58, v82
	v_mov_b32_e32 v22, s6
	s_nop 0
	v_addc_co_u32_e32 v85, vcc, 0, v83, vcc
	v_add_co_u32_e32 v86, vcc, s59, v82
	ds_read_b128 v[38:41], v22
	ds_read_b128 v[42:45], v22 offset:16
	v_addc_co_u32_e32 v87, vcc, 0, v83, vcc
	v_add_co_u32_e32 v90, vcc, s83, v82
	global_load_dwordx4 v[46:49], v[82:83], off
	s_nop 0
	v_addc_co_u32_e32 v91, vcc, 0, v83, vcc
	v_add_co_u32_e32 v94, vcc, s92, v82
	ds_read_b128 v[50:53], v22 offset:256
	ds_read_b128 v[54:57], v22 offset:272
	ds_read_b128 v[58:61], v22 offset:512
	ds_read_b128 v[62:65], v22 offset:528
	ds_read_b128 v[66:69], v22 offset:768
	ds_read_b128 v[70:73], v22 offset:784
	ds_read_b128 v[74:77], v22 offset:1024
	ds_read_b128 v[78:81], v22 offset:1040
	v_addc_co_u32_e32 v95, vcc, 0, v83, vcc
	v_add_co_u32_e32 v98, vcc, s93, v82
	s_waitcnt lgkmcnt(0)
	v_mov_b32_e32 v22, v41
	v_addc_co_u32_e32 v99, vcc, 0, v83, vcc
	v_add_co_u32_e32 v102, vcc, s94, v82
	v_mov_b32_e32 v24, v53
	s_nop 0
	v_addc_co_u32_e32 v103, vcc, 0, v83, vcc
	v_add_co_u32_e32 v106, vcc, s95, v82
	v_mov_b32_e32 v110, v61
	s_nop 0
	v_addc_co_u32_e32 v107, vcc, 0, v83, vcc
	global_load_dwordx4 v[82:85], v[84:85], off
	s_nop 0
	global_load_dwordx4 v[86:89], v[86:87], off
	s_nop 0
	global_load_dwordx4 v[90:93], v[90:91], off
	s_nop 0
	global_load_dwordx4 v[94:97], v[94:95], off
	s_nop 0
	global_load_dwordx4 v[98:101], v[98:99], off
	s_nop 0
	global_load_dwordx4 v[102:105], v[102:103], off
	s_nop 0
	global_load_dwordx4 v[106:109], v[106:107], off
	v_mov_b32_e32 v112, v69
	v_mov_b32_e32 v114, v77
	s_add_u32 s2, s2, 0x60000
	s_addc_u32 s3, s3, 0
	s_add_i32 s6, s6, 32
	v_mov_b32_e32 v116, v45
	v_mov_b32_e32 v118, v57
	v_mov_b32_e32 v120, v65
	v_mov_b32_e32 v122, v73
	v_mov_b32_e32 v124, v81
	s_cmp_lg_u32 s2, 0x300000
	s_waitcnt vmcnt(0)
	v_pk_fma_f32 v[18:19], v[46:47], v[38:39], v[18:19] op_sel_hi:[1,0,1]
	v_pk_fma_f32 v[20:21], v[48:49], v[38:39], v[20:21] op_sel_hi:[1,0,1]
	v_pk_fma_f32 v[14:15], v[46:47], v[50:51], v[14:15] op_sel_hi:[1,0,1]
	v_pk_fma_f32 v[16:17], v[48:49], v[50:51], v[16:17] op_sel_hi:[1,0,1]
	v_pk_fma_f32 v[10:11], v[46:47], v[58:59], v[10:11] op_sel_hi:[1,0,1]
	v_pk_fma_f32 v[12:13], v[48:49], v[58:59], v[12:13] op_sel_hi:[1,0,1]
	v_pk_fma_f32 v[6:7], v[46:47], v[66:67], v[6:7] op_sel_hi:[1,0,1]
	v_pk_fma_f32 v[8:9], v[48:49], v[66:67], v[8:9] op_sel_hi:[1,0,1]
	v_pk_fma_f32 v[2:3], v[46:47], v[74:75], v[2:3] op_sel_hi:[1,0,1]
	v_pk_fma_f32 v[4:5], v[48:49], v[74:75], v[4:5] op_sel_hi:[1,0,1]
	v_pk_fma_f32 v[18:19], v[82:83], v[38:39], v[18:19] op_sel:[0,1,0]
	v_pk_fma_f32 v[20:21], v[84:85], v[38:39], v[20:21] op_sel:[0,1,0]
	v_pk_fma_f32 v[14:15], v[82:83], v[50:51], v[14:15] op_sel:[0,1,0]
	v_pk_fma_f32 v[16:17], v[84:85], v[50:51], v[16:17] op_sel:[0,1,0]
	v_pk_fma_f32 v[10:11], v[82:83], v[58:59], v[10:11] op_sel:[0,1,0]
	v_pk_fma_f32 v[12:13], v[84:85], v[58:59], v[12:13] op_sel:[0,1,0]
	v_pk_fma_f32 v[6:7], v[82:83], v[66:67], v[6:7] op_sel:[0,1,0]
	v_pk_fma_f32 v[8:9], v[84:85], v[66:67], v[8:9] op_sel:[0,1,0]
	v_pk_fma_f32 v[2:3], v[82:83], v[74:75], v[2:3] op_sel:[0,1,0]
	v_pk_fma_f32 v[4:5], v[84:85], v[74:75], v[4:5] op_sel:[0,1,0]
	v_pk_fma_f32 v[18:19], v[86:87], v[40:41], v[18:19] op_sel_hi:[1,0,1]
	v_pk_fma_f32 v[20:21], v[88:89], v[40:41], v[20:21] op_sel_hi:[1,0,1]
	v_pk_fma_f32 v[14:15], v[86:87], v[52:53], v[14:15] op_sel_hi:[1,0,1]
	v_pk_fma_f32 v[16:17], v[88:89], v[52:53], v[16:17] op_sel_hi:[1,0,1]
	v_pk_fma_f32 v[10:11], v[86:87], v[60:61], v[10:11] op_sel_hi:[1,0,1]
	v_pk_fma_f32 v[12:13], v[88:89], v[60:61], v[12:13] op_sel_hi:[1,0,1]
	v_pk_fma_f32 v[6:7], v[86:87], v[68:69], v[6:7] op_sel_hi:[1,0,1]
	v_pk_fma_f32 v[8:9], v[88:89], v[68:69], v[8:9] op_sel_hi:[1,0,1]
	v_pk_fma_f32 v[2:3], v[86:87], v[76:77], v[2:3] op_sel_hi:[1,0,1]
	v_pk_fma_f32 v[4:5], v[88:89], v[76:77], v[4:5] op_sel_hi:[1,0,1]
	v_pk_fma_f32 v[18:19], v[90:91], v[22:23], v[18:19] op_sel_hi:[1,0,1]
	v_pk_fma_f32 v[20:21], v[92:93], v[22:23], v[20:21] op_sel_hi:[1,0,1]
	v_pk_fma_f32 v[14:15], v[90:91], v[24:25], v[14:15] op_sel_hi:[1,0,1]
	v_pk_fma_f32 v[16:17], v[92:93], v[24:25], v[16:17] op_sel_hi:[1,0,1]
	v_pk_fma_f32 v[10:11], v[90:91], v[110:111], v[10:11] op_sel_hi:[1,0,1]
	v_pk_fma_f32 v[12:13], v[92:93], v[110:111], v[12:13] op_sel_hi:[1,0,1]
	v_pk_fma_f32 v[6:7], v[90:91], v[112:113], v[6:7] op_sel_hi:[1,0,1]
	v_pk_fma_f32 v[8:9], v[92:93], v[112:113], v[8:9] op_sel_hi:[1,0,1]
	v_pk_fma_f32 v[2:3], v[90:91], v[114:115], v[2:3] op_sel_hi:[1,0,1]
	v_pk_fma_f32 v[4:5], v[92:93], v[114:115], v[4:5] op_sel_hi:[1,0,1]
	v_pk_fma_f32 v[18:19], v[94:95], v[42:43], v[18:19] op_sel_hi:[1,0,1]
	v_pk_fma_f32 v[20:21], v[96:97], v[42:43], v[20:21] op_sel_hi:[1,0,1]
	v_pk_fma_f32 v[14:15], v[94:95], v[54:55], v[14:15] op_sel_hi:[1,0,1]
	v_pk_fma_f32 v[16:17], v[96:97], v[54:55], v[16:17] op_sel_hi:[1,0,1]
	v_pk_fma_f32 v[10:11], v[94:95], v[62:63], v[10:11] op_sel_hi:[1,0,1]
	v_pk_fma_f32 v[12:13], v[96:97], v[62:63], v[12:13] op_sel_hi:[1,0,1]
	v_pk_fma_f32 v[6:7], v[94:95], v[70:71], v[6:7] op_sel_hi:[1,0,1]
	v_pk_fma_f32 v[8:9], v[96:97], v[70:71], v[8:9] op_sel_hi:[1,0,1]
	v_pk_fma_f32 v[2:3], v[94:95], v[78:79], v[2:3] op_sel_hi:[1,0,1]
	v_pk_fma_f32 v[4:5], v[96:97], v[78:79], v[4:5] op_sel_hi:[1,0,1]
	v_pk_fma_f32 v[18:19], v[98:99], v[42:43], v[18:19] op_sel:[0,1,0]
	v_pk_fma_f32 v[20:21], v[100:101], v[42:43], v[20:21] op_sel:[0,1,0]
	v_pk_fma_f32 v[14:15], v[98:99], v[54:55], v[14:15] op_sel:[0,1,0]
	v_pk_fma_f32 v[16:17], v[100:101], v[54:55], v[16:17] op_sel:[0,1,0]
	v_pk_fma_f32 v[10:11], v[98:99], v[62:63], v[10:11] op_sel:[0,1,0]
	v_pk_fma_f32 v[12:13], v[100:101], v[62:63], v[12:13] op_sel:[0,1,0]
	v_pk_fma_f32 v[6:7], v[98:99], v[70:71], v[6:7] op_sel:[0,1,0]
	v_pk_fma_f32 v[8:9], v[100:101], v[70:71], v[8:9] op_sel:[0,1,0]
	v_pk_fma_f32 v[2:3], v[98:99], v[78:79], v[2:3] op_sel:[0,1,0]
	v_pk_fma_f32 v[4:5], v[100:101], v[78:79], v[4:5] op_sel:[0,1,0]
	v_pk_fma_f32 v[18:19], v[102:103], v[44:45], v[18:19] op_sel_hi:[1,0,1]
	v_pk_fma_f32 v[20:21], v[104:105], v[44:45], v[20:21] op_sel_hi:[1,0,1]
	v_pk_fma_f32 v[14:15], v[102:103], v[56:57], v[14:15] op_sel_hi:[1,0,1]
	v_pk_fma_f32 v[16:17], v[104:105], v[56:57], v[16:17] op_sel_hi:[1,0,1]
	v_pk_fma_f32 v[10:11], v[102:103], v[64:65], v[10:11] op_sel_hi:[1,0,1]
	v_pk_fma_f32 v[12:13], v[104:105], v[64:65], v[12:13] op_sel_hi:[1,0,1]
	v_pk_fma_f32 v[6:7], v[102:103], v[72:73], v[6:7] op_sel_hi:[1,0,1]
	v_pk_fma_f32 v[8:9], v[104:105], v[72:73], v[8:9] op_sel_hi:[1,0,1]
	v_pk_fma_f32 v[2:3], v[102:103], v[80:81], v[2:3] op_sel_hi:[1,0,1]
	v_pk_fma_f32 v[4:5], v[104:105], v[80:81], v[4:5] op_sel_hi:[1,0,1]
	v_pk_fma_f32 v[18:19], v[106:107], v[116:117], v[18:19] op_sel_hi:[1,0,1]
	v_pk_fma_f32 v[20:21], v[108:109], v[116:117], v[20:21] op_sel_hi:[1,0,1]
	v_pk_fma_f32 v[14:15], v[106:107], v[118:119], v[14:15] op_sel_hi:[1,0,1]
	v_pk_fma_f32 v[16:17], v[108:109], v[118:119], v[16:17] op_sel_hi:[1,0,1]
	v_pk_fma_f32 v[10:11], v[106:107], v[120:121], v[10:11] op_sel_hi:[1,0,1]
	v_pk_fma_f32 v[12:13], v[108:109], v[120:121], v[12:13] op_sel_hi:[1,0,1]
	v_pk_fma_f32 v[6:7], v[106:107], v[122:123], v[6:7] op_sel_hi:[1,0,1]
	v_pk_fma_f32 v[8:9], v[108:109], v[122:123], v[8:9] op_sel_hi:[1,0,1]
	v_pk_fma_f32 v[2:3], v[106:107], v[124:125], v[2:3] op_sel_hi:[1,0,1]
	v_pk_fma_f32 v[4:5], v[108:109], v[124:125], v[4:5] op_sel_hi:[1,0,1]
	s_cbranch_scc1 .LBB0_46
	s_mul_i32 s4, s4, 0x78000
	s_add_u32 s2, s39, s4
	s_addc_u32 s3, s46, 0
	s_and_b64 s[0:1], s[0:1], exec
	s_cselect_b32 s0, 0x3c000, 0
	s_add_u32 s0, s2, s0
	s_addc_u32 s1, s3, 0
	s_lshl_b32 s2, s5, 2
	s_add_u32 s0, s0, s2
	s_addc_u32 s1, s1, 0
	v_lshl_add_u64 v[26:27], v[26:27], 2, s[0:1]
	global_store_dwordx4 v[26:27], v[18:21], off
	s_nop 1
	v_add_co_u32_e32 v18, vcc, s58, v26
	s_nop 1
	v_addc_co_u32_e32 v19, vcc, 0, v27, vcc
	global_store_dwordx4 v[18:19], v[14:17], off
	s_nop 1
	v_add_co_u32_e32 v14, vcc, s59, v26
	s_nop 1
	v_addc_co_u32_e32 v15, vcc, 0, v27, vcc
	global_store_dwordx4 v[14:15], v[10:13], off
	s_nop 1
	v_add_co_u32_e32 v10, vcc, 0x24000, v26
	s_nop 1
	v_addc_co_u32_e32 v11, vcc, 0, v27, vcc
	global_store_dwordx4 v[10:11], v[6:9], off
	s_nop 1
	v_add_co_u32_e32 v6, vcc, 0x30000, v26
	s_nop 1
	v_addc_co_u32_e32 v7, vcc, 0, v27, vcc
	global_store_dwordx4 v[6:7], v[2:5], off
	s_waitcnt lgkmcnt(0)
	s_barrier

.LBB0_83:
	s_add_i32 s23, s23, 1
	v_lshl_add_u64 v[4:5], v[4:5], 2, s[4:5]
	s_cmp_eq_u32 s23, 4
	global_store_dword v[4:5], v22, off
	s_cbranch_scc1 .LBB0_89

.LBB0_85:
	v_subrev_co_u32_e32 v83, vcc, 1, v84
	s_and_b64 s[6:7], s[2:3], vcc
	s_xor_b64 s[30:31], s[6:7], -1
	s_and_saveexec_b64 s[6:7], s[30:31]
	s_cbranch_execz .LBB0_87
	v_mov_b32_e32 v85, s28
	ds_read_b128 v[86:89], v85
	ds_read_b128 v[90:93], v85 offset:16
	ds_read_b128 v[94:97], v85 offset:32
	ds_read_b128 v[98:101], v85 offset:48
	s_add_i32 s30, s18, s29
	s_mov_b32 s31, 0x3fb8aa3b
	s_waitcnt lgkmcnt(0)
	v_fma_f32 v102, v18, v86, 0
	v_fmac_f32_e32 v102, v19, v87
	v_fmac_f32_e32 v102, v20, v88
	v_fmac_f32_e32 v102, v21, v89
	s_waitcnt lgkmcnt(2)
	v_fmac_f32_e32 v102, v24, v90
	v_fmac_f32_e32 v102, v26, v91
	v_fmac_f32_e32 v102, v27, v92
	v_fmac_f32_e32 v102, v28, v93
	s_waitcnt lgkmcnt(1)
	v_fmac_f32_e32 v102, v29, v94
	v_fmac_f32_e32 v102, v37, v95
	v_fmac_f32_e32 v102, v38, v96
	v_fmac_f32_e32 v102, v39, v97
	ds_read_b128 v[86:89], v85 offset:64
	ds_read_b128 v[90:93], v85 offset:80
	s_waitcnt lgkmcnt(2)
	v_fmac_f32_e32 v102, v40, v98
	v_fmac_f32_e32 v102, v41, v99
	v_fmac_f32_e32 v102, v42, v100
	v_fmac_f32_e32 v102, v43, v101
	s_waitcnt lgkmcnt(0)
	v_fmac_f32_e32 v102, v44, v86
	v_fmac_f32_e32 v102, v45, v87
	v_fmac_f32_e32 v102, v46, v88
	v_fmac_f32_e32 v102, v47, v89
	ds_read_b128 v[86:89], v85 offset:96
	s_waitcnt lgkmcnt(1)
	v_fmac_f32_e32 v102, v48, v90
	v_fmac_f32_e32 v102, v49, v91
	v_fmac_f32_e32 v102, v50, v92
	v_fmac_f32_e32 v102, v51, v93
	ds_read_b128 v[90:93], v85 offset:112
	s_waitcnt lgkmcnt(0)
	v_fmac_f32_e32 v102, v52, v86
	v_fmac_f32_e32 v102, v53, v87
	v_fmac_f32_e32 v102, v54, v88
	v_fmac_f32_e32 v102, v55, v89
	ds_read_b128 v[86:89], v85 offset:128
	s_waitcnt lgkmcnt(1)
	v_fmac_f32_e32 v102, v56, v90
	v_fmac_f32_e32 v102, v57, v91
	v_fmac_f32_e32 v102, v58, v92
	v_fmac_f32_e32 v102, v59, v93
	ds_read_b128 v[90:93], v85 offset:144
	s_waitcnt lgkmcnt(0)
	v_fmac_f32_e32 v102, v60, v86
	v_fmac_f32_e32 v102, v61, v87
	v_fmac_f32_e32 v102, v62, v88
	v_fmac_f32_e32 v102, v63, v89
	ds_read_b128 v[86:89], v85 offset:160
	s_waitcnt lgkmcnt(1)
	v_fmac_f32_e32 v102, v64, v90
	v_fmac_f32_e32 v102, v65, v91
	v_fmac_f32_e32 v102, v66, v92
	v_fmac_f32_e32 v102, v67, v93
	ds_read_b128 v[90:93], v85 offset:176
	s_waitcnt lgkmcnt(0)
	v_fmac_f32_e32 v102, v68, v86
	v_fmac_f32_e32 v102, v69, v87
	v_fmac_f32_e32 v102, v70, v88
	v_fmac_f32_e32 v102, v71, v89
	ds_read_b128 v[86:89], v85 offset:192
	s_waitcnt lgkmcnt(1)
	v_fmac_f32_e32 v102, v72, v90
	v_fmac_f32_e32 v102, v73, v91
	v_fmac_f32_e32 v102, v74, v92
	v_fmac_f32_e32 v102, v75, v93
	ds_read_b128 v[90:93], v85 offset:208
	s_waitcnt lgkmcnt(0)
	v_fmac_f32_e32 v102, v76, v86
	v_fmac_f32_e32 v102, v77, v87
	v_fmac_f32_e32 v102, v78, v88
	v_fmac_f32_e32 v102, v79, v89
	ds_read_b128 v[86:89], v85 offset:224
	s_waitcnt lgkmcnt(1)
	v_fmac_f32_e32 v102, v80, v90
	v_fmac_f32_e32 v102, v81, v91
	v_pk_mul_f32 v[90:91], v[8:9], v[92:93]
	s_nop 0
	v_add_f32_e32 v90, v102, v90
	v_add_f32_e32 v94, v90, v91
	ds_read_b128 v[90:93], v85 offset:240
	s_waitcnt lgkmcnt(0)
	v_pk_mul_f32 v[86:87], v[6:7], v[86:87]
	s_nop 0
	v_add_f32_e32 v85, v94, v86
	v_add_f32_e32 v85, v85, v87
	v_pk_mul_f32 v[86:87], v[10:11], v[88:89]
	v_cvt_f32_i32_e32 v88, s30
	v_add_f32_e32 v85, v85, v86
	v_add_f32_e32 v85, v85, v87
	s_waitcnt lgkmcnt(0)
	v_pk_mul_f32 v[86:87], v[12:13], v[90:91]
	v_div_scale_f32 v89, s[34:35], v3, v3, -v88
	v_rcp_f32_e32 v94, v89
	v_add_f32_e32 v85, v85, v86
	v_add_f32_e32 v85, v85, v87
	v_fma_f32 v86, -v89, v94, 1.0
	v_fmac_f32_e32 v94, v86, v94
	v_div_scale_f32 v86, vcc, -v88, v3, -v88
	v_mul_f32_e32 v87, v86, v94
	v_fma_f32 v90, -v89, v87, v86
	v_fmac_f32_e32 v87, v90, v94
	v_fma_f32 v86, -v89, v87, v86
	v_div_fmas_f32 v86, v86, v94, v87
	v_div_fixup_f32 v86, v86, v3, -v88
	v_mul_f32_e32 v88, v82, v86
	v_mul_f32_e32 v86, 0x3fb8aa3b, v88
	v_fma_f32 v87, v88, s31, -v86
	v_rndne_f32_e32 v89, v86
	v_fmac_f32_e32 v87, 0x32a5705f, v88
	v_sub_f32_e32 v86, v86, v89
	v_add_f32_e32 v86, v86, v87
	v_exp_f32_e32 v90, v86
	v_cvt_i32_f32_e32 v89, v89
	v_pk_mul_f32 v[86:87], v[14:15], v[92:93]
	s_mov_b32 s31, 0xc2ce8ed0
	v_add_f32_e32 v85, v85, v86
	v_ldexp_f32 v86, v90, v89
	v_cmp_ngt_f32_e32 vcc, s31, v88
	s_mov_b32 s31, 0x42b17218
	v_add_f32_e32 v85, v85, v87
	v_cndmask_b32_e32 v86, 0, v86, vcc
	v_cmp_nlt_f32_e32 vcc, s31, v88
	s_nop 1
	v_cndmask_b32_e32 v86, v32, v86, vcc
	v_mul_f32_e32 v85, v86, v85
	v_mov_b32_e32 v86, s30
	v_cndmask_b32_e64 v84, v84, v86, s[2:3]
	v_add_u32_e32 v84, s82, v84
	v_add_f32_e64 v22, v22, |v85|
	v_cvt_pk_bf16_f32 v86, v85, v23
	v_ashrrev_i32_e32 v85, 31, v84
	v_lshl_add_u64 v[84:85], v[84:85], 1, v[16:17]
	global_store_short v[84:85], v86, off

.LBB0_92:
	v_ashrrev_i32_e32 v13, 31, v4
	v_mov_b32_e32 v12, v4
	v_add_u32_e32 v10, -4, v10
	v_ashrrev_i32_e32 v15, 31, v5
	v_mov_b32_e32 v14, v5
	v_ashrrev_i32_e32 v17, 31, v6
	v_mov_b32_e32 v16, v6
	v_ashrrev_i32_e32 v19, 31, v7
	v_mov_b32_e32 v18, v7
	v_lshlrev_b64 v[12:13], s18, v[12:13]
	v_cmp_eq_u32_e32 vcc, 0, v10
	v_add_u32_e32 v7, 0x800, v7
	v_add_u32_e32 v6, 0x800, v6
	v_add_u32_e32 v5, 0x800, v5
	v_add_u32_e32 v4, 0x800, v4
	v_lshlrev_b64 v[18:19], s25, v[18:19]
	v_lshlrev_b64 v[16:17], s24, v[16:17]
	v_lshlrev_b64 v[14:15], s23, v[14:15]
	v_lshl_add_u64 v[12:13], v[12:13], 1, s[0:1]
	s_or_b64 s[6:7], vcc, s[6:7]
	v_lshl_add_u64 v[14:15], v[14:15], 1, s[0:1]
	v_lshl_add_u64 v[16:17], v[16:17], 1, s[0:1]
	v_lshl_add_u64 v[18:19], v[18:19], 1, s[0:1]
	global_store_short v[12:13], v23, off
	global_store_short v[14:15], v23, off
	global_store_short v[16:17], v23, off
	global_store_short v[18:19], v23, off
	s_andn2_b64 exec, exec, s[6:7]
	s_cbranch_execnz .LBB0_92
	s_or_b64 exec, exec, s[6:7]
	v_cmp_ne_u32_e32 vcc, v8, v9
	v_lshl_add_u32 v2, v9, 9, v2
	s_orn2_b64 s[6:7], vcc, exec

.LBB0_96:
	s_mov_b64 s[6:7], 0x200
	v_lshlrev_b64 v[6:7], s18, v[2:3]
	v_add_u32_e32 v4, 0x200, v4
	v_lshl_add_u64 v[2:3], v[2:3], 0, s[6:7]
	s_movk_i32 s6, 0x1ff
	v_cmp_lt_i32_e32 vcc, s6, v4
	v_lshl_add_u64 v[6:7], v[6:7], 1, s[0:1]
	s_or_b64 s[4:5], vcc, s[4:5]
	global_store_short v[6:7], v23, off
	s_andn2_b64 exec, exec, s[4:5]
	s_cbranch_execnz .LBB0_96
	s_branch .LBB0_16

.LBB0_111:
	v_cmp_lt_i32_e32 vcc, s19, v0
	s_and_saveexec_b64 s[12:13], vcc
	s_xor_b64 s[12:13], exec, s[12:13]
	s_cbranch_execz .LBB0_118
	v_cmp_lt_u32_e32 vcc, s20, v0
	s_and_saveexec_b64 s[14:15], vcc
	s_xor_b64 s[14:15], exec, s[14:15]
	s_cbranch_execz .LBB0_114
	v_and_b32_e32 v1, 0x3ff, v0
	v_lshlrev_b32_e32 v2, 2, v1
	v_lshl_add_u64 v[4:5], s[8:9], 0, v[2:3]
	v_add_co_u32_e32 v8, vcc, 0x100000, v4
	s_nop 1
	v_addc_co_u32_e32 v9, vcc, 0, v5, vcc
	v_add_co_u32_e32 v10, vcc, 0x101000, v4
	s_nop 1
	v_addc_co_u32_e32 v11, vcc, 0, v5, vcc
	v_add_co_u32_e32 v12, vcc, 0x102000, v4
	s_nop 1
	v_addc_co_u32_e32 v13, vcc, 0, v5, vcc
	v_add_co_u32_e32 v14, vcc, 0x103000, v4
	s_nop 1
	v_addc_co_u32_e32 v15, vcc, 0, v5, vcc
	v_add_co_u32_e32 v16, vcc, 0x104000, v4
	s_nop 1
	v_addc_co_u32_e32 v17, vcc, 0, v5, vcc
	v_add_co_u32_e32 v18, vcc, 0x105000, v4
	s_nop 1
	v_addc_co_u32_e32 v19, vcc, 0, v5, vcc
	v_add_co_u32_e32 v20, vcc, 0x106000, v4
	s_nop 1
	v_addc_co_u32_e32 v21, vcc, 0, v5, vcc
	v_add_co_u32_e32 v22, vcc, 0x107000, v4
	s_nop 1
	v_addc_co_u32_e32 v23, vcc, 0, v5, vcc
	global_load_dword v8, v[8:9], off
	s_nop 0
	global_load_dword v10, v[10:11], off
	s_nop 0
	global_load_dword v9, v[12:13], off
	global_load_dword v11, v[14:15], off
	s_nop 0
	global_load_dword v12, v[16:17], off
	global_load_dword v14, v[18:19], off
	global_load_dword v13, v[20:21], off
	global_load_dword v15, v[22:23], off
	v_add_co_u32_e32 v16, vcc, 0x108000, v4
	s_nop 1
	v_addc_co_u32_e32 v17, vcc, 0, v5, vcc
	v_add_co_u32_e32 v18, vcc, 0x109000, v4
	s_nop 1
	v_addc_co_u32_e32 v19, vcc, 0, v5, vcc
	v_add_co_u32_e32 v20, vcc, 0x10a000, v4
	s_nop 1
	v_addc_co_u32_e32 v21, vcc, 0, v5, vcc
	v_add_co_u32_e32 v22, vcc, 0x10b000, v4
	s_nop 1
	v_addc_co_u32_e32 v23, vcc, 0, v5, vcc
	v_add_co_u32_e32 v24, vcc, 0x10c000, v4
	s_nop 1
	v_addc_co_u32_e32 v25, vcc, 0, v5, vcc
	v_add_co_u32_e32 v26, vcc, 0x10d000, v4
	s_nop 1
	v_addc_co_u32_e32 v27, vcc, 0, v5, vcc
	v_add_co_u32_e32 v28, vcc, 0x10e000, v4
	s_nop 1
	v_addc_co_u32_e32 v29, vcc, 0, v5, vcc
	v_add_co_u32_e32 v4, vcc, 0x10f000, v4
	s_nop 1
	v_addc_co_u32_e32 v5, vcc, 0, v5, vcc
	global_load_dword v16, v[16:17], off
	s_nop 0
	global_load_dword v18, v[18:19], off
	s_nop 0
	global_load_dword v17, v[20:21], off
	global_load_dword v19, v[22:23], off
	s_nop 0
	global_load_dword v20, v[24:25], off
	global_load_dword v22, v[26:27], off
	global_load_dword v21, v[28:29], off
	global_load_dword v23, v[4:5], off
	s_waitcnt vmcnt(0) lgkmcnt(0)
	v_pk_add_f32 v[4:5], v[8:9], v[10:11]
	s_nop 0
	v_add_f32_e32 v1, 0, v4
	v_add_f32_e32 v1, v1, v5
	v_pk_add_f32 v[4:5], v[12:13], v[14:15]
	s_nop 0
	v_add_f32_e32 v1, v1, v4
	v_add_f32_e32 v1, v1, v5
	v_pk_add_f32 v[4:5], v[16:17], v[18:19]
	s_nop 0
	v_add_f32_e32 v1, v1, v4
	v_add_f32_e32 v1, v1, v5
	v_pk_add_f32 v[4:5], v[20:21], v[22:23]
	s_nop 0
	v_add_f32_e32 v1, v1, v4
	v_add_f32_e32 v2, v1, v5

.LBB0_116:
	v_lshl_add_u64 v[8:9], v[4:5], 0, s[16:17]
	v_add_co_u32_e32 v10, vcc, 0x7300000, v8
	s_add_u32 s16, s16, 0x20000
	s_nop 0
	v_addc_co_u32_e32 v11, vcc, 0, v9, vcc
	v_add_co_u32_e32 v12, vcc, 0x7301000, v8
	s_addc_u32 s17, s17, 0
	s_nop 0
	v_addc_co_u32_e32 v13, vcc, 0, v9, vcc
	v_add_co_u32_e32 v14, vcc, 0x7302000, v8
	global_load_dword v1, v[10:11], off
	global_load_dword v7, v[12:13], off
	v_addc_co_u32_e32 v15, vcc, 0, v9, vcc
	v_add_co_u32_e32 v10, vcc, 0x7303000, v8
	s_cmp_lg_u32 s16, 0x100000
	s_nop 0
	v_addc_co_u32_e32 v11, vcc, 0, v9, vcc
	v_add_co_u32_e32 v12, vcc, 0x7304000, v8
	global_load_dword v16, v[14:15], off
	global_load_dword v17, v[10:11], off
	v_addc_co_u32_e32 v13, vcc, 0, v9, vcc
	v_add_co_u32_e32 v10, vcc, 0x7305000, v8
	s_waitcnt vmcnt(0) lgkmcnt(0)
	v_add_f32_e32 v1, v1, v7
	v_addc_co_u32_e32 v11, vcc, 0, v9, vcc
	v_add_co_u32_e32 v14, vcc, 0x7306000, v8
	global_load_dword v18, v[12:13], off
	global_load_dword v19, v[10:11], off
	v_addc_co_u32_e32 v15, vcc, 0, v9, vcc
	v_add_co_u32_e32 v10, vcc, 0x7307000, v8
	v_add_f32_e32 v1, v2, v1
	s_nop 0
	v_addc_co_u32_e32 v11, vcc, 0, v9, vcc
	v_add_co_u32_e32 v12, vcc, 0x7308000, v8
	global_load_dword v20, v[14:15], off
	global_load_dword v21, v[10:11], off
	v_addc_co_u32_e32 v13, vcc, 0, v9, vcc
	v_add_co_u32_e32 v10, vcc, 0x7309000, v8
	v_add_f32_e32 v2, v16, v17
	s_nop 0
	v_addc_co_u32_e32 v11, vcc, 0, v9, vcc
	v_add_co_u32_e32 v14, vcc, 0x730a000, v8
	global_load_dword v22, v[12:13], off
	global_load_dword v23, v[10:11], off
	v_addc_co_u32_e32 v15, vcc, 0, v9, vcc
	v_add_co_u32_e32 v10, vcc, 0x730b000, v8
	v_add_f32_e32 v1, v1, v2
	s_nop 0
	v_addc_co_u32_e32 v11, vcc, 0, v9, vcc
	v_add_co_u32_e32 v12, vcc, 0x730c000, v8
	global_load_dword v24, v[14:15], off
	global_load_dword v25, v[10:11], off
	v_addc_co_u32_e32 v13, vcc, 0, v9, vcc
	v_add_co_u32_e32 v10, vcc, 0x730d000, v8
	s_waitcnt vmcnt(0) lgkmcnt(0)
	v_add_f32_e32 v2, v18, v19
	v_addc_co_u32_e32 v11, vcc, 0, v9, vcc
	v_add_co_u32_e32 v14, vcc, 0x730e000, v8
	global_load_dword v26, v[12:13], off
	global_load_dword v27, v[10:11], off
	v_addc_co_u32_e32 v15, vcc, 0, v9, vcc
	v_add_co_u32_e32 v10, vcc, 0x730f000, v8
	v_add_f32_e32 v1, v1, v2
	s_nop 0
	v_addc_co_u32_e32 v11, vcc, 0, v9, vcc
	v_add_co_u32_e32 v12, vcc, 0x7310000, v8
	global_load_dword v28, v[14:15], off
	global_load_dword v29, v[10:11], off
	v_addc_co_u32_e32 v13, vcc, 0, v9, vcc
	v_add_co_u32_e32 v10, vcc, 0x7311000, v8
	v_add_f32_e32 v2, v20, v21
	s_nop 0
	v_addc_co_u32_e32 v11, vcc, 0, v9, vcc
	v_add_co_u32_e32 v14, vcc, 0x7312000, v8
	global_load_dword v30, v[12:13], off
	global_load_dword v31, v[10:11], off
	v_addc_co_u32_e32 v15, vcc, 0, v9, vcc
	v_add_co_u32_e32 v10, vcc, 0x7313000, v8
	v_add_f32_e32 v1, v1, v2
	s_nop 0
	v_addc_co_u32_e32 v11, vcc, 0, v9, vcc
	v_add_co_u32_e32 v12, vcc, 0x7314000, v8
	global_load_dword v32, v[14:15], off
	global_load_dword v33, v[10:11], off
	v_addc_co_u32_e32 v13, vcc, 0, v9, vcc
	v_add_co_u32_e32 v10, vcc, 0x7315000, v8
	v_add_f32_e32 v2, v22, v23
	s_nop 0
	v_addc_co_u32_e32 v11, vcc, 0, v9, vcc
	v_add_co_u32_e32 v14, vcc, 0x7316000, v8
	global_load_dword v34, v[12:13], off
	global_load_dword v35, v[10:11], off
	v_addc_co_u32_e32 v15, vcc, 0, v9, vcc
	v_add_co_u32_e32 v10, vcc, 0x7317000, v8
	v_add_f32_e32 v1, v1, v2
	s_nop 0
	v_addc_co_u32_e32 v11, vcc, 0, v9, vcc
	v_add_co_u32_e32 v12, vcc, 0x7318000, v8
	global_load_dword v36, v[14:15], off
	global_load_dword v37, v[10:11], off
	v_addc_co_u32_e32 v13, vcc, 0, v9, vcc
	v_add_co_u32_e32 v10, vcc, 0x7319000, v8
	v_add_f32_e32 v2, v24, v25
	s_nop 0
	v_addc_co_u32_e32 v11, vcc, 0, v9, vcc
	v_add_co_u32_e32 v14, vcc, 0x731a000, v8
	global_load_dword v38, v[12:13], off
	global_load_dword v39, v[10:11], off
	v_addc_co_u32_e32 v15, vcc, 0, v9, vcc
	v_add_co_u32_e32 v10, vcc, 0x731b000, v8
	v_add_f32_e32 v1, v1, v2
	s_nop 0
	v_addc_co_u32_e32 v11, vcc, 0, v9, vcc
	v_add_co_u32_e32 v12, vcc, 0x731c000, v8
	global_load_dword v40, v[14:15], off
	global_load_dword v41, v[10:11], off
	v_addc_co_u32_e32 v13, vcc, 0, v9, vcc
	v_add_co_u32_e32 v10, vcc, 0x731d000, v8
	s_waitcnt vmcnt(0) lgkmcnt(0)
	v_add_f32_e32 v2, v26, v27
	v_addc_co_u32_e32 v11, vcc, 0, v9, vcc
	v_add_co_u32_e32 v14, vcc, 0x731e000, v8
	global_load_dword v12, v[12:13], off
	s_nop 0
	global_load_dword v10, v[10:11], off
	v_addc_co_u32_e32 v15, vcc, 0, v9, vcc
	v_add_co_u32_e32 v8, vcc, 0x731f000, v8
	v_add_f32_e32 v1, v1, v2
	s_nop 0
	v_addc_co_u32_e32 v9, vcc, 0, v9, vcc
	global_load_dword v11, v[14:15], off
	s_nop 0
	global_load_dword v8, v[8:9], off
	v_add_f32_e32 v2, v28, v29
	v_add_f32_e32 v1, v1, v2
	v_add_f32_e32 v2, v30, v31
	v_add_f32_e32 v1, v1, v2
	v_add_f32_e32 v2, v32, v33
	v_add_f32_e32 v1, v1, v2
	v_add_f32_e32 v2, v34, v35
	v_add_f32_e32 v1, v1, v2
	v_add_f32_e32 v2, v36, v37
	v_add_f32_e32 v1, v1, v2
	v_add_f32_e32 v2, v38, v39
	v_add_f32_e32 v1, v1, v2
	v_add_f32_e32 v2, v40, v41
	v_add_f32_e32 v1, v1, v2
	s_waitcnt vmcnt(0) lgkmcnt(0)
	v_add_f32_e32 v2, v12, v10
	v_add_f32_e32 v1, v1, v2
	v_add_f32_e32 v2, v11, v8
	v_add_f32_e32 v2, v1, v2
	s_cbranch_scc1 .LBB0_116
.LBB0_117:
	s_or_b64 exec, exec, s[14:15]
	v_mov_b32_e32 v1, v3
	v_lshl_add_u64 v[4:5], v[0:1], 2, s[0:1]
	v_add_co_u32_e32 v4, vcc, 0x30034000, v4
	s_nop 1
	v_addc_co_u32_e32 v5, vcc, 0, v5, vcc
	global_store_dword v[4:5], v2, off offset:1536
.LBB0_118:
	s_andn2_saveexec_b64 s[12:13], s[12:13]
	s_cbranch_execz .LBB0_110
	v_ashrrev_i32_e32 v1, 31, v0
	v_lshlrev_b64 v[4:5], 2, v[0:1]
	v_lshl_add_u64 v[8:9], s[4:5], 0, v[4:5]
	v_add_co_u32_e32 v10, vcc, 0x78000, v8
	v_lshl_add_u64 v[4:5], s[6:7], 0, v[4:5]
	s_nop 0
	v_addc_co_u32_e32 v11, vcc, 0, v9, vcc
	v_add_co_u32_e32 v12, vcc, 0xf0000, v8
	s_nop 1
	v_addc_co_u32_e32 v13, vcc, 0, v9, vcc
	v_add_co_u32_e32 v14, vcc, 0x168000, v8
	s_nop 1
	v_addc_co_u32_e32 v15, vcc, 0, v9, vcc
	v_add_co_u32_e32 v16, vcc, 0x1e0000, v8
	s_nop 1
	v_addc_co_u32_e32 v17, vcc, 0, v9, vcc
	v_add_co_u32_e32 v18, vcc, 0x258000, v8
	s_nop 1
	v_addc_co_u32_e32 v19, vcc, 0, v9, vcc
	v_add_co_u32_e32 v20, vcc, 0x2d0000, v8
	s_nop 1
	v_addc_co_u32_e32 v21, vcc, 0, v9, vcc
	v_add_co_u32_e32 v22, vcc, 0x348000, v8
	s_nop 1
	v_addc_co_u32_e32 v23, vcc, 0, v9, vcc
	global_load_dword v1, v[8:9], off
	global_load_dword v2, v[10:11], off
	global_load_dword v7, v[12:13], off
	global_load_dword v26, v[14:15], off
	global_load_dword v27, v[16:17], off
	global_load_dword v28, v[18:19], off
	global_load_dword v29, v[20:21], off
	global_load_dword v30, v[22:23], off
	v_add_co_u32_e32 v10, vcc, 0x3c0000, v8
	s_waitcnt vmcnt(0) lgkmcnt(0)
	v_add_f32_e32 v1, 0, v1
	v_addc_co_u32_e32 v11, vcc, 0, v9, vcc
	v_add_co_u32_e32 v12, vcc, 0x438000, v8
	v_add_f32_e32 v1, v1, v2
	s_nop 0
	v_addc_co_u32_e32 v13, vcc, 0, v9, vcc
	v_add_co_u32_e32 v14, vcc, 0x4b0000, v8
	v_add_f32_e32 v1, v1, v7
	s_nop 0
	v_addc_co_u32_e32 v15, vcc, 0, v9, vcc
	v_add_co_u32_e32 v16, vcc, 0x528000, v8
	v_add_f32_e32 v1, v1, v26
	s_nop 0
	v_addc_co_u32_e32 v17, vcc, 0, v9, vcc
	v_add_co_u32_e32 v18, vcc, 0x5a0000, v8
	v_add_f32_e32 v1, v1, v27
	s_nop 0
	v_addc_co_u32_e32 v19, vcc, 0, v9, vcc
	v_add_co_u32_e32 v20, vcc, 0x618000, v8
	v_add_f32_e32 v1, v1, v28
	s_nop 0
	v_addc_co_u32_e32 v21, vcc, 0, v9, vcc
	v_add_co_u32_e32 v22, vcc, 0x690000, v8
	v_add_f32_e32 v1, v1, v29
	s_nop 0
	v_addc_co_u32_e32 v23, vcc, 0, v9, vcc
	v_add_co_u32_e32 v24, vcc, 0x708000, v8
	v_add_f32_e32 v1, v1, v30
	s_nop 0
	v_addc_co_u32_e32 v25, vcc, 0, v9, vcc
	global_load_dword v31, v[10:11], off
	global_load_dword v32, v[12:13], off
	global_load_dword v33, v[14:15], off
	global_load_dword v34, v[16:17], off
	global_load_dword v35, v[18:19], off
	global_load_dword v36, v[20:21], off
	global_load_dword v37, v[22:23], off
	global_load_dword v38, v[24:25], off
	v_add_co_u32_e32 v10, vcc, 0x780000, v8
	s_waitcnt vmcnt(0) lgkmcnt(0)
	v_add_f32_e32 v1, v1, v31
	v_addc_co_u32_e32 v11, vcc, 0, v9, vcc
	v_add_co_u32_e32 v12, vcc, 0x7f8000, v8
	v_add_f32_e32 v1, v1, v32
	s_nop 0
	v_addc_co_u32_e32 v13, vcc, 0, v9, vcc
	v_add_co_u32_e32 v14, vcc, 0x870000, v8
	v_add_f32_e32 v1, v1, v33
	s_nop 0
	v_addc_co_u32_e32 v15, vcc, 0, v9, vcc
	v_add_co_u32_e32 v16, vcc, 0x8e8000, v8
	v_add_f32_e32 v1, v1, v34
	s_nop 0
	v_addc_co_u32_e32 v17, vcc, 0, v9, vcc
	v_add_co_u32_e32 v18, vcc, 0x960000, v8
	v_add_f32_e32 v1, v1, v35
	s_nop 0
	v_addc_co_u32_e32 v19, vcc, 0, v9, vcc
	v_add_co_u32_e32 v20, vcc, 0x9d8000, v8
	v_add_f32_e32 v1, v1, v36
	s_nop 0
	v_addc_co_u32_e32 v21, vcc, 0, v9, vcc
	v_add_co_u32_e32 v22, vcc, 0xa50000, v8
	v_add_f32_e32 v1, v1, v37
	s_nop 0
	v_addc_co_u32_e32 v23, vcc, 0, v9, vcc
	v_add_co_u32_e32 v24, vcc, 0xac8000, v8
	v_add_f32_e32 v1, v1, v38
	s_nop 0
	v_addc_co_u32_e32 v25, vcc, 0, v9, vcc
	global_load_dword v39, v[10:11], off
	global_load_dword v40, v[12:13], off
	global_load_dword v41, v[14:15], off
	global_load_dword v42, v[16:17], off
	global_load_dword v43, v[18:19], off
	global_load_dword v44, v[20:21], off
	global_load_dword v45, v[22:23], off
	s_nop 0
	global_load_dword v24, v[24:25], off
	v_add_co_u32_e32 v10, vcc, 0xb40000, v8
	s_waitcnt vmcnt(0) lgkmcnt(0)
	v_add_f32_e32 v1, v1, v39
	v_addc_co_u32_e32 v11, vcc, 0, v9, vcc
	v_add_co_u32_e32 v12, vcc, 0xbb8000, v8
	v_add_f32_e32 v1, v1, v40
	s_nop 0
	v_addc_co_u32_e32 v13, vcc, 0, v9, vcc
	v_add_co_u32_e32 v14, vcc, 0xc30000, v8
	v_add_f32_e32 v1, v1, v41
	s_nop 0
	v_addc_co_u32_e32 v15, vcc, 0, v9, vcc
	v_add_co_u32_e32 v16, vcc, 0xca8000, v8
	v_add_f32_e32 v1, v1, v42
	s_nop 0
	v_addc_co_u32_e32 v17, vcc, 0, v9, vcc
	v_add_co_u32_e32 v18, vcc, 0xd20000, v8
	v_add_f32_e32 v1, v1, v43
	s_nop 0
	v_addc_co_u32_e32 v19, vcc, 0, v9, vcc
	v_add_co_u32_e32 v20, vcc, 0xd98000, v8
	v_add_f32_e32 v1, v1, v44
	s_nop 0
	v_addc_co_u32_e32 v21, vcc, 0, v9, vcc
	v_add_co_u32_e32 v22, vcc, 0xe10000, v8
	v_add_f32_e32 v1, v1, v45
	s_nop 0
	v_addc_co_u32_e32 v23, vcc, 0, v9, vcc
	v_add_co_u32_e32 v8, vcc, 0xe88000, v8
	v_add_f32_e32 v1, v1, v24
	s_nop 0
	v_addc_co_u32_e32 v9, vcc, 0, v9, vcc
	global_load_dword v10, v[10:11], off
	s_nop 0
	global_load_dword v11, v[12:13], off
	s_nop 0
	global_load_dword v12, v[14:15], off
	global_load_dword v13, v[16:17], off
	s_nop 0
	global_load_dword v14, v[18:19], off
	global_load_dword v15, v[20:21], off
	global_load_dword v16, v[22:23], off
	s_nop 0
	global_load_dword v8, v[8:9], off
	s_waitcnt vmcnt(0) lgkmcnt(0)
	v_add_f32_e32 v1, v1, v10
	v_add_f32_e32 v1, v1, v11
	v_add_f32_e32 v1, v1, v12
	v_add_f32_e32 v1, v1, v13
	v_add_f32_e32 v1, v1, v14
	v_add_f32_e32 v1, v1, v15
	v_add_f32_e32 v1, v1, v16
	v_add_f32_e32 v1, v1, v8
	global_store_dword v[4:5], v1, off
	s_branch .LBB0_110

.LBB0_169:
	s_waitcnt vmcnt(0) lgkmcnt(0)
	v_pk_mul_f32 v[156:157], v[28:29], v[28:29]
	v_pk_mul_f32 v[178:179], v[24:25], v[24:25]
	v_pk_mul_f32 v[158:159], v[30:31], v[30:31]
	v_pk_mul_f32 v[180:181], v[26:27], v[26:27]
	v_add_f32_e32 v35, v178, v179
	v_add_f32_e32 v81, v156, v157
	v_add_f32_e32 v35, v35, v180
	v_add_f32_e32 v81, v81, v158
	v_pk_mul_f32 v[182:183], v[20:21], v[20:21]
	v_add_f32_e32 v35, v35, v181
	v_add_f32_e32 v81, v81, v159
	v_pk_mul_f32 v[184:185], v[22:23], v[22:23]
	v_add_f32_e32 v35, v81, v35
	v_add_f32_e32 v81, v182, v183
	v_add_f32_e32 v81, v81, v184
	v_pk_mul_f32 v[186:187], v[12:13], v[12:13]
	v_add_f32_e32 v81, v81, v185
	v_pk_mul_f32 v[188:189], v[14:15], v[14:15]
	v_add_f32_e32 v35, v35, v81
	v_add_f32_e32 v81, v186, v187
	v_add_f32_e32 v81, v81, v188
	v_pk_mul_f32 v[190:191], v[16:17], v[16:17]
	v_add_f32_e32 v81, v81, v189
	v_pk_mul_f32 v[192:193], v[18:19], v[18:19]
	v_add_f32_e32 v35, v35, v81
	v_add_f32_e32 v81, v190, v191
	v_add_f32_e32 v81, v81, v192
	v_pk_mul_f32 v[194:195], v[4:5], v[4:5]
	v_add_f32_e32 v81, v81, v193
	v_pk_mul_f32 v[196:197], v[6:7], v[6:7]
	v_add_f32_e32 v35, v35, v81
	v_add_f32_e32 v81, v194, v195
	v_add_f32_e32 v81, v81, v196
	v_pk_mul_f32 v[198:199], v[8:9], v[8:9]
	v_add_f32_e32 v81, v81, v197
	v_pk_mul_f32 v[200:201], v[10:11], v[10:11]
	v_add_f32_e32 v35, v35, v81
	v_add_f32_e32 v81, v198, v199
	v_add_f32_e32 v81, v81, v200
	v_pk_mul_f32 v[202:203], v[0:1], v[0:1]
	v_add_f32_e32 v81, v81, v201
	v_pk_mul_f32 v[204:205], v[2:3], v[2:3]
	v_add_f32_e32 v35, v35, v81
	v_add_f32_e32 v81, v202, v203
	v_add_f32_e32 v81, v81, v204
	v_add_f32_e32 v81, v81, v205
	v_add_f32_e32 v35, v35, v81
	ds_bpermute_b32 v81, v172, v35
	s_add_u32 s16, s16, 0x2000
	s_addc_u32 s17, s17, 0
	v_add_u32_e32 v34, 1, v34
	s_mov_b64 s[0:1], 0x1000
	s_waitcnt lgkmcnt(0)
	v_add_f32_e32 v35, v35, v81
	ds_bpermute_b32 v81, v173, v35
	s_add_u32 s8, s8, 0x2000
	s_addc_u32 s9, s9, 0
	s_waitcnt lgkmcnt(0)
	v_add_f32_e32 v35, v35, v81
	ds_bpermute_b32 v81, v174, v35
	s_waitcnt lgkmcnt(0)
	v_add_f32_e32 v35, v35, v81
	ds_bpermute_b32 v81, v175, v35
	s_waitcnt lgkmcnt(0)
	v_add_f32_e32 v35, v35, v81
	ds_bpermute_b32 v81, v176, v35
	s_waitcnt lgkmcnt(0)
	v_add_f32_e32 v35, v35, v81
	ds_bpermute_b32 v81, v177, v35
	s_waitcnt lgkmcnt(0)
	v_add_f32_e32 v35, v35, v81
	v_fmamk_f32 v35, v35, 0x3a000000, v225
	v_mul_f32_e32 v81, 0x4b800000, v35
	v_cmp_gt_f32_e32 vcc, s33, v35
	s_nop 1
	v_cndmask_b32_e32 v35, v35, v81, vcc
	v_rsq_f32_e32 v35, v35
	s_nop 0
	v_mul_f32_e32 v81, 0x45800000, v35
	v_cndmask_b32_e32 v35, v35, v81, vcc
	v_mul_f32_e32 v12, v12, v35
	v_mul_f32_e32 v13, v13, v35
	v_mul_f32_e32 v4, v4, v35
	v_mul_f32_e32 v5, v5, v35
	v_fma_f32 v12, v130, v12, v128
	v_fma_f32 v13, v131, v13, v129
	v_fma_f32 v4, v146, v4, v144
	v_fma_f32 v5, v147, v5, v145
	v_cvt_pk_bf16_f32 v12, v12, v13
	v_mul_f32_e32 v13, v14, v35
	v_cvt_pk_bf16_f32 v4, v4, v5
	v_mul_f32_e32 v5, v6, v35
	v_fma_f32 v13, v132, v13, v126
	v_mul_f32_e32 v14, v15, v35
	v_fma_f32 v5, v148, v5, v142
	v_mul_f32_e32 v6, v7, v35
	v_fma_f32 v14, v133, v14, v127
	v_cvt_pk_bf16_f32 v13, v13, v14
	v_fma_f32 v6, v149, v6, v143
	v_cvt_pk_bf16_f32 v5, v5, v6
	v_mul_f32_e32 v28, v28, v35
	v_mul_f32_e32 v29, v29, v35
	v_mul_f32_e32 v24, v24, v35
	v_mul_f32_e32 v25, v25, v35
	v_mul_f32_e32 v20, v20, v35
	v_mul_f32_e32 v21, v21, v35
	global_store_dwordx2 v[74:75], v[12:13], off offset:1536
	v_mul_f32_e32 v12, v16, v35
	v_mul_f32_e32 v13, v17, v35
	global_store_dwordx2 v[74:75], v[4:5], off offset:2560
	v_mul_f32_e32 v4, v8, v35
	v_mul_f32_e32 v5, v9, v35
	v_mul_f32_e32 v0, v0, v35
	v_mul_f32_e32 v1, v1, v35
	v_fma_f32 v28, v102, v28, v106
	v_fma_f32 v29, v103, v29, v107
	v_fma_f32 v24, v114, v24, v112
	v_fma_f32 v25, v115, v25, v113
	v_fma_f32 v20, v122, v20, v120
	v_fma_f32 v21, v123, v21, v121
	v_fma_f32 v12, v138, v12, v136
	v_fma_f32 v13, v139, v13, v137
	v_fma_f32 v4, v160, v4, v152
	v_fma_f32 v5, v161, v5, v153
	v_fma_f32 v0, v168, v0, v166
	v_fma_f32 v1, v169, v1, v167
	v_cvt_pk_bf16_f32 v28, v28, v29
	v_mul_f32_e32 v29, v30, v35
	v_cvt_pk_bf16_f32 v24, v24, v25
	v_mul_f32_e32 v25, v26, v35
	v_cvt_pk_bf16_f32 v20, v20, v21
	v_mul_f32_e32 v21, v22, v35
	v_cvt_pk_bf16_f32 v12, v12, v13
	v_mul_f32_e32 v13, v18, v35
	v_cvt_pk_bf16_f32 v4, v4, v5
	v_mul_f32_e32 v5, v10, v35
	v_cvt_pk_bf16_f32 v0, v0, v1
	v_mul_f32_e32 v1, v2, v35
	v_fma_f32 v29, v108, v29, v104
	v_mul_f32_e32 v30, v31, v35
	v_fma_f32 v25, v116, v25, v110
	v_mul_f32_e32 v26, v27, v35
	v_fma_f32 v21, v124, v21, v118
	v_mul_f32_e32 v22, v23, v35
	v_fma_f32 v13, v140, v13, v134
	v_mul_f32_e32 v14, v19, v35
	v_fma_f32 v5, v162, v5, v150
	v_mul_f32_e32 v6, v11, v35
	v_fma_f32 v1, v170, v1, v164
	v_mul_f32_e32 v2, v3, v35
	v_fma_f32 v30, v109, v30, v105
	v_cvt_pk_bf16_f32 v29, v29, v30
	global_store_dwordx2 v[74:75], v[28:29], off
	v_fma_f32 v26, v117, v26, v111
	v_cvt_pk_bf16_f32 v25, v25, v26
	global_store_dwordx2 v[74:75], v[24:25], off offset:512
	v_fma_f32 v22, v125, v22, v119
	v_cvt_pk_bf16_f32 v21, v21, v22
	global_store_dwordx2 v[74:75], v[20:21], off offset:1024
	v_fma_f32 v14, v141, v14, v135
	v_cvt_pk_bf16_f32 v13, v13, v14
	global_store_dwordx2 v[74:75], v[12:13], off offset:2048
	v_fma_f32 v6, v163, v6, v151
	v_cvt_pk_bf16_f32 v5, v5, v6
	global_store_dwordx2 v[74:75], v[4:5], off offset:3072
	v_fma_f32 v2, v171, v2, v165
	v_cvt_pk_bf16_f32 v1, v1, v2
	global_store_dwordx2 v[74:75], v[0:1], off offset:3584
	v_lshl_add_u64 v[74:75], v[74:75], 0, s[0:1]
	v_cmp_ge_i32_e32 vcc, v34, v155
	s_mov_b64 s[0:1], 0x2000
	s_or_b64 s[14:15], vcc, s[14:15]
	v_lshl_add_u64 v[76:77], v[76:77], 0, s[0:1]
	s_andn2_b64 exec, exec, s[14:15]
	s_cbranch_execz .LBB0_181
.LBB0_170:
	v_add_u32_e32 v12, 0xffffe000, v34
	s_movk_i32 s0, 0x1fff
	v_lshrrev_b32_e32 v0, 12, v12
	v_cmp_lt_i32_e64 s[2:3], s0, v34
	s_nop 1
	v_cndmask_b32_e64 v13, 4, v0, s[2:3]
	v_cmp_ne_u32_e32 vcc, v13, v79
	s_and_saveexec_b64 s[0:1], vcc
	s_cbranch_execz .LBB0_172
	v_mov_b64_e32 v[0:1], s[12:13]
	s_mov_b32 s18, 0xc000
	v_mad_u64_u32 v[0:1], s[18:19], v13, s18, v[0:1]
	s_mov_b64 s[18:19], 0x2000
	v_mov_b32_e32 v79, v33
	v_lshl_add_u64 v[8:9], v[0:1], 0, s[18:19]
	v_lshl_add_u64 v[6:7], v[0:1], 0, v[78:79]
	global_load_dwordx4 v[2:5], v[6:7], off
	global_load_dwordx4 v[14:17], v[38:39], off
	v_lshl_add_u64 v[10:11], v[8:9], 0, v[78:79]
	global_load_dwordx4 v[18:21], v[36:37], off
	global_load_dwordx4 v[22:25], v[10:11], off
	global_load_dwordx4 v[26:29], v[40:41], off
	v_mov_b32_e32 v81, v33
	v_mov_b32_e32 v83, v33
	v_mov_b32_e32 v85, v33
	v_mov_b32_e32 v87, v33
	v_mov_b32_e32 v89, v33
	v_mov_b32_e32 v91, v33
	v_mov_b32_e32 v93, v33
	v_mov_b32_e32 v79, v13
	s_waitcnt vmcnt(0) lgkmcnt(0)
	v_pk_add_f32 v[106:107], v[2:3], v[14:15]
	v_pk_add_f32 v[10:11], v[22:23], 1.0 op_sel_hi:[1,0]
	v_pk_add_f32 v[104:105], v[4:5], v[16:17]
	v_pk_add_f32 v[10:11], v[10:11], v[26:27]
	global_load_dwordx4 v[2:5], v[6:7], off offset:1024
	global_load_dwordx4 v[14:17], v[38:39], off offset:1024
	v_pk_mul_f32 v[102:103], v[18:19], v[10:11]
	v_pk_add_f32 v[10:11], v[24:25], 1.0 op_sel_hi:[1,0]
	s_waitcnt vmcnt(0) lgkmcnt(0)
	v_pk_add_f32 v[112:113], v[2:3], v[14:15]
	v_pk_add_f32 v[10:11], v[10:11], v[28:29]
	v_pk_add_f32 v[110:111], v[4:5], v[16:17]
	v_pk_mul_f32 v[108:109], v[20:21], v[10:11]
	v_lshl_add_u64 v[10:11], v[8:9], 0, v[80:81]
	global_load_dwordx4 v[18:21], v[36:37], off offset:1024
	global_load_dwordx4 v[22:25], v[10:11], off
	global_load_dwordx4 v[26:29], v[42:43], off
	global_load_dwordx4 v[2:5], v[6:7], off offset:2048
	global_load_dwordx4 v[14:17], v[38:39], off offset:2048
	s_waitcnt vmcnt(0) lgkmcnt(0)
	v_pk_add_f32 v[10:11], v[22:23], 1.0 op_sel_hi:[1,0]
	s_nop 0
	v_pk_add_f32 v[10:11], v[10:11], v[26:27]
	v_pk_add_f32 v[120:121], v[2:3], v[14:15]
	v_pk_mul_f32 v[114:115], v[18:19], v[10:11]
	v_pk_add_f32 v[10:11], v[24:25], 1.0 op_sel_hi:[1,0]
	v_pk_add_f32 v[118:119], v[4:5], v[16:17]
	v_pk_add_f32 v[10:11], v[10:11], v[28:29]
	s_nop 0
	v_pk_mul_f32 v[116:117], v[20:21], v[10:11]
	v_lshl_add_u64 v[10:11], v[8:9], 0, v[82:83]
	global_load_dwordx4 v[18:21], v[36:37], off offset:2048
	global_load_dwordx4 v[22:25], v[10:11], off
	global_load_dwordx4 v[26:29], v[44:45], off
	global_load_dwordx4 v[2:5], v[6:7], off offset:3072
	global_load_dwordx4 v[14:17], v[38:39], off offset:3072
	v_lshl_add_u64 v[6:7], v[8:9], 0, v[84:85]
	s_waitcnt vmcnt(0) lgkmcnt(0)
	v_pk_add_f32 v[10:11], v[22:23], 1.0 op_sel_hi:[1,0]
	s_nop 0
	v_pk_add_f32 v[10:11], v[10:11], v[26:27]
	v_pk_add_f32 v[128:129], v[2:3], v[14:15]
	v_pk_mul_f32 v[122:123], v[18:19], v[10:11]
	v_pk_add_f32 v[10:11], v[24:25], 1.0 op_sel_hi:[1,0]
	v_lshl_add_u64 v[2:3], v[0:1], 0, v[86:87]
	v_pk_add_f32 v[10:11], v[10:11], v[28:29]
	v_pk_add_f32 v[126:127], v[4:5], v[16:17]
	v_pk_mul_f32 v[124:125], v[20:21], v[10:11]
	global_load_dwordx4 v[18:21], v[36:37], off offset:3072
	global_load_dwordx4 v[22:25], v[6:7], off
	global_load_dwordx4 v[26:29], v[46:47], off
	s_nop 0
	global_load_dwordx4 v[2:5], v[2:3], off
	s_nop 0
	global_load_dwordx4 v[14:17], v[50:51], off
	s_waitcnt vmcnt(0) lgkmcnt(0)
	v_pk_add_f32 v[6:7], v[22:23], 1.0 op_sel_hi:[1,0]
	s_nop 0
	v_pk_add_f32 v[6:7], v[6:7], v[26:27]
	v_pk_add_f32 v[136:137], v[2:3], v[14:15]
	v_pk_mul_f32 v[130:131], v[18:19], v[6:7]
	v_pk_add_f32 v[6:7], v[24:25], 1.0 op_sel_hi:[1,0]
	v_lshl_add_u64 v[2:3], v[0:1], 0, v[88:89]
	v_pk_add_f32 v[6:7], v[6:7], v[28:29]
	v_pk_add_f32 v[134:135], v[4:5], v[16:17]
	v_pk_mul_f32 v[132:133], v[20:21], v[6:7]
	v_lshl_add_u64 v[6:7], v[8:9], 0, v[86:87]
	global_load_dwordx4 v[18:21], v[48:49], off
	global_load_dwordx4 v[22:25], v[6:7], off
	global_load_dwordx4 v[26:29], v[52:53], off
	s_nop 0
	global_load_dwordx4 v[2:5], v[2:3], off
	s_nop 0
	global_load_dwordx4 v[14:17], v[56:57], off
	s_waitcnt vmcnt(0) lgkmcnt(0)
	v_pk_add_f32 v[6:7], v[22:23], 1.0 op_sel_hi:[1,0]
	s_nop 0
	v_pk_add_f32 v[6:7], v[6:7], v[26:27]
	v_pk_add_f32 v[144:145], v[2:3], v[14:15]
	v_pk_mul_f32 v[138:139], v[18:19], v[6:7]
	v_pk_add_f32 v[6:7], v[24:25], 1.0 op_sel_hi:[1,0]
	v_lshl_add_u64 v[2:3], v[0:1], 0, v[90:91]
	v_pk_add_f32 v[6:7], v[6:7], v[28:29]
	v_pk_add_f32 v[142:143], v[4:5], v[16:17]
	v_pk_mul_f32 v[140:141], v[20:21], v[6:7]
	v_lshl_add_u64 v[6:7], v[8:9], 0, v[88:89]
	global_load_dwordx4 v[18:21], v[54:55], off
	global_load_dwordx4 v[22:25], v[6:7], off
	global_load_dwordx4 v[26:29], v[58:59], off
	s_nop 0
	global_load_dwordx4 v[2:5], v[2:3], off
	s_nop 0
	global_load_dwordx4 v[14:17], v[62:63], off
	v_lshl_add_u64 v[0:1], v[0:1], 0, v[92:93]
	s_waitcnt vmcnt(0) lgkmcnt(0)
	v_pk_add_f32 v[6:7], v[22:23], 1.0 op_sel_hi:[1,0]
	s_nop 0
	v_pk_add_f32 v[6:7], v[6:7], v[26:27]
	v_pk_add_f32 v[152:153], v[2:3], v[14:15]
	v_pk_mul_f32 v[146:147], v[18:19], v[6:7]
	v_pk_add_f32 v[6:7], v[24:25], 1.0 op_sel_hi:[1,0]
	v_lshl_add_u64 v[14:15], v[8:9], 0, v[92:93]
	v_pk_add_f32 v[6:7], v[6:7], v[28:29]
	v_pk_add_f32 v[150:151], v[4:5], v[16:17]
	v_pk_mul_f32 v[148:149], v[20:21], v[6:7]
	v_lshl_add_u64 v[6:7], v[8:9], 0, v[90:91]
	global_load_dwordx4 v[18:21], v[60:61], off
	global_load_dwordx4 v[22:25], v[6:7], off
	global_load_dwordx4 v[26:29], v[64:65], off
	s_waitcnt vmcnt(0) lgkmcnt(0)
	v_pk_add_f32 v[6:7], v[22:23], 1.0 op_sel_hi:[1,0]
	s_nop 0
	v_pk_add_f32 v[6:7], v[6:7], v[26:27]
	s_nop 0
	v_pk_mul_f32 v[160:161], v[18:19], v[6:7]
	v_pk_add_f32 v[6:7], v[24:25], 1.0 op_sel_hi:[1,0]
	s_nop 0
	v_pk_add_f32 v[6:7], v[6:7], v[28:29]
	s_nop 0
	v_pk_mul_f32 v[162:163], v[20:21], v[6:7]
	global_load_dwordx4 v[0:3], v[0:1], off
	s_nop 0
	global_load_dwordx4 v[4:7], v[68:69], off
	global_load_dwordx4 v[8:11], v[66:67], off
	s_nop 0
	global_load_dwordx4 v[14:17], v[14:15], off
	s_nop 0
	global_load_dwordx4 v[18:21], v[70:71], off
	s_waitcnt vmcnt(0) lgkmcnt(0)
	v_pk_add_f32 v[14:15], v[14:15], 1.0 op_sel_hi:[1,0]
	s_nop 0
	v_pk_add_f32 v[14:15], v[14:15], v[18:19]
	v_pk_add_f32 v[166:167], v[0:1], v[4:5]
	v_pk_mul_f32 v[168:169], v[8:9], v[14:15]
	v_pk_add_f32 v[8:9], v[16:17], 1.0 op_sel_hi:[1,0]
	v_pk_add_f32 v[164:165], v[2:3], v[6:7]
	v_pk_add_f32 v[8:9], v[8:9], v[20:21]
	s_nop 0
	v_pk_mul_f32 v[170:171], v[10:11], v[8:9]

.LBB0_179:
	v_lshl_add_u64 v[2:3], v[0:1], 0, v[32:33]
	v_mov_b32_e32 v95, v33
	v_mov_b32_e32 v97, v33
	global_load_dwordx4 v[28:31], v[2:3], off
	global_load_dwordx4 v[24:27], v[2:3], off offset:1024
	global_load_dwordx4 v[20:23], v[2:3], off offset:2048
	global_load_dwordx4 v[12:15], v[2:3], off offset:3072
	v_lshl_add_u64 v[2:3], v[0:1], 0, v[94:95]
	v_lshl_add_u64 v[4:5], v[0:1], 0, v[96:97]
	v_mov_b32_e32 v99, v33
	v_mov_b32_e32 v101, v33
	global_load_dwordx4 v[16:19], v[2:3], off
	s_nop 0
	global_load_dwordx4 v[4:7], v[4:5], off
	v_lshl_add_u64 v[2:3], v[0:1], 0, v[98:99]
	v_lshl_add_u64 v[0:1], v[0:1], 0, v[100:101]
	global_load_dwordx4 v[8:11], v[2:3], off
	s_nop 0
	global_load_dwordx4 v[0:3], v[0:1], off
	s_and_b64 vcc, exec, s[0:1]
	s_cbranch_vccnz .LBB0_169
	v_lshl_add_u64 v[156:157], v[76:77], 0, v[72:73]
	s_waitcnt vmcnt(0) lgkmcnt(0)
	global_store_dwordx4 v[156:157], v[28:31], off
	global_store_dwordx4 v[156:157], v[24:27], off offset:1024
	global_store_dwordx4 v[156:157], v[20:23], off offset:2048
	global_store_dwordx4 v[156:157], v[12:15], off offset:3072
	v_add_co_u32_e32 v156, vcc, 0x1000, v156
	s_nop 1
	v_addc_co_u32_e32 v157, vcc, 0, v157, vcc
	global_store_dwordx4 v[156:157], v[16:19], off
	global_store_dwordx4 v[156:157], v[4:7], off offset:1024
	global_store_dwordx4 v[156:157], v[8:11], off offset:2048
	global_store_dwordx4 v[156:157], v[0:3], off offset:3072
	s_branch .LBB0_169

.LBB0_184:
	s_or_b64 exec, exec, s[6:7]
	s_movk_i32 s6, 0x104
	v_mad_u64_u32 v[4:5], s[6:7], v4, s6, v[8:9]
	s_waitcnt vmcnt(0)
	ds_write2_b32 v10, v52, v53 offset1:1
	ds_write2_b32 v10, v54, v55 offset0:2 offset1:3
	ds_write2_b32 v4, v0, v1 offset1:1
	ds_write2_b32 v4, v2, v3 offset0:2 offset1:3
	v_lshlrev_b32_e32 v0, 3, v9
	v_ashrrev_i32_e32 v6, 3, v9
	v_and_b32_e32 v7, 56, v0
	v_mul_u32_u24_e32 v0, 0x104, v7
	v_lshlrev_b32_e32 v1, 2, v6
	v_add3_u32 v4, 16, v0, v1
	s_waitcnt lgkmcnt(0)
	s_barrier
	ds_read2_b32 v[0:1], v4 offset1:65
	ds_read2_b32 v[2:3], v4 offset0:130 offset1:195
	v_add_u32_e32 v4, 0x400, v4
	s_waitcnt lgkmcnt(1)
	v_cvt_pk_bf16_f32 v0, v0, v1
	s_waitcnt lgkmcnt(0)
	v_cvt_pk_bf16_f32 v1, v2, v3
	ds_read2_b32 v[2:3], v4 offset0:4 offset1:69
	ds_read2_b32 v[4:5], v4 offset0:134 offset1:199
	s_mulk_i32 s5, 0x2c00
	s_waitcnt lgkmcnt(1)
	v_cvt_pk_bf16_f32 v2, v2, v3
	s_waitcnt lgkmcnt(0)
	v_cvt_pk_bf16_f32 v3, v4, v5
	v_subrev_u32_e32 v4, s5, v6
	v_add_u32_e32 v4, s10, v4
	v_ashrrev_i32_e32 v5, 31, v4
	v_lshlrev_b64 v[4:5], 12, v[4:5]
	v_lshl_add_u64 v[4:5], s[2:3], 0, v[4:5]
	s_ashr_i32 s5, s4, 31
	v_lshl_add_u64 v[4:5], s[4:5], 1, v[4:5]
	v_lshlrev_b32_e32 v32, 1, v7
	v_lshl_add_u64 v[4:5], v[4:5], 0, v[32:33]
	global_store_dwordx4 v[4:5], v[0:3], off
	s_waitcnt lgkmcnt(0)
	s_barrier

.LBB0_186:
	s_cmpk_gt_i32 s11, 0x15ff
	s_mov_b64 s[4:5], -1
	s_cbranch_scc0 .LBB0_188
	v_mov_b32_e32 v10, v224
	s_and_b32 s7, s10, 0x7c0
	s_and_b32 s6, s9, 0x1ffc0
	v_lshlrev_b32_e32 v0, 4, v10
	s_lshl_b32 s4, s7, 2
	v_readlane_b32 s5, v254, 19
	v_ashrrev_i32_e32 v2, 4, v10
	v_and_b32_e32 v32, 0xf0, v0
	s_add_u32 s4, s5, s4
	v_readlane_b32 s5, v254, 20
	v_add_u32_e32 v0, s6, v2
	s_addc_u32 s5, s5, 0
	v_ashrrev_i32_e32 v1, 31, v0
	v_lshl_add_u64 v[6:7], s[4:5], 0, v[32:33]
	v_lshlrev_b64 v[0:1], 13, v[0:1]
	v_add_u32_e32 v4, 16, v32
	v_lshl_add_u64 v[0:1], v[6:7], 0, v[0:1]
	s_movk_i32 s12, 0x104
	v_mad_u64_u32 v[8:9], s[4:5], v2, s12, v[4:5]
	global_load_dwordx4 v[52:55], v[0:1], off
	s_lshl_b32 s66, s6, 1
	v_add_u32_e32 v0, 0x200, v10
	v_ashrrev_i32_e32 v2, 4, v0
	v_add_u32_e32 v0, s6, v2
	v_ashrrev_i32_e32 v1, 31, v0
	v_lshlrev_b64 v[0:1], 13, v[0:1]
	v_lshl_add_u64 v[0:1], v[6:7], 0, v[0:1]
	v_mad_u64_u32 v[4:5], s[4:5], v2, s12, v[4:5]
	global_load_dwordx4 v[0:3], v[0:1], off
	v_ashrrev_i32_e32 v6, 3, v10
	s_movk_i32 s4, 0x2c00
	s_waitcnt vmcnt(0)
	ds_write2_b32 v8, v52, v53 offset1:1
	ds_write2_b32 v8, v54, v55 offset0:2 offset1:3
	ds_write2_b32 v4, v0, v1 offset1:1
	ds_write2_b32 v4, v2, v3 offset0:2 offset1:3
	v_lshlrev_b32_e32 v0, 3, v10
	v_and_b32_e32 v7, 56, v0
	v_mul_u32_u24_e32 v0, 0x104, v7
	v_lshlrev_b32_e32 v1, 2, v6
	v_add3_u32 v4, 16, v0, v1
	s_waitcnt lgkmcnt(0)
	s_barrier
	ds_read2_b32 v[0:1], v4 offset1:65
	ds_read2_b32 v[2:3], v4 offset0:130 offset1:195
	v_add_u32_e32 v4, 0x400, v4
	s_waitcnt lgkmcnt(1)
	v_cvt_pk_bf16_f32 v0, v0, v1
	s_waitcnt lgkmcnt(0)
	v_cvt_pk_bf16_f32 v1, v2, v3
	ds_read2_b32 v[2:3], v4 offset0:4 offset1:69
	ds_read2_b32 v[4:5], v4 offset0:134 offset1:199
	s_waitcnt lgkmcnt(1)
	v_cvt_pk_bf16_f32 v2, v2, v3
	s_waitcnt lgkmcnt(0)
	v_cvt_pk_bf16_f32 v3, v4, v5
	v_add_u32_e32 v6, s7, v6
	v_mov_b64_e32 v[4:5], s[0:1]
	v_mad_i64_i32 v[4:5], s[4:5], v6, s4, v[4:5]
	v_lshl_add_u64 v[4:5], v[4:5], 0, s[66:67]
	v_lshlrev_b32_e32 v32, 1, v7
	v_lshl_add_u64 v[4:5], v[4:5], 0, v[32:33]
	global_store_dwordx4 v[4:5], v[0:3], off
	s_waitcnt lgkmcnt(0)
	s_barrier
	s_mov_b64 s[4:5], 0

.LBB0_244:
	s_add_u32 s20, s18, 0xfff80080
	s_addc_u32 s21, s19, -1
	s_add_i32 s61, 16, 0x10000
	v_add_u32_e32 v140, s61, v143
	ds_read_b128 v[146:149], v140
	ds_read_b128 v[150:153], v140 offset:1024
	ds_read_b128 v[160:163], v140 offset:2048
	ds_read_b128 v[164:167], v140 offset:3072
	s_cmp_eq_u32 s60, 28
	s_cselect_b32 s23, s11, s21
	s_cselect_b32 s22, s56, s20
	s_cselect_b32 s21, s9, s59
	s_cselect_b32 s20, s57, s58
	v_lshl_add_u64 v[140:141], s[18:19], 0, v[138:139]
	s_add_i32 m0, s13, 0xc000
	ds_read_b128 v[168:171], v145
	ds_read_b128 v[172:175], v145 offset:1024
	ds_read_b128 v[176:179], v145 offset:2048
	ds_read_b128 v[180:183], v145 offset:3072
	ds_read_b128 v[184:187], v145 offset:4096
	ds_read_b128 v[188:191], v145 offset:5120
	ds_read_b128 v[192:195], v145 offset:6144
	ds_read_b128 v[196:199], v145 offset:7168
	global_load_lds_dwordx4 v[140:141], off
	v_lshl_add_u64 v[140:141], s[18:19], 0, v[136:137]
	s_add_i32 m0, s13, 0xe000
	s_nop 0
	global_load_lds_dwordx4 v[140:141], off
	s_waitcnt lgkmcnt(8)
	s_barrier
	s_waitcnt lgkmcnt(0)
	s_setprio 1
	s_waitcnt lgkmcnt(0)
	v_mfma_f32_16x16x32_bf16 v[126:129], v[146:149], v[168:171], v[126:129]
	v_mfma_f32_16x16x32_bf16 v[122:125], v[160:163], v[168:171], v[122:125]
	v_mfma_f32_16x16x32_bf16 v[118:121], v[146:149], v[176:179], v[118:121]
	v_mfma_f32_16x16x32_bf16 v[110:113], v[160:163], v[176:179], v[110:113]
	v_mfma_f32_16x16x32_bf16 v[102:105], v[146:149], v[184:187], v[102:105]
	v_mfma_f32_16x16x32_bf16 v[94:97], v[160:163], v[184:187], v[94:97]
	v_mfma_f32_16x16x32_bf16 v[86:89], v[146:149], v[192:195], v[86:89]
	v_mfma_f32_16x16x32_bf16 v[78:81], v[160:163], v[192:195], v[78:81]
	v_mfma_f32_16x16x32_bf16 v[126:129], v[150:153], v[172:175], v[126:129]
	v_mfma_f32_16x16x32_bf16 v[122:125], v[164:167], v[172:175], v[122:125]
	v_mfma_f32_16x16x32_bf16 v[118:121], v[150:153], v[180:183], v[118:121]
	v_mfma_f32_16x16x32_bf16 v[110:113], v[164:167], v[180:183], v[110:113]
	v_mfma_f32_16x16x32_bf16 v[102:105], v[150:153], v[188:191], v[102:105]
	v_mfma_f32_16x16x32_bf16 v[94:97], v[164:167], v[188:191], v[94:97]
	v_mfma_f32_16x16x32_bf16 v[86:89], v[150:153], v[196:199], v[86:89]
	v_mfma_f32_16x16x32_bf16 v[78:81], v[164:167], v[196:199], v[78:81]
	s_setprio 0
	s_barrier
	s_add_i32 s64, 16, 0x14000
	v_add_u32_e32 v140, s64, v143
	s_add_i32 s61, s61, s28
	ds_read_b128 v[200:203], v140
	ds_read_b128 v[204:207], v140 offset:1024
	ds_read_b128 v[208:211], v140 offset:2048
	ds_read_b128 v[212:215], v140 offset:3072
	v_lshl_add_u64 v[140:141], s[20:21], 0, v[32:33]
	s_mov_b32 m0, s61
	v_lshl_add_u64 v[156:157], s[20:21], 0, v[130:131]
	global_load_lds_dwordx4 v[140:141], off
	s_add_i32 m0, s61, 0x2000
	s_nop 0
	global_load_lds_dwordx4 v[156:157], off
	s_barrier
	s_waitcnt lgkmcnt(0)
	s_setprio 1
	s_waitcnt lgkmcnt(0)
	v_mfma_f32_16x16x32_bf16 v[114:117], v[200:203], v[168:171], v[114:117]
	v_mfma_f32_16x16x32_bf16 v[106:109], v[208:211], v[168:171], v[106:109]
	v_mfma_f32_16x16x32_bf16 v[98:101], v[200:203], v[176:179], v[98:101]
	v_mfma_f32_16x16x32_bf16 v[90:93], v[208:211], v[176:179], v[90:93]
	v_mfma_f32_16x16x32_bf16 v[82:85], v[200:203], v[184:187], v[82:85]
	v_mfma_f32_16x16x32_bf16 v[74:77], v[208:211], v[184:187], v[74:77]
	v_mfma_f32_16x16x32_bf16 v[70:73], v[200:203], v[192:195], v[70:73]
	v_mfma_f32_16x16x32_bf16 v[66:69], v[208:211], v[192:195], v[66:69]
	v_mfma_f32_16x16x32_bf16 v[114:117], v[204:207], v[172:175], v[114:117]
	v_mfma_f32_16x16x32_bf16 v[106:109], v[212:215], v[172:175], v[106:109]
	v_mfma_f32_16x16x32_bf16 v[98:101], v[204:207], v[180:183], v[98:101]
	v_mfma_f32_16x16x32_bf16 v[90:93], v[212:215], v[180:183], v[90:93]
	v_mfma_f32_16x16x32_bf16 v[82:85], v[204:207], v[188:191], v[82:85]
	v_mfma_f32_16x16x32_bf16 v[74:77], v[212:215], v[188:191], v[74:77]
	v_mfma_f32_16x16x32_bf16 v[70:73], v[204:207], v[196:199], v[70:73]
	v_mfma_f32_16x16x32_bf16 v[66:69], v[212:215], v[196:199], v[66:69]
	s_setprio 0
	s_mov_b32 m0, s13
	v_lshl_add_u64 v[158:159], s[22:23], 0, v[134:135]
	s_barrier
	ds_read_b128 v[168:171], v145 offset:16384
	ds_read_b128 v[172:175], v145 offset:17408
	ds_read_b128 v[176:179], v145 offset:18432
	ds_read_b128 v[180:183], v145 offset:19456
	ds_read_b128 v[184:187], v145 offset:20480
	ds_read_b128 v[188:191], v145 offset:21504
	ds_read_b128 v[192:195], v145 offset:22528
	ds_read_b128 v[196:199], v145 offset:23552
	global_load_lds_dwordx4 v[158:159], off
	v_lshl_add_u64 v[216:217], s[22:23], 0, v[132:133]
	s_mov_b32 m0, s35
	s_nop 0
	global_load_lds_dwordx4 v[216:217], off
	s_barrier
	s_waitcnt lgkmcnt(0)
	s_setprio 1
	s_waitcnt lgkmcnt(0)
	v_mfma_f32_16x16x32_bf16 v[62:65], v[146:149], v[168:171], v[62:65]
	v_mfma_f32_16x16x32_bf16 v[58:61], v[160:163], v[168:171], v[58:61]
	v_mfma_f32_16x16x32_bf16 v[54:57], v[146:149], v[176:179], v[54:57]
	v_mfma_f32_16x16x32_bf16 v[46:49], v[160:163], v[176:179], v[46:49]
	v_mfma_f32_16x16x32_bf16 v[38:41], v[146:149], v[184:187], v[38:41]
	v_mfma_f32_16x16x32_bf16 v[28:31], v[160:163], v[184:187], v[28:31]
	v_mfma_f32_16x16x32_bf16 v[20:23], v[146:149], v[192:195], v[20:23]
	v_mfma_f32_16x16x32_bf16 v[12:15], v[160:163], v[192:195], v[12:15]
	v_mfma_f32_16x16x32_bf16 v[62:65], v[150:153], v[172:175], v[62:65]
	v_mfma_f32_16x16x32_bf16 v[58:61], v[164:167], v[172:175], v[58:61]
	v_mfma_f32_16x16x32_bf16 v[54:57], v[150:153], v[180:183], v[54:57]
	v_mfma_f32_16x16x32_bf16 v[46:49], v[164:167], v[180:183], v[46:49]
	v_mfma_f32_16x16x32_bf16 v[38:41], v[150:153], v[188:191], v[38:41]
	v_mfma_f32_16x16x32_bf16 v[28:31], v[164:167], v[188:191], v[28:31]
	v_mfma_f32_16x16x32_bf16 v[20:23], v[150:153], v[196:199], v[20:23]
	v_mfma_f32_16x16x32_bf16 v[12:15], v[164:167], v[196:199], v[12:15]
	s_setprio 0
	s_barrier
	s_add_u32 s62, s20, 0x80000
	s_addc_u32 s63, s21, 0
	s_add_i32 s61, s64, s28
	v_lshl_add_u64 v[146:147], s[62:63], 0, v[32:33]
	s_mov_b32 m0, s61
	s_nop 0
	global_load_lds_dwordx4 v[146:147], off
	v_lshl_add_u64 v[146:147], s[62:63], 0, v[130:131]
	s_add_i32 m0, s61, 0x2000
	s_nop 0
	global_load_lds_dwordx4 v[146:147], off
	s_waitcnt vmcnt(6)
	s_barrier
	s_setprio 1
	v_mfma_f32_16x16x32_bf16 v[50:53], v[200:203], v[168:171], v[50:53]
	v_mfma_f32_16x16x32_bf16 v[42:45], v[208:211], v[168:171], v[42:45]
	v_mfma_f32_16x16x32_bf16 v[34:37], v[200:203], v[176:179], v[34:37]
	v_mfma_f32_16x16x32_bf16 v[24:27], v[208:211], v[176:179], v[24:27]
	v_mfma_f32_16x16x32_bf16 v[16:19], v[200:203], v[184:187], v[16:19]
	v_mfma_f32_16x16x32_bf16 v[8:11], v[208:211], v[184:187], v[8:11]
	v_mfma_f32_16x16x32_bf16 v[4:7], v[200:203], v[192:195], v[4:7]
	v_mfma_f32_16x16x32_bf16 v[0:3], v[208:211], v[192:195], v[0:3]
	v_mfma_f32_16x16x32_bf16 v[50:53], v[204:207], v[172:175], v[50:53]
	v_mfma_f32_16x16x32_bf16 v[42:45], v[212:215], v[172:175], v[42:45]
	v_mfma_f32_16x16x32_bf16 v[34:37], v[204:207], v[180:183], v[34:37]
	v_mfma_f32_16x16x32_bf16 v[24:27], v[212:215], v[180:183], v[24:27]
	v_mfma_f32_16x16x32_bf16 v[16:19], v[204:207], v[188:191], v[16:19]
	v_mfma_f32_16x16x32_bf16 v[8:11], v[212:215], v[188:191], v[8:11]
	v_mfma_f32_16x16x32_bf16 v[4:7], v[204:207], v[196:199], v[4:7]
	v_mfma_f32_16x16x32_bf16 v[0:3], v[212:215], v[196:199], v[0:3]
	s_setprio 0
	s_add_i32 s61, 16, 0x18000
	v_add_u32_e32 v155, s61, v143
	s_barrier
	ds_read_b128 v[146:149], v155
	ds_read_b128 v[150:153], v155 offset:1024
	ds_read_b128 v[160:163], v155 offset:2048
	ds_read_b128 v[164:167], v155 offset:3072
	s_add_u32 s22, s22, 0x80000
	s_addc_u32 s23, s23, 0
	s_mov_b32 m0, s36
	v_lshl_add_u64 v[200:201], s[22:23], 0, v[134:135]
	ds_read_b128 v[168:171], v145 offset:32768
	ds_read_b128 v[172:175], v145 offset:33792
	ds_read_b128 v[176:179], v145 offset:34816
	ds_read_b128 v[180:183], v145 offset:35840
	ds_read_b128 v[184:187], v145 offset:36864
	ds_read_b128 v[188:191], v145 offset:37888
	ds_read_b128 v[192:195], v145 offset:38912
	ds_read_b128 v[196:199], v145 offset:39936
	global_load_lds_dwordx4 v[200:201], off
	v_lshl_add_u64 v[200:201], s[22:23], 0, v[132:133]
	s_mov_b32 m0, s37
	s_nop 0
	global_load_lds_dwordx4 v[200:201], off
	s_waitcnt lgkmcnt(8)
	s_barrier
	s_waitcnt lgkmcnt(0)
	s_setprio 1
	s_waitcnt lgkmcnt(0)
	v_mfma_f32_16x16x32_bf16 v[126:129], v[146:149], v[168:171], v[126:129]
	v_mfma_f32_16x16x32_bf16 v[122:125], v[160:163], v[168:171], v[122:125]
	v_mfma_f32_16x16x32_bf16 v[118:121], v[146:149], v[176:179], v[118:121]
	v_mfma_f32_16x16x32_bf16 v[110:113], v[160:163], v[176:179], v[110:113]
	v_mfma_f32_16x16x32_bf16 v[102:105], v[146:149], v[184:187], v[102:105]
	v_mfma_f32_16x16x32_bf16 v[94:97], v[160:163], v[184:187], v[94:97]
	v_mfma_f32_16x16x32_bf16 v[86:89], v[146:149], v[192:195], v[86:89]
	v_mfma_f32_16x16x32_bf16 v[78:81], v[160:163], v[192:195], v[78:81]
	v_mfma_f32_16x16x32_bf16 v[126:129], v[150:153], v[172:175], v[126:129]
	v_mfma_f32_16x16x32_bf16 v[122:125], v[164:167], v[172:175], v[122:125]
	v_mfma_f32_16x16x32_bf16 v[118:121], v[150:153], v[180:183], v[118:121]
	v_mfma_f32_16x16x32_bf16 v[110:113], v[164:167], v[180:183], v[110:113]
	v_mfma_f32_16x16x32_bf16 v[102:105], v[150:153], v[188:191], v[102:105]
	v_mfma_f32_16x16x32_bf16 v[94:97], v[164:167], v[188:191], v[94:97]
	v_mfma_f32_16x16x32_bf16 v[86:89], v[150:153], v[196:199], v[86:89]
	v_mfma_f32_16x16x32_bf16 v[78:81], v[164:167], v[196:199], v[78:81]
	s_setprio 0
	s_barrier
	s_add_i32 s22, 16, 0x1c000
	s_add_i32 s23, s61, s28
	v_add_u32_e32 v155, s22, v143
	v_lshl_add_u64 v[140:141], v[140:141], 0, s[50:51]
	s_mov_b32 m0, s23
	ds_read_b128 v[200:203], v155
	ds_read_b128 v[204:207], v155 offset:1024
	ds_read_b128 v[208:211], v155 offset:2048
	ds_read_b128 v[212:215], v155 offset:3072
	global_load_lds_dwordx4 v[140:141], off
	v_lshl_add_u64 v[140:141], v[156:157], 0, s[50:51]
	s_add_i32 m0, s23, 0x2000
	s_nop 0
	global_load_lds_dwordx4 v[140:141], off
	s_barrier
	s_waitcnt lgkmcnt(0)
	s_setprio 1
	s_waitcnt lgkmcnt(0)
	v_mfma_f32_16x16x32_bf16 v[114:117], v[200:203], v[168:171], v[114:117]
	v_mfma_f32_16x16x32_bf16 v[106:109], v[208:211], v[168:171], v[106:109]
	v_mfma_f32_16x16x32_bf16 v[98:101], v[200:203], v[176:179], v[98:101]
	v_mfma_f32_16x16x32_bf16 v[90:93], v[208:211], v[176:179], v[90:93]
	v_mfma_f32_16x16x32_bf16 v[82:85], v[200:203], v[184:187], v[82:85]
	v_mfma_f32_16x16x32_bf16 v[74:77], v[208:211], v[184:187], v[74:77]
	v_mfma_f32_16x16x32_bf16 v[70:73], v[200:203], v[192:195], v[70:73]
	v_mfma_f32_16x16x32_bf16 v[66:69], v[208:211], v[192:195], v[66:69]
	v_mfma_f32_16x16x32_bf16 v[114:117], v[204:207], v[172:175], v[114:117]
	v_mfma_f32_16x16x32_bf16 v[106:109], v[212:215], v[172:175], v[106:109]
	v_mfma_f32_16x16x32_bf16 v[98:101], v[204:207], v[180:183], v[98:101]
	v_mfma_f32_16x16x32_bf16 v[90:93], v[212:215], v[180:183], v[90:93]
	v_mfma_f32_16x16x32_bf16 v[82:85], v[204:207], v[188:191], v[82:85]
	v_mfma_f32_16x16x32_bf16 v[74:77], v[212:215], v[188:191], v[74:77]
	v_mfma_f32_16x16x32_bf16 v[70:73], v[204:207], v[196:199], v[70:73]
	v_mfma_f32_16x16x32_bf16 v[66:69], v[212:215], v[196:199], v[66:69]
	s_setprio 0
	s_mov_b32 m0, s38
	v_lshl_add_u64 v[140:141], v[158:159], 0, s[50:51]
	s_barrier
	ds_read_b128 v[168:171], v145 offset:49152
	ds_read_b128 v[172:175], v145 offset:50176
	ds_read_b128 v[176:179], v145 offset:51200
	ds_read_b128 v[180:183], v145 offset:52224
	ds_read_b128 v[184:187], v145 offset:53248
	ds_read_b128 v[188:191], v145 offset:54272
	ds_read_b128 v[192:195], v145 offset:55296
	ds_read_b128 v[196:199], v145 offset:56320
	global_load_lds_dwordx4 v[140:141], off
	v_lshl_add_u64 v[140:141], v[216:217], 0, s[50:51]
	s_mov_b32 m0, s39
	s_nop 0
	global_load_lds_dwordx4 v[140:141], off
	s_barrier
	s_waitcnt lgkmcnt(0)
	s_setprio 1
	s_waitcnt lgkmcnt(0)
	v_mfma_f32_16x16x32_bf16 v[62:65], v[146:149], v[168:171], v[62:65]
	v_mfma_f32_16x16x32_bf16 v[58:61], v[160:163], v[168:171], v[58:61]
	v_mfma_f32_16x16x32_bf16 v[54:57], v[146:149], v[176:179], v[54:57]
	v_mfma_f32_16x16x32_bf16 v[46:49], v[160:163], v[176:179], v[46:49]
	v_mfma_f32_16x16x32_bf16 v[38:41], v[146:149], v[184:187], v[38:41]
	v_mfma_f32_16x16x32_bf16 v[28:31], v[160:163], v[184:187], v[28:31]
	v_mfma_f32_16x16x32_bf16 v[20:23], v[146:149], v[192:195], v[20:23]
	v_mfma_f32_16x16x32_bf16 v[12:15], v[160:163], v[192:195], v[12:15]
	v_mfma_f32_16x16x32_bf16 v[62:65], v[150:153], v[172:175], v[62:65]
	v_mfma_f32_16x16x32_bf16 v[58:61], v[164:167], v[172:175], v[58:61]
	v_mfma_f32_16x16x32_bf16 v[54:57], v[150:153], v[180:183], v[54:57]
	v_mfma_f32_16x16x32_bf16 v[46:49], v[164:167], v[180:183], v[46:49]
	v_mfma_f32_16x16x32_bf16 v[38:41], v[150:153], v[188:191], v[38:41]
	v_mfma_f32_16x16x32_bf16 v[28:31], v[164:167], v[188:191], v[28:31]
	v_mfma_f32_16x16x32_bf16 v[20:23], v[150:153], v[196:199], v[20:23]
	v_mfma_f32_16x16x32_bf16 v[12:15], v[164:167], v[196:199], v[12:15]
	s_setprio 0
	s_barrier
	s_add_u32 s20, s20, 0x80080
	s_addc_u32 s21, s21, 0
	s_add_i32 s22, s22, s28
	v_lshl_add_u64 v[140:141], s[20:21], 0, v[32:33]
	s_mov_b32 m0, s22
	s_nop 0
	global_load_lds_dwordx4 v[140:141], off
	v_lshl_add_u64 v[140:141], s[20:21], 0, v[130:131]
	s_add_i32 m0, s22, 0x2000
	s_nop 0
	global_load_lds_dwordx4 v[140:141], off
	s_waitcnt vmcnt(6)
	s_barrier
	s_setprio 1
	v_mfma_f32_16x16x32_bf16 v[50:53], v[200:203], v[168:171], v[50:53]
	v_mfma_f32_16x16x32_bf16 v[42:45], v[208:211], v[168:171], v[42:45]
	v_mfma_f32_16x16x32_bf16 v[34:37], v[200:203], v[176:179], v[34:37]
	v_mfma_f32_16x16x32_bf16 v[24:27], v[208:211], v[176:179], v[24:27]
	v_mfma_f32_16x16x32_bf16 v[16:19], v[200:203], v[184:187], v[16:19]
	v_mfma_f32_16x16x32_bf16 v[8:11], v[208:211], v[184:187], v[8:11]
	v_mfma_f32_16x16x32_bf16 v[4:7], v[200:203], v[192:195], v[4:7]
	v_mfma_f32_16x16x32_bf16 v[0:3], v[208:211], v[192:195], v[0:3]
	v_mfma_f32_16x16x32_bf16 v[50:53], v[204:207], v[172:175], v[50:53]
	v_mfma_f32_16x16x32_bf16 v[42:45], v[212:215], v[172:175], v[42:45]
	v_mfma_f32_16x16x32_bf16 v[34:37], v[204:207], v[180:183], v[34:37]
	v_mfma_f32_16x16x32_bf16 v[24:27], v[212:215], v[180:183], v[24:27]
	v_mfma_f32_16x16x32_bf16 v[16:19], v[204:207], v[188:191], v[16:19]
	v_mfma_f32_16x16x32_bf16 v[8:11], v[212:215], v[188:191], v[8:11]
	v_mfma_f32_16x16x32_bf16 v[4:7], v[204:207], v[196:199], v[4:7]
	v_mfma_f32_16x16x32_bf16 v[0:3], v[212:215], v[196:199], v[0:3]
	s_setprio 0
	s_add_i32 s60, s60, 2
	s_add_u32 s58, s58, 0x100
	s_addc_u32 s59, s59, 0
	s_add_u32 s18, s18, 0x100
	s_addc_u32 s19, s19, 0
	s_cmp_gt_u32 s60, 29
	s_barrier
	s_cbranch_scc0 .LBB0_244
	v_lshl_add_u32 v148, s12, 8, v142
	v_lshl_or_b32 v140, s47, 8, v144
	v_ashrrev_i32_e32 v141, 31, v140
	v_mad_i64_i32 v[146:147], s[18:19], v148, s26, 0
	v_cvt_pk_bf16_f32 v114, v114, v115
	v_cvt_pk_bf16_f32 v115, v116, v117
	v_cvt_pk_bf16_f32 v116, v106, v107
	v_or_b32_e32 v106, 16, v148
	v_lshl_add_u64 v[146:147], v[146:147], 1, s[6:7]
	v_lshlrev_b64 v[140:141], 1, v[140:141]
	v_mad_i64_i32 v[106:107], s[18:19], v106, s26, 0
	v_cvt_pk_bf16_f32 v98, v98, v99
	v_cvt_pk_bf16_f32 v99, v100, v101
	v_cvt_pk_bf16_f32 v100, v90, v91
	v_or_b32_e32 v90, 32, v148
	v_lshl_add_u64 v[146:147], v[146:147], 0, v[140:141]
	v_lshl_add_u64 v[106:107], v[106:107], 1, s[6:7]
	v_mad_i64_i32 v[90:91], s[18:19], v90, s26, 0
	v_cvt_pk_bf16_f32 v82, v82, v83
	v_cvt_pk_bf16_f32 v83, v84, v85
	v_cvt_pk_bf16_f32 v84, v74, v75
	v_or_b32_e32 v74, 48, v148
	v_cvt_pk_bf16_f32 v70, v70, v71
	v_cvt_pk_bf16_f32 v71, v72, v73
	v_cvt_pk_bf16_f32 v72, v66, v67
	v_add_u32_e32 v66, 0x80, v148
	v_cvt_pk_bf16_f32 v117, v108, v109
	global_store_dwordx4 v[146:147], v[114:117], off offset:256
	v_lshl_add_u64 v[90:91], v[90:91], 1, s[6:7]
	v_mad_i64_i32 v[74:75], s[18:19], v74, s26, 0
	v_lshl_add_u64 v[114:115], v[106:107], 0, v[140:141]
	v_mad_i64_i32 v[66:67], s[18:19], v66, s26, 0
	v_cvt_pk_bf16_f32 v50, v50, v51
	v_cvt_pk_bf16_f32 v51, v52, v53
	v_cvt_pk_bf16_f32 v52, v42, v43
	v_add_u32_e32 v42, 0x90, v148
	v_cvt_pk_bf16_f32 v126, v126, v127
	v_cvt_pk_bf16_f32 v127, v128, v129
	v_cvt_pk_bf16_f32 v128, v122, v123
	v_cvt_pk_bf16_f32 v129, v124, v125
	global_store_dwordx4 v[146:147], v[126:129], off
	v_cvt_pk_bf16_f32 v101, v92, v93
	global_store_dwordx4 v[114:115], v[98:101], off offset:256
	v_lshl_add_u64 v[74:75], v[74:75], 1, s[6:7]
	v_lshl_add_u64 v[66:67], v[66:67], 1, s[6:7]
	v_lshl_add_u64 v[98:99], v[90:91], 0, v[140:141]
	v_mad_i64_i32 v[42:43], s[18:19], v42, s26, 0
	v_cvt_pk_bf16_f32 v34, v34, v35
	v_cvt_pk_bf16_f32 v35, v36, v37
	v_cvt_pk_bf16_f32 v36, v24, v25
	v_add_u32_e32 v24, 0xa0, v148
	v_cvt_pk_bf16_f32 v106, v118, v119
	v_cvt_pk_bf16_f32 v107, v120, v121
	v_cvt_pk_bf16_f32 v108, v110, v111
	v_cvt_pk_bf16_f32 v109, v112, v113
	global_store_dwordx4 v[114:115], v[106:109], off
	v_cvt_pk_bf16_f32 v85, v76, v77
	global_store_dwordx4 v[98:99], v[82:85], off offset:256
	v_lshl_add_u64 v[66:67], v[66:67], 0, v[140:141]
	v_lshl_add_u64 v[42:43], v[42:43], 1, s[6:7]
	v_lshl_add_u64 v[82:83], v[74:75], 0, v[140:141]
	v_mad_i64_i32 v[24:25], s[18:19], v24, s26, 0
	v_cvt_pk_bf16_f32 v16, v16, v17
	v_cvt_pk_bf16_f32 v17, v18, v19
	v_cvt_pk_bf16_f32 v18, v8, v9
	v_add_u32_e32 v8, 0xb0, v148
	v_cvt_pk_bf16_f32 v90, v102, v103
	v_cvt_pk_bf16_f32 v91, v104, v105
	v_cvt_pk_bf16_f32 v92, v94, v95
	v_cvt_pk_bf16_f32 v93, v96, v97
	global_store_dwordx4 v[98:99], v[90:93], off
	v_cvt_pk_bf16_f32 v74, v86, v87
	v_cvt_pk_bf16_f32 v75, v88, v89
	v_cvt_pk_bf16_f32 v76, v78, v79
	v_cvt_pk_bf16_f32 v77, v80, v81
	global_store_dwordx4 v[82:83], v[74:77], off
	v_cvt_pk_bf16_f32 v73, v68, v69
	global_store_dwordx4 v[82:83], v[70:73], off offset:256
	v_cvt_pk_bf16_f32 v53, v44, v45
	global_store_dwordx4 v[66:67], v[50:53], off offset:256
	v_lshl_add_u64 v[24:25], v[24:25], 1, s[6:7]
	v_mad_i64_i32 v[8:9], s[18:19], v8, s26, 0
	v_lshl_add_u64 v[50:51], v[42:43], 0, v[140:141]
	v_cvt_pk_bf16_f32 v62, v62, v63
	v_cvt_pk_bf16_f32 v63, v64, v65
	v_cvt_pk_bf16_f32 v64, v58, v59
	v_cvt_pk_bf16_f32 v65, v60, v61
	global_store_dwordx4 v[66:67], v[62:65], off
	v_cvt_pk_bf16_f32 v37, v26, v27
	global_store_dwordx4 v[50:51], v[34:37], off offset:256
	v_lshl_add_u64 v[8:9], v[8:9], 1, s[6:7]
	v_cvt_pk_bf16_f32 v42, v54, v55
	v_cvt_pk_bf16_f32 v43, v56, v57
	v_cvt_pk_bf16_f32 v44, v46, v47
	v_cvt_pk_bf16_f32 v45, v48, v49
	s_nop 0
	v_lshl_add_u64 v[34:35], v[24:25], 0, v[140:141]
	global_store_dwordx4 v[50:51], v[42:45], off
	v_cvt_pk_bf16_f32 v19, v10, v11
	global_store_dwordx4 v[34:35], v[16:19], off offset:256
	s_and_b64 vcc, exec, s[2:3]
	s_mov_b32 s47, s8
	v_lshl_add_u64 v[16:17], v[8:9], 0, v[140:141]
	s_mov_b32 s12, s10
	s_mov_b64 s[18:19], s[16:17]
	s_mov_b64 s[20:21], s[14:15]
	v_cvt_pk_bf16_f32 v24, v38, v39
	v_cvt_pk_bf16_f32 v25, v40, v41
	v_cvt_pk_bf16_f32 v26, v28, v29
	v_cvt_pk_bf16_f32 v27, v30, v31
	global_store_dwordx4 v[34:35], v[24:27], off
	v_cvt_pk_bf16_f32 v8, v20, v21
	v_cvt_pk_bf16_f32 v9, v22, v23
	v_cvt_pk_bf16_f32 v10, v12, v13
	v_cvt_pk_bf16_f32 v11, v14, v15
	global_store_dwordx4 v[16:17], v[8:11], off
	v_cvt_pk_bf16_f32 v4, v4, v5
	v_cvt_pk_bf16_f32 v5, v6, v7
	v_cvt_pk_bf16_f32 v6, v0, v1
	v_cvt_pk_bf16_f32 v7, v2, v3
	global_store_dwordx4 v[16:17], v[4:7], off offset:256
	s_cbranch_vccz .LBB0_241
	s_waitcnt vmcnt(0)
	s_cmpk_gt_u32 s27, 0xff
	s_cbranch_scc1 .LBB0_248
	s_barrier

.LBB0_299:
	v_ashrrev_i32_e32 v1, 5, v2
	v_add_u32_e32 v1, s34, v1
	v_mov_b64_e32 v[10:11], s[30:31]
	v_ashrrev_i32_e32 v9, 5, v3
	v_mad_i64_i32 v[12:13], s[8:9], v1, s93, v[10:11]
	v_lshlrev_b32_e32 v32, 1, v4
	v_add_u32_e32 v9, s1, v9
	v_lshl_add_u64 v[12:13], v[12:13], 0, v[32:33]
	v_mad_i64_i32 v[10:11], s[8:9], v9, s93, v[10:11]
	v_add_co_u32_e32 v12, vcc, s10, v12
	v_lshl_add_u64 v[10:11], v[10:11], 0, v[32:33]
	s_nop 0
	v_addc_co_u32_e32 v13, vcc, 0, v13, vcc
	v_add_co_u32_e32 v10, vcc, s10, v10
	global_load_ushort v1, v[12:13], off
	s_nop 0
	v_addc_co_u32_e32 v11, vcc, 0, v11, vcc
	global_load_ushort v9, v[10:11], off
	v_add_u32_e32 v8, -2, v8
	v_add_u32_e32 v10, 0xfffff800, v7
	v_cmp_eq_u32_e32 vcc, 0, v8
	v_add_u32_e32 v3, 0x400, v3
	v_add_u32_e32 v2, 0x400, v2
	s_or_b64 s[6:7], vcc, s[6:7]
	s_waitcnt vmcnt(0) lgkmcnt(0)
	v_lshlrev_b32_e32 v1, 16, v1
	v_lshlrev_b32_e32 v9, 16, v9
	ds_write_b32 v10, v1
	ds_write_b32 v7, v9
	v_add_u32_e32 v7, 0x1000, v7
	s_andn2_b64 exec, exec, s[6:7]
	s_cbranch_execnz .LBB0_299
	s_or_b64 exec, exec, s[6:7]
	v_cmp_ne_u32_e32 vcc, v5, v6
	v_lshl_add_u32 v1, v6, 9, v0
	s_orn2_b64 s[6:7], vcc, exec

.LBB0_303:
	v_ashrrev_i32_e32 v3, 5, v1
	v_add_u32_e32 v3, s34, v3
	v_mov_b64_e32 v[6:7], s[30:31]
	v_mad_i64_i32 v[6:7], s[6:7], v3, s93, v[6:7]
	v_lshlrev_b32_e32 v32, 1, v4
	v_lshl_add_u64 v[6:7], v[6:7], 0, v[32:33]
	v_add_co_u32_e32 v6, vcc, 0x3000, v6
	s_movk_i32 s1, 0x5ff
	s_nop 0
	v_addc_co_u32_e32 v7, vcc, 0, v7, vcc
	global_load_ushort v3, v[6:7], off
	v_cmp_lt_i32_e32 vcc, s1, v1
	s_or_b64 s[4:5], vcc, s[4:5]
	s_waitcnt vmcnt(0) lgkmcnt(0)
	v_lshlrev_b32_e32 v3, 16, v3
	ds_write_b32 v2, v3
	v_add_u32_e32 v3, 0x200, v1
	v_add_u32_e32 v2, 0x800, v2
	v_mov_b32_e32 v1, v3
	s_andn2_b64 exec, exec, s[4:5]
	s_cbranch_execnz .LBB0_303

.LBB0_312:
	ds_read_u16 v19, v17
	ds_read_u16 v32, v17 offset:1040
	ds_read_u16 v48, v17 offset:2080
	ds_read_u16 v49, v17 offset:3120
	ds_read_u16 v50, v17 offset:4160
	ds_read_u16 v52, v17 offset:5200
	ds_read_u16 v51, v17 offset:6240
	ds_read_u16 v53, v17 offset:7280
	ds_read_b128 v[60:63], v243 offset:4608
	ds_read_b128 v[64:67], v243 offset:6912
	s_waitcnt lgkmcnt(0)
	v_perm_b32 v50, v52, v50, s74
	v_perm_b32 v49, v49, v48, s74
	s_waitcnt lgkmcnt(2)
	v_perm_b32 v51, v53, v51, s74
	ds_read_b128 v[52:55], v243
	ds_read_b128 v[56:59], v243 offset:2304
	v_perm_b32 v48, v32, v19, s74
	s_waitcnt lgkmcnt(3)
	s_nop 0
	v_mfma_f32_16x16x32_bf16 v[60:63], v[60:63], v[48:51], 0
	s_waitcnt lgkmcnt(0)
	v_mfma_f32_16x16x32_bf16 v[52:55], v[52:55], v[48:51], 0
	s_waitcnt lgkmcnt(0)
	v_mfma_f32_16x16x32_bf16 v[56:59], v[56:59], v[48:51], 0
	v_mfma_f32_16x16x32_bf16 v[48:51], v[64:67], v[48:51], 0
	ds_read_u16 v19, v17 offset:33280
	ds_read_u16 v32, v17 offset:34320
	ds_read_u16 v64, v17 offset:35360
	ds_read_u16 v65, v17 offset:36400
	ds_read_u16 v66, v17 offset:37440
	ds_read_u16 v68, v17 offset:38480
	ds_read_u16 v67, v17 offset:39520
	ds_read_u16 v69, v17 offset:40560
	s_waitcnt lgkmcnt(0)
	v_perm_b32 v65, v65, v64, s74
	v_perm_b32 v64, v32, v19, s74
	s_waitcnt lgkmcnt(2)
	v_perm_b32 v66, v68, v66, s74
	v_cvt_pk_bf16_f32 v19, v52, v33
	s_waitcnt lgkmcnt(0)
	v_perm_b32 v67, v69, v67, s74
	ds_read_b128 v[68:71], v243 offset:4672
	v_add_u32_e32 v17, 32, v17
	s_waitcnt lgkmcnt(0)
	v_mfma_f32_16x16x32_bf16 v[60:63], v[68:71], v[64:67], v[60:63]
	ds_read_b128 v[68:71], v243 offset:6976
	s_waitcnt lgkmcnt(0)
	v_mfma_f32_16x16x32_bf16 v[48:51], v[68:71], v[64:67], v[48:51]
	v_lshl_add_u64 v[64:65], v[46:47], 0, s[38:39]
	global_store_short v[64:65], v19, off
	v_cvt_pk_bf16_f32 v19, v53, v33
	v_lshl_add_u64 v[52:53], v[44:45], 0, s[38:39]
	global_store_short v[52:53], v19, off
	v_cvt_pk_bf16_f32 v19, v54, v33
	v_lshl_add_u64 v[52:53], v[42:43], 0, s[38:39]
	global_store_short v[52:53], v19, off
	v_cvt_pk_bf16_f32 v19, v55, v33
	v_lshl_add_u64 v[52:53], v[40:41], 0, s[38:39]
	global_store_short v[52:53], v19, off
	v_cvt_pk_bf16_f32 v19, v56, v33
	v_lshl_add_u64 v[52:53], v[38:39], 0, s[38:39]
	global_store_short v[52:53], v19, off
	v_cvt_pk_bf16_f32 v19, v57, v33
	v_lshl_add_u64 v[52:53], v[36:37], 0, s[38:39]
	global_store_short v[52:53], v19, off
	v_cvt_pk_bf16_f32 v19, v58, v33
	v_lshl_add_u64 v[52:53], v[34:35], 0, s[38:39]
	global_store_short v[52:53], v19, off
	v_cvt_pk_bf16_f32 v19, v59, v33
	v_lshl_add_u64 v[52:53], v[30:31], 0, s[38:39]
	global_store_short v[52:53], v19, off
	v_cvt_pk_bf16_f32 v19, v60, v33
	v_lshl_add_u64 v[52:53], v[28:29], 0, s[38:39]
	global_store_short v[52:53], v19, off
	v_cvt_pk_bf16_f32 v19, v61, v33
	v_lshl_add_u64 v[52:53], v[26:27], 0, s[38:39]
	global_store_short v[52:53], v19, off
	v_cvt_pk_bf16_f32 v19, v62, v33
	v_lshl_add_u64 v[52:53], v[24:25], 0, s[38:39]
	global_store_short v[52:53], v19, off
	v_cvt_pk_bf16_f32 v19, v63, v33
	v_lshl_add_u64 v[52:53], v[22:23], 0, s[38:39]
	global_store_short v[52:53], v19, off
	v_cvt_pk_bf16_f32 v19, v48, v33
	v_lshl_add_u64 v[52:53], v[20:21], 0, s[38:39]
	global_store_short v[52:53], v19, off
	v_cvt_pk_bf16_f32 v19, v49, v33
	v_lshl_add_u64 v[48:49], v[4:5], 0, s[38:39]
	global_store_short v[48:49], v19, off
	v_lshl_add_u64 v[48:49], v[2:3], 0, s[38:39]
	v_cvt_pk_bf16_f32 v19, v50, v33
	global_store_short v[48:49], v19, off
	v_lshl_add_u64 v[48:49], v[0:1], 0, s[38:39]
	s_add_u32 s38, s38, 32
	s_addc_u32 s39, s39, 0
	s_cmpk_eq_i32 s38, 0x80
	v_cvt_pk_bf16_f32 v19, v51, v33
	global_store_short v[48:49], v19, off
	s_cbranch_scc0 .LBB0_312
	s_mov_b32 s37, 0
	s_mov_b64 s[64:65], 0
	s_mov_b64 s[38:39], -1
	s_and_b64 vcc, exec, s[0:1]
	s_waitcnt lgkmcnt(0)
	s_barrier
	s_cbranch_vccz .LBB0_305
	v_readlane_b32 s0, v253, 8
	v_readlane_b32 s6, v253, 14
	s_add_i32 s57, s57, s6
	s_add_i32 s56, s56, s6
	s_cmpk_gt_i32 s57, 0x5ff
	v_readlane_b32 s1, v253, 9
	v_readlane_b32 s2, v253, 10
	v_readlane_b32 s3, v253, 11
	v_readlane_b32 s4, v253, 12
	v_readlane_b32 s5, v253, 13
	v_readlane_b32 s7, v253, 15
	s_cbranch_scc0 .LBB0_296

.LBB0_444:
	s_and_b64 vcc, exec, s[8:9]
	s_cbranch_vccz .LBB0_361
	s_add_u32 s2, s26, s10
	s_addc_u32 s3, s27, s11
	v_lshl_add_u64 v[0:1], s[2:3], 0, v[32:33]
	v_lshlrev_b64 v[2:3], 11, v[98:99]
	v_lshlrev_b64 v[4:5], 11, v[100:101]
	v_lshlrev_b64 v[6:7], 11, v[102:103]
	v_lshlrev_b64 v[8:9], 11, v[104:105]
	v_lshl_add_u64 v[2:3], v[0:1], 0, v[2:3]
	v_lshl_add_u64 v[4:5], v[0:1], 0, v[4:5]
	v_lshl_add_u64 v[6:7], v[0:1], 0, v[6:7]
	v_lshl_add_u64 v[8:9], v[0:1], 0, v[8:9]
	global_store_dword v[2:3], v38, off
	global_store_dword v[4:5], v39, off
	global_store_dword v[6:7], v40, off
	global_store_dword v[8:9], v41, off
	global_store_dword v[2:3], v46, off offset:64
	global_store_dword v[4:5], v47, off offset:64
	global_store_dword v[6:7], v48, off offset:64
	global_store_dword v[8:9], v49, off offset:64
	global_store_dword v[2:3], v50, off offset:128
	global_store_dword v[4:5], v51, off offset:128
	global_store_dword v[6:7], v52, off offset:128
	global_store_dword v[8:9], v53, off offset:128
	global_store_dword v[2:3], v62, off offset:192
	global_store_dword v[4:5], v63, off offset:192
	global_store_dword v[6:7], v64, off offset:192
	global_store_dword v[8:9], v65, off offset:192
	v_lshlrev_b64 v[2:3], 11, v[106:107]
	v_lshlrev_b64 v[4:5], 11, v[108:109]
	v_lshlrev_b64 v[6:7], 11, v[110:111]
	v_lshlrev_b64 v[8:9], 11, v[112:113]
	v_lshl_add_u64 v[2:3], v[0:1], 0, v[2:3]
	v_lshl_add_u64 v[4:5], v[0:1], 0, v[4:5]
	v_lshl_add_u64 v[6:7], v[0:1], 0, v[6:7]
	v_lshl_add_u64 v[0:1], v[0:1], 0, v[8:9]
	global_store_dword v[2:3], v42, off
	global_store_dword v[4:5], v43, off
	global_store_dword v[6:7], v44, off
	global_store_dword v[0:1], v45, off
	global_store_dword v[2:3], v54, off offset:64
	global_store_dword v[4:5], v55, off offset:64
	global_store_dword v[6:7], v56, off offset:64
	global_store_dword v[0:1], v57, off offset:64
	global_store_dword v[2:3], v58, off offset:128
	global_store_dword v[4:5], v59, off offset:128
	global_store_dword v[6:7], v60, off offset:128
	global_store_dword v[0:1], v61, off offset:128
	global_store_dword v[2:3], v66, off offset:192
	global_store_dword v[4:5], v67, off offset:192
	global_store_dword v[6:7], v68, off offset:192
	global_store_dword v[0:1], v69, off offset:192
	s_branch .LBB0_361

.LBB0_492:
	v_ashrrev_i32_e32 v6, 2, v26
	v_ashrrev_i32_e32 v7, 31, v6
	v_lshlrev_b64 v[4:5], 12, v[6:7]
	v_and_b32_e32 v3, 0x600, v35
	v_lshl_add_u64 v[8:9], s[4:5], 0, v[4:5]
	v_lshlrev_b32_e32 v32, 1, v3
	v_lshl_add_u64 v[8:9], v[8:9], 0, v[32:33]
	v_mov_b32_e32 v3, v33
	v_lshl_add_u64 v[8:9], v[8:9], 0, v[2:3]
	global_load_dwordx4 v[36:39], v[8:9], off
	v_lshl_add_u64 v[8:9], s[6:7], 0, v[4:5]
	v_lshl_add_u64 v[8:9], v[8:9], 0, v[32:33]
	v_lshl_add_u64 v[8:9], v[8:9], 0, v[2:3]
	global_load_dwordx4 v[40:43], v[8:9], off
	v_mov_b64_e32 v[8:9], s[0:1]
	v_mad_i64_i32 v[6:7], s[12:13], v6, s93, v[8:9]
	v_lshl_add_u64 v[6:7], v[6:7], 0, v[32:33]
	v_lshl_add_u64 v[6:7], v[6:7], 0, v[2:3]
	s_mov_b32 s12, 0xc402000
	v_add_co_u32_e32 v6, vcc, s12, v6
	v_lshl_add_u64 v[4:5], s[8:9], 0, v[4:5]
	s_nop 0
	v_addc_co_u32_e32 v7, vcc, 0, v7, vcc
	global_load_dwordx4 v[6:9], v[6:7], off
	v_add_u32_e32 v26, s71, v26
	s_mov_b32 s12, 0x17fff
	v_lshl_add_u64 v[4:5], v[4:5], 0, v[32:33]
	v_lshl_add_u64 v[4:5], v[4:5], 0, v[2:3]
	v_add_u32_e32 v35, s20, v35
	s_waitcnt vmcnt(0) lgkmcnt(0)
	v_and_b32_e32 v11, 0xffff0000, v36
	v_and_b32_e32 v15, 0xffff0000, v37
	v_lshlrev_b32_e32 v21, 16, v38
	v_and_b32_e32 v20, 0xffff0000, v38
	v_lshlrev_b32_e32 v13, 16, v41
	v_lshlrev_b32_e32 v17, 16, v42
	v_and_b32_e32 v16, 0xffff0000, v42
	v_pk_add_f32 v[20:21], v[20:21], v[16:17]
	v_lshlrev_b32_e32 v17, 16, v43
	v_and_b32_e32 v16, 0xffff0000, v43
	v_lshlrev_b32_e32 v24, 16, v6
	v_and_b32_e32 v22, 0xffff0000, v6
	v_lshlrev_b32_e32 v18, 16, v7
	v_and_b32_e32 v14, 0xffff0000, v7
	v_lshlrev_b32_e32 v12, 16, v8
	v_and_b32_e32 v10, 0xffff0000, v8
	v_lshlrev_b32_e32 v8, 16, v9
	v_and_b32_e32 v6, 0xffff0000, v9
	v_lshlrev_b32_e32 v7, 16, v36
	v_lshlrev_b32_e32 v9, 16, v40
	v_add_f32_e32 v7, v9, v7
	v_and_b32_e32 v9, 0xffff0000, v40
	v_add_f32_e32 v9, v9, v11
	v_lshlrev_b32_e32 v11, 16, v37
	v_add_f32_e32 v11, v13, v11
	v_and_b32_e32 v13, 0xffff0000, v41
	v_add_f32_e32 v13, v13, v15
	v_mul_f32_e32 v15, v7, v7
	v_fmac_f32_e32 v15, v9, v9
	v_fmac_f32_e32 v15, v11, v11
	v_pk_mul_f32 v[36:37], v[20:21], v[20:21]
	v_lshlrev_b32_e32 v41, 16, v39
	v_and_b32_e32 v40, 0xffff0000, v39
	v_fmac_f32_e32 v15, v13, v13
	v_pk_add_f32 v[16:17], v[40:41], v[16:17]
	v_add_f32_e32 v15, v37, v15
	v_pk_mul_f32 v[38:39], v[16:17], v[16:17]
	v_add_f32_e32 v15, v36, v15
	v_add_f32_e32 v15, v39, v15
	v_add_f32_e32 v15, v38, v15
	global_load_dwordx4 v[36:39], v[0:1], off offset:16
	global_load_dwordx4 v[40:43], v[0:1], off
	ds_bpermute_b32 v19, v27, v15
	s_waitcnt lgkmcnt(0)
	v_add_f32_e32 v15, v15, v19
	ds_bpermute_b32 v19, v28, v15
	s_waitcnt lgkmcnt(0)
	v_add_f32_e32 v15, v15, v19
	ds_bpermute_b32 v19, v29, v15
	s_waitcnt lgkmcnt(0)
	v_add_f32_e32 v15, v15, v19
	ds_bpermute_b32 v19, v30, v15
	s_waitcnt lgkmcnt(0)
	v_add_f32_e32 v15, v15, v19
	ds_bpermute_b32 v19, v31, v15
	s_waitcnt lgkmcnt(0)
	v_add_f32_e32 v15, v15, v19
	ds_bpermute_b32 v19, v34, v15
	s_waitcnt lgkmcnt(0)
	v_add_f32_e32 v15, v15, v19
	v_fmamk_f32 v15, v15, 0x3b000000, v225
	v_cmp_gt_f32_e32 vcc, s33, v15
	v_mul_f32_e32 v19, 0x4b800000, v15
	s_waitcnt vmcnt(0)
	v_mov_b32_e32 v45, v40
	v_cndmask_b32_e32 v15, v15, v19, vcc
	v_rsq_f32_e32 v15, v15
	s_nop 0
	v_mul_f32_e32 v19, 0x45800000, v15
	v_cndmask_b32_e32 v46, v15, v19, vcc
	v_mul_f32_e32 v25, v7, v46
	v_mul_f32_e32 v7, 0xbfb8aa3b, v24
	v_exp_f32_e32 v7, v7
	v_mul_f32_e32 v23, v9, v46
	v_mul_f32_e32 v19, v11, v46
	v_mul_f32_e32 v15, v13, v46
	v_add_f32_e32 v7, 1.0, v7
	v_rcp_f32_e32 v44, v7
	v_mul_f32_e32 v7, 0xbfb8aa3b, v22
	v_exp_f32_e32 v7, v7
	v_mul_f32_e32 v13, v21, v46
	v_pk_mul_f32 v[24:25], v[44:45], v[24:25]
	v_mul_f32_e32 v11, v20, v46
	v_add_f32_e32 v7, 1.0, v7
	v_rcp_f32_e32 v40, v7
	v_mul_f32_e32 v7, 0xbfb8aa3b, v18
	v_exp_f32_e32 v7, v7
	v_mul_f32_e32 v24, v24, v25
	v_pk_mul_f32 v[22:23], v[40:41], v[22:23]
	v_mul_f32_e32 v9, v17, v46
	v_add_f32_e32 v7, 1.0, v7
	v_mul_f32_e32 v25, v22, v23
	v_rcp_f32_e32 v22, v7
	v_mul_f32_e32 v7, 0xbfb8aa3b, v14
	v_exp_f32_e32 v7, v7
	v_mov_b32_e32 v23, v42
	v_pk_mul_f32 v[18:19], v[22:23], v[18:19]
	v_cmp_lt_i32_e32 vcc, s12, v26
	v_add_f32_e32 v7, 1.0, v7
	v_rcp_f32_e32 v42, v7
	v_mul_f32_e32 v7, 0xbfb8aa3b, v12
	v_exp_f32_e32 v7, v7
	v_mul_f32_e32 v18, v18, v19
	v_pk_mul_f32 v[14:15], v[42:43], v[14:15]
	s_or_b64 s[10:11], vcc, s[10:11]
	v_add_f32_e32 v7, 1.0, v7
	v_mul_f32_e32 v19, v14, v15
	v_rcp_f32_e32 v14, v7
	v_mul_f32_e32 v7, 0xbfb8aa3b, v10
	v_exp_f32_e32 v7, v7
	v_mov_b32_e32 v15, v36
	v_pk_mul_f32 v[12:13], v[14:15], v[12:13]
	v_add_f32_e32 v7, 1.0, v7
	v_rcp_f32_e32 v36, v7
	v_mul_f32_e32 v7, 0xbfb8aa3b, v8
	v_exp_f32_e32 v7, v7
	v_mul_f32_e32 v12, v12, v13
	v_pk_mul_f32 v[10:11], v[36:37], v[10:11]
	v_add_f32_e32 v7, 1.0, v7
	v_mul_f32_e32 v13, v10, v11
	v_rcp_f32_e32 v10, v7
	v_mov_b32_e32 v11, v38
	v_mul_f32_e32 v7, v16, v46
	v_pk_mul_f32 v[8:9], v[10:11], v[8:9]
	s_nop 0
	v_mul_f32_e32 v9, v8, v9
	v_mul_f32_e32 v8, 0xbfb8aa3b, v6
	v_exp_f32_e32 v8, v8
	s_nop 0
	v_add_f32_e32 v8, 1.0, v8
	v_rcp_f32_e32 v38, v8
	v_cvt_pk_bf16_f32 v8, v12, v13
	s_nop 0
	v_pk_mul_f32 v[6:7], v[38:39], v[6:7]
	s_nop 0
	v_mul_f32_e32 v10, v6, v7
	v_cvt_pk_bf16_f32 v6, v24, v25
	v_cvt_pk_bf16_f32 v7, v18, v19
	v_cvt_pk_bf16_f32 v9, v9, v10
	global_store_dwordx4 v[4:5], v[6:9], off
	s_andn2_b64 exec, exec, s[10:11]
	s_cbranch_execnz .LBB0_492

.LBB0_538:
	s_and_b64 vcc, exec, s[0:1]
	s_cbranch_vccz .LBB0_979
	v_readlane_b32 s0, v253, 8
	v_readlane_b32 s1, v253, 9
	v_readlane_b32 s2, v253, 10
	v_readlane_b32 s3, v253, 11
	v_readlane_b32 s4, v253, 12
	v_readlane_b32 s5, v253, 13
	v_readlane_b32 s6, v253, 14
	v_readlane_b32 s7, v253, 15
	s_mov_b64 s[0:1], s[2:3]
	s_mov_b64 s[6:7], s[4:5]
	v_mov_b32_e32 v0, v224
	v_readlane_b32 s0, v254, 27
	v_readlane_b32 s1, v254, 28
	s_andn2_b64 vcc, exec, s[0:1]
	s_nop 0
	v_cndmask_b32_e64 v1, 0, 1, s[0:1]
	v_cmp_ne_u32_e64 s[2:3], 1, v1
	s_nop 1
	v_writelane_b32 v255, s2, 32
	s_nop 1
	v_writelane_b32 v255, s3, 33
	s_cbranch_vccnz .LBB0_562
	s_add_u32 s4, s6, 0xc400000
	v_ashrrev_i32_e32 v99, 3, v0
	v_lshlrev_b32_e32 v0, 3, v0
	v_readlane_b32 s0, v254, 38
	s_addc_u32 s5, s7, 0
	v_and_b32_e32 v98, 56, v0
	v_add_u32_e32 v7, s0, v99
	v_readlane_b32 s0, v254, 31
	v_readlane_b32 s1, v254, 39
	v_mov_b64_e32 v[0:1], s[4:5]
	v_or_b32_e32 v16, s0, v98
	v_mad_i64_i32 v[8:9], s[0:1], v7, s96, v[0:1]
	v_lshlrev_b32_e32 v32, 1, v16
	v_lshl_add_u64 v[10:11], v[8:9], 0, v[32:33]
	global_load_dwordx4 v[0:3], v[10:11], off offset:2048
	v_cmp_gt_i32_e32 vcc, s75, v7
	v_mov_b32_e32 v4, 0
	v_add_u32_e32 v24, -1, v7
	v_cndmask_b32_e32 v5, v228, v229, vcc
	v_and_b32_e32 v6, v5, v7
	v_cmp_ne_u32_e64 s[0:1], 0, v6
	v_mov_b32_e32 v12, 0
	v_mov_b32_e32 v13, 0
	v_mov_b32_e32 v14, 0
	v_mov_b32_e32 v15, 0
	s_and_saveexec_b64 s[2:3], s[0:1]
	s_cbranch_execz .LBB0_542
	v_mov_b64_e32 v[12:13], s[4:5]
	v_mad_i64_i32 v[12:13], s[8:9], v24, s96, v[12:13]
	v_lshl_add_u64 v[12:13], v[12:13], 0, v[32:33]
	global_load_dwordx4 v[12:15], v[12:13], off offset:2048
.LBB0_542:
	s_or_b64 exec, exec, s[2:3]
	v_cmp_ne_u32_e64 s[2:3], v6, v5
	v_mov_b32_e32 v5, 0
	v_mov_b32_e32 v6, 0
	v_mov_b32_e32 v7, 0
	s_and_saveexec_b64 s[8:9], s[2:3]
	s_cbranch_execz .LBB0_544
	s_mov_b64 s[10:11], 0x800
	v_lshl_add_u64 v[4:5], v[10:11], 0, s[10:11]
	v_add_co_u32_e32 v4, vcc, 0x3000, v4
	s_nop 1
	v_addc_co_u32_e32 v5, vcc, 0, v5, vcc
	global_load_dwordx4 v[4:7], v[4:5], off offset:1024
.LBB0_544:
	s_or_b64 exec, exec, s[8:9]
	v_or_b32_e32 v10, 0x800, v16
	v_lshlrev_b32_e32 v32, 1, v10
	v_lshl_add_u64 v[10:11], v[8:9], 0, v[32:33]
	global_load_dwordx4 v[16:19], v[10:11], off
	v_mov_b32_e32 v20, v33
	v_mov_b32_e32 v21, v33
	v_mov_b32_e32 v22, v33
	v_mov_b32_e32 v23, v33
	s_and_saveexec_b64 s[8:9], s[0:1]
	s_cbranch_execz .LBB0_546
	v_mov_b64_e32 v[8:9], s[4:5]
	v_mad_i64_i32 v[8:9], s[0:1], v24, s96, v[8:9]
	v_lshl_add_u64 v[8:9], v[8:9], 0, v[32:33]
	global_load_dwordx4 v[20:23], v[8:9], off
.LBB0_546:
	s_or_b64 exec, exec, s[8:9]
	v_mov_b32_e32 v8, 0
	v_mov_b32_e32 v28, 0
	v_mov_b32_e32 v29, 0
	v_mov_b32_e32 v30, 0
	v_mov_b32_e32 v31, 0
	s_and_saveexec_b64 s[0:1], s[2:3]
	s_cbranch_execz .LBB0_548
	v_add_co_u32_e32 v10, vcc, 0x3000, v10
	s_nop 1
	v_addc_co_u32_e32 v11, vcc, 0, v11, vcc
	global_load_dwordx4 v[28:31], v[10:11], off offset:1024

.LBB0_550:
	s_and_b32 s0, s16, 0x3c0
	v_or_b32_e32 v32, s0, v98
	v_lshlrev_b32_e32 v50, 2, v32
	v_readlane_b32 s16, v253, 48
	v_or_b32_e32 v32, 0x1000, v50
	v_readlane_b32 s17, v253, 49
	s_mov_b64 s[2:3], 0x3000
	v_or_b32_e32 v102, 0x2000, v50
	v_lshl_add_u64 v[58:59], s[16:17], 0, v[32:33]
	v_add_co_u32_e32 v56, vcc, s34, v58
	v_lshl_add_u64 v[54:55], v[58:59], 0, s[2:3]
	s_nop 0
	v_addc_co_u32_e32 v57, vcc, 0, v59, vcc
	global_load_dwordx4 v[50:53], v32, s[16:17] offset:16
	global_load_dwordx4 v[82:85], v32, s[16:17]
	global_load_dwordx4 v[86:89], v[56:57], off
	s_nop 0
	global_load_dwordx4 v[54:57], v[54:55], off offset:16
	s_mov_b64 s[10:11], 0x6000
	s_movk_i32 s1, 0x6000
	v_lshl_add_u64 v[60:61], v[58:59], 0, s[10:11]
	s_waitcnt vmcnt(0) lgkmcnt(0)
	v_lshlrev_b32_e32 v64, 16, v0
	v_and_b32_e32 v65, 0xffff0000, v0
	v_add_co_u32_e32 v58, vcc, s1, v58
	v_lshlrev_b32_e32 v62, 16, v12
	v_and_b32_e32 v63, 0xffff0000, v12
	v_addc_co_u32_e32 v59, vcc, 0, v59, vcc
	v_readlane_b32 s18, v253, 50
	v_readlane_b32 s19, v253, 51
	v_lshlrev_b32_e32 v66, 16, v4
	v_and_b32_e32 v67, 0xffff0000, v4
	v_mov_b32_e32 v103, v33
	v_lshl_add_u64 v[74:75], s[16:17], 0, v[102:103]
	v_add_co_u32_e32 v72, vcc, s34, v74
	v_lshl_add_u64 v[70:71], v[74:75], 0, s[2:3]
	s_nop 0
	v_addc_co_u32_e32 v73, vcc, 0, v75, vcc
	v_lshl_add_u64 v[76:77], v[74:75], 0, s[10:11]
	v_add_co_u32_e32 v74, vcc, s1, v74
	v_lshlrev_b32_e32 v78, 16, v20
	s_nop 0
	v_addc_co_u32_e32 v75, vcc, 0, v75, vcc
	v_and_b32_e32 v79, 0xffff0000, v20
	v_lshlrev_b32_e32 v0, 16, v1
	v_and_b32_e32 v1, 0xffff0000, v1
	v_lshlrev_b32_e32 v12, 16, v13
	v_and_b32_e32 v13, 0xffff0000, v13
	v_lshlrev_b32_e32 v4, 16, v5
	v_and_b32_e32 v5, 0xffff0000, v5
	s_and_b32 s2, s13, 0xffffffc0
	s_ashr_i32 s3, s2, 31
	v_mov_b32_e32 v101, v33
	v_readlane_b32 s24, v253, 56
	v_readlane_b32 s25, v253, 57
	s_andn2_b64 vcc, exec, s[8:9]
	s_mov_b32 s13, s15
	v_readlane_b32 s24, v253, 6
	v_readlane_b32 s25, v255, 22
	v_readlane_b32 s20, v253, 52
	v_readlane_b32 s21, v253, 53
	v_readlane_b32 s22, v253, 54
	v_readlane_b32 s23, v253, 55
	v_readlane_b32 s26, v253, 58
	v_readlane_b32 s27, v253, 59
	v_readlane_b32 s28, v253, 60
	v_readlane_b32 s29, v253, 61
	v_readlane_b32 s30, v253, 62
	v_readlane_b32 s31, v253, 63
	v_pk_mul_f32 v[64:65], v[86:87], v[64:65]
	s_nop 0
	v_pk_fma_f32 v[68:69], v[82:83], v[62:63], v[64:65]
	global_load_dwordx4 v[90:93], v[58:59], off
	global_load_dwordx4 v[62:65], v[60:61], off offset:16
	v_pk_mul_f32 v[0:1], v[88:89], v[0:1]
	s_waitcnt vmcnt(1)
	v_pk_fma_f32 v[58:59], v[90:91], v[66:67], v[68:69]
	global_load_dwordx4 v[66:69], v32, s[18:19] offset:16
	global_load_dwordx4 v[94:97], v32, s[18:19]
	v_lshlrev_b32_e32 v90, 16, v16
	v_and_b32_e32 v91, 0xffff0000, v16
	v_pk_fma_f32 v[0:1], v[84:85], v[12:13], v[0:1]
	v_lshlrev_b32_e32 v12, 16, v17
	v_and_b32_e32 v13, 0xffff0000, v17
	v_pk_fma_f32 v[0:1], v[92:93], v[4:5], v[0:1]
	v_lshlrev_b32_e32 v4, 16, v21
	v_and_b32_e32 v5, 0xffff0000, v21
	v_lshlrev_b32_e32 v16, 16, v29
	v_and_b32_e32 v17, 0xffff0000, v29
	v_mov_b32_e32 v29, v47
	s_waitcnt vmcnt(0)
	v_pk_add_f32 v[86:87], v[94:95], v[58:59]
	global_load_dwordx4 v[58:61], v102, s[16:17] offset:16
	global_load_dwordx4 v[80:83], v102, s[16:17]
	global_load_dwordx4 v[106:109], v[72:73], off
	s_nop 0
	global_load_dwordx4 v[70:73], v[70:71], off offset:16
	s_nop 0
	global_load_dwordx4 v[110:113], v[74:75], off
	s_nop 0
	global_load_dwordx4 v[74:77], v[76:77], off offset:16
	v_lshlrev_b32_e32 v94, 16, v28
	v_and_b32_e32 v95, 0xffff0000, v28
	v_pk_add_f32 v[0:1], v[96:97], v[0:1]
	s_mov_b32 s16, s14
	v_mov_b32_e32 v28, v46
	s_waitcnt vmcnt(3)
	v_pk_mul_f32 v[90:91], v[106:107], v[90:91]
	s_nop 0
	v_pk_fma_f32 v[78:79], v[80:81], v[78:79], v[90:91]
	v_pk_mul_f32 v[12:13], v[108:109], v[12:13]
	s_waitcnt vmcnt(1)
	v_pk_fma_f32 v[90:91], v[110:111], v[94:95], v[78:79]
	global_load_dwordx4 v[78:81], v102, s[18:19] offset:16
	global_load_dwordx4 v[114:117], v102, s[18:19]
	v_pk_fma_f32 v[4:5], v[82:83], v[4:5], v[12:13]
	v_lshlrev_b32_e32 v12, 16, v6
	v_pk_fma_f32 v[4:5], v[112:113], v[16:17], v[4:5]
	v_and_b32_e32 v13, 0xffff0000, v6
	v_lshlrev_b32_e32 v16, 16, v30
	v_and_b32_e32 v17, 0xffff0000, v30
	v_lshlrev_b32_e32 v6, 16, v31
	v_mov_b32_e32 v30, v48
	s_waitcnt vmcnt(0)
	v_pk_add_f32 v[4:5], v[116:117], v[4:5]
	s_nop 0
	v_pk_mul_f32 v[0:1], v[0:1], v[4:5]
	v_lshlrev_b32_e32 v4, 16, v2
	v_and_b32_e32 v5, 0xffff0000, v2
	ds_write2_b32 v104, v0, v1 offset0:2 offset1:3
	v_lshlrev_b32_e32 v0, 16, v14
	v_and_b32_e32 v1, 0xffff0000, v14
	v_pk_mul_f32 v[4:5], v[54:55], v[4:5]
	v_lshlrev_b32_e32 v2, 16, v3
	v_pk_fma_f32 v[0:1], v[50:51], v[0:1], v[4:5]
	v_lshlrev_b32_e32 v4, 16, v22
	v_pk_fma_f32 v[0:1], v[62:63], v[12:13], v[0:1]
	v_lshlrev_b32_e32 v12, 16, v18
	v_and_b32_e32 v13, 0xffff0000, v18
	v_and_b32_e32 v5, 0xffff0000, v22
	v_pk_mul_f32 v[12:13], v[70:71], v[12:13]
	v_pk_add_f32 v[0:1], v[66:67], v[0:1]
	v_pk_fma_f32 v[4:5], v[58:59], v[4:5], v[12:13]
	v_and_b32_e32 v3, 0xffff0000, v3
	v_pk_fma_f32 v[4:5], v[74:75], v[16:17], v[4:5]
	v_pk_mul_f32 v[2:3], v[56:57], v[2:3]
	v_pk_add_f32 v[4:5], v[78:79], v[4:5]
	v_pk_add_f32 v[90:91], v[114:115], v[90:91]
	v_pk_mul_f32 v[0:1], v[0:1], v[4:5]
	ds_write2_b32 v104, v0, v1 offset0:4 offset1:5
	v_lshlrev_b32_e32 v0, 16, v15
	v_and_b32_e32 v1, 0xffff0000, v15
	v_lshlrev_b32_e32 v4, 16, v7
	v_and_b32_e32 v5, 0xffff0000, v7
	v_pk_fma_f32 v[0:1], v[52:53], v[0:1], v[2:3]
	v_lshlrev_b32_e32 v2, 16, v23
	v_pk_fma_f32 v[0:1], v[64:65], v[4:5], v[0:1]
	v_lshlrev_b32_e32 v4, 16, v19
	v_and_b32_e32 v5, 0xffff0000, v19
	v_and_b32_e32 v3, 0xffff0000, v23
	v_pk_mul_f32 v[4:5], v[72:73], v[4:5]
	v_and_b32_e32 v7, 0xffff0000, v31
	v_pk_fma_f32 v[2:3], v[60:61], v[2:3], v[4:5]
	v_pk_add_f32 v[0:1], v[68:69], v[0:1]
	v_pk_fma_f32 v[2:3], v[76:77], v[6:7], v[2:3]
	v_pk_mul_f32 v[86:87], v[86:87], v[90:91]
	v_pk_add_f32 v[2:3], v[80:81], v[2:3]
	ds_write2_b32 v104, v86, v87 offset1:1
	v_pk_mul_f32 v[0:1], v[0:1], v[2:3]
	ds_write2_b32 v104, v0, v1 offset0:6 offset1:7
	s_waitcnt lgkmcnt(0)
	s_barrier
	ds_read2_b32 v[0:1], v105 offset1:65
	ds_read2_b32 v[2:3], v105 offset0:130 offset1:195
	v_add_u32_e32 v4, 0x400, v105
	s_waitcnt lgkmcnt(1)
	v_cvt_pk_bf16_f32 v0, v0, v1
	s_waitcnt lgkmcnt(0)
	v_cvt_pk_bf16_f32 v1, v2, v3
	ds_read2_b32 v[2:3], v4 offset0:4 offset1:69
	ds_read2_b32 v[4:5], v4 offset0:134 offset1:199
	s_waitcnt lgkmcnt(1)
	v_cvt_pk_bf16_f32 v2, v2, v3
	s_waitcnt lgkmcnt(0)
	v_cvt_pk_bf16_f32 v3, v4, v5
	v_add_u32_e32 v6, s0, v99
	v_mov_b64_e32 v[4:5], s[6:7]
	s_mov_b32 s0, 0xc000
	v_mad_i64_i32 v[4:5], s[0:1], v6, s0, v[4:5]
	v_lshl_add_u64 v[4:5], s[2:3], 1, v[4:5]
	v_lshl_add_u64 v[4:5], v[4:5], 0, v[100:101]
	v_mov_b64_e32 v[16:17], v[38:39]
	v_mov_b64_e32 v[20:21], v[42:43]
	global_store_dwordx4 v[4:5], v[0:3], off
	v_mov_b64_e32 v[18:19], v[40:41]
	v_mov_b64_e32 v[22:23], v[44:45]
	v_mov_b32_e32 v4, v34
	v_mov_b32_e32 v5, v35
	v_mov_b32_e32 v6, v36
	v_mov_b32_e32 v7, v37
	v_mov_b32_e32 v0, v24
	v_mov_b32_e32 v1, v25
	v_mov_b32_e32 v2, v26
	v_mov_b32_e32 v3, v27
	v_mov_b32_e32 v12, v8
	v_mov_b32_e32 v13, v9
	v_mov_b32_e32 v14, v10
	v_mov_b32_e32 v15, v11
	v_mov_b32_e32 v31, v49
	s_waitcnt lgkmcnt(0)
	s_barrier
	s_cbranch_vccz .LBB0_562

.LBB0_553:
	s_andn2_b64 vcc, exec, s[0:1]
	s_movk_i32 s34, 0x3000
	s_cbranch_vccnz .LBB0_550
	v_readlane_b32 s0, v255, 8
	v_readlane_b32 s1, v253, 4
	s_add_i32 s15, s0, s13
	s_add_i32 s14, s1, s16
	s_and_b32 s0, s15, 0xffffffc0
	s_and_b32 s1, s14, 0x3c0
	v_add_u32_e32 v10, s0, v99
	v_or_b32_e32 v42, s1, v98
	v_mov_b64_e32 v[8:9], s[4:5]
	v_mad_i64_i32 v[38:39], s[0:1], v10, s96, v[8:9]
	v_lshlrev_b32_e32 v32, 1, v42
	v_lshl_add_u64 v[40:41], v[38:39], 0, v[32:33]
	global_load_dwordx4 v[24:27], v[40:41], off offset:2048
	v_cmp_gt_i32_e32 vcc, s75, v10
	v_mov_b32_e32 v34, 0
	v_add_u32_e32 v46, -1, v10
	v_cndmask_b32_e32 v35, v228, v229, vcc
	v_and_b32_e32 v36, v35, v10
	v_cmp_ne_u32_e64 s[0:1], 0, v36
	v_mov_b32_e32 v8, 0
	v_mov_b32_e32 v9, 0
	v_mov_b32_e32 v10, 0
	v_mov_b32_e32 v11, 0
	s_and_saveexec_b64 s[2:3], s[0:1]
	s_cbranch_execz .LBB0_556
	v_mov_b64_e32 v[8:9], s[4:5]
	v_mad_i64_i32 v[8:9], s[10:11], v46, s96, v[8:9]
	v_lshl_add_u64 v[8:9], v[8:9], 0, v[32:33]
	global_load_dwordx4 v[8:11], v[8:9], off offset:2048
.LBB0_556:
	s_or_b64 exec, exec, s[2:3]
	v_cmp_ne_u32_e64 s[2:3], v36, v35
	v_mov_b32_e32 v35, 0
	v_mov_b32_e32 v36, 0
	v_mov_b32_e32 v37, 0
	s_and_saveexec_b64 s[10:11], s[2:3]
	s_cbranch_execz .LBB0_558
	s_mov_b64 s[18:19], 0x800
	v_lshl_add_u64 v[34:35], v[40:41], 0, s[18:19]
	v_add_co_u32_e32 v34, vcc, 0x3000, v34
	s_nop 1
	v_addc_co_u32_e32 v35, vcc, 0, v35, vcc
	global_load_dwordx4 v[34:37], v[34:35], off offset:1024
.LBB0_558:
	s_or_b64 exec, exec, s[10:11]
	v_or_b32_e32 v32, 0x800, v42
	v_lshlrev_b32_e32 v32, 1, v32
	v_lshl_add_u64 v[50:51], v[38:39], 0, v[32:33]
	global_load_dwordx4 v[38:41], v[50:51], off
	v_mov_b32_e32 v42, v33
	v_mov_b32_e32 v43, v33
	v_mov_b32_e32 v44, v33
	v_mov_b32_e32 v45, v33
	s_and_saveexec_b64 s[10:11], s[0:1]
	s_cbranch_execz .LBB0_560
	v_mov_b64_e32 v[42:43], s[4:5]
	v_mad_i64_i32 v[42:43], s[0:1], v46, s96, v[42:43]
	v_lshl_add_u64 v[42:43], v[42:43], 0, v[32:33]
	global_load_dwordx4 v[42:45], v[42:43], off
.LBB0_560:
	s_or_b64 exec, exec, s[10:11]
	v_mov_b32_e32 v49, 0
	v_mov_b32_e32 v48, 0
	v_mov_b32_e32 v47, 0
	v_mov_b32_e32 v46, 0
	s_and_saveexec_b64 s[0:1], s[2:3]
	s_cbranch_execz .LBB0_549
	v_add_co_u32_e32 v46, vcc, 0x3000, v50
	s_nop 1
	v_addc_co_u32_e32 v47, vcc, 0, v51, vcc
	global_load_dwordx4 v[46:49], v[46:47], off offset:1024
	s_branch .LBB0_549

.LBB0_568:
	v_ashrrev_i32_e32 v6, 8, v5
	v_add_u32_e32 v11, s17, v6
	v_mov_b64_e32 v[2:3], s[2:3]
	v_mad_i64_i32 v[2:3], s[12:13], v11, s96, v[2:3]
	v_lshl_add_u64 v[2:3], v[2:3], 0, v[32:33]
	v_add_co_u32_e32 v8, vcc, 0xc403000, v2
	s_mov_b64 s[12:13], 0xc403000
	s_nop 0
	v_addc_co_u32_e32 v9, vcc, 0, v3, vcc
	global_load_ushort v7, v[8:9], off
	v_cmp_gt_i32_e32 vcc, s75, v11
	v_lshl_add_u64 v[2:3], v[2:3], 0, s[12:13]
	v_mov_b32_e32 v8, 0
	v_cndmask_b32_e32 v10, v228, v229, vcc
	v_and_b32_e32 v11, v10, v11
	v_cmp_ne_u32_e32 vcc, 0, v11
	v_mov_b32_e32 v9, 0
	s_and_saveexec_b64 s[12:13], vcc
	s_cbranch_execz .LBB0_570
	v_add_co_u32_e32 v12, vcc, 0xffffcc00, v2
	s_nop 1
	v_addc_co_u32_e32 v13, vcc, -1, v3, vcc
	global_load_ushort v9, v[12:13], off
	s_waitcnt vmcnt(0) lgkmcnt(0)
	v_lshlrev_b32_e32 v9, 16, v9
.LBB0_570:
	s_or_b64 exec, exec, s[12:13]
	v_cmp_ne_u32_e32 vcc, v11, v10
	s_and_saveexec_b64 s[12:13], vcc
	s_cbranch_execz .LBB0_572
	v_add_co_u32_e32 v2, vcc, 0x3000, v2
	s_nop 1
	v_addc_co_u32_e32 v3, vcc, 0, v3, vcc
	global_load_ushort v2, v[2:3], off offset:1024
	s_waitcnt vmcnt(0) lgkmcnt(0)
	v_lshlrev_b32_e32 v8, 16, v2

.LBB0_579:
	v_ashrrev_i32_e32 v49, 31, v48
	v_lshl_add_u64 v[16:17], v[48:49], 0, s[66:67]
	v_lshlrev_b64 v[16:17], 7, v[16:17]
	v_lshl_add_u64 v[20:21], v[46:47], 0, v[16:17]
	global_load_dwordx4 v[16:19], v[20:21], off
	s_nop 0
	global_load_dwordx4 v[20:23], v[20:21], off offset:64
	v_lshl_add_u64 v[60:61], v[48:49], 2, s[0:1]
	global_load_dword v64, v[60:61], off
	s_waitcnt vmcnt(0) lgkmcnt(0)
	v_mfma_f32_16x16x32_bf16 v[60:63], v[0:3], v[16:19], 0
	v_mfma_f32_16x16x32_bf16 v[16:19], v[8:11], v[16:19], 0
	v_mfma_f32_16x16x32_bf16 v[60:63], v[4:7], v[20:23], v[60:63]
	v_mfma_f32_16x16x32_bf16 v[16:19], v[12:15], v[20:23], v[16:19]
	s_nop 6
	v_add_f32_e32 v49, v64, v60
	v_mul_f32_e32 v49, 0xbfb8aa3b, v49
	v_exp_f32_e32 v49, v49
	v_add_f32_e32 v16, v64, v16
	v_mul_f32_e32 v16, 0xbfb8aa3b, v16
	v_exp_f32_e32 v16, v16
	v_add_f32_e32 v49, 1.0, v49
	v_rcp_f32_e32 v49, v49
	v_add_f32_e32 v16, 1.0, v16
	v_rcp_f32_e32 v16, v16
	v_mul_f32_e32 v49, v59, v49
	v_cvt_pk_bf16_f32 v60, v49, v33
	v_add_u32_e32 v49, s9, v32
	ds_write_b16 v49, v60
	v_add_f32_e32 v60, v64, v61
	v_mul_f32_e32 v16, v59, v16
	v_mul_f32_e32 v60, 0xbfb8aa3b, v60
	v_cvt_pk_bf16_f32 v16, v16, v33
	v_exp_f32_e32 v60, v60
	ds_write_b16 v49, v16 offset:33024
	v_add_f32_e32 v16, v64, v17
	v_mul_f32_e32 v16, 0xbfb8aa3b, v16
	v_exp_f32_e32 v16, v16
	v_add_f32_e32 v60, 1.0, v60
	v_rcp_f32_e32 v60, v60
	s_add_i32 s9, s9, 64
	v_add_f32_e32 v16, 1.0, v16
	v_rcp_f32_e32 v16, v16
	v_mul_f32_e32 v60, v59, v60
	v_cvt_pk_bf16_f32 v60, v60, v33
	ds_write_b16 v49, v60 offset:2064
	v_add_f32_e32 v60, v64, v62
	v_mul_f32_e32 v16, v59, v16
	v_mul_f32_e32 v60, 0xbfb8aa3b, v60
	v_cvt_pk_bf16_f32 v16, v16, v33
	v_exp_f32_e32 v60, v60
	ds_write_b16 v49, v16 offset:35088
	v_add_f32_e32 v16, v64, v18
	v_mul_f32_e32 v16, 0xbfb8aa3b, v16
	v_exp_f32_e32 v16, v16
	v_add_f32_e32 v60, 1.0, v60
	v_rcp_f32_e32 v60, v60
	s_cmpk_eq_i32 s9, 0x100
	v_add_f32_e32 v16, 1.0, v16
	v_rcp_f32_e32 v16, v16
	v_mul_f32_e32 v60, v59, v60
	v_cvt_pk_bf16_f32 v60, v60, v33
	ds_write_b16 v49, v60 offset:4128
	v_add_f32_e32 v60, v64, v63
	v_mul_f32_e32 v16, v59, v16
	v_mul_f32_e32 v60, 0xbfb8aa3b, v60
	v_cvt_pk_bf16_f32 v16, v16, v33
	v_exp_f32_e32 v60, v60
	ds_write_b16 v49, v16 offset:37152
	v_add_f32_e32 v16, v64, v19
	v_mul_f32_e32 v16, 0xbfb8aa3b, v16
	v_exp_f32_e32 v16, v16
	v_add_f32_e32 v60, 1.0, v60
	v_rcp_f32_e32 v60, v60
	v_add_f32_e32 v16, 1.0, v16
	v_rcp_f32_e32 v16, v16
	v_mul_f32_e32 v60, v59, v60
	v_cvt_pk_bf16_f32 v60, v60, v33
	ds_write_b16 v49, v60 offset:6192
	v_mul_f32_e32 v16, v59, v16
	v_add_u32_e32 v60, 16, v48
	v_cvt_pk_bf16_f32 v16, v16, v33
	v_ashrrev_i32_e32 v61, 31, v60
	ds_write_b16 v49, v16 offset:39216
	v_lshl_add_u64 v[16:17], v[60:61], 0, s[66:67]
	v_lshlrev_b64 v[16:17], 7, v[16:17]
	v_lshl_add_u64 v[20:21], v[46:47], 0, v[16:17]
	global_load_dwordx4 v[16:19], v[20:21], off
	s_nop 0
	global_load_dwordx4 v[20:23], v[20:21], off offset:64
	v_lshl_add_u64 v[60:61], v[60:61], 2, s[0:1]
	global_load_dword v64, v[60:61], off
	v_add_u32_e32 v48, 32, v48
	s_waitcnt vmcnt(0) lgkmcnt(0)
	v_mfma_f32_16x16x32_bf16 v[60:63], v[0:3], v[16:19], 0
	v_mfma_f32_16x16x32_bf16 v[16:19], v[8:11], v[16:19], 0
	v_mfma_f32_16x16x32_bf16 v[60:63], v[4:7], v[20:23], v[60:63]
	v_mfma_f32_16x16x32_bf16 v[16:19], v[12:15], v[20:23], v[16:19]
	s_nop 6
	v_add_f32_e32 v60, v64, v60
	v_add_f32_e32 v16, v64, v16
	v_mul_f32_e32 v60, 0xbfb8aa3b, v60
	v_mul_f32_e32 v16, 0xbfb8aa3b, v16
	v_exp_f32_e32 v60, v60
	v_exp_f32_e32 v16, v16
	v_add_f32_e32 v60, 1.0, v60
	v_add_f32_e32 v16, 1.0, v16
	v_rcp_f32_e32 v60, v60
	v_rcp_f32_e32 v16, v16
	v_mul_f32_e32 v60, v59, v60
	v_mul_f32_e32 v16, v59, v16
	v_cvt_pk_bf16_f32 v60, v60, v33
	v_cvt_pk_bf16_f32 v16, v16, v33
	ds_write_b16 v49, v60 offset:32
	v_add_f32_e32 v60, v64, v61
	ds_write_b16 v49, v16 offset:33056
	v_add_f32_e32 v16, v64, v17
	v_mul_f32_e32 v60, 0xbfb8aa3b, v60
	v_mul_f32_e32 v16, 0xbfb8aa3b, v16
	v_exp_f32_e32 v60, v60
	v_exp_f32_e32 v16, v16
	v_add_f32_e32 v60, 1.0, v60
	v_add_f32_e32 v16, 1.0, v16
	v_rcp_f32_e32 v60, v60
	v_rcp_f32_e32 v16, v16
	v_mul_f32_e32 v60, v59, v60
	v_mul_f32_e32 v16, v59, v16
	v_cvt_pk_bf16_f32 v60, v60, v33
	v_cvt_pk_bf16_f32 v16, v16, v33
	ds_write_b16 v49, v60 offset:2096
	v_add_f32_e32 v60, v64, v62
	ds_write_b16 v49, v16 offset:35120
	v_add_f32_e32 v16, v64, v18
	v_mul_f32_e32 v60, 0xbfb8aa3b, v60
	v_mul_f32_e32 v16, 0xbfb8aa3b, v16
	v_exp_f32_e32 v60, v60
	v_exp_f32_e32 v16, v16
	v_add_f32_e32 v60, 1.0, v60
	v_add_f32_e32 v16, 1.0, v16
	v_rcp_f32_e32 v60, v60
	v_rcp_f32_e32 v16, v16
	v_mul_f32_e32 v60, v59, v60
	v_mul_f32_e32 v16, v59, v16
	v_cvt_pk_bf16_f32 v60, v60, v33
	v_cvt_pk_bf16_f32 v16, v16, v33
	ds_write_b16 v49, v60 offset:4160
	v_add_f32_e32 v60, v64, v63
	ds_write_b16 v49, v16 offset:37184
	v_add_f32_e32 v16, v64, v19
	v_mul_f32_e32 v60, 0xbfb8aa3b, v60
	v_mul_f32_e32 v16, 0xbfb8aa3b, v16
	v_exp_f32_e32 v60, v60
	v_exp_f32_e32 v16, v16
	v_add_f32_e32 v60, 1.0, v60
	v_add_f32_e32 v16, 1.0, v16
	v_rcp_f32_e32 v60, v60
	v_rcp_f32_e32 v16, v16
	v_mul_f32_e32 v60, v59, v60
	v_mul_f32_e32 v16, v59, v16
	v_cvt_pk_bf16_f32 v60, v60, v33
	ds_write_b16 v49, v60 offset:6224
	v_cvt_pk_bf16_f32 v16, v16, v33
	ds_write_b16 v49, v16 offset:39248
	s_cbranch_scc0 .LBB0_579
	s_waitcnt lgkmcnt(0)
	s_barrier
	ds_read_b128 v[0:3], v51 offset:18432
	s_lshl_b32 s66, s66, 1
	v_lshl_add_u64 v[4:5], v[26:27], 0, s[66:67]
	v_lshl_add_u64 v[6:7], v[4:5], 0, v[28:29]
	s_add_i32 s8, s8, 1
	s_waitcnt lgkmcnt(0)
	global_store_dwordx4 v[6:7], v[0:3], off
	ds_read_b128 v[0:3], v52 offset:18432
	v_lshl_add_u64 v[6:7], v[4:5], 0, v[30:31]
	s_cmp_eq_u32 s8, 4
	s_waitcnt lgkmcnt(0)
	global_store_dwordx4 v[6:7], v[0:3], off
	ds_read_b128 v[0:3], v53 offset:18432
	v_lshl_add_u64 v[6:7], v[4:5], 0, v[34:35]
	s_waitcnt lgkmcnt(0)
	global_store_dwordx4 v[6:7], v[0:3], off
	ds_read_b128 v[0:3], v54 offset:18432
	v_lshl_add_u64 v[6:7], v[4:5], 0, v[36:37]
	s_waitcnt lgkmcnt(0)
	global_store_dwordx4 v[6:7], v[0:3], off
	ds_read_b128 v[0:3], v55 offset:18432
	v_lshl_add_u64 v[6:7], v[4:5], 0, v[38:39]
	s_waitcnt lgkmcnt(0)
	global_store_dwordx4 v[6:7], v[0:3], off
	ds_read_b128 v[0:3], v56 offset:18432
	v_lshl_add_u64 v[6:7], v[4:5], 0, v[40:41]
	s_waitcnt lgkmcnt(0)
	global_store_dwordx4 v[6:7], v[0:3], off
	ds_read_b128 v[0:3], v57 offset:18432
	v_lshl_add_u64 v[6:7], v[4:5], 0, v[42:43]
	v_lshl_add_u64 v[4:5], v[4:5], 0, v[44:45]
	s_waitcnt lgkmcnt(0)
	global_store_dwordx4 v[6:7], v[0:3], off
	ds_read_b128 v[0:3], v58 offset:18432
	s_waitcnt lgkmcnt(0)
	global_store_dwordx4 v[4:5], v[0:3], off
	s_waitcnt lgkmcnt(0)
	s_barrier
	s_cbranch_scc0 .LBB0_578
	v_readlane_b32 s8, v253, 8
	v_readlane_b32 s14, v253, 14
	s_add_i32 s16, s16, s14
	s_cmpk_gt_i32 s16, 0x1aff
	v_readlane_b32 s9, v253, 9
	v_readlane_b32 s10, v253, 10
	v_readlane_b32 s11, v253, 11
	v_readlane_b32 s12, v253, 12
	v_readlane_b32 s13, v253, 13
	v_readlane_b32 s15, v253, 15
	s_cbranch_scc0 .LBB0_564

.LBB0_631:
	s_or_b64 exec, exec, s[12:13]
	v_lshlrev_b64 v[38:39], 13, v[38:39]
	v_lshl_add_u64 v[38:39], s[4:5], 0, v[38:39]
	v_lshl_add_u64 v[38:39], v[38:39], 0, v[32:33]
	global_load_dwordx2 v[60:61], v[38:39], off
	v_add_co_u32_e32 v38, vcc, s94, v38
	s_waitcnt vmcnt(0) lgkmcnt(0)
	v_lshlrev_b32_e32 v82, 16, v44
	v_addc_co_u32_e32 v39, vcc, 0, v39, vcc
	global_load_dwordx2 v[80:81], v[38:39], off
	v_and_b32_e32 v83, 0xffff0000, v44
	v_lshlrev_b32_e32 v84, 16, v40
	v_and_b32_e32 v85, 0xffff0000, v40
	v_lshlrev_b32_e32 v86, 16, v41
	v_and_b32_e32 v87, 0xffff0000, v41
	v_pk_add_f32 v[40:41], v[48:49], v[68:69]
	v_pk_add_f32 v[48:49], v[52:53], v[64:65]
	v_lshlrev_b32_e32 v44, 16, v45
	v_and_b32_e32 v45, 0xffff0000, v45
	v_pk_add_f32 v[52:53], v[54:55], v[66:67]
	v_pk_fma_f32 v[48:49], v[48:49], 0.5, v[82:83] op_sel_hi:[1,0,1] neg_lo:[0,0,1] neg_hi:[0,0,1]
	v_lshlrev_b32_e32 v38, 16, v42
	v_and_b32_e32 v39, 0xffff0000, v42
	v_pk_fma_f32 v[52:53], v[52:53], 0.5, v[44:45] op_sel_hi:[1,0,1] neg_lo:[0,0,1] neg_hi:[0,0,1]
	v_pk_fma_f32 v[48:49], v[12:13], v[48:49], v[82:83]
	v_pk_fma_f32 v[40:41], v[40:41], 0.5, v[38:39] op_sel_hi:[1,0,1] neg_lo:[0,0,1] neg_hi:[0,0,1]
	v_pk_fma_f32 v[52:53], v[14:15], v[52:53], v[44:45]
	v_pk_mul_f32 v[44:45], v[8:9], v[48:49]
	v_pk_add_f32 v[46:47], v[56:57], v[46:47]
	v_pk_fma_f32 v[38:39], v[4:5], v[40:41], v[38:39]
	v_pk_mul_f32 v[56:57], v[10:11], v[52:53]
	v_pk_mul_f32 v[40:41], v[44:45], v[44:45]
	v_pk_add_f32 v[54:55], v[58:59], v[62:63]
	v_pk_mul_f32 v[58:59], v[56:57], v[56:57]
	v_add_f32_e32 v32, v40, v41
	v_add_f32_e32 v32, v32, v58
	v_add_f32_e32 v32, v32, v59
	v_lshlrev_b32_e32 v42, 16, v43
	v_and_b32_e32 v43, 0xffff0000, v43
	v_add_f32_dpp v32, v32, v32 quad_perm:[1,0,3,2] row_mask:0xf bank_mask:0xf bound_ctrl:1
	v_pk_add_f32 v[50:51], v[50:51], v[70:71]
	v_mad_u32_u24 v62, v78, s95, v77
	v_add_f32_dpp v32, v32, v32 quad_perm:[2,3,0,1] row_mask:0xf bank_mask:0xf bound_ctrl:1
	v_pk_fma_f32 v[50:51], v[50:51], 0.5, v[42:43] op_sel_hi:[1,0,1] neg_lo:[0,0,1] neg_hi:[0,0,1]
	v_pk_fma_f32 v[46:47], v[46:47], 0.5, v[84:85] op_sel_hi:[1,0,1] neg_lo:[0,0,1] neg_hi:[0,0,1]
	v_add_f32_dpp v32, v32, v32 row_half_mirror row_mask:0xf bank_mask:0xf bound_ctrl:1
	v_pk_fma_f32 v[54:55], v[54:55], 0.5, v[86:87] op_sel_hi:[1,0,1] neg_lo:[0,0,1] neg_hi:[0,0,1]
	s_xor_b64 s[10:11], s[10:11], -1
	v_add_f32_dpp v32, v32, v32 row_mirror row_mask:0xf bank_mask:0xf bound_ctrl:1
	v_add_f32_e32 v32, 0x2b8cbccc, v32
	v_mul_f32_e32 v40, 0x4b800000, v32
	v_cmp_gt_f32_e32 vcc, s33, v32
	s_mov_b32 s12, 16
	v_lshl_add_u32 v63, v78, 8, v77
	v_cndmask_b32_e32 v32, v32, v40, vcc
	v_rsq_f32_e32 v32, v32
	v_pk_fma_f32 v[40:41], v[6:7], v[50:51], v[42:43]
	ds_write_b128 v62, v[38:41] offset:1024
	v_pk_fma_f32 v[42:43], v[0:1], v[46:47], v[84:85]
	v_mul_f32_e32 v38, 0x45800000, v32
	v_cndmask_b32_e32 v32, v32, v38, vcc
	v_pk_mul_f32 v[38:39], v[44:45], v[32:33] op_sel_hi:[1,0]
	v_pk_mul_f32 v[40:41], v[56:57], v[32:33] op_sel_hi:[1,0]
	ds_write_b128 v62, v[38:41]
	s_andn2_b64 vcc, exec, s[10:11]
	s_mov_b64 s[10:11], 0
	v_lshlrev_b32_e32 v32, 16, v60
	v_and_b32_e32 v44, 0xffff0000, v60
	v_lshlrev_b32_e32 v45, 16, v61
	v_and_b32_e32 v46, 0xffff0000, v61
	v_mul_f32_e32 v32, 0xbfb8aa3b, v32
	v_mul_f32_e32 v47, 0xbfb8aa3b, v44
	v_mul_f32_e32 v58, 0xbfb8aa3b, v45
	v_mul_f32_e32 v59, 0xbfb8aa3b, v46
	s_waitcnt vmcnt(0) lgkmcnt(0)
	v_lshlrev_b32_e32 v50, 16, v80
	v_and_b32_e32 v51, 0xffff0000, v80
	v_lshlrev_b32_e32 v56, 16, v81
	v_and_b32_e32 v57, 0xffff0000, v81
	v_exp_f32_e32 v44, v32
	v_exp_f32_e32 v45, v47
	v_exp_f32_e32 v46, v58
	v_exp_f32_e32 v47, v59
	v_pk_mul_f32 v[38:39], v[38:39], v[50:51]
	v_pk_mul_f32 v[40:41], v[40:41], v[56:57]
	v_pk_add_f32 v[50:51], v[50:51], -1.0 op_sel_hi:[1,0]
	v_pk_add_f32 v[56:57], v[56:57], -1.0 op_sel_hi:[1,0]
	ds_write_b128 v62, v[38:41] offset:512
	v_pk_fma_f32 v[38:39], v[16:17], v[50:51], 1.0 op_sel_hi:[1,1,0]
	v_pk_fma_f32 v[40:41], v[18:19], v[56:57], 1.0 op_sel_hi:[1,1,0]
	v_pk_mul_f32 v[38:39], v[48:49], v[38:39]
	v_pk_mul_f32 v[40:41], v[52:53], v[40:41]
	ds_write_b128 v62, v[38:41] offset:768
	ds_write_b128 v62, v[44:47] offset:256
	v_pk_fma_f32 v[44:45], v[2:3], v[54:55], v[86:87]
	ds_write_b128 v63, v[42:45] offset:40960
	s_cbranch_vccz .LBB0_636
.LBB0_632:
	v_or_b32_e32 v78, s12, v74
	v_bitop3_b32 v32, s12, v228, v74 bitop3:0x36
	v_cndmask_b32_e64 v47, v32, v78, s[6:7]
	v_or_b32_e32 v38, s18, v47
	v_mov_b64_e32 v[40:41], s[16:17]
	v_mad_u64_u32 v[40:41], s[12:13], v38, s96, v[40:41]
	v_mov_b32_e32 v32, 0x3400
	v_mad_i32_i24 v41, s19, v32, v41
	v_lshlrev_b32_e32 v32, 1, v79
	v_lshl_add_u64 v[62:63], v[40:41], 0, v[32:33]
	v_add_co_u32_e32 v40, vcc, 0x1000, v62
	v_lshl_add_u64 v[60:61], v[62:63], 0, s[68:69]
	s_nop 0
	v_addc_co_u32_e32 v41, vcc, 0, v63, vcc
	v_add_co_u32_e32 v44, vcc, 0x2000, v62
	v_mov_b32_e32 v39, s19
	s_nop 0
	v_addc_co_u32_e32 v45, vcc, 0, v63, vcc
	global_load_dwordx2 v[42:43], v[40:41], off offset:2048
	s_nop 0
	global_load_dwordx2 v[40:41], v[44:45], off offset:2048
	s_nop 0
	global_load_dwordx2 v[44:45], v[60:61], off offset:2048
	v_cmp_ne_u32_e32 vcc, 0, v47
	v_mov_b32_e32 v46, 0
	v_mov_b32_e32 v56, 0
	v_mov_b32_e32 v57, 0
	v_mov_b32_e32 v58, 0
	v_mov_b32_e32 v59, 0
	v_mov_b32_e32 v52, 0
	v_mov_b32_e32 v53, 0
	v_mov_b32_e32 v54, 0
	v_mov_b32_e32 v55, 0
	v_mov_b32_e32 v48, 0
	v_mov_b32_e32 v49, 0
	v_mov_b32_e32 v50, 0
	v_mov_b32_e32 v51, 0
	s_and_saveexec_b64 s[12:13], vcc
	s_cbranch_execz .LBB0_634
	v_add_co_u32_e32 v50, vcc, 0xffffe400, v62
	s_movk_i32 s21, 0xf400
	s_nop 0
	v_addc_co_u32_e32 v51, vcc, -1, v63, vcc
	s_movk_i32 s22, 0xe400
	v_add_co_u32_e32 v52, vcc, s21, v62
	s_mov_b32 s23, -1
	s_nop 0
	v_addc_co_u32_e32 v53, vcc, -1, v63, vcc
	v_lshl_add_u64 v[48:49], v[62:63], 0, s[22:23]
	global_load_dwordx2 v[50:51], v[50:51], off
	s_nop 0
	global_load_dwordx2 v[58:59], v[52:53], off
	global_load_dwordx2 v[54:55], v[48:49], off offset:2048
	s_waitcnt vmcnt(0) lgkmcnt(0)
	v_lshlrev_b32_e32 v48, 16, v50
	v_and_b32_e32 v49, 0xffff0000, v50
	v_lshlrev_b32_e32 v50, 16, v51
	v_and_b32_e32 v51, 0xffff0000, v51
	v_lshlrev_b32_e32 v52, 16, v54
	v_and_b32_e32 v53, 0xffff0000, v54
	v_lshlrev_b32_e32 v54, 16, v55
	v_and_b32_e32 v55, 0xffff0000, v55
	v_lshlrev_b32_e32 v56, 16, v58
	v_and_b32_e32 v57, 0xffff0000, v58
	v_lshlrev_b32_e32 v58, 16, v59
	v_and_b32_e32 v59, 0xffff0000, v59
.LBB0_634:
	s_or_b64 exec, exec, s[12:13]
	v_cmp_ne_u32_e32 vcc, s92, v47
	v_mov_b32_e32 v47, 0
	v_mov_b32_e32 v62, 0
	v_mov_b32_e32 v63, 0
	v_mov_b32_e32 v64, 0
	v_mov_b32_e32 v65, 0
	v_mov_b32_e32 v66, 0
	v_mov_b32_e32 v67, 0
	v_mov_b32_e32 v68, 0
	v_mov_b32_e32 v69, 0
	v_mov_b32_e32 v70, 0
	v_mov_b32_e32 v71, 0
	s_and_saveexec_b64 s[12:13], vcc
	s_cbranch_execz .LBB0_631
	v_add_co_u32_e32 v46, vcc, 0x3000, v60
	s_movk_i32 s21, 0x4000
	s_nop 0
	v_addc_co_u32_e32 v47, vcc, 0, v61, vcc
	v_add_co_u32_e32 v60, vcc, s21, v60
	global_load_dwordx2 v[62:63], v[46:47], off offset:1024
	s_nop 0
	global_load_dwordx2 v[46:47], v[46:47], off offset:3072
	v_addc_co_u32_e32 v61, vcc, 0, v61, vcc
	global_load_dwordx2 v[60:61], v[60:61], off offset:1024
	s_waitcnt vmcnt(0) lgkmcnt(0)
	v_lshlrev_b32_e32 v68, 16, v62
	v_and_b32_e32 v69, 0xffff0000, v62
	v_lshlrev_b32_e32 v70, 16, v63
	v_and_b32_e32 v71, 0xffff0000, v63
	v_lshlrev_b32_e32 v64, 16, v46
	v_and_b32_e32 v65, 0xffff0000, v46
	v_lshlrev_b32_e32 v66, 16, v47
	v_and_b32_e32 v67, 0xffff0000, v47
	v_lshlrev_b32_e32 v46, 16, v60
	v_and_b32_e32 v47, 0xffff0000, v60
	v_lshlrev_b32_e32 v62, 16, v61
	v_and_b32_e32 v63, 0xffff0000, v61
	s_branch .LBB0_631

.LBB0_642:
	v_or_b32_e32 v43, s28, v74
	v_or_b32_e32 v42, v43, v41
	v_sub_u32_e32 v45, 0xfff, v42
	v_cndmask_b32_e64 v42, v45, v42, s[6:7]
	v_lshl_add_u32 v43, v43, 8, v40
	ds_read_b128 v[46:49], v43 offset:49152
	v_ashrrev_i32_e32 v43, 31, v42
	v_lshl_add_u64 v[42:43], v[42:43], 0, s[18:19]
	v_lshlrev_b64 v[42:43], 11, v[42:43]
	v_lshl_add_u64 v[42:43], v[38:39], 0, v[42:43]
	s_mov_b32 s28, 16
	s_and_b64 vcc, exec, s[26:27]
	s_mov_b64 s[26:27], 0
	s_waitcnt lgkmcnt(0)
	v_cvt_pk_bf16_f32 v46, v46, v47
	v_cvt_pk_bf16_f32 v47, v48, v49
	global_store_dwordx2 v[42:43], v[46:47], off
	s_cbranch_vccnz .LBB0_642

.LBB0_718:
	v_mov_b32_e32 v3, 0xfffff01f
	v_or_b32_e32 v1, s8, v74
	v_bitop3_b32 v3, s8, v3, v74 bitop3:0x36
	v_or_b32_e32 v2, 0xfe0, v1
	v_add_u32_e32 v3, 0x1000, v3
	v_lshl_add_u32 v1, v1, 8, v0
	v_cndmask_b32_e64 v32, v3, v2, s[6:7]
	ds_read_b128 v[2:5], v1
	s_waitcnt lgkmcnt(0)
	v_cvt_pk_bf16_f32 v2, v2, v3
	v_cvt_pk_bf16_f32 v3, v4, v5
	v_lshl_add_u64 v[4:5], v[32:33], 0, s[18:19]
	v_lshlrev_b64 v[4:5], 11, v[4:5]
	v_lshl_add_u64 v[4:5], v[38:39], 0, v[4:5]
	s_mov_b32 s8, 16
	s_and_b64 vcc, exec, s[4:5]
	s_mov_b64 s[4:5], 0
	global_store_dwordx2 v[4:5], v[2:3], off
	s_cbranch_vccnz .LBB0_718
	s_branch .LBB0_628

.LBB0_745:
	s_or_b64 exec, exec, s[4:5]
	v_cndmask_b32_e64 v32, 8, 12, vcc
	v_lshlrev_b32_e32 v32, v32, v49
	v_lshlrev_b32_e32 v32, 1, v32
	v_lshl_add_u64 v[34:35], v[42:43], 0, v[32:33]
	v_ashrrev_i32_e32 v47, 31, v46
	v_lshl_add_u64 v[34:35], v[46:47], 1, v[34:35]
	v_lshlrev_b32_e32 v32, 3, v48
	v_lshl_add_u64 v[34:35], v[34:35], 0, v[32:33]
	v_cvt_pk_bf16_f32 v16, v16, v17
	v_cvt_pk_bf16_f32 v17, v18, v19
	global_store_dwordx2 v[34:35], v[16:17], off
	v_cvt_pk_bf16_f32 v16, v20, v21
	v_cvt_pk_bf16_f32 v17, v22, v23
	global_store_dwordx2 v[34:35], v[16:17], off offset:16
	v_cvt_pk_bf16_f32 v16, v24, v25
	v_cvt_pk_bf16_f32 v17, v26, v27
	global_store_dwordx2 v[34:35], v[16:17], off offset:32
	v_cvt_pk_bf16_f32 v16, v28, v29
	v_cvt_pk_bf16_f32 v17, v30, v31
	global_store_dwordx2 v[34:35], v[16:17], off offset:48
	s_and_saveexec_b64 s[0:1], vcc
	s_cbranch_execz .LBB0_747
	v_lshlrev_b32_e32 v32, 13, v49
	v_lshlrev_b32_e32 v18, 2, v48
	v_lshl_add_u64 v[16:17], v[42:43], 0, v[32:33]
	v_ashrrev_i32_e32 v45, 31, v44
	v_lshl_add_u64 v[16:17], v[44:45], 1, v[16:17]
	v_lshlrev_b32_e32 v32, 1, v18
	v_lshl_add_u64 v[16:17], v[16:17], 0, v[32:33]
	v_cvt_pk_bf16_f32 v0, v0, v1
	v_cvt_pk_bf16_f32 v1, v2, v3
	global_store_dwordx2 v[16:17], v[0:1], off
	v_cvt_pk_bf16_f32 v0, v4, v5
	v_cvt_pk_bf16_f32 v1, v6, v7
	global_store_dwordx2 v[16:17], v[0:1], off offset:16
	v_cvt_pk_bf16_f32 v0, v8, v9
	v_cvt_pk_bf16_f32 v1, v10, v11
	global_store_dwordx2 v[16:17], v[0:1], off offset:32
	v_cvt_pk_bf16_f32 v0, v12, v13
	v_cvt_pk_bf16_f32 v1, v14, v15
	global_store_dwordx2 v[16:17], v[0:1], off offset:48

.LBB0_751:
	s_or_b64 exec, exec, s[10:11]
	v_mov_b32_e32 v27, v33
	v_lshlrev_b64 v[26:27], 13, v[26:27]
	v_lshl_add_u64 v[26:27], v[22:23], 0, v[26:27]
	v_lshl_add_u64 v[26:27], v[26:27], 0, v[32:33]
	global_load_dwordx2 v[50:51], v[26:27], off
	v_add_co_u32_e32 v26, vcc, s94, v26
	s_waitcnt vmcnt(0) lgkmcnt(0)
	v_lshlrev_b32_e32 v68, 16, v30
	v_addc_co_u32_e32 v27, vcc, 0, v27, vcc
	global_load_dwordx2 v[66:67], v[26:27], off
	v_and_b32_e32 v69, 0xffff0000, v30
	v_lshlrev_b32_e32 v70, 16, v24
	v_and_b32_e32 v71, 0xffff0000, v24
	v_lshlrev_b32_e32 v72, 16, v25
	v_and_b32_e32 v73, 0xffff0000, v25
	v_pk_add_f32 v[24:25], v[36:37], v[58:59]
	v_pk_add_f32 v[36:37], v[42:43], v[54:55]
	v_lshlrev_b32_e32 v30, 16, v31
	v_and_b32_e32 v31, 0xffff0000, v31
	v_pk_add_f32 v[42:43], v[44:45], v[56:57]
	v_pk_fma_f32 v[36:37], v[36:37], 0.5, v[68:69] op_sel_hi:[1,0,1] neg_lo:[0,0,1] neg_hi:[0,0,1]
	v_lshlrev_b32_e32 v26, 16, v28
	v_and_b32_e32 v27, 0xffff0000, v28
	v_pk_add_f32 v[34:35], v[46:47], v[34:35]
	v_pk_fma_f32 v[42:43], v[42:43], 0.5, v[30:31] op_sel_hi:[1,0,1] neg_lo:[0,0,1] neg_hi:[0,0,1]
	v_pk_fma_f32 v[46:47], v[12:13], v[36:37], v[68:69]
	v_pk_fma_f32 v[24:25], v[24:25], 0.5, v[26:27] op_sel_hi:[1,0,1] neg_lo:[0,0,1] neg_hi:[0,0,1]
	v_pk_fma_f32 v[30:31], v[14:15], v[42:43], v[30:31]
	v_pk_mul_f32 v[36:37], v[8:9], v[46:47]
	v_pk_fma_f32 v[24:25], v[4:5], v[24:25], v[26:27]
	v_pk_mul_f32 v[42:43], v[10:11], v[30:31]
	v_pk_mul_f32 v[26:27], v[36:37], v[36:37]
	v_pk_add_f32 v[44:45], v[48:49], v[52:53]
	v_pk_mul_f32 v[48:49], v[42:43], v[42:43]
	v_add_f32_e32 v26, v26, v27
	v_add_f32_e32 v26, v26, v48
	v_add_f32_e32 v26, v26, v49
	v_lshlrev_b32_e32 v28, 16, v29
	v_and_b32_e32 v29, 0xffff0000, v29
	v_add_f32_dpp v26, v26, v26 quad_perm:[1,0,3,2] row_mask:0xf bank_mask:0xf bound_ctrl:1
	v_pk_add_f32 v[40:41], v[40:41], v[60:61]
	v_mad_u32_u24 v32, v21, s95, v83
	v_add_f32_dpp v26, v26, v26 quad_perm:[2,3,0,1] row_mask:0xf bank_mask:0xf bound_ctrl:1
	v_pk_fma_f32 v[40:41], v[40:41], 0.5, v[28:29] op_sel_hi:[1,0,1] neg_lo:[0,0,1] neg_hi:[0,0,1]
	v_pk_fma_f32 v[34:35], v[34:35], 0.5, v[70:71] op_sel_hi:[1,0,1] neg_lo:[0,0,1] neg_hi:[0,0,1]
	v_add_f32_dpp v26, v26, v26 row_half_mirror row_mask:0xf bank_mask:0xf bound_ctrl:1
	v_pk_fma_f32 v[44:45], v[44:45], 0.5, v[72:73] op_sel_hi:[1,0,1] neg_lo:[0,0,1] neg_hi:[0,0,1]
	s_xor_b64 s[4:5], s[4:5], -1
	v_add_f32_dpp v26, v26, v26 row_mirror row_mask:0xf bank_mask:0xf bound_ctrl:1
	v_add_f32_e32 v26, 0x2b8cbccc, v26
	v_mul_f32_e32 v27, 0x4b800000, v26
	v_cmp_gt_f32_e32 vcc, s33, v26
	s_mov_b32 s10, 16
	v_lshl_add_u32 v21, v21, 8, v83
	v_cndmask_b32_e32 v26, v26, v27, vcc
	v_rsq_f32_e32 v48, v26
	v_pk_fma_f32 v[26:27], v[6:7], v[40:41], v[28:29]
	ds_write_b128 v32, v[24:27] offset:1024
	v_pk_fma_f32 v[28:29], v[0:1], v[34:35], v[70:71]
	v_mul_f32_e32 v24, 0x45800000, v48
	v_cndmask_b32_e32 v26, v48, v24, vcc
	v_pk_mul_f32 v[24:25], v[36:37], v[26:27] op_sel_hi:[1,0]
	v_pk_mul_f32 v[26:27], v[42:43], v[26:27] op_sel_hi:[1,0]
	ds_write_b128 v32, v[24:27]
	s_andn2_b64 vcc, exec, s[4:5]
	s_mov_b64 s[4:5], 0
	v_lshlrev_b32_e32 v34, 16, v50
	v_and_b32_e32 v35, 0xffff0000, v50
	v_lshlrev_b32_e32 v36, 16, v51
	v_and_b32_e32 v37, 0xffff0000, v51
	v_mul_f32_e32 v34, 0xbfb8aa3b, v34
	v_mul_f32_e32 v35, 0xbfb8aa3b, v35
	v_mul_f32_e32 v36, 0xbfb8aa3b, v36
	v_mul_f32_e32 v37, 0xbfb8aa3b, v37
	s_waitcnt vmcnt(0) lgkmcnt(0)
	v_lshlrev_b32_e32 v40, 16, v66
	v_and_b32_e32 v41, 0xffff0000, v66
	v_lshlrev_b32_e32 v42, 16, v67
	v_and_b32_e32 v43, 0xffff0000, v67
	v_exp_f32_e32 v34, v34
	v_exp_f32_e32 v35, v35
	v_exp_f32_e32 v36, v36
	v_exp_f32_e32 v37, v37
	v_pk_mul_f32 v[24:25], v[24:25], v[40:41]
	v_pk_mul_f32 v[26:27], v[26:27], v[42:43]
	v_pk_add_f32 v[40:41], v[40:41], -1.0 op_sel_hi:[1,0]
	v_pk_add_f32 v[42:43], v[42:43], -1.0 op_sel_hi:[1,0]
	ds_write_b128 v32, v[24:27] offset:512
	v_pk_fma_f32 v[24:25], v[16:17], v[40:41], 1.0 op_sel_hi:[1,1,0]
	v_pk_fma_f32 v[26:27], v[18:19], v[42:43], 1.0 op_sel_hi:[1,1,0]
	v_pk_mul_f32 v[24:25], v[46:47], v[24:25]
	v_pk_mul_f32 v[26:27], v[30:31], v[26:27]
	v_pk_fma_f32 v[30:31], v[2:3], v[44:45], v[72:73]
	ds_write_b128 v32, v[24:27] offset:768
	ds_write_b128 v32, v[34:37] offset:256
	ds_write_b128 v21, v[28:31] offset:40960
	s_cbranch_vccz .LBB0_756
.LBB0_752:
	v_or_b32_e32 v21, s10, v81
	v_bitop3_b32 v24, s10, v229, v81 bitop3:0x36
	v_cndmask_b32_e64 v27, v24, v21, s[6:7]
	v_or_b32_e32 v26, v27, v38
	v_mov_b64_e32 v[24:25], s[28:29]
	v_mad_u64_u32 v[24:25], s[10:11], v26, s96, v[24:25]
	v_lshlrev_b32_e32 v32, 1, v62
	v_lshl_add_u64 v[52:53], v[24:25], 0, v[32:33]
	v_add_co_u32_e32 v24, vcc, 0x1000, v52
	v_lshl_add_u64 v[50:51], v[52:53], 0, s[68:69]
	s_nop 0
	v_addc_co_u32_e32 v25, vcc, 0, v53, vcc
	v_add_co_u32_e32 v30, vcc, 0x2000, v52
	v_mov_b32_e32 v34, 0
	s_nop 0
	v_addc_co_u32_e32 v31, vcc, 0, v53, vcc
	global_load_dwordx2 v[28:29], v[24:25], off offset:2048
	s_nop 0
	global_load_dwordx2 v[24:25], v[30:31], off offset:2048
	s_nop 0
	global_load_dwordx2 v[30:31], v[50:51], off offset:2048
	v_cmp_ne_u32_e32 vcc, 0, v27
	v_mov_b32_e32 v46, 0
	v_mov_b32_e32 v47, 0
	v_mov_b32_e32 v48, 0
	v_mov_b32_e32 v49, 0
	v_mov_b32_e32 v42, 0
	v_mov_b32_e32 v43, 0
	v_mov_b32_e32 v44, 0
	v_mov_b32_e32 v45, 0
	v_mov_b32_e32 v36, 0
	v_mov_b32_e32 v37, 0
	v_mov_b32_e32 v40, 0
	v_mov_b32_e32 v41, 0
	s_and_saveexec_b64 s[10:11], vcc
	s_cbranch_execz .LBB0_754
	s_movk_i32 s12, 0xe400
	s_mov_b32 s13, -1
	v_add_co_u32_e32 v40, vcc, 0xffffe400, v52
	v_lshl_add_u64 v[36:37], v[52:53], 0, s[12:13]
	s_nop 0
	v_addc_co_u32_e32 v41, vcc, -1, v53, vcc
	s_movk_i32 s12, 0xf400
	v_add_co_u32_e32 v42, vcc, s12, v52
	global_load_dwordx2 v[40:41], v[40:41], off
	s_nop 0
	v_addc_co_u32_e32 v43, vcc, -1, v53, vcc
	global_load_dwordx2 v[48:49], v[42:43], off
	global_load_dwordx2 v[44:45], v[36:37], off offset:2048
	s_waitcnt vmcnt(0) lgkmcnt(0)
	v_lshlrev_b32_e32 v36, 16, v40
	v_and_b32_e32 v37, 0xffff0000, v40
	v_lshlrev_b32_e32 v40, 16, v41
	v_and_b32_e32 v41, 0xffff0000, v41
	v_lshlrev_b32_e32 v42, 16, v44
	v_and_b32_e32 v43, 0xffff0000, v44
	v_lshlrev_b32_e32 v44, 16, v45
	v_and_b32_e32 v45, 0xffff0000, v45
	v_lshlrev_b32_e32 v46, 16, v48
	v_and_b32_e32 v47, 0xffff0000, v48
	v_lshlrev_b32_e32 v48, 16, v49
	v_and_b32_e32 v49, 0xffff0000, v49
.LBB0_754:
	s_or_b64 exec, exec, s[10:11]
	s_movk_i32 s10, 0xff
	v_cmp_ne_u32_e32 vcc, s10, v27
	v_mov_b32_e32 v35, 0
	v_mov_b32_e32 v52, 0
	v_mov_b32_e32 v53, 0
	v_mov_b32_e32 v54, 0
	v_mov_b32_e32 v55, 0
	v_mov_b32_e32 v56, 0
	v_mov_b32_e32 v57, 0
	v_mov_b32_e32 v58, 0
	v_mov_b32_e32 v59, 0
	v_mov_b32_e32 v60, 0
	v_mov_b32_e32 v61, 0
	s_and_saveexec_b64 s[10:11], vcc
	s_cbranch_execz .LBB0_751
	v_add_co_u32_e32 v34, vcc, 0x3000, v50
	s_movk_i32 s12, 0x4000
	s_nop 0
	v_addc_co_u32_e32 v35, vcc, 0, v51, vcc
	v_add_co_u32_e32 v50, vcc, s12, v50
	global_load_dwordx2 v[52:53], v[34:35], off offset:1024
	s_nop 0
	global_load_dwordx2 v[34:35], v[34:35], off offset:3072
	v_addc_co_u32_e32 v51, vcc, 0, v51, vcc
	global_load_dwordx2 v[50:51], v[50:51], off offset:1024
	s_waitcnt vmcnt(0) lgkmcnt(0)
	v_lshlrev_b32_e32 v58, 16, v52
	v_and_b32_e32 v59, 0xffff0000, v52
	v_lshlrev_b32_e32 v60, 16, v53
	v_and_b32_e32 v61, 0xffff0000, v53
	v_lshlrev_b32_e32 v54, 16, v34
	v_and_b32_e32 v55, 0xffff0000, v34
	v_lshlrev_b32_e32 v56, 16, v35
	v_and_b32_e32 v57, 0xffff0000, v35
	v_lshlrev_b32_e32 v34, 16, v50
	v_and_b32_e32 v35, 0xffff0000, v50
	v_lshlrev_b32_e32 v52, 16, v51
	v_and_b32_e32 v53, 0xffff0000, v51
	s_branch .LBB0_751

.LBB0_762:
	v_or_b32_e32 v47, s46, v81
	v_or_b32_e32 v46, v47, v45
	v_sub_u32_e32 v49, 0xff, v46
	v_cndmask_b32_e64 v46, v49, v46, s[6:7]
	v_lshl_add_u32 v47, v47, 8, v44
	ds_read_b128 v[50:53], v47 offset:49152
	v_ashrrev_i32_e32 v47, 31, v46
	v_lshl_add_u64 v[46:47], v[46:47], 0, v[38:39]
	v_lshlrev_b64 v[46:47], 11, v[46:47]
	v_lshl_add_u64 v[46:47], v[40:41], 0, v[46:47]
	s_mov_b32 s46, 16
	s_and_b64 vcc, exec, s[26:27]
	s_mov_b64 s[26:27], 0
	s_waitcnt lgkmcnt(0)
	v_cvt_pk_bf16_f32 v50, v50, v51
	v_cvt_pk_bf16_f32 v51, v52, v53
	global_store_dwordx2 v[46:47], v[50:51], off
	s_cbranch_vccnz .LBB0_762

.LBB0_838:
	v_mov_b32_e32 v3, 0xffffff1f
	v_or_b32_e32 v1, s8, v81
	v_bitop3_b32 v3, s8, v3, v81 bitop3:0x36
	v_or_b32_e32 v2, 0xe0, v1
	v_add_u32_e32 v3, 0x100, v3
	v_cndmask_b32_e64 v6, v3, v2, s[6:7]
	v_lshl_add_u32 v1, v1, 8, v0
	ds_read_b128 v[2:5], v1
	v_or_b32_e32 v32, v6, v38
	s_waitcnt lgkmcnt(0)
	v_cvt_pk_bf16_f32 v2, v2, v3
	v_cvt_pk_bf16_f32 v3, v4, v5
	v_lshlrev_b64 v[4:5], 11, v[32:33]
	v_lshl_add_u64 v[4:5], v[40:41], 0, v[4:5]
	s_mov_b32 s8, 16
	s_and_b64 vcc, exec, s[4:5]
	s_mov_b64 s[4:5], 0
	global_store_dwordx2 v[4:5], v[2:3], off
	s_cbranch_vccnz .LBB0_838
.LBB0_839:
	s_or_b64 exec, exec, s[2:3]
	s_and_saveexec_b64 s[2:3], s[10:11]
	s_cbranch_execz .LBB0_720
	s_waitcnt vmcnt(0)
	v_and_b32_e32 v0, 0x3e0, v78
	v_lshlrev_b32_e32 v1, 4, v80
	v_or3_b32 v0, v1, v0, v79
	v_lshlrev_b32_e32 v0, 12, v0
	v_lshlrev_b32_e32 v1, 6, v84
	v_or3_b32 v32, v1, v0, v85
	v_lshl_add_u64 v[0:1], v[32:33], 2, s[36:37]
	global_store_dwordx4 v[0:1], v[20:23], off
	global_store_dwordx4 v[0:1], v[24:27], off offset:16
	global_store_dwordx4 v[0:1], v[34:37], off offset:256
	global_store_dwordx4 v[0:1], v[28:31], off offset:272
	s_branch .LBB0_720

.LBB0_885:
	s_or_b64 exec, exec, s[34:35]
	v_readlane_b32 s0, v253, 8
	v_readlane_b32 s1, v253, 9
	v_readlane_b32 s2, v253, 10
	v_readlane_b32 s3, v253, 11
	v_readlane_b32 s4, v253, 12
	v_readlane_b32 s5, v253, 13
	s_mov_b64 s[10:11], s[4:5]
	s_mov_b64 s[0:1], s[2:3]
	s_waitcnt lgkmcnt(0)
	s_barrier
	s_waitcnt vmcnt(0)
	v_mov_b32_e32 v0, v224
	v_readlane_b32 s0, v255, 32
	v_readlane_b32 s1, v255, 33
	s_and_b64 vcc, exec, s[0:1]
	v_readlane_b32 s6, v253, 14
	v_readlane_b32 s7, v253, 15
	s_cbranch_vccnz .LBB0_916
	s_add_u32 s2, s10, 0xc400000
	v_ashrrev_i32_e32 v155, 3, v0
	v_lshlrev_b32_e32 v0, 3, v0
	v_readlane_b32 s0, v254, 38
	s_addc_u32 s3, s11, 0
	v_and_b32_e32 v160, 56, v0
	v_add_u32_e32 v7, s0, v155
	v_readlane_b32 s0, v254, 31
	v_readlane_b32 s1, v254, 39
	v_mov_b64_e32 v[0:1], s[2:3]
	v_or_b32_e32 v6, s0, v160
	v_mad_i64_i32 v[0:1], s[0:1], v7, s96, v[0:1]
	v_lshlrev_b32_e32 v4, 1, v6
	v_mov_b32_e32 v5, v33
	v_lshl_add_u64 v[2:3], v[0:1], 0, v[4:5]
	global_load_dwordx4 v[90:93], v[2:3], off
	v_cmp_gt_i32_e32 vcc, s75, v7
	v_mov_b32_e32 v44, v33
	v_mov_b32_e32 v45, v33
	v_cndmask_b32_e32 v8, v228, v229, vcc
	v_and_b32_e32 v9, v8, v7
	v_mov_b32_e32 v42, v33
	v_mov_b32_e32 v43, v33
	v_mov_b64_e32 v[96:97], v[44:45]
	v_cmp_ne_u32_e64 s[0:1], 0, v9
	v_add_u32_e32 v7, -1, v7
	v_mov_b64_e32 v[94:95], v[42:43]
	s_and_saveexec_b64 s[4:5], s[0:1]
	s_cbranch_execz .LBB0_888
	v_mov_b64_e32 v[10:11], s[2:3]
	v_mad_i64_i32 v[10:11], s[6:7], v7, s96, v[10:11]
	v_lshl_add_u64 v[10:11], v[10:11], 0, v[4:5]
	global_load_dwordx4 v[94:97], v[10:11], off
.LBB0_888:
	s_or_b64 exec, exec, s[4:5]
	v_cmp_ne_u32_e64 s[4:5], v9, v8
	s_and_saveexec_b64 s[6:7], s[4:5]
	s_cbranch_execz .LBB0_890
	v_add_co_u32_e32 v8, vcc, 0x3000, v2
	s_nop 1
	v_addc_co_u32_e32 v9, vcc, 0, v3, vcc
	global_load_dwordx4 v[42:45], v[8:9], off offset:1024
.LBB0_890:
	s_or_b64 exec, exec, s[6:7]
	global_load_dwordx4 v[54:57], v[2:3], off offset:2048
	v_mov_b32_e32 v34, v33
	v_mov_b32_e32 v35, v33
	v_mov_b32_e32 v32, v33
	v_mov_b64_e32 v[60:61], v[34:35]
	v_mov_b64_e32 v[58:59], v[32:33]
	s_and_saveexec_b64 s[6:7], s[0:1]
	s_cbranch_execz .LBB0_892
	v_mov_b64_e32 v[8:9], s[2:3]
	v_mad_i64_i32 v[8:9], s[8:9], v7, s96, v[8:9]
	v_mov_b32_e32 v5, v33
	v_lshl_add_u64 v[4:5], v[8:9], 0, v[4:5]
	global_load_dwordx4 v[58:61], v[4:5], off offset:2048
.LBB0_892:
	s_or_b64 exec, exec, s[6:7]
	v_mov_b64_e32 v[64:65], v[34:35]
	v_mov_b64_e32 v[62:63], v[32:33]
	s_and_saveexec_b64 s[6:7], s[4:5]
	s_cbranch_execz .LBB0_894
	s_mov_b64 s[8:9], 0x800
	v_lshl_add_u64 v[2:3], v[2:3], 0, s[8:9]
	v_add_co_u32_e32 v2, vcc, 0x3000, v2
	s_nop 1
	v_addc_co_u32_e32 v3, vcc, 0, v3, vcc
	global_load_dwordx4 v[62:65], v[2:3], off offset:1024
.LBB0_894:
	s_or_b64 exec, exec, s[6:7]
	v_or_b32_e32 v2, 0x800, v6
	v_lshlrev_b32_e32 v32, 1, v2
	v_lshl_add_u64 v[0:1], v[0:1], 0, v[32:33]
	global_load_dwordx4 v[66:69], v[0:1], off
	v_mov_b32_e32 v74, v33
	v_mov_b32_e32 v75, v33
	v_mov_b32_e32 v76, v33
	v_mov_b32_e32 v77, v33
	v_mov_b64_e32 v[70:71], v[74:75]
	v_mov_b64_e32 v[72:73], v[76:77]
	s_and_saveexec_b64 s[6:7], s[0:1]
	s_cbranch_execz .LBB0_896
	v_mov_b64_e32 v[2:3], s[2:3]
	v_mad_i64_i32 v[2:3], s[0:1], v7, s96, v[2:3]
	v_lshl_add_u64 v[2:3], v[2:3], 0, v[32:33]
	global_load_dwordx4 v[70:73], v[2:3], off
.LBB0_896:
	s_or_b64 exec, exec, s[6:7]
	s_and_saveexec_b64 s[0:1], s[4:5]
	s_cbranch_execz .LBB0_898
	v_add_co_u32_e32 v0, vcc, 0x3000, v0
	s_nop 1
	v_addc_co_u32_e32 v1, vcc, 0, v1, vcc
	global_load_dwordx4 v[74:77], v[0:1], off offset:1024
.LBB0_898:
	s_or_b64 exec, exec, s[0:1]
	s_add_u32 s6, s10, 0x2bc00000
	s_addc_u32 s7, s11, 0
	v_readlane_b32 s0, v254, 31
	v_mov_b64_e32 v[0:1], s[6:7]
	v_lshlrev_b32_e32 v32, 1, v160
	v_add_u32_e32 v2, s0, v155
	s_mov_b32 s0, 0xc000
	v_mad_i64_i32 v[0:1], s[0:1], v2, s0, v[0:1]
	v_readlane_b32 s0, v254, 38
	v_readlane_b32 s1, v254, 39
	s_add_u32 s8, s10, 0x6400000
	s_addc_u32 s9, s11, 0
	v_lshl_add_u64 v[0:1], s[0:1], 1, v[0:1]
	v_lshl_add_u64 v[0:1], v[0:1], 0, v[32:33]
	global_load_dwordx4 v[46:49], v[0:1], off
	s_movk_i32 s0, 0x104
	v_lshl_add_u32 v0, v160, 2, 16
	v_lshl_add_u32 v1, v155, 2, 16
	v_mul_lo_u32 v2, v155, s0
	v_mul_u32_u24_e32 v3, 0x104, v160
	s_add_u32 s10, s10, 0x300ac600
	s_addc_u32 s11, s11, 0
	v_add_u32_e32 v161, v1, v3
	v_add_u32_e32 v233, v0, v2
	v_lshlrev_b32_e32 v162, 1, v160
	v_readlane_b32 s22, v254, 29
	v_readlane_b32 s21, v254, 30
	s_mov_b32 s18, s70
	s_branch .LBB0_901
.LBB0_899:
	s_or_b64 exec, exec, s[0:1]
	v_add_u32_e32 v32, s15, v155
	v_mov_b64_e32 v[38:39], s[6:7]
	s_mov_b32 s0, 0xc000
	v_mad_i64_i32 v[38:39], s[0:1], v32, s0, v[38:39]
	s_ashr_i32 s15, s14, 31
	v_lshl_add_u64 v[38:39], s[14:15], 1, v[38:39]
	v_mov_b32_e32 v163, v33
	v_lshl_add_u64 v[38:39], v[38:39], 0, v[162:163]
	global_load_dwordx4 v[38:41], v[38:39], off
.LBB0_900:
	s_waitcnt vmcnt(0) lgkmcnt(0)
	v_lshlrev_b32_e32 v32, 16, v46
	v_and_b32_e32 v46, 0xffff0000, v46
	v_lshlrev_b32_e32 v50, 16, v47
	v_and_b32_e32 v47, 0xffff0000, v47
	v_lshlrev_b32_e32 v51, 16, v48
	v_and_b32_e32 v48, 0xffff0000, v48
	ds_write2_b32 v161, v32, v46 offset1:65
	ds_write2_b32 v161, v50, v47 offset0:130 offset1:195
	v_add_u32_e32 v32, 0x400, v161
	s_and_b32 s0, s21, 0x3c0
	v_readlane_b32 s76, v253, 48
	v_lshlrev_b32_e32 v52, 16, v49
	v_and_b32_e32 v49, 0xffff0000, v49
	ds_write2_b32 v32, v51, v48 offset0:4 offset1:69
	ds_write2_b32 v32, v52, v49 offset0:134 offset1:199
	v_or_b32_e32 v32, s0, v160
	v_readlane_b32 s77, v253, 49
	v_lshlrev_b32_e32 v32, 2, v32
	v_readlane_b32 s78, v253, 50
	v_readlane_b32 s79, v253, 51
	s_mov_b64 s[36:37], s[76:77]
	s_waitcnt lgkmcnt(0)
	s_barrier
	global_load_dwordx4 v[98:101], v32, s[36:37] offset:16
	global_load_dwordx4 v[102:105], v32, s[36:37]
	v_lshl_add_u64 v[46:47], s[36:37], 0, v[32:33]
	s_and_b32 s1, s22, 0xffffffc0
	v_lshlrev_b32_e32 v180, 16, v44
	v_and_b32_e32 v178, 0xffff0000, v44
	v_add_co_u32_e32 v44, vcc, s23, v46
	v_add_u32_e32 v164, s1, v155
	v_lshlrev_b32_e32 v168, 16, v45
	v_and_b32_e32 v166, 0xffff0000, v45
	s_mov_b64 s[4:5], 0x3000
	v_addc_co_u32_e32 v45, vcc, 0, v47, vcc
	s_mov_b64 s[14:15], 0x6000
	s_movk_i32 s1, 0x6000
	v_lshlrev_b32_e32 v196, 16, v42
	v_and_b32_e32 v194, 0xffff0000, v42
	v_lshlrev_b32_e32 v192, 16, v43
	v_and_b32_e32 v190, 0xffff0000, v43
	v_lshl_add_u64 v[42:43], v[46:47], 0, s[4:5]
	v_lshl_add_u64 v[48:49], v[46:47], 0, s[14:15]
	v_add_co_u32_e32 v46, vcc, s1, v46
	v_or_b32_e32 v118, 0x1000, v32
	v_mov_b32_e32 v119, v33
	v_addc_co_u32_e32 v47, vcc, 0, v47, vcc
	v_lshlrev_b32_e32 v186, 16, v96
	v_and_b32_e32 v182, 0xffff0000, v96
	v_lshlrev_b32_e32 v174, 16, v97
	v_and_b32_e32 v170, 0xffff0000, v97
	v_lshlrev_b32_e32 v206, 16, v94
	v_and_b32_e32 v210, 0xffff0000, v94
	v_lshlrev_b32_e32 v202, 16, v95
	v_and_b32_e32 v198, 0xffff0000, v95
	v_or_b32_e32 v150, 0x2000, v32
	v_mov_b32_e32 v151, v33
	v_lshl_add_u64 v[130:131], s[36:37], 0, v[150:151]
	v_lshl_add_u64 v[126:127], v[130:131], 0, s[4:5]
	s_mov_b64 s[38:39], s[78:79]
	global_load_dwordx4 v[78:81], v[44:45], off
	s_nop 0
	global_load_dwordx4 v[42:45], v[42:43], off offset:16
	v_lshlrev_b32_e32 v207, 16, v90
	global_load_dwordx4 v[86:89], v[46:47], off
	global_load_dwordx4 v[50:53], v[48:49], off offset:16
	s_nop 0
	global_load_dwordx4 v[46:49], v32, s[38:39] offset:16
	global_load_dwordx4 v[82:85], v32, s[38:39]
	v_and_b32_e32 v211, 0xffff0000, v90
	v_lshlrev_b32_e32 v203, 16, v91
	v_and_b32_e32 v199, 0xffff0000, v91
	v_lshlrev_b32_e32 v187, 16, v92
	v_and_b32_e32 v183, 0xffff0000, v92
	v_lshlrev_b32_e32 v175, 16, v93
	v_and_b32_e32 v171, 0xffff0000, v93
	global_load_dwordx4 v[90:93], v118, s[36:37] offset:16
	global_load_dwordx4 v[106:109], v118, s[36:37]
	v_lshl_add_u64 v[132:133], v[130:131], 0, s[14:15]
	v_lshlrev_b32_e32 v159, 16, v66
	v_lshlrev_b32_e32 v158, 16, v54
	v_lshlrev_b32_e32 v157, 16, v70
	v_lshlrev_b32_e32 v156, 16, v58
	v_lshlrev_b32_e32 v215, 16, v74
	v_lshlrev_b32_e32 v214, 16, v62
	v_ashrrev_i32_e32 v165, 31, v164
	s_lshl_b32 s66, s0, 1
	v_mov_b32_e32 v163, v33
	v_readlane_b32 s80, v253, 52
	v_readlane_b32 s81, v253, 53
	v_readlane_b32 s82, v253, 54
	v_readlane_b32 s83, v253, 55
	v_readlane_b32 s84, v253, 56
	v_readlane_b32 s85, v253, 57
	v_readlane_b32 s86, v253, 58
	v_readlane_b32 s87, v253, 59
	v_readlane_b32 s88, v253, 60
	v_readlane_b32 s89, v253, 61
	v_readlane_b32 s90, v253, 62
	v_readlane_b32 s91, v253, 63
	v_readlane_b32 s76, v254, 0
	s_mov_b32 s22, s20
	s_mov_b32 s21, s19
	v_readlane_b32 s77, v254, 1
	v_readlane_b32 s78, v254, 2
	v_readlane_b32 s79, v254, 3
	s_waitcnt vmcnt(9)
	v_mov_b32_e32 v188, v98
	v_mov_b32_e32 v184, v99
	v_lshl_add_u64 v[98:99], s[36:37], 0, v[118:119]
	v_add_co_u32_e32 v96, vcc, s23, v98
	v_mov_b32_e32 v176, v100
	s_nop 0
	v_addc_co_u32_e32 v97, vcc, 0, v99, vcc
	v_mov_b32_e32 v172, v101
	v_lshl_add_u64 v[94:95], v[98:99], 0, s[4:5]
	v_lshl_add_u64 v[100:101], v[98:99], 0, s[14:15]
	v_add_co_u32_e32 v98, vcc, s1, v98
	s_waitcnt vmcnt(8)
	v_mov_b32_e32 v208, v102
	v_addc_co_u32_e32 v99, vcc, 0, v99, vcc
	v_add_co_u32_e32 v128, vcc, s23, v130
	v_mov_b32_e32 v212, v103
	s_nop 0
	v_addc_co_u32_e32 v129, vcc, 0, v131, vcc
	v_mov_b32_e32 v204, v104
	v_mov_b32_e32 v200, v105
	global_load_dwordx4 v[110:113], v[96:97], off
	s_nop 0
	global_load_dwordx4 v[94:97], v[94:95], off offset:16
	s_nop 0
	global_load_dwordx4 v[114:117], v[98:99], off
	global_load_dwordx4 v[102:105], v[100:101], off offset:16
	s_nop 0
	global_load_dwordx4 v[98:101], v118, s[38:39] offset:16
	s_nop 0
	global_load_dwordx4 v[118:121], v118, s[38:39]
	s_nop 0
	global_load_dwordx4 v[122:125], v150, s[36:37] offset:16
	global_load_dwordx4 v[138:141], v150, s[36:37]
	global_load_dwordx4 v[142:145], v[128:129], off
	s_nop 0
	global_load_dwordx4 v[126:129], v[126:127], off offset:16
	v_add_co_u32_e32 v130, vcc, s1, v130
	v_readlane_b32 s80, v254, 4
	s_nop 0
	v_addc_co_u32_e32 v131, vcc, 0, v131, vcc
	global_load_dwordx4 v[146:149], v[130:131], off
	global_load_dwordx4 v[134:137], v[132:133], off offset:16
	s_nop 0
	global_load_dwordx4 v[130:133], v150, s[38:39] offset:16
	s_nop 0
	global_load_dwordx4 v[150:153], v150, s[38:39]
	v_cmp_gt_i32_e32 vcc, s75, v164
	v_readlane_b32 s81, v254, 5
	v_readlane_b32 s82, v254, 6
	v_readlane_b32 s83, v254, 7
	v_readlane_b32 s84, v254, 8
	v_readlane_b32 s85, v254, 9
	v_readlane_b32 s86, v254, 10
	s_waitcnt vmcnt(21)
	v_mov_b32_e32 v209, v78
	v_mov_b32_e32 v213, v79
	v_mov_b32_e32 v205, v80
	v_mov_b32_e32 v201, v81
	s_waitcnt vmcnt(20)
	v_mov_b32_e32 v189, v42
	v_mul_f32_e32 v42, v42, v187
	v_mov_b32_e32 v185, v43
	v_mov_b32_e32 v177, v44
	v_mov_b32_e32 v173, v45
	v_readlane_b32 s87, v254, 11
	v_readlane_b32 s88, v254, 12
	s_waitcnt vmcnt(14)
	v_mov_b32_e32 v216, v106
	v_readlane_b32 s89, v254, 13
	v_readlane_b32 s90, v254, 14
	v_readlane_b32 s91, v254, 15
	s_waitcnt vmcnt(13)
	v_mov_b32_e32 v218, v110
	v_lshlrev_b32_e32 v110, 16, v59
	s_waitcnt vmcnt(5)
	v_mov_b32_e32 v219, v142
	v_mov_b32_e32 v217, v138
	v_pk_mul_f32 v[158:159], v[218:219], v[158:159]
	v_mov_b32_e32 v142, v111
	v_pk_fma_f32 v[156:157], v[216:217], v[156:157], v[158:159]
	v_mov_b32_e32 v158, v114
	s_waitcnt vmcnt(3)
	v_mov_b32_e32 v159, v146
	v_pk_fma_f32 v[156:157], v[158:159], v[214:215], v[156:157]
	v_mov_b32_e32 v158, v118
	s_waitcnt vmcnt(0)
	v_mov_b32_e32 v159, v150
	v_pk_add_f32 v[214:215], v[158:159], v[156:157]
	v_and_b32_e32 v159, 0xffff0000, v66
	v_and_b32_e32 v158, 0xffff0000, v54
	v_and_b32_e32 v157, 0xffff0000, v70
	v_and_b32_e32 v156, 0xffff0000, v58
	v_mov_b32_e32 v138, v107
	v_pk_mul_f32 v[106:107], v[142:143], v[158:159]
	v_mov_b32_e32 v146, v115
	v_lshlrev_b32_e32 v115, 16, v67
	v_lshlrev_b32_e32 v114, 16, v55
	v_mov_b32_e32 v142, v112
	v_mov_b32_e32 v143, v144
	v_and_b32_e32 v70, 0xffff0000, v59
	v_and_b32_e32 v59, 0xffff0000, v67
	v_and_b32_e32 v58, 0xffff0000, v55
	v_mov_b32_e32 v144, v113
	v_pk_fma_f32 v[106:107], v[138:139], v[156:157], v[106:107]
	v_lshlrev_b32_e32 v111, 16, v71
	v_mov_b32_e32 v138, v108
	v_mov_b32_e32 v139, v140
	v_pk_mul_f32 v[114:115], v[142:143], v[114:115]
	v_and_b32_e32 v71, 0xffff0000, v71
	v_mov_b32_e32 v140, v109
	v_pk_mul_f32 v[58:59], v[144:145], v[58:59]
	v_mov_b32_e32 v150, v119
	v_lshlrev_b32_e32 v119, 16, v75
	v_lshlrev_b32_e32 v118, 16, v63
	v_pk_fma_f32 v[110:111], v[138:139], v[110:111], v[114:115]
	v_mov_b32_e32 v114, v116
	v_mov_b32_e32 v115, v148
	v_and_b32_e32 v55, 0xffff0000, v75
	v_and_b32_e32 v54, 0xffff0000, v63
	v_pk_fma_f32 v[58:59], v[140:141], v[70:71], v[58:59]
	v_mov_b32_e32 v148, v117
	v_and_b32_e32 v217, 0xffff0000, v74
	v_and_b32_e32 v216, 0xffff0000, v62
	v_pk_fma_f32 v[110:111], v[114:115], v[118:119], v[110:111]
	v_mov_b32_e32 v115, v152
	v_pk_fma_f32 v[54:55], v[148:149], v[54:55], v[58:59]
	v_mov_b32_e32 v152, v121
	v_lshlrev_b32_e32 v63, 16, v68
	v_lshlrev_b32_e32 v62, 16, v56
	v_mov_b32_e32 v74, v94
	v_mov_b32_e32 v75, v126
	v_pk_add_f32 v[58:59], v[152:153], v[54:55]
	v_lshlrev_b32_e32 v55, 16, v72
	v_lshlrev_b32_e32 v54, 16, v60
	v_mov_b32_e32 v70, v90
	v_mov_b32_e32 v71, v122
	v_pk_mul_f32 v[62:63], v[74:75], v[62:63]
	v_lshlrev_b32_e32 v67, 16, v76
	v_lshlrev_b32_e32 v66, 16, v64
	v_pk_fma_f32 v[54:55], v[70:71], v[54:55], v[62:63]
	v_mov_b32_e32 v62, v102
	v_mov_b32_e32 v63, v134
	v_pk_fma_f32 v[54:55], v[62:63], v[66:67], v[54:55]
	v_mov_b32_e32 v62, v98
	v_mov_b32_e32 v63, v130
	v_pk_add_f32 v[70:71], v[62:63], v[54:55]
	v_and_b32_e32 v63, 0xffff0000, v68
	v_and_b32_e32 v62, 0xffff0000, v56
	v_mov_b32_e32 v126, v95
	v_and_b32_e32 v55, 0xffff0000, v72
	v_and_b32_e32 v54, 0xffff0000, v60
	v_mov_b32_e32 v122, v91
	v_pk_mul_f32 v[62:63], v[126:127], v[62:63]
	v_and_b32_e32 v67, 0xffff0000, v76
	v_and_b32_e32 v66, 0xffff0000, v64
	v_pk_fma_f32 v[54:55], v[122:123], v[54:55], v[62:63]
	v_mov_b32_e32 v134, v103
	v_pk_fma_f32 v[54:55], v[134:135], v[66:67], v[54:55]
	v_mov_b32_e32 v130, v99
	v_lshlrev_b32_e32 v63, 16, v69
	v_lshlrev_b32_e32 v62, 16, v57
	v_mov_b32_e32 v94, v96
	v_mov_b32_e32 v95, v128
	v_pk_add_f32 v[74:75], v[130:131], v[54:55]
	v_lshlrev_b32_e32 v55, 16, v73
	v_lshlrev_b32_e32 v54, 16, v61
	v_mov_b32_e32 v90, v92
	v_mov_b32_e32 v91, v124
	v_pk_mul_f32 v[62:63], v[94:95], v[62:63]
	v_lshlrev_b32_e32 v67, 16, v77
	v_lshlrev_b32_e32 v66, 16, v65
	v_pk_fma_f32 v[54:55], v[90:91], v[54:55], v[62:63]
	v_mov_b32_e32 v62, v104
	v_mov_b32_e32 v63, v136
	v_pk_fma_f32 v[54:55], v[62:63], v[66:67], v[54:55]
	v_mov_b32_e32 v62, v100
	v_mov_b32_e32 v63, v132
	v_pk_add_f32 v[66:67], v[62:63], v[54:55]
	v_and_b32_e32 v54, 0xffff0000, v61
	v_and_b32_e32 v61, 0xffff0000, v69
	v_and_b32_e32 v60, 0xffff0000, v57
	v_mov_b32_e32 v128, v97
	v_and_b32_e32 v55, 0xffff0000, v73
	v_mov_b32_e32 v124, v93
	v_pk_mul_f32 v[60:61], v[128:129], v[60:61]
	v_and_b32_e32 v57, 0xffff0000, v77
	v_and_b32_e32 v56, 0xffff0000, v65
	v_pk_fma_f32 v[54:55], v[124:125], v[54:55], v[60:61]
	v_mov_b32_e32 v136, v105
	v_pk_fma_f32 v[54:55], v[136:137], v[56:57], v[54:55]
	v_mov_b32_e32 v132, v101
	v_pk_add_f32 v[62:63], v[132:133], v[54:55]
	v_cndmask_b32_e32 v54, 0, v231, vcc
	v_mov_b32_e32 v55, v33
	v_lshl_add_u64 v[54:55], s[10:11], 0, v[54:55]
	v_lshl_add_u64 v[60:61], v[54:55], 0, v[32:33]
	global_load_dwordx4 v[90:93], v[60:61], off
	ds_read2_b32 v[64:65], v233 offset1:1
	global_load_dwordx4 v[54:57], v32, s[40:41] offset:16
	global_load_dwordx4 v[94:97], v32, s[40:41]
	v_mul_f32_e32 v68, v214, v215
	v_mul_f32_e32 v32, v78, v207
	v_pk_fma_f32 v[72:73], v[208:209], v[206:207], v[32:33] op_sel_hi:[1,1,0]
	v_pk_fma_f32 v[106:107], v[146:147], v[216:217], v[106:107]
	s_waitcnt lgkmcnt(0)
	v_mov_b32_e32 v69, v64
	v_pk_add_f32 v[106:107], v[150:151], v[106:107]
	v_mov_b32_e32 v114, v120
	v_mul_f32_e32 v64, v106, v107
	v_pk_add_f32 v[110:111], v[114:115], v[110:111]
	v_mul_f32_e32 v58, v58, v59
	s_andn2_b64 vcc, exec, s[12:13]
	s_waitcnt vmcnt(0)
	v_rcp_f32_e32 v197, v90
	v_rcp_f32_e32 v195, v91
	v_mul_f32_e32 v76, v68, v94
	v_mov_b32_e32 v68, v86
	v_mov_b32_e32 v73, v76
	v_pk_fma_f32 v[68:69], v[68:69], v[196:197], v[72:73]
	v_mul_f32_e32 v72, v64, v95
	v_add_f32_e32 v32, v82, v68
	v_mul_f32_e32 v68, v79, v211
	v_mul_f32_e32 v32, v32, v69
	v_pk_fma_f32 v[68:69], v[212:213], v[210:211], v[68:69] op_sel_hi:[1,1,0]
	v_mov_b32_e32 v64, v87
	v_mov_b32_e32 v69, v72
	v_pk_fma_f32 v[64:65], v[64:65], v[194:195], v[68:69]
	v_rcp_f32_e32 v193, v92
	v_add_f32_e32 v64, v83, v64
	v_mul_f32_e32 v68, v64, v65
	ds_read2_b32 v[64:65], v233 offset0:2 offset1:3
	v_mul_f32_e32 v69, v110, v111
	v_mul_f32_e32 v69, v69, v96
	v_mov_b32_e32 v72, v88
	v_rcp_f32_e32 v191, v93
	s_waitcnt lgkmcnt(0)
	v_mov_b32_e32 v73, v64
	v_mul_f32_e32 v64, v80, v203
	v_pk_fma_f32 v[76:77], v[204:205], v[202:203], v[64:65] op_sel_hi:[1,1,0]
	v_mov_b64_e32 v[92:93], v[2:3]
	v_mov_b32_e32 v77, v69
	v_pk_fma_f32 v[72:73], v[72:73], v[192:193], v[76:77]
	v_pk_fma_f32 v[76:77], v[188:189], v[186:187], v[42:43] op_sel_hi:[1,1,0]
	v_add_f32_e32 v64, v84, v72
	v_mul_f32_e32 v72, v58, v97
	v_mul_f32_e32 v58, v81, v199
	v_pk_fma_f32 v[58:59], v[200:201], v[198:199], v[58:59] op_sel_hi:[1,1,0]
	v_mul_f32_e32 v69, v64, v73
	v_mov_b32_e32 v64, v89
	v_mov_b32_e32 v59, v72
	v_pk_fma_f32 v[58:59], v[64:65], v[190:191], v[58:59]
	ds_read2_b32 v[64:65], v233 offset0:4 offset1:5
	v_add_f32_e32 v58, v85, v58
	v_mul_f32_e32 v72, v58, v59
	global_load_dwordx4 v[58:61], v[60:61], off offset:16
	v_mov_b64_e32 v[96:97], v[10:11]
	v_mov_b64_e32 v[94:95], v[8:9]
	v_mov_b64_e32 v[90:91], v[0:1]
	s_waitcnt vmcnt(0) lgkmcnt(0)
	v_rcp_f32_e32 v181, v58
	v_mul_f32_e32 v58, v70, v71
	v_mul_f32_e32 v54, v58, v54
	v_mov_b32_e32 v70, v50
	v_mov_b32_e32 v71, v64
	v_mov_b32_e32 v77, v54
	v_pk_fma_f32 v[70:71], v[70:71], v[180:181], v[76:77]
	v_rcp_f32_e32 v179, v59
	v_add_f32_e32 v42, v46, v70
	v_mul_f32_e32 v54, v42, v71
	v_mul_f32_e32 v42, v74, v75
	v_mul_f32_e32 v46, v42, v55
	v_mul_f32_e32 v42, v43, v183
	v_pk_fma_f32 v[42:43], v[184:185], v[182:183], v[42:43] op_sel_hi:[1,1,0]
	v_mov_b32_e32 v64, v51
	v_mov_b32_e32 v43, v46
	v_pk_fma_f32 v[42:43], v[64:65], v[178:179], v[42:43]
	v_rcp_f32_e32 v169, v60
	v_add_f32_e32 v42, v47, v42
	v_mul_f32_e32 v55, v42, v43
	ds_read2_b32 v[42:43], v233 offset0:6 offset1:7
	v_mul_f32_e32 v46, v66, v67
	v_mul_f32_e32 v56, v46, v56
	v_mov_b32_e32 v46, v52
	v_rcp_f32_e32 v167, v61
	s_waitcnt lgkmcnt(0)
	v_mov_b32_e32 v47, v42
	v_mul_f32_e32 v42, v44, v175
	v_pk_fma_f32 v[50:51], v[176:177], v[174:175], v[42:43] op_sel_hi:[1,1,0]
	v_mul_f32_e32 v44, v45, v171
	v_mov_b32_e32 v51, v56
	v_pk_fma_f32 v[46:47], v[46:47], v[168:169], v[50:51]
	v_pk_fma_f32 v[44:45], v[172:173], v[170:171], v[44:45] op_sel_hi:[1,1,0]
	v_add_f32_e32 v42, v48, v46
	v_mul_f32_e32 v46, v42, v47
	v_mul_f32_e32 v42, v62, v63
	v_mul_f32_e32 v47, v42, v57
	v_mov_b32_e32 v42, v53
	v_mov_b32_e32 v45, v47
	v_pk_fma_f32 v[42:43], v[42:43], v[166:167], v[44:45]
	v_cvt_pk_bf16_f32 v44, v54, v55
	v_mov_b64_e32 v[76:77], v[30:31]
	v_add_f32_e32 v42, v49, v42
	v_mul_f32_e32 v45, v42, v43
	v_cvt_pk_bf16_f32 v45, v46, v45
	v_lshlrev_b64 v[46:47], 12, v[164:165]
	v_lshl_add_u64 v[46:47], s[8:9], 0, v[46:47]
	v_lshl_add_u64 v[46:47], v[46:47], 0, s[66:67]
	v_cvt_pk_bf16_f32 v42, v32, v68
	v_cvt_pk_bf16_f32 v43, v69, v72
	v_lshl_add_u64 v[46:47], v[46:47], 0, v[162:163]
	global_store_dwordx4 v[46:47], v[42:45], off
	v_mov_b64_e32 v[72:73], v[36:37]
	v_mov_b64_e32 v[68:69], v[26:27]
	v_mov_b64_e32 v[60:61], v[18:19]
	v_mov_b64_e32 v[56:57], v[14:15]
	v_mov_b64_e32 v[64:65], v[22:23]
	v_mov_b64_e32 v[44:45], v[6:7]
	v_mov_b64_e32 v[48:49], v[40:41]
	v_mov_b64_e32 v[70:71], v[34:35]
	v_mov_b64_e32 v[66:67], v[24:25]
	v_mov_b64_e32 v[74:75], v[28:29]
	v_mov_b64_e32 v[58:59], v[16:17]
	v_mov_b64_e32 v[54:55], v[12:13]
	v_mov_b64_e32 v[62:63], v[20:21]
	v_mov_b64_e32 v[42:43], v[4:5]
	v_mov_b64_e32 v[46:47], v[38:39]
	s_waitcnt lgkmcnt(0)
	s_barrier
	s_cbranch_vccz .LBB0_916

.LBB0_903:
	s_andn2_b64 vcc, exec, s[0:1]
	s_movk_i32 s23, 0x3000
	s_cbranch_vccnz .LBB0_900
	v_readlane_b32 s0, v255, 8
	s_add_i32 s20, s0, s22
	v_readlane_b32 s0, v253, 4
	s_add_i32 s19, s0, s21
	s_and_b32 s14, s20, 0xffffffc0
	s_and_b32 s15, s19, 0x3c0
	v_add_u32_e32 v8, s14, v155
	v_or_b32_e32 v28, s15, v160
	v_mov_b64_e32 v[0:1], s[2:3]
	v_mad_i64_i32 v[24:25], s[0:1], v8, s96, v[0:1]
	v_lshlrev_b32_e32 v20, 1, v28
	v_mov_b32_e32 v21, v33
	v_lshl_add_u64 v[26:27], v[24:25], 0, v[20:21]
	global_load_dwordx4 v[0:3], v[26:27], off
	v_cmp_gt_i32_e32 vcc, s75, v8
	v_mov_b32_e32 v6, v33
	v_mov_b32_e32 v7, v33
	v_cndmask_b32_e32 v12, v228, v229, vcc
	v_and_b32_e32 v13, v12, v8
	v_mov_b32_e32 v4, v33
	v_mov_b32_e32 v5, v33
	v_add_u32_e32 v40, -1, v8
	v_mov_b64_e32 v[10:11], v[6:7]
	v_cmp_ne_u32_e64 s[0:1], 0, v13
	v_mov_b64_e32 v[8:9], v[4:5]
	s_and_saveexec_b64 s[4:5], s[0:1]
	s_cbranch_execz .LBB0_906
	v_mov_b64_e32 v[8:9], s[2:3]
	v_mad_i64_i32 v[8:9], s[16:17], v40, s96, v[8:9]
	v_lshl_add_u64 v[8:9], v[8:9], 0, v[20:21]
	global_load_dwordx4 v[8:11], v[8:9], off
.LBB0_906:
	s_or_b64 exec, exec, s[4:5]
	v_cmp_ne_u32_e64 s[4:5], v13, v12
	s_and_saveexec_b64 s[16:17], s[4:5]
	s_cbranch_execz .LBB0_908
	v_add_co_u32_e32 v4, vcc, 0x3000, v26
	s_nop 1
	v_addc_co_u32_e32 v5, vcc, 0, v27, vcc
	global_load_dwordx4 v[4:7], v[4:5], off offset:1024
.LBB0_908:
	s_or_b64 exec, exec, s[16:17]
	global_load_dwordx4 v[12:15], v[26:27], off offset:2048
	v_mov_b32_e32 v32, v33
	v_mov_b32_e32 v34, v33
	v_mov_b32_e32 v35, v33
	v_mov_b64_e32 v[16:17], v[32:33]
	v_mov_b64_e32 v[18:19], v[34:35]
	s_and_saveexec_b64 s[16:17], s[0:1]
	s_cbranch_execz .LBB0_910
	v_mov_b64_e32 v[16:17], s[2:3]
	v_mad_i64_i32 v[16:17], s[26:27], v40, s96, v[16:17]
	v_mov_b32_e32 v21, v33
	v_lshl_add_u64 v[16:17], v[16:17], 0, v[20:21]
	global_load_dwordx4 v[16:19], v[16:17], off offset:2048
.LBB0_910:
	s_or_b64 exec, exec, s[16:17]
	v_mov_b64_e32 v[20:21], v[32:33]
	v_mov_b64_e32 v[22:23], v[34:35]
	s_and_saveexec_b64 s[16:17], s[4:5]
	s_cbranch_execz .LBB0_912
	s_mov_b64 s[26:27], 0x800
	v_lshl_add_u64 v[20:21], v[26:27], 0, s[26:27]
	v_add_co_u32_e32 v20, vcc, 0x3000, v20
	s_nop 1
	v_addc_co_u32_e32 v21, vcc, 0, v21, vcc
	global_load_dwordx4 v[20:23], v[20:21], off offset:1024
.LBB0_912:
	s_or_b64 exec, exec, s[16:17]
	v_or_b32_e32 v26, 0x800, v28
	v_lshlrev_b32_e32 v32, 1, v26
	v_lshl_add_u64 v[38:39], v[24:25], 0, v[32:33]
	global_load_dwordx4 v[24:27], v[38:39], off
	v_mov_b32_e32 v30, v33
	v_mov_b32_e32 v31, v33
	v_mov_b32_e32 v28, v33
	v_mov_b32_e32 v29, v33
	v_mov_b64_e32 v[36:37], v[30:31]
	v_mov_b64_e32 v[34:35], v[28:29]
	s_and_saveexec_b64 s[16:17], s[0:1]
	s_cbranch_execz .LBB0_914
	v_mov_b64_e32 v[34:35], s[2:3]
	v_mad_i64_i32 v[34:35], s[0:1], v40, s96, v[34:35]
	v_lshl_add_u64 v[34:35], v[34:35], 0, v[32:33]
	global_load_dwordx4 v[34:37], v[34:35], off
.LBB0_914:
	s_or_b64 exec, exec, s[16:17]
	s_and_saveexec_b64 s[0:1], s[4:5]
	s_cbranch_execz .LBB0_899
	v_add_co_u32_e32 v28, vcc, 0x3000, v38
	s_nop 1
	v_addc_co_u32_e32 v29, vcc, 0, v39, vcc
	global_load_dwordx4 v[28:31], v[28:29], off offset:1024
	s_branch .LBB0_899

.LBB0_922:
	v_ashrrev_i32_e32 v0, 7, v4
	v_add_u32_e32 v9, s9, v0
	v_mov_b64_e32 v[0:1], s[2:3]
	v_mad_i64_i32 v[0:1], s[14:15], v9, s96, v[0:1]
	v_lshl_add_u64 v[0:1], v[0:1], 0, v[32:33]
	v_add_co_u32_e32 v6, vcc, 0x3000, v0
	s_mov_b64 s[14:15], 0x3200
	s_nop 0
	v_addc_co_u32_e32 v7, vcc, 0, v1, vcc
	global_load_ushort v5, v[6:7], off offset:512
	v_cmp_gt_i32_e32 vcc, s75, v9
	v_lshl_add_u64 v[0:1], v[0:1], 0, s[14:15]
	v_mov_b32_e32 v6, 0
	v_cndmask_b32_e32 v8, v228, v229, vcc
	v_and_b32_e32 v9, v8, v9
	v_cmp_ne_u32_e32 vcc, 0, v9
	v_mov_b32_e32 v7, 0
	s_and_saveexec_b64 s[14:15], vcc
	s_cbranch_execz .LBB0_924
	v_add_co_u32_e32 v10, vcc, 0xffffcc00, v0
	s_nop 1
	v_addc_co_u32_e32 v11, vcc, -1, v1, vcc
	global_load_ushort v7, v[10:11], off
	s_waitcnt vmcnt(0) lgkmcnt(0)
	v_lshlrev_b32_e32 v7, 16, v7
.LBB0_924:
	s_or_b64 exec, exec, s[14:15]
	v_cmp_ne_u32_e32 vcc, v9, v8
	s_and_saveexec_b64 s[14:15], vcc
	s_cbranch_execz .LBB0_921
	v_add_co_u32_e32 v0, vcc, 0x3000, v0
	s_nop 1
	v_addc_co_u32_e32 v1, vcc, 0, v1, vcc
	global_load_ushort v0, v[0:1], off offset:1024
	s_waitcnt vmcnt(0) lgkmcnt(0)
	v_lshlrev_b32_e32 v6, 16, v0
	s_branch .LBB0_921

.LBB0_929:
	s_or_b64 exec, exec, s[10:11]
	s_waitcnt vmcnt(0) lgkmcnt(0)
	v_and_b32_e32 v145, 0xffff0000, v60
	v_lshlrev_b32_e32 v144, 16, v60
	v_lshlrev_b32_e32 v116, 16, v50
	v_and_b32_e32 v60, 0xffff0000, v50
	v_lshlrev_b32_e32 v112, 16, v51
	v_and_b32_e32 v114, 0xffff0000, v51
	v_lshl_add_u64 v[50:51], v[76:77], 0, v[70:71]
	s_mov_b32 s9, 0x1fc01000
	v_lshlrev_b32_e32 v156, 16, v54
	v_and_b32_e32 v165, 0xffff0000, v54
	v_add_co_u32_e32 v54, vcc, s9, v50
	v_lshlrev_b32_e32 v161, 16, v55
	v_and_b32_e32 v99, 0xffff0000, v55
	v_addc_co_u32_e32 v55, vcc, 0, v51, vcc
	v_lshlrev_b32_e32 v157, 16, v58
	v_and_b32_e32 v166, 0xffff0000, v58
	v_lshlrev_b32_e32 v102, 16, v52
	v_and_b32_e32 v108, 0xffff0000, v52
	v_lshlrev_b32_e32 v98, 16, v53
	v_and_b32_e32 v58, 0xffff0000, v53
	global_load_dwordx4 v[50:53], v[54:55], off
	v_and_b32_e32 v147, 0xffff0000, v56
	v_lshlrev_b32_e32 v146, 16, v56
	v_and_b32_e32 v143, 0xffff0000, v57
	v_lshlrev_b32_e32 v142, 16, v57
	global_load_dwordx4 v[54:57], v[54:55], off offset:2048
	v_and_b32_e32 v141, 0xffff0000, v61
	v_lshlrev_b32_e32 v140, 16, v61
	s_mov_b32 s9, 0xd000000
	v_add_f32_e32 v164, v164, v173
	v_add_f32_e32 v163, v163, v172
	v_fma_f32 v164, v164, 0.5, -v156
	v_fma_f32 v163, v163, 0.5, -v157
	v_fmac_f32_e32 v156, v20, v164
	v_fmac_f32_e32 v157, v12, v163
	v_mul_f32_e32 v156, v157, v156
	v_add_f32_e32 v0, v0, v152
	v_add_f32_e32 v117, v117, v167
	v_add_f32_e32 v109, v109, v155
	v_fma_f32 v0, v0, 0.5, -v99
	v_lshlrev_b32_e32 v162, 16, v59
	v_and_b32_e32 v59, 0xffff0000, v59
	v_fma_f32 v117, v117, 0.5, -v165
	v_add_f32_e32 v115, v115, v160
	v_fma_f32 v109, v109, 0.5, -v161
	v_fmac_f32_e32 v99, v23, v0
	v_add_f32_e32 v0, v103, v151
	v_pk_add_f32 v[104:105], v[104:105], v[136:137]
	v_pk_add_f32 v[100:101], v[100:101], v[132:133]
	v_fmac_f32_e32 v165, v21, v117
	v_fma_f32 v115, v115, 0.5, -v166
	v_fmac_f32_e32 v161, v22, v109
	v_add_f32_e32 v109, v113, v153
	v_fma_f32 v0, v0, 0.5, -v59
	v_pk_fma_f32 v[104:105], v[104:105], 0.5, v[146:147] op_sel_hi:[1,0,1] neg_lo:[0,0,1] neg_hi:[0,0,1]
	v_pk_fma_f32 v[100:101], v[100:101], 0.5, v[144:145] op_sel_hi:[1,0,1] neg_lo:[0,0,1] neg_hi:[0,0,1]
	v_fmac_f32_e32 v166, v13, v115
	v_fma_f32 v109, v109, 0.5, -v162
	v_fmac_f32_e32 v59, v15, v0
	v_pk_fma_f32 v[104:105], v[24:25], v[104:105], v[146:147]
	v_pk_fma_f32 v[100:101], v[16:17], v[100:101], v[144:145]
	v_mul_f32_e32 v115, v166, v165
	v_fmac_f32_e32 v162, v14, v109
	v_mul_f32_e32 v0, v59, v99
	v_pk_mul_f32 v[100:101], v[100:101], v[104:105]
	v_mul_f32_e32 v109, v162, v161
	v_pk_add_f32 v[110:111], v[110:111], v[138:139]
	v_pk_add_f32 v[106:107], v[106:107], v[134:135]
	s_mov_b32 s10, 0.5
	ds_read_b128 v[174:177], v149
	s_add_i32 s12, s12, 4
	v_add_u32_e32 v149, 0x2000, v149
	s_cmp_lg_u32 s12, 32
	s_waitcnt vmcnt(0) lgkmcnt(0)
	v_lshlrev_b32_e32 v158, 16, v50
	v_and_b32_e32 v159, 0xffff0000, v50
	v_lshlrev_b32_e32 v178, 16, v51
	v_and_b32_e32 v61, 0xffff0000, v51
	v_lshl_add_u64 v[50:51], v[74:75], 0, v[70:71]
	v_lshlrev_b32_e32 v179, 16, v54
	v_and_b32_e32 v180, 0xffff0000, v54
	v_add_co_u32_e32 v54, vcc, s9, v50
	v_lshlrev_b32_e32 v181, 16, v55
	v_and_b32_e32 v182, 0xffff0000, v55
	v_addc_co_u32_e32 v55, vcc, 0, v51, vcc
	global_load_dwordx4 v[168:171], v[54:55], off
	s_brev_b32 s9, 8
	v_add_co_u32_e32 v50, vcc, s9, v50
	v_add_f32_e32 v157, v158, v179
	s_nop 0
	v_addc_co_u32_e32 v51, vcc, 0, v51, vcc
	v_add_f32_e32 v157, -2.0, v157
	v_fma_f32 v157, v28, v157, 2.0
	v_mul_f32_e32 v156, v156, v157
	v_add_f32_e32 v117, v159, v180
	v_fma_f32 v158, v34, v156, 0
	v_add_f32_e32 v117, -2.0, v117
	v_add_f32_e32 v113, v178, v181
	v_and_b32_e32 v153, 0xffff0000, v52
	v_lshlrev_b32_e32 v152, 16, v52
	v_and_b32_e32 v157, 0xffff0000, v56
	v_lshlrev_b32_e32 v156, 16, v56
	v_fma_f32 v117, v29, v117, 2.0
	v_add_f32_e32 v113, -2.0, v113
	v_add_f32_e32 v59, v61, v182
	v_pk_add_f32 v[104:105], v[152:153], v[156:157]
	v_mul_f32_e32 v115, v115, v117
	v_fma_f32 v113, v30, v113, 2.0
	v_add_f32_e32 v59, -2.0, v59
	v_pk_add_f32 v[104:105], v[104:105], -2.0 op_sel_hi:[1,0]
	v_fmac_f32_e32 v158, v35, v115
	v_mul_f32_e32 v109, v109, v113
	v_fma_f32 v59, v31, v59, 2.0
	v_pk_fma_f32 v[104:105], v[38:39], v[104:105], 2.0 op_sel_hi:[1,1,0]
	v_fmac_f32_e32 v158, v36, v109
	v_mul_f32_e32 v0, v0, v59
	v_pk_mul_f32 v[100:101], v[100:101], v[104:105]
	v_fmac_f32_e32 v158, v37, v0
	v_pk_mul_f32 v[100:101], v[42:43], v[100:101]
	v_lshlrev_b32_e32 v52, 16, v57
	v_add_f32_e32 v0, v100, v158
	v_add_f32_e32 v0, v101, v0
	v_and_b32_e32 v101, 0xffff0000, v53
	v_lshlrev_b32_e32 v100, 16, v53
	v_and_b32_e32 v53, 0xffff0000, v57
	v_pk_fma_f32 v[56:57], v[110:111], 0.5, v[142:143] op_sel_hi:[1,0,1] neg_lo:[0,0,1] neg_hi:[0,0,1]
	v_pk_fma_f32 v[104:105], v[106:107], 0.5, v[140:141] op_sel_hi:[1,0,1] neg_lo:[0,0,1] neg_hi:[0,0,1]
	v_pk_add_f32 v[52:53], v[100:101], v[52:53]
	v_pk_fma_f32 v[56:57], v[26:27], v[56:57], v[142:143]
	v_pk_fma_f32 v[104:105], v[18:19], v[104:105], v[140:141]
	v_pk_add_f32 v[52:53], v[52:53], -2.0 op_sel_hi:[1,0]
	v_pk_mul_f32 v[56:57], v[104:105], v[56:57]
	v_pk_fma_f32 v[52:53], v[40:41], v[52:53], 2.0 op_sel_hi:[1,1,0]
	v_mov_b32_e32 v59, 0x3a27c5ac
	v_pk_mul_f32 v[52:53], v[56:57], v[52:53]
	v_lshlrev_b32_e32 v55, 16, v176
	v_pk_mul_f32 v[52:53], v[44:45], v[52:53]
	v_and_b32_e32 v54, 0xffff0000, v176
	v_add_f32_e32 v0, v52, v0
	v_add_f32_e32 v0, v53, v0
	s_waitcnt vmcnt(0) lgkmcnt(0)
	v_lshlrev_b32_e32 v83, 16, v168
	v_and_b32_e32 v81, 0xffff0000, v168
	v_lshlrev_b32_e32 v89, 16, v169
	v_and_b32_e32 v87, 0xffff0000, v169
	v_lshlrev_b32_e32 v93, 16, v170
	v_and_b32_e32 v91, 0xffff0000, v170
	v_lshlrev_b32_e32 v97, 16, v171
	v_and_b32_e32 v95, 0xffff0000, v171
	global_load_dwordx4 v[168:171], v[50:51], off
	v_add_f32_dpp v0, v0, v0 quad_perm:[1,0,3,2] row_mask:0xf bank_mask:0xf bound_ctrl:1
	v_lshlrev_b32_e32 v51, 16, v177
	v_and_b32_e32 v50, 0xffff0000, v177
	v_add_f32_dpp v0, v0, v0 quad_perm:[2,3,0,1] row_mask:0xf bank_mask:0xf bound_ctrl:1
	s_waitcnt vmcnt(0) lgkmcnt(0)
	v_lshlrev_b32_e32 v121, 16, v168
	v_and_b32_e32 v119, 0xffff0000, v168
	v_pk_add_f32 v[82:83], v[82:83], v[120:121]
	v_lshlrev_b32_e32 v125, 16, v169
	v_add_f32_dpp v132, v0, v0 row_half_mirror row_mask:0xf bank_mask:0xf bound_ctrl:1
	v_add_f32_e32 v0, 0, v83
	v_pk_add_f32 v[80:81], v[80:81], v[118:119]
	v_and_b32_e32 v123, 0xffff0000, v169
	v_pk_add_f32 v[88:89], v[88:89], v[124:125]
	v_add_f32_e32 v0, v81, v0
	v_lshlrev_b32_e32 v129, 16, v170
	v_and_b32_e32 v85, 0xffff0000, v171
	v_pk_add_f32 v[86:87], v[86:87], v[122:123]
	v_add_f32_e32 v0, v89, v0
	v_and_b32_e32 v127, 0xffff0000, v170
	v_pk_add_f32 v[56:57], v[94:95], v[84:85]
	v_pk_add_f32 v[84:85], v[92:93], v[128:129]
	v_add_f32_e32 v0, v87, v0
	v_lshlrev_b32_e32 v131, 16, v171
	v_pk_add_f32 v[90:91], v[90:91], v[126:127]
	v_add_f32_e32 v0, v85, v0
	v_pk_add_f32 v[52:53], v[96:97], v[130:131]
	v_add_f32_e32 v0, v91, v0
	v_add_f32_e32 v0, v53, v0
	v_add_f32_e32 v0, v57, v0
	v_lshlrev_b32_e32 v171, 16, v174
	v_and_b32_e32 v170, 0xffff0000, v174
	v_add_f32_dpp v0, v0, v0 quad_perm:[1,0,3,2] row_mask:0xf bank_mask:0xf bound_ctrl:1
	v_lshlrev_b32_e32 v169, 16, v175
	v_and_b32_e32 v168, 0xffff0000, v175
	v_add_f32_dpp v0, v0, v0 quad_perm:[2,3,0,1] row_mask:0xf bank_mask:0xf bound_ctrl:1
	s_nop 1
	v_add_f32_dpp v0, v0, v0 row_half_mirror row_mask:0xf bank_mask:0xf bound_ctrl:1
	v_mul_f32_e32 v155, 0x3c800000, v0
	v_pk_add_f32 v[92:93], v[82:83], v[154:155] neg_lo:[0,1] neg_hi:[0,1]
	v_pk_add_f32 v[94:95], v[80:81], v[154:155] neg_lo:[0,1] neg_hi:[0,1]
	v_mov_b32_e32 v96, v93
	v_mov_b32_e32 v97, v95
	v_pk_add_f32 v[100:101], v[88:89], v[154:155] neg_lo:[0,1] neg_hi:[0,1]
	v_pk_add_f32 v[104:105], v[86:87], v[154:155] neg_lo:[0,1] neg_hi:[0,1]
	v_pk_mul_f32 v[96:97], v[96:97], v[96:97]
	v_mov_b32_e32 v106, v105
	v_mov_b32_e32 v107, v101
	v_pk_mul_f32 v[106:107], v[106:107], v[106:107]
	v_pk_add_f32 v[110:111], v[84:85], v[154:155] neg_lo:[0,1] neg_hi:[0,1]
	v_pk_add_f32 v[118:119], v[90:91], v[154:155] neg_lo:[0,1] neg_hi:[0,1]
	v_add_f32_e32 v0, v96, v97
	v_mov_b32_e32 v120, v119
	v_mov_b32_e32 v121, v111
	v_add_f32_e32 v0, v107, v0
	v_pk_mul_f32 v[120:121], v[120:121], v[120:121]
	v_pk_add_f32 v[122:123], v[52:53], v[154:155] neg_lo:[0,1] neg_hi:[0,1]
	v_pk_add_f32 v[124:125], v[56:57], v[154:155] neg_lo:[0,1] neg_hi:[0,1]
	v_add_f32_e32 v0, v106, v0
	v_mov_b32_e32 v126, v125
	v_mov_b32_e32 v127, v123
	v_add_f32_e32 v0, v121, v0
	v_pk_mul_f32 v[126:127], v[126:127], v[126:127]
	v_add_f32_e32 v0, v120, v0
	v_add_f32_e32 v0, v127, v0
	v_add_f32_e32 v0, v126, v0
	s_nop 1
	v_add_f32_dpp v0, v0, v0 quad_perm:[1,0,3,2] row_mask:0xf bank_mask:0xf bound_ctrl:1
	s_nop 1
	v_add_f32_dpp v0, v0, v0 quad_perm:[2,3,0,1] row_mask:0xf bank_mask:0xf bound_ctrl:1
	s_nop 1
	v_add_f32_dpp v0, v0, v0 row_half_mirror row_mask:0xf bank_mask:0xf bound_ctrl:1
	v_fmamk_f32 v0, v0, 0x3c800000, v59
	v_cmp_gt_f32_e32 vcc, s33, v0
	v_mul_f32_e32 v59, 0x4b800000, v0
	s_nop 0
	v_cndmask_b32_e32 v0, v0, v59, vcc
	v_rsq_f32_e32 v0, v0
	s_nop 0
	v_mul_f32_e32 v59, 0x45800000, v0
	v_cndmask_b32_e32 v61, v0, v59, vcc
	v_mov_b32_e32 v117, v61
	v_pk_fma_f32 v[82:83], v[82:83], s[10:11], v[116:117] neg_lo:[0,0,1] neg_hi:[0,0,1]
	v_pk_mul_f32 v[92:93], v[92:93], v[116:117]
	v_mov_b32_e32 v115, v61
	v_mov_b32_e32 v83, v93
	v_pk_fma_f32 v[86:87], v[86:87], s[10:11], v[114:115] neg_lo:[0,0,1] neg_hi:[0,0,1]
	v_pk_mul_f32 v[92:93], v[104:105], v[114:115]
	v_mov_b32_e32 v113, v61
	v_mov_b32_e32 v87, v93
	v_pk_fma_f32 v[88:89], v[88:89], s[10:11], v[112:113] neg_lo:[0,0,1] neg_hi:[0,0,1]
	v_pk_mul_f32 v[92:93], v[100:101], v[112:113]
	v_mov_b32_e32 v109, v61
	v_mov_b32_e32 v89, v93
	v_pk_fma_f32 v[90:91], v[90:91], s[10:11], v[108:109] neg_lo:[0,0,1] neg_hi:[0,0,1]
	v_pk_mul_f32 v[92:93], v[118:119], v[108:109]
	v_mov_b32_e32 v103, v61
	v_mov_b32_e32 v91, v93
	v_pk_fma_f32 v[84:85], v[84:85], s[10:11], v[102:103] neg_lo:[0,0,1] neg_hi:[0,0,1]
	v_pk_mul_f32 v[92:93], v[110:111], v[102:103]
	v_mov_b32_e32 v117, v148
	v_mov_b32_e32 v109, v47
	v_mov_b32_e32 v85, v93
	v_mov_b32_e32 v103, v46
	v_pk_fma_f32 v[80:81], v[80:81], s[10:11], v[60:61] neg_lo:[0,0,1] neg_hi:[0,0,1]
	v_pk_mul_f32 v[94:95], v[94:95], v[60:61]
	v_pk_fma_f32 v[82:83], v[68:69], v[82:83], v[116:117]
	v_pk_fma_f32 v[90:91], v[4:5], v[90:91], v[108:109]
	v_pk_fma_f32 v[84:85], v[64:65], v[84:85], v[102:103]
	v_mov_b32_e32 v81, v95
	v_mov_b32_e32 v0, v60
	v_fmac_f32_e32 v83, v82, v132
	v_fmac_f32_e32 v85, v84, v132
	v_fmac_f32_e32 v91, v90, v132
	v_mov_b32_e32 v99, v61
	v_pk_fma_f32 v[80:81], v[8:9], v[80:81], v[0:1]
	v_mul_f32_e32 v0, v83, v171
	v_mul_f32_e32 v82, v85, v55
	v_mul_f32_e32 v83, v91, v54
	v_pk_fma_f32 v[52:53], v[52:53], s[10:11], v[98:99] neg_lo:[0,0,1] neg_hi:[0,0,1]
	v_pk_mul_f32 v[54:55], v[122:123], v[98:99]
	v_mov_b32_e32 v99, v48
	v_mov_b32_e32 v53, v55
	v_pk_fma_f32 v[52:53], v[62:63], v[52:53], v[98:99]
	v_mov_b32_e32 v59, v61
	v_fmac_f32_e32 v53, v52, v132
	v_mul_f32_e32 v84, v53, v51
	v_pk_fma_f32 v[52:53], v[56:57], s[10:11], v[58:59] neg_lo:[0,0,1] neg_hi:[0,0,1]
	v_pk_mul_f32 v[54:55], v[124:125], v[58:59]
	s_mov_b64 s[10:11], 0x4000
	v_mov_b32_e32 v53, v55
	v_mov_b32_e32 v59, v49
	v_lshl_add_u64 v[54:55], v[72:73], 0, v[70:71]
	v_lshl_add_u64 v[72:73], v[72:73], 0, s[10:11]
	s_mov_b64 s[10:11], 0x2000
	v_mov_b32_e32 v115, v3
	v_mov_b32_e32 v113, v2
	v_pk_fma_f32 v[52:53], v[6:7], v[52:53], v[58:59]
	v_lshl_add_u64 v[74:75], v[74:75], 0, s[10:11]
	s_mov_b64 s[10:11], 0x8000
	v_pk_fma_f32 v[86:87], v[10:11], v[86:87], v[114:115]
	v_pk_fma_f32 v[88:89], v[66:67], v[88:89], v[112:113]
	v_fmac_f32_e32 v53, v52, v132
	v_lshl_add_u64 v[76:77], v[76:77], 0, s[10:11]
	s_mov_b64 s[10:11], 0xd000
	v_fmac_f32_e32 v81, v80, v132
	v_fmac_f32_e32 v89, v88, v132
	v_fmac_f32_e32 v87, v86, v132
	v_mul_f32_e32 v53, v53, v50
	v_lshl_add_u64 v[78:79], v[78:79], 0, s[10:11]
	v_mul_f32_e32 v60, v81, v170
	v_mul_f32_e32 v80, v89, v169
	v_mul_f32_e32 v81, v87, v168
	v_cvt_pk_bf16_f32 v50, v0, v60
	v_cvt_pk_bf16_f32 v51, v80, v81
	v_cvt_pk_bf16_f32 v52, v82, v83
	v_cvt_pk_bf16_f32 v53, v84, v53
	global_store_dwordx4 v[54:55], v[50:53], off
	s_cbranch_scc0 .LBB0_918
.LBB0_930:
	v_lshl_add_u64 v[98:99], v[78:79], 0, v[70:71]
	v_add_co_u32_e32 v50, vcc, 0xc401000, v98
	v_add_u32_e32 v85, s12, v150
	s_nop 0
	v_addc_co_u32_e32 v51, vcc, 0, v99, vcc
	v_add_co_u32_e32 v52, vcc, 0xc402000, v98
	v_subrev_u32_e32 v0, 32, v85
	s_nop 0
	v_addc_co_u32_e32 v53, vcc, 0, v99, vcc
	global_load_dwordx4 v[54:57], v[50:51], off offset:2048
	global_load_dwordx4 v[58:61], v[52:53], off
	s_nop 0
	global_load_dwordx4 v[50:53], v[52:53], off offset:2048
	v_cmp_gt_i32_e32 vcc, s75, v0
	v_mov_b32_e32 v84, 0
	v_mov_b32_e32 v94, 0
	v_cndmask_b32_e32 v81, v228, v229, vcc
	v_and_b32_e32 v83, v81, v0
	v_cmp_ne_u32_e32 vcc, 0, v83
	v_mov_b32_e32 v96, 0
	v_mov_b32_e32 v90, 0
	v_mov_b32_e32 v92, 0
	v_mov_b32_e32 v86, 0
	v_mov_b32_e32 v88, 0
	v_mov_b32_e32 v80, 0
	v_mov_b32_e32 v82, 0
	v_mov_b32_e32 v163, 0
	v_mov_b32_e32 v115, 0
	v_mov_b32_e32 v113, 0
	v_mov_b32_e32 v103, 0
	v_mov_b32_e32 v100, 0
	v_mov_b32_e32 v101, 0
	v_mov_b32_e32 v106, 0
	v_mov_b32_e32 v107, 0
	v_mov_b32_e32 v164, 0
	v_mov_b32_e32 v117, 0
	v_mov_b32_e32 v109, 0
	v_mov_b32_e32 v0, 0
	v_mov_b32_e32 v104, 0
	v_mov_b32_e32 v105, 0
	v_mov_b32_e32 v110, 0
	v_mov_b32_e32 v111, 0
	s_and_saveexec_b64 s[10:11], vcc
	s_cbranch_execz .LBB0_932
	v_subrev_u32_e32 v0, 33, v85
	v_mov_b64_e32 v[86:87], s[2:3]
	v_mad_i64_i32 v[86:87], s[14:15], v0, s96, v[86:87]
	v_lshl_add_u64 v[94:95], v[86:87], 0, v[32:33]
	v_add_co_u32_e32 v86, vcc, 0x1000, v94
	v_lshl_add_u64 v[90:91], v[94:95], 0, s[68:69]
	s_nop 0
	v_addc_co_u32_e32 v87, vcc, 0, v95, vcc
	v_add_co_u32_e32 v94, vcc, 0x2000, v94
	global_load_dwordx4 v[86:89], v[86:87], off offset:2048
	s_nop 0
	v_addc_co_u32_e32 v95, vcc, 0, v95, vcc
	global_load_dwordx4 v[90:93], v[90:91], off offset:2048
	s_waitcnt vmcnt(0) lgkmcnt(0)
	v_lshlrev_b32_e32 v164, 16, v86
	global_load_dwordx4 v[94:97], v[94:95], off offset:2048
	v_and_b32_e32 v117, 0xffff0000, v86
	v_lshlrev_b32_e32 v109, 16, v87
	v_and_b32_e32 v0, 0xffff0000, v87
	v_lshlrev_b32_e32 v104, 16, v88
	v_and_b32_e32 v105, 0xffff0000, v88
	v_lshlrev_b32_e32 v110, 16, v89
	v_and_b32_e32 v111, 0xffff0000, v89
	v_lshlrev_b32_e32 v163, 16, v90
	v_and_b32_e32 v115, 0xffff0000, v90
	v_lshlrev_b32_e32 v113, 16, v91
	v_and_b32_e32 v103, 0xffff0000, v91
	v_lshlrev_b32_e32 v100, 16, v92
	v_and_b32_e32 v101, 0xffff0000, v92
	v_lshlrev_b32_e32 v106, 16, v93
	v_and_b32_e32 v107, 0xffff0000, v93
	s_waitcnt vmcnt(0) lgkmcnt(0)
	v_lshlrev_b32_e32 v82, 16, v94
	v_and_b32_e32 v80, 0xffff0000, v94
	v_lshlrev_b32_e32 v88, 16, v95
	v_and_b32_e32 v86, 0xffff0000, v95
	v_lshlrev_b32_e32 v92, 16, v96
	v_and_b32_e32 v90, 0xffff0000, v96
	v_lshlrev_b32_e32 v96, 16, v97
	v_and_b32_e32 v94, 0xffff0000, v97
.LBB0_932:
	s_or_b64 exec, exec, s[10:11]
	v_cmp_ne_u32_e32 vcc, v83, v81
	v_mov_b32_e32 v130, 0
	v_mov_b32_e32 v126, 0
	v_mov_b32_e32 v128, 0
	v_mov_b32_e32 v122, 0
	v_mov_b32_e32 v124, 0
	v_mov_b32_e32 v118, 0
	v_mov_b32_e32 v120, 0
	v_mov_b32_e32 v172, 0
	v_mov_b32_e32 v160, 0
	v_mov_b32_e32 v153, 0
	v_mov_b32_e32 v151, 0
	v_mov_b32_e32 v132, 0
	v_mov_b32_e32 v133, 0
	v_mov_b32_e32 v134, 0
	v_mov_b32_e32 v135, 0
	v_mov_b32_e32 v173, 0
	v_mov_b32_e32 v167, 0
	v_mov_b32_e32 v155, 0
	v_mov_b32_e32 v152, 0
	v_mov_b32_e32 v136, 0
	v_mov_b32_e32 v137, 0
	v_mov_b32_e32 v138, 0
	v_mov_b32_e32 v139, 0
	s_and_saveexec_b64 s[10:11], vcc
	s_cbranch_execz .LBB0_929
	v_add_co_u32_e32 v84, vcc, 0xc404000, v98
	s_mov_b32 s9, 0xc405000
	s_nop 0
	v_addc_co_u32_e32 v85, vcc, 0, v99, vcc
	global_load_dwordx4 v[118:121], v[84:85], off offset:3072
	v_add_co_u32_e32 v84, vcc, s9, v98
	s_waitcnt vmcnt(0) lgkmcnt(0)
	v_lshlrev_b32_e32 v173, 16, v118
	v_addc_co_u32_e32 v85, vcc, 0, v99, vcc
	global_load_dwordx4 v[122:125], v[84:85], off offset:1024
	global_load_dwordx4 v[128:131], v[84:85], off offset:3072
	v_and_b32_e32 v167, 0xffff0000, v118
	v_lshlrev_b32_e32 v155, 16, v119
	v_and_b32_e32 v152, 0xffff0000, v119
	v_lshlrev_b32_e32 v136, 16, v120
	v_and_b32_e32 v137, 0xffff0000, v120
	v_lshlrev_b32_e32 v138, 16, v121
	v_and_b32_e32 v139, 0xffff0000, v121
	s_waitcnt vmcnt(0) lgkmcnt(0)
	v_lshlrev_b32_e32 v172, 16, v122
	v_and_b32_e32 v160, 0xffff0000, v122
	v_lshlrev_b32_e32 v153, 16, v123
	v_and_b32_e32 v151, 0xffff0000, v123
	v_lshlrev_b32_e32 v132, 16, v124
	v_and_b32_e32 v133, 0xffff0000, v124
	v_lshlrev_b32_e32 v134, 16, v125
	v_and_b32_e32 v135, 0xffff0000, v125
	v_lshlrev_b32_e32 v120, 16, v128
	v_and_b32_e32 v118, 0xffff0000, v128
	v_lshlrev_b32_e32 v124, 16, v129
	v_and_b32_e32 v122, 0xffff0000, v129
	v_lshlrev_b32_e32 v128, 16, v130
	v_and_b32_e32 v126, 0xffff0000, v130
	v_lshlrev_b32_e32 v130, 16, v131
	v_and_b32_e32 v84, 0xffff0000, v131
	s_branch .LBB0_929

.LBB0_983:
	v_lshl_or_b32 v136, s39, 8, v171
	s_lshl_b64 s[2:3], s[2:3], 2
	s_add_u32 s2, s34, s2
	v_ashrrev_i32_e32 v137, 31, v136
	s_addc_u32 s3, s35, s3
	v_lshlrev_b64 v[160:161], 2, v[136:137]
	v_lshl_add_u64 v[150:151], s[2:3], 0, v[160:161]
	v_lshl_add_u64 v[162:163], s[10:11], 0, v[160:161]
	global_load_dwordx4 v[138:141], v[150:151], off
	global_load_dwordx4 v[142:145], v[162:163], off
	v_lshl_add_u32 v152, s46, 8, v155
	v_ashrrev_i32_e32 v153, 31, v152
	v_lshl_add_u64 v[178:179], s[0:1], 0, v[160:161]
	v_lshlrev_b64 v[194:195], 13, v[152:153]
	v_lshl_add_u64 v[174:175], v[178:179], 0, v[194:195]
	v_or_b32_e32 v180, 16, v152
	v_ashrrev_i32_e32 v181, 31, v180
	v_lshlrev_b64 v[210:211], 13, v[180:181]
	v_lshl_add_u64 v[190:191], v[178:179], 0, v[210:211]
	v_lshl_add_u64 v[194:195], s[0:1], 0, v[194:195]
	v_lshl_add_u64 v[212:213], v[194:195], 0, v[160:161]
	v_or_b32_e32 v194, 32, v152
	v_ashrrev_i32_e32 v195, 31, v194
	v_lshlrev_b64 v[194:195], 13, v[194:195]
	v_lshl_add_u64 v[194:195], s[0:1], 0, v[194:195]
	v_lshl_add_u64 v[214:215], v[194:195], 0, v[160:161]
	s_mov_b64 s[2:3], 0x100000
	s_mov_b32 s39, s12
	s_mov_b32 s46, s14
	s_mov_b64 s[20:21], s[18:19]
	s_mov_b64 s[22:23], s[16:17]
	s_waitcnt vmcnt(0) lgkmcnt(0)
	v_pk_add_f32 v[136:137], v[140:141], v[144:145]
	v_pk_add_f32 v[138:139], v[138:139], v[142:143]
	global_load_dwordx4 v[142:145], v[150:151], off offset:64
	global_load_dwordx4 v[146:149], v[162:163], off offset:64
	s_waitcnt vmcnt(0) lgkmcnt(0)
	v_pk_add_f32 v[140:141], v[144:145], v[148:149]
	v_pk_add_f32 v[142:143], v[142:143], v[146:147]
	global_load_dwordx4 v[146:149], v[150:151], off offset:512
	global_load_dwordx4 v[156:159], v[162:163], off offset:512
	s_waitcnt vmcnt(0) lgkmcnt(0)
	v_pk_add_f32 v[144:145], v[148:149], v[158:159]
	v_pk_add_f32 v[146:147], v[146:147], v[156:157]
	global_load_dwordx4 v[156:159], v[150:151], off offset:576
	s_nop 0
	global_load_dwordx4 v[162:165], v[162:163], off offset:576
	s_waitcnt vmcnt(0) lgkmcnt(0)
	v_pk_add_f32 v[148:149], v[158:159], v[164:165]
	v_pk_add_f32 v[150:151], v[156:157], v[162:163]
	global_load_dwordx4 v[156:159], v[174:175], off
	global_load_dwordx4 v[162:165], v[174:175], off offset:64
	global_load_dwordx4 v[166:169], v[174:175], off offset:512
	s_nop 0
	global_load_dwordx4 v[174:177], v[174:175], off offset:576
	s_nop 0
	global_load_dwordx4 v[178:181], v[190:191], off
	global_load_dwordx4 v[182:185], v[190:191], off offset:64
	global_load_dwordx4 v[186:189], v[190:191], off offset:512
	s_nop 0
	global_load_dwordx4 v[190:193], v[190:191], off offset:576
	s_nop 0
	global_load_dwordx4 v[194:197], v[214:215], off
	global_load_dwordx4 v[198:201], v[214:215], off offset:64
	global_load_dwordx4 v[202:205], v[214:215], off offset:512
	global_load_dwordx4 v[206:209], v[214:215], off offset:576
	s_waitcnt vmcnt(0) lgkmcnt(0)
	v_pk_fma_f32 v[126:127], v[126:127], v[138:139], v[156:157]
	v_pk_fma_f32 v[128:129], v[128:129], v[136:137], v[158:159]
	v_pk_fma_f32 v[124:125], v[124:125], v[140:141], v[164:165]
	v_pk_fma_f32 v[116:117], v[116:117], v[148:149], v[176:177]
	v_pk_fma_f32 v[114:115], v[114:115], v[150:151], v[174:175]
	global_store_dwordx4 v[212:213], v[114:117], off offset:576
	v_pk_fma_f32 v[122:123], v[122:123], v[142:143], v[162:163]
	v_pk_fma_f32 v[120:121], v[120:121], v[144:145], v[168:169]
	v_lshl_add_u64 v[114:115], s[0:1], 0, v[210:211]
	v_lshl_add_u64 v[156:157], v[114:115], 0, v[160:161]
	v_or_b32_e32 v114, 48, v152
	v_ashrrev_i32_e32 v115, 31, v114
	v_lshlrev_b64 v[114:115], 13, v[114:115]
	v_pk_fma_f32 v[118:119], v[118:119], v[146:147], v[166:167]
	v_lshl_add_u64 v[114:115], s[0:1], 0, v[114:115]
	global_store_dwordx4 v[212:213], v[126:129], off
	global_store_dwordx4 v[212:213], v[122:125], off offset:64
	global_store_dwordx4 v[212:213], v[118:121], off offset:512
	v_lshl_add_u64 v[168:169], v[114:115], 0, v[160:161]
	global_load_dwordx4 v[126:129], v[168:169], off
	global_load_dwordx4 v[122:125], v[168:169], off offset:64
	global_load_dwordx4 v[118:121], v[168:169], off offset:512
	global_load_dwordx4 v[114:117], v[168:169], off offset:576
	v_lshl_add_u64 v[164:165], v[212:213], 0, s[2:3]
	s_mov_b32 s2, 0x100000
	v_pk_fma_f32 v[112:113], v[112:113], v[136:137], v[180:181]
	v_pk_fma_f32 v[110:111], v[110:111], v[138:139], v[178:179]
	v_pk_fma_f32 v[108:109], v[108:109], v[140:141], v[184:185]
	v_pk_fma_f32 v[106:107], v[106:107], v[142:143], v[182:183]
	v_pk_fma_f32 v[96:97], v[96:97], v[144:145], v[188:189]
	v_pk_fma_f32 v[94:95], v[94:95], v[146:147], v[186:187]
	v_pk_fma_f32 v[92:93], v[92:93], v[148:149], v[192:193]
	v_pk_fma_f32 v[90:91], v[90:91], v[150:151], v[190:191]
	v_add_co_u32_e32 v166, vcc, s2, v212
	global_store_dwordx4 v[156:157], v[110:113], off
	global_store_dwordx4 v[156:157], v[106:109], off offset:64
	global_store_dwordx4 v[156:157], v[94:97], off offset:512
	global_store_dwordx4 v[156:157], v[90:93], off offset:576
	v_addc_co_u32_e32 v167, vcc, 0, v213, vcc
	global_load_dwordx4 v[110:113], v[166:167], off
	global_load_dwordx4 v[106:109], v[164:165], off offset:64
	global_load_dwordx4 v[94:97], v[164:165], off offset:512
	global_load_dwordx4 v[90:93], v[164:165], off offset:576
	v_pk_fma_f32 v[84:85], v[84:85], v[148:149], v[208:209]
	v_pk_fma_f32 v[82:83], v[82:83], v[150:151], v[206:207]
	global_store_dwordx4 v[214:215], v[82:85], off offset:576
	v_pk_fma_f32 v[104:105], v[104:105], v[136:137], v[196:197]
	v_pk_fma_f32 v[102:103], v[102:103], v[138:139], v[194:195]
	v_add_u32_e32 v82, 0x90, v152
	v_ashrrev_i32_e32 v83, 31, v82
	v_lshlrev_b64 v[82:83], 13, v[82:83]
	v_pk_fma_f32 v[100:101], v[100:101], v[140:141], v[200:201]
	v_pk_fma_f32 v[98:99], v[98:99], v[142:143], v[198:199]
	v_pk_fma_f32 v[88:89], v[88:89], v[144:145], v[204:205]
	v_pk_fma_f32 v[86:87], v[86:87], v[146:147], v[202:203]
	v_lshl_add_u64 v[82:83], s[0:1], 0, v[82:83]
	global_store_dwordx4 v[214:215], v[102:105], off
	global_store_dwordx4 v[214:215], v[98:101], off offset:64
	global_store_dwordx4 v[214:215], v[86:89], off offset:512
	v_lshl_add_u64 v[162:163], v[82:83], 0, v[160:161]
	global_load_dwordx4 v[86:89], v[162:163], off
	global_load_dwordx4 v[82:85], v[162:163], off offset:64
	global_load_dwordx4 v[102:105], v[162:163], off offset:512
	global_load_dwordx4 v[98:101], v[162:163], off offset:576
	s_and_b64 vcc, exec, s[4:5]
	s_waitcnt vmcnt(0) lgkmcnt(0)
	v_pk_fma_f32 v[80:81], v[80:81], v[136:137], v[128:129]
	v_pk_fma_f32 v[78:79], v[78:79], v[138:139], v[126:127]
	v_pk_fma_f32 v[76:77], v[76:77], v[140:141], v[124:125]
	v_pk_fma_f32 v[68:69], v[68:69], v[148:149], v[116:117]
	v_pk_fma_f32 v[66:67], v[66:67], v[150:151], v[114:115]
	global_store_dwordx4 v[168:169], v[66:69], off offset:576
	v_pk_fma_f32 v[74:75], v[74:75], v[142:143], v[122:123]
	v_pk_fma_f32 v[72:73], v[72:73], v[144:145], v[120:121]
	v_add_u32_e32 v66, 0xa0, v152
	v_ashrrev_i32_e32 v67, 31, v66
	v_lshlrev_b64 v[66:67], 13, v[66:67]
	v_pk_fma_f32 v[70:71], v[70:71], v[146:147], v[118:119]
	v_lshl_add_u64 v[66:67], s[0:1], 0, v[66:67]
	global_store_dwordx4 v[168:169], v[78:81], off
	global_store_dwordx4 v[168:169], v[74:77], off offset:64
	global_store_dwordx4 v[168:169], v[70:73], off offset:512
	v_lshl_add_u64 v[114:115], v[66:67], 0, v[160:161]
	global_load_dwordx4 v[78:81], v[114:115], off
	global_load_dwordx4 v[74:77], v[114:115], off offset:64
	global_load_dwordx4 v[70:73], v[114:115], off offset:512
	global_load_dwordx4 v[66:69], v[114:115], off offset:576
	v_pk_fma_f32 v[64:65], v[64:65], v[136:137], v[112:113]
	v_pk_fma_f32 v[62:63], v[62:63], v[138:139], v[110:111]
	v_pk_fma_f32 v[60:61], v[60:61], v[140:141], v[108:109]
	v_pk_fma_f32 v[52:53], v[52:53], v[148:149], v[92:93]
	v_pk_fma_f32 v[50:51], v[50:51], v[150:151], v[90:91]
	global_store_dwordx4 v[164:165], v[50:53], off offset:576
	v_pk_fma_f32 v[58:59], v[58:59], v[142:143], v[106:107]
	v_pk_fma_f32 v[56:57], v[56:57], v[144:145], v[96:97]
	v_add_u32_e32 v50, 0xb0, v152
	v_ashrrev_i32_e32 v51, 31, v50
	v_lshlrev_b64 v[50:51], 13, v[50:51]
	v_pk_fma_f32 v[54:55], v[54:55], v[146:147], v[94:95]
	v_lshl_add_u64 v[50:51], s[0:1], 0, v[50:51]
	global_store_dwordx4 v[166:167], v[62:65], off
	global_store_dwordx4 v[164:165], v[58:61], off offset:64
	global_store_dwordx4 v[164:165], v[54:57], off offset:512
	v_lshl_add_u64 v[90:91], v[50:51], 0, v[160:161]
	global_load_dwordx4 v[62:65], v[90:91], off
	global_load_dwordx4 v[58:61], v[90:91], off offset:64
	global_load_dwordx4 v[54:57], v[90:91], off offset:512
	global_load_dwordx4 v[50:53], v[90:91], off offset:576
	v_pk_fma_f32 v[48:49], v[48:49], v[136:137], v[88:89]
	v_pk_fma_f32 v[46:47], v[46:47], v[138:139], v[86:87]
	v_pk_fma_f32 v[44:45], v[44:45], v[140:141], v[84:85]
	v_pk_fma_f32 v[26:27], v[26:27], v[148:149], v[100:101]
	v_pk_fma_f32 v[24:25], v[24:25], v[150:151], v[98:99]
	global_store_dwordx4 v[162:163], v[24:27], off offset:576
	v_pk_fma_f32 v[42:43], v[42:43], v[142:143], v[82:83]
	v_pk_fma_f32 v[36:37], v[36:37], v[144:145], v[104:105]
	v_pk_fma_f32 v[34:35], v[34:35], v[146:147], v[102:103]
	global_store_dwordx4 v[162:163], v[46:49], off
	global_store_dwordx4 v[162:163], v[42:45], off offset:64
	global_store_dwordx4 v[162:163], v[34:37], off offset:512
	s_waitcnt vmcnt(0) lgkmcnt(0)
	v_pk_fma_f32 v[26:27], v[40:41], v[136:137], v[80:81]
	v_pk_fma_f32 v[24:25], v[38:39], v[138:139], v[78:79]
	global_store_dwordx4 v[114:115], v[24:27], off
	v_pk_fma_f32 v[10:11], v[10:11], v[148:149], v[68:69]
	v_pk_fma_f32 v[8:9], v[8:9], v[150:151], v[66:67]
	global_store_dwordx4 v[114:115], v[8:11], off offset:576
	v_pk_fma_f32 v[26:27], v[30:31], v[140:141], v[76:77]
	v_pk_fma_f32 v[24:25], v[28:29], v[142:143], v[74:75]
	v_pk_fma_f32 v[18:19], v[18:19], v[144:145], v[72:73]
	v_pk_fma_f32 v[16:17], v[16:17], v[146:147], v[70:71]
	global_store_dwordx4 v[114:115], v[24:27], off offset:64
	global_store_dwordx4 v[114:115], v[16:19], off offset:512
	v_pk_fma_f32 v[10:11], v[22:23], v[136:137], v[64:65]
	v_pk_fma_f32 v[8:9], v[20:21], v[138:139], v[62:63]
	global_store_dwordx4 v[90:91], v[8:11], off
	v_pk_fma_f32 v[6:7], v[6:7], v[144:145], v[56:57]
	v_pk_fma_f32 v[4:5], v[4:5], v[146:147], v[54:55]
	v_pk_fma_f32 v[10:11], v[14:15], v[140:141], v[60:61]
	v_pk_fma_f32 v[8:9], v[12:13], v[142:143], v[58:59]
	v_pk_fma_f32 v[2:3], v[2:3], v[148:149], v[52:53]
	v_pk_fma_f32 v[0:1], v[0:1], v[150:151], v[50:51]
	global_store_dwordx4 v[90:91], v[8:11], off offset:64
	global_store_dwordx4 v[90:91], v[4:7], off offset:512
	global_store_dwordx4 v[90:91], v[0:3], off offset:576
	s_cbranch_vccnz .LBB0_990

.LBB0_1039:
	s_or_b64 exec, exec, s[10:11]
	global_load_dwordx4 v[28:31], v[78:79], off
	global_load_dwordx4 v[24:27], v[78:79], off offset:1024
	global_load_dwordx4 v[20:23], v[78:79], off offset:2048
	global_load_dwordx4 v[16:19], v[78:79], off offset:3072
	v_add_co_u32_e32 v4, vcc, s94, v78
	v_add_u32_e32 v34, 1, v34
	s_nop 0
	v_addc_co_u32_e32 v5, vcc, 0, v79, vcc
	s_mov_b64 s[2:3], 0x2000
	v_lshl_add_u64 v[78:79], v[78:79], 0, s[2:3]
	s_mov_b64 s[2:3], 0x1000
	s_waitcnt vmcnt(0) lgkmcnt(0)
	v_mul_f32_e32 v0, v29, v29
	v_mul_f32_e32 v1, v25, v25
	v_fmac_f32_e32 v0, v28, v28
	v_fmac_f32_e32 v1, v24, v24
	v_fmac_f32_e32 v0, v30, v30
	v_fmac_f32_e32 v1, v26, v26
	v_fmac_f32_e32 v0, v31, v31
	v_fmac_f32_e32 v1, v27, v27
	v_add_f32_e32 v0, v0, v1
	v_mul_f32_e32 v1, v21, v21
	v_fmac_f32_e32 v1, v20, v20
	v_fmac_f32_e32 v1, v22, v22
	v_fmac_f32_e32 v1, v23, v23
	v_add_f32_e32 v0, v0, v1
	v_mul_f32_e32 v1, v17, v17
	v_fmac_f32_e32 v1, v16, v16
	v_fmac_f32_e32 v1, v18, v18
	v_fmac_f32_e32 v1, v19, v19
	v_add_f32_e32 v10, v0, v1
	global_load_dwordx4 v[12:15], v[4:5], off
	global_load_dwordx4 v[0:3], v[4:5], off offset:1024
	s_waitcnt vmcnt(0) lgkmcnt(0)
	v_mov_b32_e32 v8, v13
	v_mov_b32_e32 v9, v1
	v_mov_b32_e32 v6, v12
	v_mov_b32_e32 v7, v0
	v_pk_mul_f32 v[8:9], v[8:9], v[8:9]
	s_nop 0
	v_pk_fma_f32 v[6:7], v[6:7], v[6:7], v[8:9]
	v_mov_b32_e32 v8, v14
	v_mov_b32_e32 v9, v2
	v_pk_fma_f32 v[6:7], v[8:9], v[8:9], v[6:7]
	v_mov_b32_e32 v8, v15
	v_mov_b32_e32 v9, v3
	v_pk_fma_f32 v[6:7], v[8:9], v[8:9], v[6:7]
	s_nop 0
	v_add_f32_e32 v6, v10, v6
	v_add_f32_e32 v35, v6, v7
	global_load_dwordx4 v[8:11], v[4:5], off offset:2048
	s_nop 0
	global_load_dwordx4 v[4:7], v[4:5], off offset:3072
	s_waitcnt vmcnt(0) lgkmcnt(0)
	v_mov_b32_e32 v158, v9
	v_mov_b32_e32 v159, v5
	v_mov_b32_e32 v156, v8
	v_mov_b32_e32 v157, v4
	v_pk_mul_f32 v[158:159], v[158:159], v[158:159]
	s_nop 0
	v_pk_fma_f32 v[156:157], v[156:157], v[156:157], v[158:159]
	v_mov_b32_e32 v158, v10
	v_mov_b32_e32 v159, v6
	v_pk_fma_f32 v[156:157], v[158:159], v[158:159], v[156:157]
	v_mov_b32_e32 v158, v11
	v_mov_b32_e32 v159, v7
	v_pk_fma_f32 v[156:157], v[158:159], v[158:159], v[156:157]
	s_nop 0
	v_add_f32_e32 v35, v35, v156
	v_add_f32_e32 v35, v35, v157
	ds_bpermute_b32 v85, v166, v35
	s_waitcnt lgkmcnt(0)
	v_add_f32_e32 v35, v35, v85
	ds_bpermute_b32 v85, v167, v35
	s_waitcnt lgkmcnt(0)
	v_add_f32_e32 v35, v35, v85
	ds_bpermute_b32 v85, v168, v35
	s_waitcnt lgkmcnt(0)
	v_add_f32_e32 v35, v35, v85
	ds_bpermute_b32 v85, v169, v35
	s_waitcnt lgkmcnt(0)
	v_add_f32_e32 v35, v35, v85
	ds_bpermute_b32 v85, v170, v35
	s_waitcnt lgkmcnt(0)
	v_add_f32_e32 v35, v35, v85
	ds_bpermute_b32 v85, v171, v35
	s_waitcnt lgkmcnt(0)
	v_add_f32_e32 v35, v35, v85
	v_fmamk_f32 v35, v35, 0x3a000000, v225
	v_cmp_gt_f32_e32 vcc, s33, v35
	v_mul_f32_e32 v85, 0x4b800000, v35
	s_nop 0
	v_cndmask_b32_e32 v35, v35, v85, vcc
	v_rsq_f32_e32 v35, v35
	s_nop 0
	v_mul_f32_e32 v85, 0x45800000, v35
	v_cndmask_b32_e32 v35, v35, v85, vcc
	v_mul_f32_e32 v0, v0, v35
	v_mul_f32_e32 v1, v1, v35
	v_fma_f32 v0, v140, v0, v138
	v_fma_f32 v1, v141, v1, v139
	v_cvt_pk_bf16_f32 v0, v0, v1
	v_mul_f32_e32 v1, v2, v35
	v_fma_f32 v1, v142, v1, v136
	v_mul_f32_e32 v2, v3, v35
	v_fma_f32 v2, v143, v2, v137
	v_cvt_pk_bf16_f32 v1, v1, v2
	global_store_dwordx2 v[80:81], v[0:1], off offset:2560
	v_mul_f32_e32 v0, v8, v35
	v_mul_f32_e32 v1, v9, v35
	v_fma_f32 v0, v148, v0, v146
	v_fma_f32 v1, v149, v1, v147
	v_cvt_pk_bf16_f32 v0, v0, v1
	v_mul_f32_e32 v1, v10, v35
	v_fma_f32 v1, v150, v1, v144
	v_mul_f32_e32 v2, v11, v35
	v_fma_f32 v2, v151, v2, v145
	v_cvt_pk_bf16_f32 v1, v1, v2
	v_mul_f32_e32 v28, v28, v35
	v_mul_f32_e32 v29, v29, v35
	v_mul_f32_e32 v24, v24, v35
	v_mul_f32_e32 v25, v25, v35
	v_mul_f32_e32 v20, v20, v35
	v_mul_f32_e32 v21, v21, v35
	v_mul_f32_e32 v16, v16, v35
	v_mul_f32_e32 v17, v17, v35
	v_mul_f32_e32 v12, v12, v35
	v_mul_f32_e32 v13, v13, v35
	global_store_dwordx2 v[80:81], v[0:1], off offset:3072
	v_mul_f32_e32 v0, v4, v35
	v_mul_f32_e32 v1, v5, v35
	v_fma_f32 v28, v96, v28, v100
	v_fma_f32 v29, v97, v29, v101
	v_fma_f32 v24, v108, v24, v106
	v_fma_f32 v25, v109, v25, v107
	v_fma_f32 v20, v116, v20, v114
	v_fma_f32 v21, v117, v21, v115
	v_fma_f32 v16, v124, v16, v122
	v_fma_f32 v17, v125, v17, v123
	v_fma_f32 v12, v132, v12, v130
	v_fma_f32 v13, v133, v13, v131
	v_fma_f32 v0, v162, v0, v160
	v_fma_f32 v1, v163, v1, v161
	v_cvt_pk_bf16_f32 v28, v28, v29
	v_mul_f32_e32 v29, v30, v35
	v_cvt_pk_bf16_f32 v24, v24, v25
	v_mul_f32_e32 v25, v26, v35
	v_cvt_pk_bf16_f32 v20, v20, v21
	v_mul_f32_e32 v21, v22, v35
	v_cvt_pk_bf16_f32 v16, v16, v17
	v_mul_f32_e32 v17, v18, v35
	v_cvt_pk_bf16_f32 v12, v12, v13
	v_mul_f32_e32 v13, v14, v35
	v_cvt_pk_bf16_f32 v0, v0, v1
	v_mul_f32_e32 v1, v6, v35
	v_fma_f32 v29, v102, v29, v98
	v_mul_f32_e32 v30, v31, v35
	v_fma_f32 v25, v110, v25, v104
	v_mul_f32_e32 v26, v27, v35
	v_fma_f32 v21, v118, v21, v112
	v_mul_f32_e32 v22, v23, v35
	v_fma_f32 v17, v126, v17, v120
	v_mul_f32_e32 v18, v19, v35
	v_fma_f32 v13, v134, v13, v128
	v_mul_f32_e32 v14, v15, v35
	v_fma_f32 v1, v164, v1, v152
	v_mul_f32_e32 v2, v7, v35
	v_cmp_ge_i32_e32 vcc, v34, v155
	v_fma_f32 v30, v103, v30, v99
	v_cvt_pk_bf16_f32 v29, v29, v30
	global_store_dwordx2 v[80:81], v[28:29], off
	v_fma_f32 v26, v111, v26, v105
	v_cvt_pk_bf16_f32 v25, v25, v26
	global_store_dwordx2 v[80:81], v[24:25], off offset:512
	v_fma_f32 v22, v119, v22, v113
	v_cvt_pk_bf16_f32 v21, v21, v22
	global_store_dwordx2 v[80:81], v[20:21], off offset:1024
	v_fma_f32 v18, v127, v18, v121
	v_cvt_pk_bf16_f32 v17, v17, v18
	global_store_dwordx2 v[80:81], v[16:17], off offset:1536
	v_fma_f32 v14, v135, v14, v129
	v_cvt_pk_bf16_f32 v13, v13, v14
	global_store_dwordx2 v[80:81], v[12:13], off offset:2048
	v_fma_f32 v2, v165, v2, v153
	v_cvt_pk_bf16_f32 v1, v1, v2
	global_store_dwordx2 v[80:81], v[0:1], off offset:3584
	v_lshl_add_u64 v[80:81], v[80:81], 0, s[2:3]
	s_or_b64 s[8:9], vcc, s[8:9]
	s_andn2_b64 exec, exec, s[8:9]
	s_cbranch_execz .LBB0_1042
.LBB0_1040:
	v_add_u32_e32 v0, 0xffffe000, v34
	s_movk_i32 s2, 0x1fff
	v_lshrrev_b32_e32 v0, 12, v0
	v_cmp_lt_i32_e32 vcc, s2, v34
	s_nop 1
	v_cndmask_b32_e32 v12, 4, v0, vcc
	v_cmp_ne_u32_e32 vcc, v12, v83
	s_and_saveexec_b64 s[10:11], vcc
	s_cbranch_execz .LBB0_1039
	v_mov_b64_e32 v[0:1], s[6:7]
	s_mov_b32 s2, 0xc000
	v_mad_u64_u32 v[2:3], s[2:3], v12, s2, v[0:1]
	s_mov_b64 s[2:3], 0x6000
	s_nop 0
	v_lshl_add_u64 v[0:1], v[2:3], 0, s[2:3]
	s_mov_b64 s[2:3], 0x8000
	v_lshl_add_u64 v[8:9], v[2:3], 0, s[2:3]
	v_lshl_add_u64 v[2:3], v[0:1], 0, v[32:33]
	global_load_dwordx4 v[2:5], v[2:3], off
	s_nop 0
	global_load_dwordx4 v[14:17], v[38:39], off
	v_lshl_add_u64 v[6:7], v[8:9], 0, v[32:33]
	global_load_dwordx4 v[18:21], v[36:37], off
	global_load_dwordx4 v[22:25], v[6:7], off
	global_load_dwordx4 v[26:29], v[40:41], off
	v_mov_b32_e32 v83, v33
	v_mov_b32_e32 v85, v33
	v_mov_b32_e32 v87, v33
	v_mov_b32_e32 v89, v33
	v_mov_b32_e32 v91, v33
	v_mov_b32_e32 v93, v33
	v_mov_b32_e32 v95, v33
	s_waitcnt vmcnt(0) lgkmcnt(0)
	v_pk_add_f32 v[100:101], v[2:3], v[14:15]
	v_pk_add_f32 v[6:7], v[22:23], 1.0 op_sel_hi:[1,0]
	v_lshl_add_u64 v[2:3], v[0:1], 0, v[82:83]
	v_pk_add_f32 v[6:7], v[6:7], v[26:27]
	v_pk_add_f32 v[98:99], v[4:5], v[16:17]
	v_pk_mul_f32 v[96:97], v[18:19], v[6:7]
	v_pk_add_f32 v[6:7], v[24:25], 1.0 op_sel_hi:[1,0]
	global_load_dwordx4 v[2:5], v[2:3], off
	s_nop 0
	global_load_dwordx4 v[14:17], v[42:43], off
	v_pk_add_f32 v[6:7], v[6:7], v[28:29]
	s_waitcnt vmcnt(0) lgkmcnt(0)
	v_pk_add_f32 v[106:107], v[2:3], v[14:15]
	v_pk_mul_f32 v[102:103], v[20:21], v[6:7]
	v_lshl_add_u64 v[6:7], v[8:9], 0, v[82:83]
	global_load_dwordx4 v[18:21], v[36:37], off offset:1024
	global_load_dwordx4 v[22:25], v[6:7], off
	global_load_dwordx4 v[26:29], v[44:45], off
	v_lshl_add_u64 v[2:3], v[0:1], 0, v[84:85]
	v_pk_add_f32 v[104:105], v[4:5], v[16:17]
	global_load_dwordx4 v[2:5], v[2:3], off
	s_nop 0
	global_load_dwordx4 v[14:17], v[46:47], off
	v_mov_b32_e32 v83, v12
	s_waitcnt vmcnt(0) lgkmcnt(0)
	v_pk_add_f32 v[6:7], v[22:23], 1.0 op_sel_hi:[1,0]
	s_nop 0
	v_pk_add_f32 v[6:7], v[6:7], v[26:27]
	v_pk_add_f32 v[114:115], v[2:3], v[14:15]
	v_pk_mul_f32 v[108:109], v[18:19], v[6:7]
	v_pk_add_f32 v[6:7], v[24:25], 1.0 op_sel_hi:[1,0]
	v_lshl_add_u64 v[2:3], v[0:1], 0, v[86:87]
	v_pk_add_f32 v[6:7], v[6:7], v[28:29]
	v_pk_add_f32 v[112:113], v[4:5], v[16:17]
	v_pk_mul_f32 v[110:111], v[20:21], v[6:7]
	v_lshl_add_u64 v[6:7], v[8:9], 0, v[84:85]
	global_load_dwordx4 v[18:21], v[36:37], off offset:2048
	global_load_dwordx4 v[22:25], v[6:7], off
	global_load_dwordx4 v[26:29], v[48:49], off
	s_nop 0
	global_load_dwordx4 v[2:5], v[2:3], off
	s_nop 0
	global_load_dwordx4 v[14:17], v[50:51], off
	s_waitcnt vmcnt(0) lgkmcnt(0)
	v_pk_add_f32 v[6:7], v[22:23], 1.0 op_sel_hi:[1,0]
	s_nop 0
	v_pk_add_f32 v[6:7], v[6:7], v[26:27]
	v_pk_add_f32 v[122:123], v[2:3], v[14:15]
	v_pk_mul_f32 v[116:117], v[18:19], v[6:7]
	v_pk_add_f32 v[6:7], v[24:25], 1.0 op_sel_hi:[1,0]
	v_lshl_add_u64 v[2:3], v[0:1], 0, v[88:89]
	v_pk_add_f32 v[6:7], v[6:7], v[28:29]
	v_pk_add_f32 v[120:121], v[4:5], v[16:17]
	v_pk_mul_f32 v[118:119], v[20:21], v[6:7]
	v_lshl_add_u64 v[6:7], v[8:9], 0, v[86:87]
	global_load_dwordx4 v[18:21], v[36:37], off offset:3072
	global_load_dwordx4 v[22:25], v[6:7], off
	global_load_dwordx4 v[26:29], v[52:53], off
	s_nop 0
	global_load_dwordx4 v[2:5], v[2:3], off
	s_nop 0
	global_load_dwordx4 v[14:17], v[56:57], off
	s_waitcnt vmcnt(0) lgkmcnt(0)
	v_pk_add_f32 v[6:7], v[22:23], 1.0 op_sel_hi:[1,0]
	s_nop 0
	v_pk_add_f32 v[6:7], v[6:7], v[26:27]
	v_pk_add_f32 v[130:131], v[2:3], v[14:15]
	v_pk_mul_f32 v[124:125], v[18:19], v[6:7]
	v_pk_add_f32 v[6:7], v[24:25], 1.0 op_sel_hi:[1,0]
	v_lshl_add_u64 v[2:3], v[0:1], 0, v[90:91]
	v_pk_add_f32 v[6:7], v[6:7], v[28:29]
	v_pk_add_f32 v[128:129], v[4:5], v[16:17]
	v_pk_mul_f32 v[126:127], v[20:21], v[6:7]
	v_lshl_add_u64 v[6:7], v[8:9], 0, v[88:89]
	global_load_dwordx4 v[18:21], v[54:55], off
	global_load_dwordx4 v[22:25], v[6:7], off
	global_load_dwordx4 v[26:29], v[58:59], off
	s_nop 0
	global_load_dwordx4 v[2:5], v[2:3], off
	s_nop 0
	global_load_dwordx4 v[14:17], v[62:63], off
	s_waitcnt vmcnt(0) lgkmcnt(0)
	v_pk_add_f32 v[6:7], v[22:23], 1.0 op_sel_hi:[1,0]
	s_nop 0
	v_pk_add_f32 v[6:7], v[6:7], v[26:27]
	v_pk_add_f32 v[138:139], v[2:3], v[14:15]
	v_pk_mul_f32 v[132:133], v[18:19], v[6:7]
	v_pk_add_f32 v[6:7], v[24:25], 1.0 op_sel_hi:[1,0]
	v_lshl_add_u64 v[2:3], v[0:1], 0, v[92:93]
	v_pk_add_f32 v[6:7], v[6:7], v[28:29]
	v_pk_add_f32 v[136:137], v[4:5], v[16:17]
	v_pk_mul_f32 v[134:135], v[20:21], v[6:7]
	v_lshl_add_u64 v[6:7], v[8:9], 0, v[90:91]
	global_load_dwordx4 v[18:21], v[60:61], off
	global_load_dwordx4 v[22:25], v[6:7], off
	global_load_dwordx4 v[26:29], v[64:65], off
	s_nop 0
	global_load_dwordx4 v[2:5], v[2:3], off
	s_nop 0
	global_load_dwordx4 v[14:17], v[68:69], off
	v_lshl_add_u64 v[0:1], v[0:1], 0, v[94:95]
	s_waitcnt vmcnt(0) lgkmcnt(0)
	v_pk_add_f32 v[6:7], v[22:23], 1.0 op_sel_hi:[1,0]
	s_nop 0
	v_pk_add_f32 v[6:7], v[6:7], v[26:27]
	v_pk_add_f32 v[146:147], v[2:3], v[14:15]
	v_pk_mul_f32 v[140:141], v[18:19], v[6:7]
	v_pk_add_f32 v[6:7], v[24:25], 1.0 op_sel_hi:[1,0]
	v_lshl_add_u64 v[14:15], v[8:9], 0, v[94:95]
	v_pk_add_f32 v[6:7], v[6:7], v[28:29]
	v_pk_add_f32 v[144:145], v[4:5], v[16:17]
	v_pk_mul_f32 v[142:143], v[20:21], v[6:7]
	v_lshl_add_u64 v[6:7], v[8:9], 0, v[92:93]
	global_load_dwordx4 v[18:21], v[66:67], off
	global_load_dwordx4 v[22:25], v[6:7], off
	global_load_dwordx4 v[26:29], v[70:71], off
	s_waitcnt vmcnt(0) lgkmcnt(0)
	v_pk_add_f32 v[6:7], v[22:23], 1.0 op_sel_hi:[1,0]
	s_nop 0
	v_pk_add_f32 v[6:7], v[6:7], v[26:27]
	s_nop 0
	v_pk_mul_f32 v[148:149], v[18:19], v[6:7]
	v_pk_add_f32 v[6:7], v[24:25], 1.0 op_sel_hi:[1,0]
	s_nop 0
	v_pk_add_f32 v[6:7], v[6:7], v[28:29]
	s_nop 0
	v_pk_mul_f32 v[150:151], v[20:21], v[6:7]
	global_load_dwordx4 v[0:3], v[0:1], off
	s_nop 0
	global_load_dwordx4 v[4:7], v[74:75], off
	global_load_dwordx4 v[8:11], v[72:73], off
	s_nop 0
	global_load_dwordx4 v[14:17], v[14:15], off
	s_nop 0
	global_load_dwordx4 v[18:21], v[76:77], off
	s_waitcnt vmcnt(0) lgkmcnt(0)
	v_pk_add_f32 v[14:15], v[14:15], 1.0 op_sel_hi:[1,0]
	s_nop 0
	v_pk_add_f32 v[14:15], v[14:15], v[18:19]
	v_pk_add_f32 v[160:161], v[0:1], v[4:5]
	v_pk_mul_f32 v[162:163], v[8:9], v[14:15]
	v_pk_add_f32 v[8:9], v[16:17], 1.0 op_sel_hi:[1,0]
	v_pk_add_f32 v[152:153], v[2:3], v[6:7]
	v_pk_add_f32 v[8:9], v[8:9], v[20:21]
	s_nop 0
	v_pk_mul_f32 v[164:165], v[10:11], v[8:9]
	s_branch .LBB0_1039

.LBB0_1044:
	s_or_b64 exec, exec, s[6:7]
	s_movk_i32 s6, 0x104
	v_mad_u64_u32 v[4:5], s[6:7], v4, s6, v[8:9]
	s_waitcnt vmcnt(0)
	ds_write2_b32 v10, v52, v53 offset1:1
	ds_write2_b32 v10, v54, v55 offset0:2 offset1:3
	ds_write2_b32 v4, v0, v1 offset1:1
	ds_write2_b32 v4, v2, v3 offset0:2 offset1:3
	v_lshlrev_b32_e32 v0, 3, v9
	v_ashrrev_i32_e32 v6, 3, v9
	v_and_b32_e32 v7, 56, v0
	v_mul_u32_u24_e32 v0, 0x104, v7
	v_lshlrev_b32_e32 v1, 2, v6
	v_add3_u32 v4, 16, v0, v1
	s_waitcnt lgkmcnt(0)
	s_barrier
	ds_read2_b32 v[0:1], v4 offset1:65
	ds_read2_b32 v[2:3], v4 offset0:130 offset1:195
	v_add_u32_e32 v4, 0x400, v4
	s_waitcnt lgkmcnt(1)
	v_cvt_pk_bf16_f32 v0, v0, v1
	s_waitcnt lgkmcnt(0)
	v_cvt_pk_bf16_f32 v1, v2, v3
	ds_read2_b32 v[2:3], v4 offset0:4 offset1:69
	ds_read2_b32 v[4:5], v4 offset0:134 offset1:199
	s_mulk_i32 s3, 0x1900
	s_waitcnt lgkmcnt(1)
	v_cvt_pk_bf16_f32 v2, v2, v3
	s_waitcnt lgkmcnt(0)
	v_cvt_pk_bf16_f32 v3, v4, v5
	v_subrev_u32_e32 v4, s3, v6
	v_add_u32_e32 v4, s10, v4
	v_ashrrev_i32_e32 v5, 31, v4
	v_lshlrev_b64 v[4:5], 12, v[4:5]
	v_lshl_add_u64 v[4:5], s[0:1], 0, v[4:5]
	s_ashr_i32 s3, s2, 31
	v_lshl_add_u64 v[4:5], s[2:3], 1, v[4:5]
	v_lshlrev_b32_e32 v32, 1, v7
	v_lshl_add_u64 v[4:5], v[4:5], 0, v[32:33]
	v_readlane_b32 s24, v253, 6
	v_readlane_b32 s25, v255, 22
	global_store_dwordx4 v[4:5], v[0:3], off
	s_waitcnt lgkmcnt(0)
	s_barrier

.LBB0_1046:
	s_cmpk_gt_i32 s11, 0xc7f
	s_mov_b64 s[2:3], -1
	s_cbranch_scc0 .LBB0_1048
	v_mov_b32_e32 v10, v224
	s_and_b32 s7, s10, 0x7c0
	v_readlane_b32 s12, v254, 0
	s_and_b32 s6, s9, 0x1ffc0
	v_lshlrev_b32_e32 v0, 4, v10
	s_lshl_b32 s2, s7, 2
	v_readlane_b32 s22, v254, 10
	v_ashrrev_i32_e32 v2, 4, v10
	v_and_b32_e32 v32, 0xf0, v0
	v_readlane_b32 s23, v254, 11
	s_add_u32 s2, s22, s2
	v_add_u32_e32 v0, s6, v2
	s_addc_u32 s3, s23, 0
	v_ashrrev_i32_e32 v1, 31, v0
	v_lshl_add_u64 v[6:7], s[2:3], 0, v[32:33]
	v_lshlrev_b64 v[0:1], 13, v[0:1]
	v_add_u32_e32 v4, 16, v32
	v_lshl_add_u64 v[0:1], v[6:7], 0, v[0:1]
	s_movk_i32 s12, 0x104
	v_mad_u64_u32 v[8:9], s[2:3], v2, s12, v[4:5]
	global_load_dwordx4 v[52:55], v[0:1], off
	s_lshl_b32 s66, s6, 1
	v_readlane_b32 s24, v254, 12
	v_readlane_b32 s25, v254, 13
	v_readlane_b32 s13, v254, 1
	v_readlane_b32 s14, v254, 2
	v_readlane_b32 s15, v254, 3
	v_readlane_b32 s16, v254, 4
	v_readlane_b32 s17, v254, 5
	v_readlane_b32 s18, v254, 6
	v_readlane_b32 s19, v254, 7
	v_readlane_b32 s20, v254, 8
	v_readlane_b32 s21, v254, 9
	v_readlane_b32 s26, v254, 14
	v_readlane_b32 s27, v254, 15
	v_readlane_b32 s25, v255, 22
	v_readlane_b32 s24, v253, 6
	v_add_u32_e32 v0, 0x200, v10
	v_ashrrev_i32_e32 v2, 4, v0
	v_add_u32_e32 v0, s6, v2
	v_ashrrev_i32_e32 v1, 31, v0
	v_lshlrev_b64 v[0:1], 13, v[0:1]
	v_lshl_add_u64 v[0:1], v[6:7], 0, v[0:1]
	v_mad_u64_u32 v[4:5], s[2:3], v2, s12, v[4:5]
	global_load_dwordx4 v[0:3], v[0:1], off
	v_ashrrev_i32_e32 v6, 3, v10
	s_mov_b64 s[2:3], 0
	s_waitcnt vmcnt(0)
	ds_write2_b32 v8, v52, v53 offset1:1
	ds_write2_b32 v8, v54, v55 offset0:2 offset1:3
	ds_write2_b32 v4, v0, v1 offset1:1
	ds_write2_b32 v4, v2, v3 offset0:2 offset1:3
	v_lshlrev_b32_e32 v0, 3, v10
	v_and_b32_e32 v7, 56, v0
	v_mul_u32_u24_e32 v0, 0x104, v7
	v_lshlrev_b32_e32 v1, 2, v6
	v_add3_u32 v4, 16, v0, v1
	s_waitcnt lgkmcnt(0)
	s_barrier
	ds_read2_b32 v[0:1], v4 offset1:65
	ds_read2_b32 v[2:3], v4 offset0:130 offset1:195
	v_add_u32_e32 v4, 0x400, v4
	s_waitcnt lgkmcnt(1)
	v_cvt_pk_bf16_f32 v0, v0, v1
	s_waitcnt lgkmcnt(0)
	v_cvt_pk_bf16_f32 v1, v2, v3
	ds_read2_b32 v[2:3], v4 offset0:4 offset1:69
	ds_read2_b32 v[4:5], v4 offset0:134 offset1:199
	s_waitcnt lgkmcnt(1)
	v_cvt_pk_bf16_f32 v2, v2, v3
	s_waitcnt lgkmcnt(0)
	v_cvt_pk_bf16_f32 v3, v4, v5
	v_add_u32_e32 v4, s7, v6
	v_ashrrev_i32_e32 v5, 31, v4
	v_lshlrev_b64 v[4:5], 12, v[4:5]
	v_lshl_add_u64 v[4:5], s[4:5], 0, v[4:5]
	v_lshl_add_u64 v[4:5], v[4:5], 0, s[66:67]
	v_lshlrev_b32_e32 v32, 1, v7
	v_lshl_add_u64 v[4:5], v[4:5], 0, v[32:33]
	global_store_dwordx4 v[4:5], v[0:3], off
	s_waitcnt lgkmcnt(0)
	s_barrier

.LBB0_1104:
	s_add_u32 s2, s18, 0xfff80080
	s_addc_u32 s3, s19, -1
	s_add_i32 s56, 16, 0x10000
	v_add_u32_e32 v152, s56, v145
	ds_read_b128 v[140:143], v152
	ds_read_b128 v[148:151], v152 offset:1024
	ds_read_b128 v[156:159], v152 offset:2048
	ds_read_b128 v[160:163], v152 offset:3072
	s_cmp_eq_u32 s47, 28
	s_cselect_b32 s21, s13, s3
	s_cselect_b32 s20, s37, s2
	s_cselect_b32 s3, s11, s46
	s_cselect_b32 s2, s38, s39
	v_lshl_add_u64 v[152:153], s[18:19], 0, v[138:139]
	s_add_i32 m0, s26, 0xc000
	ds_read_b128 v[164:167], v147
	ds_read_b128 v[168:171], v147 offset:1024
	ds_read_b128 v[172:175], v147 offset:2048
	ds_read_b128 v[176:179], v147 offset:3072
	ds_read_b128 v[180:183], v147 offset:4096
	ds_read_b128 v[184:187], v147 offset:5120
	ds_read_b128 v[188:191], v147 offset:6144
	ds_read_b128 v[192:195], v147 offset:7168
	global_load_lds_dwordx4 v[152:153], off
	v_lshl_add_u64 v[152:153], s[18:19], 0, v[136:137]
	s_add_i32 m0, s26, 0xe000
	s_nop 0
	global_load_lds_dwordx4 v[152:153], off
	s_waitcnt lgkmcnt(8)
	s_barrier
	s_waitcnt lgkmcnt(0)
	s_setprio 1
	s_waitcnt lgkmcnt(0)
	v_mfma_f32_16x16x32_bf16 v[126:129], v[140:143], v[164:167], v[126:129]
	v_mfma_f32_16x16x32_bf16 v[122:125], v[156:159], v[164:167], v[122:125]
	v_mfma_f32_16x16x32_bf16 v[118:121], v[140:143], v[172:175], v[118:121]
	v_mfma_f32_16x16x32_bf16 v[110:113], v[156:159], v[172:175], v[110:113]
	v_mfma_f32_16x16x32_bf16 v[102:105], v[140:143], v[180:183], v[102:105]
	v_mfma_f32_16x16x32_bf16 v[94:97], v[156:159], v[180:183], v[94:97]
	v_mfma_f32_16x16x32_bf16 v[86:89], v[140:143], v[188:191], v[86:89]
	v_mfma_f32_16x16x32_bf16 v[78:81], v[156:159], v[188:191], v[78:81]
	v_mfma_f32_16x16x32_bf16 v[126:129], v[148:151], v[168:171], v[126:129]
	v_mfma_f32_16x16x32_bf16 v[122:125], v[160:163], v[168:171], v[122:125]
	v_mfma_f32_16x16x32_bf16 v[118:121], v[148:151], v[176:179], v[118:121]
	v_mfma_f32_16x16x32_bf16 v[110:113], v[160:163], v[176:179], v[110:113]
	v_mfma_f32_16x16x32_bf16 v[102:105], v[148:151], v[184:187], v[102:105]
	v_mfma_f32_16x16x32_bf16 v[94:97], v[160:163], v[184:187], v[94:97]
	v_mfma_f32_16x16x32_bf16 v[86:89], v[148:151], v[192:195], v[86:89]
	v_mfma_f32_16x16x32_bf16 v[78:81], v[160:163], v[192:195], v[78:81]
	s_setprio 0
	s_barrier
	s_add_i32 s58, 16, 0x14000
	v_add_u32_e32 v152, s58, v145
	s_add_i32 s56, s56, s23
	ds_read_b128 v[196:199], v152
	ds_read_b128 v[200:203], v152 offset:1024
	ds_read_b128 v[204:207], v152 offset:2048
	ds_read_b128 v[208:211], v152 offset:3072
	v_lshl_add_u64 v[152:153], s[2:3], 0, v[32:33]
	s_mov_b32 m0, s56
	v_lshl_add_u64 v[212:213], s[2:3], 0, v[130:131]
	global_load_lds_dwordx4 v[152:153], off
	s_add_i32 m0, s56, 0x2000
	s_nop 0
	global_load_lds_dwordx4 v[212:213], off
	s_barrier
	s_waitcnt lgkmcnt(0)
	s_setprio 1
	s_waitcnt lgkmcnt(0)
	v_mfma_f32_16x16x32_bf16 v[114:117], v[196:199], v[164:167], v[114:117]
	v_mfma_f32_16x16x32_bf16 v[106:109], v[204:207], v[164:167], v[106:109]
	v_mfma_f32_16x16x32_bf16 v[98:101], v[196:199], v[172:175], v[98:101]
	v_mfma_f32_16x16x32_bf16 v[90:93], v[204:207], v[172:175], v[90:93]
	v_mfma_f32_16x16x32_bf16 v[82:85], v[196:199], v[180:183], v[82:85]
	v_mfma_f32_16x16x32_bf16 v[74:77], v[204:207], v[180:183], v[74:77]
	v_mfma_f32_16x16x32_bf16 v[70:73], v[196:199], v[188:191], v[70:73]
	v_mfma_f32_16x16x32_bf16 v[66:69], v[204:207], v[188:191], v[66:69]
	v_mfma_f32_16x16x32_bf16 v[114:117], v[200:203], v[168:171], v[114:117]
	v_mfma_f32_16x16x32_bf16 v[106:109], v[208:211], v[168:171], v[106:109]
	v_mfma_f32_16x16x32_bf16 v[98:101], v[200:203], v[176:179], v[98:101]
	v_mfma_f32_16x16x32_bf16 v[90:93], v[208:211], v[176:179], v[90:93]
	v_mfma_f32_16x16x32_bf16 v[82:85], v[200:203], v[184:187], v[82:85]
	v_mfma_f32_16x16x32_bf16 v[74:77], v[208:211], v[184:187], v[74:77]
	v_mfma_f32_16x16x32_bf16 v[70:73], v[200:203], v[192:195], v[70:73]
	v_mfma_f32_16x16x32_bf16 v[66:69], v[208:211], v[192:195], v[66:69]
	s_setprio 0
	s_mov_b32 m0, s26
	v_lshl_add_u64 v[214:215], s[20:21], 0, v[134:135]
	s_barrier
	ds_read_b128 v[164:167], v147 offset:16384
	ds_read_b128 v[168:171], v147 offset:17408
	ds_read_b128 v[172:175], v147 offset:18432
	ds_read_b128 v[176:179], v147 offset:19456
	ds_read_b128 v[180:183], v147 offset:20480
	ds_read_b128 v[184:187], v147 offset:21504
	ds_read_b128 v[188:191], v147 offset:22528
	ds_read_b128 v[192:195], v147 offset:23552
	global_load_lds_dwordx4 v[214:215], off
	v_lshl_add_u64 v[216:217], s[20:21], 0, v[132:133]
	s_mov_b32 m0, s27
	s_nop 0
	global_load_lds_dwordx4 v[216:217], off
	s_barrier
	s_waitcnt lgkmcnt(0)
	s_setprio 1
	s_waitcnt lgkmcnt(0)
	v_mfma_f32_16x16x32_bf16 v[62:65], v[140:143], v[164:167], v[62:65]
	v_mfma_f32_16x16x32_bf16 v[58:61], v[156:159], v[164:167], v[58:61]
	v_mfma_f32_16x16x32_bf16 v[54:57], v[140:143], v[172:175], v[54:57]
	v_mfma_f32_16x16x32_bf16 v[46:49], v[156:159], v[172:175], v[46:49]
	v_mfma_f32_16x16x32_bf16 v[38:41], v[140:143], v[180:183], v[38:41]
	v_mfma_f32_16x16x32_bf16 v[28:31], v[156:159], v[180:183], v[28:31]
	v_mfma_f32_16x16x32_bf16 v[20:23], v[140:143], v[188:191], v[20:23]
	v_mfma_f32_16x16x32_bf16 v[12:15], v[156:159], v[188:191], v[12:15]
	v_mfma_f32_16x16x32_bf16 v[62:65], v[148:151], v[168:171], v[62:65]
	v_mfma_f32_16x16x32_bf16 v[58:61], v[160:163], v[168:171], v[58:61]
	v_mfma_f32_16x16x32_bf16 v[54:57], v[148:151], v[176:179], v[54:57]
	v_mfma_f32_16x16x32_bf16 v[46:49], v[160:163], v[176:179], v[46:49]
	v_mfma_f32_16x16x32_bf16 v[38:41], v[148:151], v[184:187], v[38:41]
	v_mfma_f32_16x16x32_bf16 v[28:31], v[160:163], v[184:187], v[28:31]
	v_mfma_f32_16x16x32_bf16 v[20:23], v[148:151], v[192:195], v[20:23]
	v_mfma_f32_16x16x32_bf16 v[12:15], v[160:163], v[192:195], v[12:15]
	s_setprio 0
	s_barrier
	s_add_u32 s56, s2, 0x80000
	s_addc_u32 s57, s3, 0
	s_add_i32 s58, s58, s23
	v_lshl_add_u64 v[140:141], s[56:57], 0, v[32:33]
	s_mov_b32 m0, s58
	s_nop 0
	global_load_lds_dwordx4 v[140:141], off
	v_lshl_add_u64 v[140:141], s[56:57], 0, v[130:131]
	s_add_i32 m0, s58, 0x2000
	s_nop 0
	global_load_lds_dwordx4 v[140:141], off
	s_waitcnt vmcnt(6)
	s_barrier
	s_setprio 1
	v_mfma_f32_16x16x32_bf16 v[50:53], v[196:199], v[164:167], v[50:53]
	v_mfma_f32_16x16x32_bf16 v[42:45], v[204:207], v[164:167], v[42:45]
	v_mfma_f32_16x16x32_bf16 v[34:37], v[196:199], v[172:175], v[34:37]
	v_mfma_f32_16x16x32_bf16 v[24:27], v[204:207], v[172:175], v[24:27]
	v_mfma_f32_16x16x32_bf16 v[16:19], v[196:199], v[180:183], v[16:19]
	v_mfma_f32_16x16x32_bf16 v[8:11], v[204:207], v[180:183], v[8:11]
	v_mfma_f32_16x16x32_bf16 v[4:7], v[196:199], v[188:191], v[4:7]
	v_mfma_f32_16x16x32_bf16 v[0:3], v[204:207], v[188:191], v[0:3]
	v_mfma_f32_16x16x32_bf16 v[50:53], v[200:203], v[168:171], v[50:53]
	v_mfma_f32_16x16x32_bf16 v[42:45], v[208:211], v[168:171], v[42:45]
	v_mfma_f32_16x16x32_bf16 v[34:37], v[200:203], v[176:179], v[34:37]
	v_mfma_f32_16x16x32_bf16 v[24:27], v[208:211], v[176:179], v[24:27]
	v_mfma_f32_16x16x32_bf16 v[16:19], v[200:203], v[184:187], v[16:19]
	v_mfma_f32_16x16x32_bf16 v[8:11], v[208:211], v[184:187], v[8:11]
	v_mfma_f32_16x16x32_bf16 v[4:7], v[200:203], v[192:195], v[4:7]
	v_mfma_f32_16x16x32_bf16 v[0:3], v[208:211], v[192:195], v[0:3]
	s_setprio 0
	s_add_i32 s56, 16, 0x18000
	v_add_u32_e32 v155, s56, v145
	s_barrier
	ds_read_b128 v[140:143], v155
	ds_read_b128 v[148:151], v155 offset:1024
	ds_read_b128 v[156:159], v155 offset:2048
	ds_read_b128 v[160:163], v155 offset:3072
	s_add_u32 s20, s20, 0x80000
	s_addc_u32 s21, s21, 0
	s_mov_b32 m0, s28
	v_lshl_add_u64 v[196:197], s[20:21], 0, v[134:135]
	ds_read_b128 v[164:167], v147 offset:32768
	ds_read_b128 v[168:171], v147 offset:33792
	ds_read_b128 v[172:175], v147 offset:34816
	ds_read_b128 v[176:179], v147 offset:35840
	ds_read_b128 v[180:183], v147 offset:36864
	ds_read_b128 v[184:187], v147 offset:37888
	ds_read_b128 v[188:191], v147 offset:38912
	ds_read_b128 v[192:195], v147 offset:39936
	global_load_lds_dwordx4 v[196:197], off
	v_lshl_add_u64 v[196:197], s[20:21], 0, v[132:133]
	s_mov_b32 m0, s29
	s_nop 0
	global_load_lds_dwordx4 v[196:197], off
	s_waitcnt lgkmcnt(8)
	s_barrier
	s_waitcnt lgkmcnt(0)
	s_setprio 1
	s_waitcnt lgkmcnt(0)
	v_mfma_f32_16x16x32_bf16 v[126:129], v[140:143], v[164:167], v[126:129]
	v_mfma_f32_16x16x32_bf16 v[122:125], v[156:159], v[164:167], v[122:125]
	v_mfma_f32_16x16x32_bf16 v[118:121], v[140:143], v[172:175], v[118:121]
	v_mfma_f32_16x16x32_bf16 v[110:113], v[156:159], v[172:175], v[110:113]
	v_mfma_f32_16x16x32_bf16 v[102:105], v[140:143], v[180:183], v[102:105]
	v_mfma_f32_16x16x32_bf16 v[94:97], v[156:159], v[180:183], v[94:97]
	v_mfma_f32_16x16x32_bf16 v[86:89], v[140:143], v[188:191], v[86:89]
	v_mfma_f32_16x16x32_bf16 v[78:81], v[156:159], v[188:191], v[78:81]
	v_mfma_f32_16x16x32_bf16 v[126:129], v[148:151], v[168:171], v[126:129]
	v_mfma_f32_16x16x32_bf16 v[122:125], v[160:163], v[168:171], v[122:125]
	v_mfma_f32_16x16x32_bf16 v[118:121], v[148:151], v[176:179], v[118:121]
	v_mfma_f32_16x16x32_bf16 v[110:113], v[160:163], v[176:179], v[110:113]
	v_mfma_f32_16x16x32_bf16 v[102:105], v[148:151], v[184:187], v[102:105]
	v_mfma_f32_16x16x32_bf16 v[94:97], v[160:163], v[184:187], v[94:97]
	v_mfma_f32_16x16x32_bf16 v[86:89], v[148:151], v[192:195], v[86:89]
	v_mfma_f32_16x16x32_bf16 v[78:81], v[160:163], v[192:195], v[78:81]
	s_setprio 0
	s_barrier
	s_add_i32 s20, 16, 0x1c000
	s_add_i32 s21, s56, s23
	v_add_u32_e32 v155, s20, v145
	v_lshl_add_u64 v[152:153], v[152:153], 0, s[50:51]
	s_mov_b32 m0, s21
	ds_read_b128 v[196:199], v155
	ds_read_b128 v[200:203], v155 offset:1024
	ds_read_b128 v[204:207], v155 offset:2048
	ds_read_b128 v[208:211], v155 offset:3072
	global_load_lds_dwordx4 v[152:153], off
	v_lshl_add_u64 v[152:153], v[212:213], 0, s[50:51]
	s_add_i32 m0, s21, 0x2000
	s_nop 0
	global_load_lds_dwordx4 v[152:153], off
	s_barrier
	s_waitcnt lgkmcnt(0)
	s_setprio 1
	s_waitcnt lgkmcnt(0)
	v_mfma_f32_16x16x32_bf16 v[114:117], v[196:199], v[164:167], v[114:117]
	v_mfma_f32_16x16x32_bf16 v[106:109], v[204:207], v[164:167], v[106:109]
	v_mfma_f32_16x16x32_bf16 v[98:101], v[196:199], v[172:175], v[98:101]
	v_mfma_f32_16x16x32_bf16 v[90:93], v[204:207], v[172:175], v[90:93]
	v_mfma_f32_16x16x32_bf16 v[82:85], v[196:199], v[180:183], v[82:85]
	v_mfma_f32_16x16x32_bf16 v[74:77], v[204:207], v[180:183], v[74:77]
	v_mfma_f32_16x16x32_bf16 v[70:73], v[196:199], v[188:191], v[70:73]
	v_mfma_f32_16x16x32_bf16 v[66:69], v[204:207], v[188:191], v[66:69]
	v_mfma_f32_16x16x32_bf16 v[114:117], v[200:203], v[168:171], v[114:117]
	v_mfma_f32_16x16x32_bf16 v[106:109], v[208:211], v[168:171], v[106:109]
	v_mfma_f32_16x16x32_bf16 v[98:101], v[200:203], v[176:179], v[98:101]
	v_mfma_f32_16x16x32_bf16 v[90:93], v[208:211], v[176:179], v[90:93]
	v_mfma_f32_16x16x32_bf16 v[82:85], v[200:203], v[184:187], v[82:85]
	v_mfma_f32_16x16x32_bf16 v[74:77], v[208:211], v[184:187], v[74:77]
	v_mfma_f32_16x16x32_bf16 v[70:73], v[200:203], v[192:195], v[70:73]
	v_mfma_f32_16x16x32_bf16 v[66:69], v[208:211], v[192:195], v[66:69]
	s_setprio 0
	s_mov_b32 m0, s30
	v_lshl_add_u64 v[152:153], v[214:215], 0, s[50:51]
	s_barrier
	ds_read_b128 v[164:167], v147 offset:49152
	ds_read_b128 v[168:171], v147 offset:50176
	ds_read_b128 v[172:175], v147 offset:51200
	ds_read_b128 v[176:179], v147 offset:52224
	ds_read_b128 v[180:183], v147 offset:53248
	ds_read_b128 v[184:187], v147 offset:54272
	ds_read_b128 v[188:191], v147 offset:55296
	ds_read_b128 v[192:195], v147 offset:56320
	global_load_lds_dwordx4 v[152:153], off
	v_lshl_add_u64 v[152:153], v[216:217], 0, s[50:51]
	s_mov_b32 m0, s31
	s_nop 0
	global_load_lds_dwordx4 v[152:153], off
	s_barrier
	s_waitcnt lgkmcnt(0)
	s_setprio 1
	s_waitcnt lgkmcnt(0)
	v_mfma_f32_16x16x32_bf16 v[62:65], v[140:143], v[164:167], v[62:65]
	v_mfma_f32_16x16x32_bf16 v[58:61], v[156:159], v[164:167], v[58:61]
	v_mfma_f32_16x16x32_bf16 v[54:57], v[140:143], v[172:175], v[54:57]
	v_mfma_f32_16x16x32_bf16 v[46:49], v[156:159], v[172:175], v[46:49]
	v_mfma_f32_16x16x32_bf16 v[38:41], v[140:143], v[180:183], v[38:41]
	v_mfma_f32_16x16x32_bf16 v[28:31], v[156:159], v[180:183], v[28:31]
	v_mfma_f32_16x16x32_bf16 v[20:23], v[140:143], v[188:191], v[20:23]
	v_mfma_f32_16x16x32_bf16 v[12:15], v[156:159], v[188:191], v[12:15]
	v_mfma_f32_16x16x32_bf16 v[62:65], v[148:151], v[168:171], v[62:65]
	v_mfma_f32_16x16x32_bf16 v[58:61], v[160:163], v[168:171], v[58:61]
	v_mfma_f32_16x16x32_bf16 v[54:57], v[148:151], v[176:179], v[54:57]
	v_mfma_f32_16x16x32_bf16 v[46:49], v[160:163], v[176:179], v[46:49]
	v_mfma_f32_16x16x32_bf16 v[38:41], v[148:151], v[184:187], v[38:41]
	v_mfma_f32_16x16x32_bf16 v[28:31], v[160:163], v[184:187], v[28:31]
	v_mfma_f32_16x16x32_bf16 v[20:23], v[148:151], v[192:195], v[20:23]
	v_mfma_f32_16x16x32_bf16 v[12:15], v[160:163], v[192:195], v[12:15]
	s_setprio 0
	s_barrier
	s_add_u32 s2, s2, 0x80080
	s_addc_u32 s3, s3, 0
	s_add_i32 s20, s20, s23
	v_lshl_add_u64 v[140:141], s[2:3], 0, v[32:33]
	s_mov_b32 m0, s20
	s_nop 0
	global_load_lds_dwordx4 v[140:141], off
	v_lshl_add_u64 v[140:141], s[2:3], 0, v[130:131]
	s_add_i32 m0, s20, 0x2000
	s_nop 0
	global_load_lds_dwordx4 v[140:141], off
	s_waitcnt vmcnt(6)
	s_barrier
	s_setprio 1
	v_mfma_f32_16x16x32_bf16 v[50:53], v[196:199], v[164:167], v[50:53]
	v_mfma_f32_16x16x32_bf16 v[42:45], v[204:207], v[164:167], v[42:45]
	v_mfma_f32_16x16x32_bf16 v[34:37], v[196:199], v[172:175], v[34:37]
	v_mfma_f32_16x16x32_bf16 v[24:27], v[204:207], v[172:175], v[24:27]
	v_mfma_f32_16x16x32_bf16 v[16:19], v[196:199], v[180:183], v[16:19]
	v_mfma_f32_16x16x32_bf16 v[8:11], v[204:207], v[180:183], v[8:11]
	v_mfma_f32_16x16x32_bf16 v[4:7], v[196:199], v[188:191], v[4:7]
	v_mfma_f32_16x16x32_bf16 v[0:3], v[204:207], v[188:191], v[0:3]
	v_mfma_f32_16x16x32_bf16 v[50:53], v[200:203], v[168:171], v[50:53]
	v_mfma_f32_16x16x32_bf16 v[42:45], v[208:211], v[168:171], v[42:45]
	v_mfma_f32_16x16x32_bf16 v[34:37], v[200:203], v[176:179], v[34:37]
	v_mfma_f32_16x16x32_bf16 v[24:27], v[208:211], v[176:179], v[24:27]
	v_mfma_f32_16x16x32_bf16 v[16:19], v[200:203], v[184:187], v[16:19]
	v_mfma_f32_16x16x32_bf16 v[8:11], v[208:211], v[184:187], v[8:11]
	v_mfma_f32_16x16x32_bf16 v[4:7], v[200:203], v[192:195], v[4:7]
	v_mfma_f32_16x16x32_bf16 v[0:3], v[208:211], v[192:195], v[0:3]
	s_setprio 0
	s_add_i32 s47, s47, 2
	s_add_u32 s39, s39, 0x100
	s_addc_u32 s46, s46, 0
	s_add_u32 s18, s18, 0x100
	s_addc_u32 s19, s19, 0
	s_cmp_gt_u32 s47, 29
	s_barrier
	s_cbranch_scc0 .LBB0_1104
	v_lshl_add_u32 v150, s36, 8, v144
	v_lshl_or_b32 v142, s35, 8, v146
	v_ashrrev_i32_e32 v143, 31, v142
	v_mov_b64_e32 v[140:141], s[8:9]
	s_movk_i32 s11, 0x5800
	v_cvt_pk_bf16_f32 v70, v70, v71
	v_cvt_pk_bf16_f32 v71, v72, v73
	v_cvt_pk_bf16_f32 v72, v66, v67
	v_add_u32_e32 v66, 0x80, v150
	v_mad_i64_i32 v[148:149], s[2:3], v150, s11, v[140:141]
	v_lshlrev_b64 v[142:143], 1, v[142:143]
	v_cvt_pk_bf16_f32 v114, v114, v115
	v_cvt_pk_bf16_f32 v115, v116, v117
	v_cvt_pk_bf16_f32 v116, v106, v107
	v_or_b32_e32 v106, 16, v150
	v_mad_i64_i32 v[66:67], s[2:3], v66, s11, v[140:141]
	v_cvt_pk_bf16_f32 v50, v50, v51
	v_cvt_pk_bf16_f32 v51, v52, v53
	v_cvt_pk_bf16_f32 v52, v42, v43
	v_add_u32_e32 v42, 0x90, v150
	v_lshl_add_u64 v[148:149], v[148:149], 0, v[142:143]
	v_mad_i64_i32 v[106:107], s[2:3], v106, s11, v[140:141]
	v_cvt_pk_bf16_f32 v98, v98, v99
	v_cvt_pk_bf16_f32 v99, v100, v101
	v_cvt_pk_bf16_f32 v100, v90, v91
	v_or_b32_e32 v90, 32, v150
	v_lshl_add_u64 v[66:67], v[66:67], 0, v[142:143]
	v_mad_i64_i32 v[42:43], s[2:3], v42, s11, v[140:141]
	v_cvt_pk_bf16_f32 v34, v34, v35
	v_cvt_pk_bf16_f32 v35, v36, v37
	v_cvt_pk_bf16_f32 v36, v24, v25
	v_add_u32_e32 v24, 0xa0, v150
	v_cvt_pk_bf16_f32 v117, v108, v109
	global_store_dwordx4 v[148:149], v[114:117], off offset:256
	v_mad_i64_i32 v[90:91], s[2:3], v90, s11, v[140:141]
	s_nop 0
	v_lshl_add_u64 v[114:115], v[106:107], 0, v[142:143]
	v_cvt_pk_bf16_f32 v82, v82, v83
	v_cvt_pk_bf16_f32 v83, v84, v85
	v_cvt_pk_bf16_f32 v84, v74, v75
	v_or_b32_e32 v74, 48, v150
	v_cvt_pk_bf16_f32 v53, v44, v45
	global_store_dwordx4 v[66:67], v[50:53], off offset:256
	v_mad_i64_i32 v[24:25], s[2:3], v24, s11, v[140:141]
	s_nop 0
	v_lshl_add_u64 v[50:51], v[42:43], 0, v[142:143]
	v_cvt_pk_bf16_f32 v16, v16, v17
	v_cvt_pk_bf16_f32 v17, v18, v19
	v_cvt_pk_bf16_f32 v18, v8, v9
	v_add_u32_e32 v8, 0xb0, v150
	v_cvt_pk_bf16_f32 v101, v92, v93
	global_store_dwordx4 v[114:115], v[98:101], off offset:256
	v_mad_i64_i32 v[74:75], s[2:3], v74, s11, v[140:141]
	s_nop 0
	v_lshl_add_u64 v[98:99], v[90:91], 0, v[142:143]
	v_cvt_pk_bf16_f32 v37, v26, v27
	global_store_dwordx4 v[50:51], v[34:37], off offset:256
	v_mad_i64_i32 v[8:9], s[2:3], v8, s11, v[140:141]
	s_nop 0
	v_lshl_add_u64 v[34:35], v[24:25], 0, v[142:143]
	v_cvt_pk_bf16_f32 v85, v76, v77
	global_store_dwordx4 v[98:99], v[82:85], off offset:256
	v_cvt_pk_bf16_f32 v19, v10, v11
	global_store_dwordx4 v[34:35], v[16:19], off offset:256
	s_and_b64 vcc, exec, s[4:5]
	v_lshl_add_u64 v[82:83], v[74:75], 0, v[142:143]
	v_lshl_add_u64 v[16:17], v[8:9], 0, v[142:143]
	s_mov_b32 s35, s10
	s_mov_b32 s36, s12
	s_mov_b64 s[18:19], s[16:17]
	s_mov_b64 s[20:21], s[14:15]
	v_cvt_pk_bf16_f32 v126, v126, v127
	v_cvt_pk_bf16_f32 v127, v128, v129
	v_cvt_pk_bf16_f32 v128, v122, v123
	v_cvt_pk_bf16_f32 v129, v124, v125
	global_store_dwordx4 v[148:149], v[126:129], off
	v_cvt_pk_bf16_f32 v106, v118, v119
	v_cvt_pk_bf16_f32 v107, v120, v121
	v_cvt_pk_bf16_f32 v108, v110, v111
	v_cvt_pk_bf16_f32 v109, v112, v113
	global_store_dwordx4 v[114:115], v[106:109], off
	v_cvt_pk_bf16_f32 v90, v102, v103
	v_cvt_pk_bf16_f32 v91, v104, v105
	v_cvt_pk_bf16_f32 v92, v94, v95
	v_cvt_pk_bf16_f32 v93, v96, v97
	global_store_dwordx4 v[98:99], v[90:93], off
	v_cvt_pk_bf16_f32 v74, v86, v87
	v_cvt_pk_bf16_f32 v75, v88, v89
	v_cvt_pk_bf16_f32 v76, v78, v79
	v_cvt_pk_bf16_f32 v77, v80, v81
	global_store_dwordx4 v[82:83], v[74:77], off
	v_cvt_pk_bf16_f32 v73, v68, v69
	global_store_dwordx4 v[82:83], v[70:73], off offset:256
	v_cvt_pk_bf16_f32 v62, v62, v63
	v_cvt_pk_bf16_f32 v63, v64, v65
	v_cvt_pk_bf16_f32 v64, v58, v59
	v_cvt_pk_bf16_f32 v65, v60, v61
	global_store_dwordx4 v[66:67], v[62:65], off
	v_cvt_pk_bf16_f32 v42, v54, v55
	v_cvt_pk_bf16_f32 v43, v56, v57
	v_cvt_pk_bf16_f32 v44, v46, v47
	v_cvt_pk_bf16_f32 v45, v48, v49
	global_store_dwordx4 v[50:51], v[42:45], off
	v_cvt_pk_bf16_f32 v24, v38, v39
	v_cvt_pk_bf16_f32 v25, v40, v41
	v_cvt_pk_bf16_f32 v26, v28, v29
	v_cvt_pk_bf16_f32 v27, v30, v31
	global_store_dwordx4 v[34:35], v[24:27], off
	v_cvt_pk_bf16_f32 v8, v20, v21
	v_cvt_pk_bf16_f32 v9, v22, v23
	v_cvt_pk_bf16_f32 v10, v12, v13
	v_cvt_pk_bf16_f32 v11, v14, v15
	global_store_dwordx4 v[16:17], v[8:11], off
	v_cvt_pk_bf16_f32 v4, v4, v5
	v_cvt_pk_bf16_f32 v5, v6, v7
	v_cvt_pk_bf16_f32 v6, v0, v1
	v_cvt_pk_bf16_f32 v7, v2, v3
	global_store_dwordx4 v[16:17], v[4:7], off offset:256
	s_cbranch_vccz .LBB0_1101
	s_waitcnt vmcnt(0)
	s_cmpk_gt_u32 s22, 0xff
	s_cbranch_scc1 .LBB0_1108
	s_barrier

.LBB0_1160:
	s_movk_i32 s0, 0x1fff
	v_cmp_lt_i32_e32 vcc, s0, v116
	s_and_saveexec_b64 s[0:1], vcc
	s_xor_b64 s[0:1], exec, s[0:1]
	v_bfe_u32 v0, v116, 6, 6
	v_and_b32_e32 v200, 63, v116
	v_cmp_ne_u32_e64 s[10:11], 0, v0
	v_cmp_ne_u32_e64 s[12:13], 63, v0
	s_or_saveexec_b64 s[0:1], s[0:1]
	v_mov_b32_e32 v136, 64
	s_xor_b64 exec, exec, s[0:1]
	v_and_b32_e32 v200, 0xff, v116
	v_mov_b32_e32 v136, 0x100
	s_andn2_b64 s[12:13], s[12:13], exec
	s_andn2_b64 s[10:11], s[10:11], exec
	s_or_b64 exec, exec, s[0:1]
	v_ashrrev_i32_e32 v101, 31, v100
	v_lshl_add_u64 v[34:35], v[100:101], 2, s[8:9]
	s_mov_b64 s[0:1], 0x5800
	v_lshl_add_u64 v[12:13], v[34:35], 0, s[0:1]
	v_add_co_u32_e32 v8, vcc, 0x5000, v34
	s_mov_b64 s[0:1], 0xb000
	s_nop 0
	v_addc_co_u32_e32 v9, vcc, 0, v35, vcc
	v_lshl_add_u64 v[20:21], v[34:35], 0, s[0:1]
	s_mov_b32 s0, 0xb000
	v_add_co_u32_e32 v16, vcc, s0, v34
	s_mov_b64 s[0:1], 0x10800
	s_nop 0
	v_addc_co_u32_e32 v17, vcc, 0, v35, vcc
	v_lshl_add_u64 v[28:29], v[34:35], 0, s[0:1]
	s_mov_b32 s0, 0x10000
	v_add_co_u32_e32 v24, vcc, s0, v34
	s_mov_b64 s[0:1], 0x16000
	s_nop 0
	v_addc_co_u32_e32 v25, vcc, 0, v35, vcc
	v_lshl_add_u64 v[40:41], v[34:35], 0, s[0:1]
	s_mov_b32 s0, 0x16000
	v_add_co_u32_e32 v36, vcc, s0, v34
	s_mov_b64 s[0:1], 0x1b800
	s_nop 0
	v_addc_co_u32_e32 v37, vcc, 0, v35, vcc
	v_lshl_add_u64 v[48:49], v[34:35], 0, s[0:1]
	s_mov_b32 s0, 0x1b000
	v_add_co_u32_e32 v44, vcc, s0, v34
	s_mov_b64 s[0:1], 0x21000
	s_nop 0
	v_addc_co_u32_e32 v45, vcc, 0, v35, vcc
	v_lshl_add_u64 v[56:57], v[34:35], 0, s[0:1]
	s_mov_b32 s0, 0x21000
	v_add_co_u32_e32 v52, vcc, s0, v34
	s_mov_b64 s[0:1], 0x26800
	s_nop 0
	v_addc_co_u32_e32 v53, vcc, 0, v35, vcc
	v_lshl_add_u64 v[64:65], v[34:35], 0, s[0:1]
	s_mov_b32 s0, 0x26000
	v_add_co_u32_e32 v60, vcc, s0, v34
	s_mov_b64 s[0:1], 0x2c000
	s_nop 0
	v_addc_co_u32_e32 v61, vcc, 0, v35, vcc
	global_load_dwordx4 v[0:3], v[34:35], off offset:16
	global_load_dwordx4 v[4:7], v[34:35], off
	v_lshl_add_u64 v[72:73], v[34:35], 0, s[0:1]
	v_add_co_u32_e32 v34, vcc, 0x2c000, v34
	global_load_dwordx4 v[8:11], v[8:9], off offset:2048
	s_nop 0
	global_load_dwordx4 v[12:15], v[12:13], off offset:16
	v_addc_co_u32_e32 v35, vcc, 0, v35, vcc
	global_load_dwordx4 v[16:19], v[16:17], off
	s_nop 0
	global_load_dwordx4 v[20:23], v[20:21], off offset:16
	s_nop 0
	global_load_dwordx4 v[24:27], v[24:25], off offset:2048
	s_nop 0
	global_load_dwordx4 v[28:31], v[28:29], off offset:16
	s_nop 0
	global_load_dwordx4 v[36:39], v[36:37], off
	s_nop 0
	global_load_dwordx4 v[40:43], v[40:41], off offset:16
	s_nop 0
	global_load_dwordx4 v[44:47], v[44:45], off offset:2048
	s_nop 0
	global_load_dwordx4 v[48:51], v[48:49], off offset:16
	s_nop 0
	global_load_dwordx4 v[52:55], v[52:53], off
	s_nop 0
	global_load_dwordx4 v[56:59], v[56:57], off offset:16
	s_nop 0
	global_load_dwordx4 v[60:63], v[60:61], off offset:2048
	s_nop 0
	global_load_dwordx4 v[64:67], v[64:65], off offset:16
	s_nop 0
	global_load_dwordx4 v[68:71], v[34:35], off
	s_nop 0
	global_load_dwordx4 v[72:75], v[72:73], off offset:16
	v_ashrrev_i32_e32 v117, 31, v116
	v_cmp_ne_u32_e32 vcc, 0, v200
	v_lshl_add_u64 v[34:35], v[116:117], 0, -1
	s_and_b64 s[0:1], s[10:11], vcc
	v_mov_b32_e32 v138, 0
	v_mov_b32_e32 v208, 0
	v_mov_b32_e32 v207, 0
	v_mov_b32_e32 v206, 0
	v_mov_b32_e32 v205, 0
	v_mov_b32_e32 v204, 0
	v_mov_b32_e32 v203, 0
	v_mov_b32_e32 v202, 0
	v_mov_b32_e32 v201, 0
	s_and_saveexec_b64 s[2:3], s[0:1]
	s_cbranch_execz .LBB0_1166
	v_sub_co_u32_e64 v32, s[0:1], v34, v136
	v_mov_b64_e32 v[88:89], s[6:7]
	s_movk_i32 s14, 0x5800
	v_subbrev_co_u32_e64 v90, s[0:1], 0, v35, s[0:1]
	v_mad_u64_u32 v[88:89], s[0:1], v32, s14, v[88:89]
	v_mad_i32_i24 v89, v90, s14, v89
	v_lshl_add_u64 v[88:89], v[100:101], 1, v[88:89]
	global_load_dwordx4 v[88:91], v[88:89], off
	s_waitcnt vmcnt(0) lgkmcnt(0)
	v_lshlrev_b32_e32 v208, 16, v88
	v_and_b32_e32 v207, 0xffff0000, v88
	v_lshlrev_b32_e32 v206, 16, v89
	v_and_b32_e32 v205, 0xffff0000, v89
	v_lshlrev_b32_e32 v204, 16, v90
	v_and_b32_e32 v203, 0xffff0000, v90
	v_lshlrev_b32_e32 v202, 16, v91
	v_and_b32_e32 v201, 0xffff0000, v91
.LBB0_1166:
	s_or_b64 exec, exec, s[2:3]
	v_mov_b32_e32 v140, 0
	v_mov_b32_e32 v142, 0
	v_mov_b32_e32 v144, 0
	v_mov_b32_e32 v146, 0
	v_mov_b32_e32 v148, 0
	v_mov_b32_e32 v150, 0
	v_mov_b32_e32 v152, 0
	s_and_saveexec_b64 s[0:1], vcc
	s_cbranch_execz .LBB0_1168
	v_mov_b64_e32 v[88:89], s[6:7]
	s_movk_i32 s14, 0x5800
	v_mad_u64_u32 v[88:89], s[2:3], v34, s14, v[88:89]
	v_mad_i32_i24 v89, v35, s14, v89
	v_lshl_add_u64 v[88:89], v[100:101], 1, v[88:89]
	global_load_dwordx4 v[88:91], v[88:89], off
	s_waitcnt vmcnt(0) lgkmcnt(0)
	v_lshlrev_b32_e32 v138, 16, v88
	v_and_b32_e32 v140, 0xffff0000, v88
	v_lshlrev_b32_e32 v142, 16, v89
	v_and_b32_e32 v144, 0xffff0000, v89
	v_lshlrev_b32_e32 v146, 16, v90
	v_and_b32_e32 v148, 0xffff0000, v90
	v_lshlrev_b32_e32 v150, 16, v91
	v_and_b32_e32 v152, 0xffff0000, v91
.LBB0_1168:
	s_or_b64 exec, exec, s[0:1]
	s_and_b64 s[2:3], s[12:13], vcc
	v_mov_b32_e32 v161, 0
	v_mov_b32_e32 v139, 0
	v_mov_b32_e32 v141, 0
	v_mov_b32_e32 v143, 0
	v_mov_b32_e32 v145, 0
	v_mov_b32_e32 v147, 0
	v_mov_b32_e32 v149, 0
	v_mov_b32_e32 v151, 0
	v_mov_b32_e32 v153, 0
	s_and_saveexec_b64 s[0:1], s[2:3]
	s_cbranch_execz .LBB0_1170
	v_mov_b32_e32 v137, v33
	v_lshl_add_u64 v[34:35], v[34:35], 0, v[136:137]
	v_mov_b64_e32 v[88:89], s[6:7]
	s_movk_i32 s14, 0x5800
	v_mad_u64_u32 v[88:89], s[2:3], v34, s14, v[88:89]
	v_mad_i32_i24 v89, v35, s14, v89
	v_lshl_add_u64 v[34:35], v[100:101], 1, v[88:89]
	global_load_dwordx4 v[88:91], v[34:35], off
	s_waitcnt vmcnt(0) lgkmcnt(0)
	v_lshlrev_b32_e32 v139, 16, v88
	v_and_b32_e32 v141, 0xffff0000, v88
	v_lshlrev_b32_e32 v143, 16, v89
	v_and_b32_e32 v145, 0xffff0000, v89
	v_lshlrev_b32_e32 v147, 16, v90
	v_and_b32_e32 v149, 0xffff0000, v90
	v_lshlrev_b32_e32 v151, 16, v91
	v_and_b32_e32 v153, 0xffff0000, v91
.LBB0_1170:
	s_or_b64 exec, exec, s[0:1]
	v_mov_b32_e32 v163, 0
	v_mov_b32_e32 v165, 0
	v_mov_b32_e32 v167, 0
	v_mov_b32_e32 v169, 0
	v_mov_b32_e32 v171, 0
	v_mov_b32_e32 v173, 0
	v_mov_b32_e32 v175, 0
	s_and_saveexec_b64 s[0:1], s[10:11]
	s_cbranch_execz .LBB0_1172
	v_sub_co_u32_e32 v32, vcc, v116, v136
	v_mov_b64_e32 v[34:35], s[6:7]
	s_movk_i32 s14, 0x5800
	v_subbrev_co_u32_e32 v88, vcc, 0, v117, vcc
	v_mad_u64_u32 v[34:35], s[2:3], v32, s14, v[34:35]
	v_mad_i32_i24 v35, v88, s14, v35
	v_lshl_add_u64 v[34:35], v[100:101], 1, v[34:35]
	global_load_dwordx4 v[88:91], v[34:35], off
	s_waitcnt vmcnt(0) lgkmcnt(0)
	v_lshlrev_b32_e32 v175, 16, v88
	v_and_b32_e32 v173, 0xffff0000, v88
	v_lshlrev_b32_e32 v171, 16, v89
	v_and_b32_e32 v169, 0xffff0000, v89
	v_lshlrev_b32_e32 v167, 16, v90
	v_and_b32_e32 v165, 0xffff0000, v90
	v_lshlrev_b32_e32 v163, 16, v91
	v_and_b32_e32 v161, 0xffff0000, v91
.LBB0_1172:
	s_or_b64 exec, exec, s[0:1]
	v_mov_b64_e32 v[34:35], s[6:7]
	s_movk_i32 s0, 0x5800
	v_mad_i64_i32 v[102:103], s[0:1], v116, s0, v[34:35]
	v_lshl_add_u64 v[92:93], v[100:101], 1, v[102:103]
	global_load_dwordx4 v[112:115], v[92:93], off
	v_mov_b32_e32 v177, 0
	v_mov_b32_e32 v179, 0
	v_mov_b32_e32 v183, 0
	v_mov_b32_e32 v181, 0
	v_mov_b32_e32 v187, 0
	v_mov_b32_e32 v185, 0
	v_mov_b32_e32 v191, 0
	v_mov_b32_e32 v189, 0
	s_and_saveexec_b64 s[0:1], s[12:13]
	s_cbranch_execz .LBB0_1174
	v_mov_b32_e32 v137, v33
	v_lshl_add_u64 v[34:35], v[136:137], 0, v[116:117]
	v_mov_b64_e32 v[88:89], s[6:7]
	s_movk_i32 s14, 0x5800
	v_mad_u64_u32 v[88:89], s[2:3], v34, s14, v[88:89]
	v_mad_i32_i24 v89, v35, s14, v89
	v_lshl_add_u64 v[34:35], v[100:101], 1, v[88:89]
	global_load_dwordx4 v[88:91], v[34:35], off
	s_waitcnt vmcnt(0) lgkmcnt(0)
	v_lshlrev_b32_e32 v189, 16, v88
	v_and_b32_e32 v191, 0xffff0000, v88
	v_lshlrev_b32_e32 v185, 16, v89
	v_and_b32_e32 v187, 0xffff0000, v89
	v_lshlrev_b32_e32 v181, 16, v90
	v_and_b32_e32 v183, 0xffff0000, v90
	v_lshlrev_b32_e32 v179, 16, v91
	v_and_b32_e32 v177, 0xffff0000, v91
.LBB0_1174:
	s_or_b64 exec, exec, s[0:1]
	v_add_u32_e32 v32, 1, v200
	v_mov_b32_e32 v34, v33
	v_mov_b32_e32 v35, v33
	v_cmp_lt_u32_e64 s[0:1], v32, v136
	v_mov_b32_e32 v32, v33
	v_mov_b64_e32 v[130:131], v[34:35]
	v_lshl_add_u64 v[88:89], v[116:117], 0, 1
	s_and_b64 s[14:15], s[10:11], s[0:1]
	v_mov_b64_e32 v[128:129], v[32:33]
	s_and_saveexec_b64 s[2:3], s[14:15]
	s_cbranch_execz .LBB0_1176
	v_sub_co_u32_e32 v94, vcc, v88, v136
	v_mov_b64_e32 v[90:91], s[6:7]
	s_movk_i32 s16, 0x5800
	v_subbrev_co_u32_e32 v95, vcc, 0, v89, vcc
	v_mad_u64_u32 v[90:91], s[14:15], v94, s16, v[90:91]
	v_mad_i32_i24 v91, v95, s16, v91
	v_lshl_add_u64 v[90:91], v[100:101], 1, v[90:91]
	global_load_dwordx4 v[128:131], v[90:91], off
.LBB0_1176:
	s_or_b64 exec, exec, s[2:3]
	v_mov_b64_e32 v[106:107], v[34:35]
	v_mov_b64_e32 v[104:105], v[32:33]
	s_and_saveexec_b64 s[2:3], s[0:1]
	s_cbranch_execz .LBB0_1178
	v_add_co_u32_e32 v34, vcc, 0x5000, v92
	s_nop 1
	v_addc_co_u32_e32 v35, vcc, 0, v93, vcc
	global_load_dwordx4 v[104:107], v[34:35], off offset:2048
.LBB0_1178:
	s_or_b64 exec, exec, s[2:3]
	v_mov_b32_e32 v34, v33
	v_mov_b32_e32 v35, v33
	v_mov_b32_e32 v32, v33
	v_mov_b64_e32 v[110:111], v[34:35]
	s_and_b64 s[2:3], s[12:13], s[0:1]
	v_mov_b64_e32 v[108:109], v[32:33]
	s_and_saveexec_b64 s[0:1], s[2:3]
	s_cbranch_execz .LBB0_1180
	v_mov_b32_e32 v137, v33
	v_lshl_add_u64 v[88:89], v[88:89], 0, v[136:137]
	v_mov_b64_e32 v[90:91], s[6:7]
	s_movk_i32 s14, 0x5800
	v_mad_u64_u32 v[90:91], s[2:3], v88, s14, v[90:91]
	v_mad_i32_i24 v91, v89, s14, v91
	v_lshl_add_u64 v[88:89], v[100:101], 1, v[90:91]
	global_load_dwordx4 v[108:111], v[88:89], off
.LBB0_1180:
	s_or_b64 exec, exec, s[0:1]
	v_add_u32_e32 v88, 2, v200
	v_cmp_lt_u32_e64 s[0:1], v88, v136
	v_mov_b64_e32 v[98:99], v[34:35]
	v_lshl_add_u64 v[118:119], v[116:117], 0, 2
	s_and_b64 s[14:15], s[10:11], s[0:1]
	v_mov_b64_e32 v[96:97], v[32:33]
	s_and_saveexec_b64 s[2:3], s[14:15]
	s_cbranch_execz .LBB0_1182
	v_sub_co_u32_e32 v32, vcc, v118, v136
	v_mov_b64_e32 v[34:35], s[6:7]
	s_movk_i32 s16, 0x5800
	v_subbrev_co_u32_e32 v88, vcc, 0, v119, vcc
	v_mad_u64_u32 v[34:35], s[14:15], v32, s16, v[34:35]
	v_mad_i32_i24 v35, v88, s16, v35
	v_lshl_add_u64 v[34:35], v[100:101], 1, v[34:35]
	global_load_dwordx4 v[96:99], v[34:35], off
.LBB0_1182:
	s_or_b64 exec, exec, s[2:3]
	v_mov_b32_e32 v34, v33
	v_mov_b32_e32 v35, v33
	v_mov_b32_e32 v32, v33
	v_mov_b64_e32 v[90:91], v[34:35]
	v_mov_b64_e32 v[88:89], v[32:33]
	s_and_saveexec_b64 s[2:3], s[0:1]
	s_cbranch_execz .LBB0_1184
	v_add_co_u32_e32 v88, vcc, 0xb000, v92
	s_nop 1
	v_addc_co_u32_e32 v89, vcc, 0, v93, vcc
	global_load_dwordx4 v[88:91], v[88:89], off
.LBB0_1184:
	s_or_b64 exec, exec, s[2:3]
	v_mov_b64_e32 v[94:95], v[34:35]
	s_and_b64 s[2:3], s[12:13], s[0:1]
	v_mov_b32_e32 v137, v33
	v_mov_b64_e32 v[92:93], v[32:33]
	s_and_saveexec_b64 s[0:1], s[2:3]
	s_cbranch_execz .LBB0_1186
	v_lshl_add_u64 v[34:35], v[118:119], 0, v[136:137]
	v_mov_b64_e32 v[92:93], s[6:7]
	s_movk_i32 s14, 0x5800
	v_mad_u64_u32 v[92:93], s[2:3], v34, s14, v[92:93]
	v_mad_i32_i24 v93, v35, s14, v93
	v_lshl_add_u64 v[34:35], v[100:101], 1, v[92:93]
	global_load_dwordx4 v[92:95], v[34:35], off
.LBB0_1186:
	s_or_b64 exec, exec, s[0:1]
	v_lshlrev_b64 v[34:35], 1, v[100:101]
	v_lshl_add_u64 v[100:101], v[102:103], 0, v[34:35]
	s_movk_i32 s2, 0x2000
	v_add_u32_e32 v32, 1, v116
	v_mov_b64_e32 v[102:103], s[6:7]
	s_movk_i32 s3, 0x5800
	v_add_co_u32_e32 v100, vcc, s2, v100
	v_mad_i64_i32 v[102:103], s[0:1], v32, s3, v[102:103]
	s_nop 0
	v_addc_co_u32_e32 v101, vcc, 0, v101, vcc
	v_lshl_add_u64 v[102:103], v[102:103], 0, v[34:35]
	v_add_co_u32_e32 v102, vcc, s2, v102
	s_waitcnt vmcnt(0) lgkmcnt(0)
	v_lshlrev_b32_e32 v180, 16, v114
	v_addc_co_u32_e32 v103, vcc, 0, v103, vcc
	global_load_dwordx4 v[132:135], v[100:101], off offset:3072
	s_nop 0
	global_load_dwordx4 v[100:103], v[102:103], off offset:3072
	v_and_b32_e32 v182, 0xffff0000, v114
	v_mov_b32_e32 v114, v45
	v_mov_b32_e32 v45, v47
	v_mov_b32_e32 v47, v49
	v_mad_i64_i32 v[118:119], s[0:1], v116, s3, 0
	v_lshlrev_b32_e32 v188, 16, v112
	v_and_b32_e32 v190, 0xffff0000, v112
	v_lshlrev_b32_e32 v184, 16, v113
	v_and_b32_e32 v186, 0xffff0000, v113
	v_lshlrev_b32_e32 v178, 16, v115
	v_and_b32_e32 v176, 0xffff0000, v115
	v_mov_b32_e32 v112, v25
	v_mov_b32_e32 v25, v27
	v_mov_b32_e32 v27, v29
	v_mov_b32_e32 v113, v37
	v_mov_b32_e32 v37, v39
	v_mov_b32_e32 v39, v41
	v_mov_b32_e32 v29, v43
	v_mov_b32_e32 v41, v51
	v_mov_b32_e32 v47, v70
	v_mov_b32_e32 v70, v45
	v_mov_b32_e32 v45, v68
	v_mov_b32_e32 v68, v114
	v_lshl_add_u64 v[114:115], v[116:117], 0, v[136:137]
	v_mov_b32_e32 v41, v64
	v_mov_b32_e32 v29, v56
	v_mov_b32_e32 v64, v39
	v_mov_b32_e32 v56, v27
	v_mov_b32_e32 v39, v62
	v_mov_b32_e32 v27, v54
	v_mov_b32_e32 v62, v37
	v_mov_b32_e32 v54, v25
	v_mov_b32_e32 v37, v60
	v_mov_b32_e32 v25, v52
	v_mov_b32_e32 v60, v113
	v_mov_b32_e32 v52, v112
	v_lshl_add_u64 v[112:113], v[118:119], 0, v[34:35]
	v_mad_u64_u32 v[34:35], s[0:1], v114, s3, v[34:35]
	v_mad_i32_i24 v35, v115, s3, v35
	v_mov_b32_e32 v32, v17
	v_mov_b32_e32 v17, v19
	v_mov_b32_e32 v19, v21
	v_mov_b32_e32 v21, v23
	v_mov_b32_e32 v23, v31
	v_lshl_add_u64 v[194:195], s[4:5], 0, v[34:35]
	v_mul_u32_u24_e32 v34, 0x5800, v136
	v_mov_b32_e32 v23, v14
	v_mov_b32_e32 v14, v21
	v_mov_b32_e32 v21, v12
	v_mov_b32_e32 v12, v19
	v_mov_b32_e32 v19, v10
	v_mov_b32_e32 v10, v17
	v_mov_b32_e32 v17, v8
	v_mov_b32_e32 v8, v32
	v_mul_hi_u32_u24_e32 v32, 0x5800, v136
	v_sub_co_u32_e32 v34, vcc, v112, v34
	s_movk_i32 s75, 0x2000
	s_nop 0
	v_subb_co_u32_e32 v35, vcc, v113, v32, vcc
	s_mov_b32 s19, 0
	v_swap_b32 v51, v74
	v_swap_b32 v43, v66
	v_swap_b32 v31, v58
	v_swap_b32 v49, v72
	v_lshl_add_u64 v[192:193], s[4:5], 0, v[112:113]
	v_lshl_add_u64 v[196:197], s[4:5], 0, v[34:35]
	s_mov_b64 s[14:15], 0
.LBB0_1187:
	s_cmp_lt_u32 s19, 14
	s_waitcnt vmcnt(0) lgkmcnt(0)
	v_mov_b64_e32 v[122:123], v[102:103]
	v_mov_b64_e32 v[118:119], v[82:83]
	v_mov_b64_e32 v[114:115], v[78:79]
	v_mov_b64_e32 v[126:127], v[86:87]
	s_cselect_b64 s[16:17], -1, 0
	s_cmp_gt_u32 s19, 13
	v_mov_b64_e32 v[120:121], v[100:101]
	v_mov_b64_e32 v[116:117], v[80:81]
	v_mov_b64_e32 v[112:113], v[76:77]
	v_mov_b64_e32 v[124:125], v[84:85]
	s_cbranch_scc1 .LBB0_1195
	v_add3_u32 v32, v200, s19, 3
	v_mov_b32_e32 v114, v33
	v_mov_b32_e32 v115, v33
	v_cmp_lt_u32_e64 s[0:1], v32, v136
	v_mov_b32_e32 v112, v33
	v_mov_b32_e32 v113, v33
	v_mov_b64_e32 v[118:119], v[114:115]
	s_and_b64 s[20:21], s[10:11], s[0:1]
	v_mov_b64_e32 v[116:117], v[112:113]
	s_and_saveexec_b64 s[2:3], s[20:21]
	s_cbranch_execz .LBB0_1190
	v_lshl_add_u64 v[34:35], v[196:197], 0, s[14:15]
	v_add_co_u32_e32 v34, vcc, 0xc410000, v34
	s_nop 1
	v_addc_co_u32_e32 v35, vcc, 0, v35, vcc
	global_load_dwordx4 v[116:119], v[34:35], off offset:2048
.LBB0_1190:
	s_or_b64 exec, exec, s[2:3]
	s_and_saveexec_b64 s[2:3], s[0:1]
	s_cbranch_execz .LBB0_1192
	v_lshl_add_u64 v[34:35], v[192:193], 0, s[14:15]
	v_add_co_u32_e32 v34, vcc, 0xc410000, v34
	s_nop 1
	v_addc_co_u32_e32 v35, vcc, 0, v35, vcc
	global_load_dwordx4 v[112:115], v[34:35], off offset:2048
.LBB0_1192:
	s_or_b64 exec, exec, s[2:3]
	v_mov_b32_e32 v34, v33
	v_mov_b32_e32 v35, v33
	v_mov_b32_e32 v32, v33
	v_mov_b64_e32 v[126:127], v[34:35]
	s_and_b64 s[2:3], s[12:13], s[0:1]
	v_mov_b64_e32 v[124:125], v[32:33]
	s_and_saveexec_b64 s[0:1], s[2:3]
	s_cbranch_execz .LBB0_1194
	v_lshl_add_u64 v[34:35], v[194:195], 0, s[14:15]
	v_add_co_u32_e32 v34, vcc, 0xc410000, v34
	s_nop 1
	v_addc_co_u32_e32 v35, vcc, 0, v35, vcc
	global_load_dwordx4 v[124:127], v[34:35], off offset:2048
.LBB0_1194:
	s_or_b64 exec, exec, s[0:1]
	v_lshl_add_u64 v[34:35], v[192:193], 0, s[14:15]
	v_add_co_u32_e32 v34, vcc, 0xc40d000, v34
	s_nop 1
	v_addc_co_u32_e32 v35, vcc, 0, v35, vcc
	global_load_dwordx4 v[120:123], v[34:35], off offset:3072
.LBB0_1195:
	v_lshlrev_b32_e32 v174, 16, v128
	v_pk_mul_f32 v[34:35], v[16:17], v[174:175]
	v_and_b32_e32 v172, 0xffff0000, v128
	v_fma_f32 v35, v4, v208, v35
	v_add_f32_e32 v34, v34, v35
	v_add_f32_e32 v81, 0, v34
	v_pk_mul_f32 v[34:35], v[24:25], v[138:139]
	v_lshlrev_b32_e32 v139, 16, v108
	v_lshlrev_b32_e32 v138, 16, v104
	v_pk_fma_f32 v[34:35], v[36:37], v[188:189], v[34:35]
	v_lshlrev_b32_e32 v170, 16, v129
	v_pk_fma_f32 v[34:35], v[44:45], v[138:139], v[34:35]
	v_lshlrev_b32_e32 v32, 16, v132
	v_add_f32_e32 v34, v81, v34
	v_add_f32_e32 v81, v34, v35
	v_mul_f32_e32 v34, 0xbfb8aa3b, v81
	v_exp_f32_e32 v82, v34
	v_pk_mul_f32 v[34:35], v[8:9], v[172:173]
	v_and_b32_e32 v168, 0xffff0000, v129
	v_fma_f32 v35, v5, v207, v35
	v_add_f32_e32 v34, v34, v35
	v_add_f32_e32 v83, 0, v34
	v_pk_mul_f32 v[34:35], v[52:53], v[140:141]
	v_and_b32_e32 v141, 0xffff0000, v108
	v_and_b32_e32 v140, 0xffff0000, v104
	v_pk_fma_f32 v[34:35], v[60:61], v[190:191], v[34:35]
	v_add_f32_e32 v82, 1.0, v82
	v_pk_fma_f32 v[34:35], v[68:69], v[140:141], v[34:35]
	v_rcp_f32_e32 v82, v82
	v_add_f32_e32 v34, v83, v34
	v_add_f32_e32 v34, v34, v35
	v_mul_f32_e32 v35, 0xbfb8aa3b, v34
	v_exp_f32_e32 v35, v35
	v_mul_f32_e32 v81, v81, v82
	v_mul_f32_e32 v32, v81, v32
	v_lshlrev_b32_e32 v166, 16, v130
	v_add_f32_e32 v35, 1.0, v35
	v_rcp_f32_e32 v35, v35
	v_and_b32_e32 v76, 0xffff0000, v132
	v_and_b32_e32 v164, 0xffff0000, v130
	v_lshlrev_b32_e32 v77, 16, v133
	v_mul_f32_e32 v81, v34, v35
	v_pk_mul_f32 v[34:35], v[18:19], v[170:171]
	v_mul_f32_e32 v76, v81, v76
	v_fma_f32 v35, v6, v206, v35
	v_add_f32_e32 v34, v34, v35
	v_add_f32_e32 v82, 0, v34
	v_pk_mul_f32 v[34:35], v[26:27], v[142:143]
	v_lshlrev_b32_e32 v143, 16, v109
	v_lshlrev_b32_e32 v142, 16, v105
	v_pk_fma_f32 v[34:35], v[38:39], v[184:185], v[34:35]
	v_lshlrev_b32_e32 v162, 16, v131
	v_pk_fma_f32 v[34:35], v[46:47], v[142:143], v[34:35]
	v_and_b32_e32 v78, 0xffff0000, v133
	v_add_f32_e32 v34, v82, v34
	v_add_f32_e32 v82, v34, v35
	v_mul_f32_e32 v34, 0xbfb8aa3b, v82
	v_exp_f32_e32 v85, v34
	v_pk_mul_f32 v[34:35], v[10:11], v[168:169]
	v_lshlrev_b32_e32 v79, 16, v134
	v_fma_f32 v35, v7, v205, v35
	v_add_f32_e32 v34, v34, v35
	v_add_f32_e32 v86, 0, v34
	v_pk_mul_f32 v[34:35], v[54:55], v[144:145]
	v_and_b32_e32 v145, 0xffff0000, v109
	v_and_b32_e32 v144, 0xffff0000, v105
	v_pk_fma_f32 v[34:35], v[62:63], v[186:187], v[34:35]
	v_and_b32_e32 v160, 0xffff0000, v131
	v_pk_fma_f32 v[34:35], v[70:71], v[144:145], v[34:35]
	v_and_b32_e32 v80, 0xffff0000, v134
	v_add_f32_e32 v34, v86, v34
	v_add_f32_e32 v86, v34, v35
	v_mul_f32_e32 v34, 0xbfb8aa3b, v86
	v_exp_f32_e32 v34, v34
	v_add_f32_e32 v35, 1.0, v85
	v_rcp_f32_e32 v81, v35
	v_and_b32_e32 v84, 0xffff0000, v135
	v_add_f32_e32 v34, 1.0, v34
	v_rcp_f32_e32 v85, v34
	v_pk_mul_f32 v[34:35], v[20:21], v[166:167]
	v_lshlrev_b32_e32 v83, 16, v135
	v_fma_f32 v35, v0, v204, v35
	v_add_f32_e32 v34, v34, v35
	v_add_f32_e32 v87, 0, v34
	v_pk_mul_f32 v[34:35], v[28:29], v[146:147]
	v_lshlrev_b32_e32 v147, 16, v110
	v_lshlrev_b32_e32 v146, 16, v106
	v_pk_fma_f32 v[34:35], v[40:41], v[180:181], v[34:35]
	v_lshl_add_u64 v[104:105], v[192:193], 0, s[14:15]
	v_pk_fma_f32 v[34:35], v[48:49], v[146:147], v[34:35]
	v_cvt_pk_bf16_f32 v76, v32, v76
	s_waitcnt vmcnt(0) lgkmcnt(0)
	v_mov_b64_e32 v[134:135], v[122:123]
	v_add_f32_e32 v34, v87, v34
	v_add_f32_e32 v87, v34, v35
	v_mul_f32_e32 v34, 0xbfb8aa3b, v87
	v_exp_f32_e32 v34, v34
	v_mul_f32_e32 v35, v82, v81
	v_mul_f32_e32 v77, v35, v77
	v_mul_f32_e32 v81, v86, v85
	v_add_f32_e32 v34, 1.0, v34
	v_rcp_f32_e32 v82, v34
	v_pk_mul_f32 v[34:35], v[12:13], v[164:165]
	v_mul_f32_e32 v78, v81, v78
	v_fma_f32 v35, v1, v203, v35
	v_add_f32_e32 v34, v34, v35
	v_add_f32_e32 v85, 0, v34
	v_pk_mul_f32 v[34:35], v[56:57], v[148:149]
	v_and_b32_e32 v149, 0xffff0000, v110
	v_and_b32_e32 v148, 0xffff0000, v106
	v_pk_fma_f32 v[34:35], v[64:65], v[182:183], v[34:35]
	v_cvt_pk_bf16_f32 v77, v77, v78
	v_mov_b64_e32 v[132:133], v[120:121]
	v_pk_fma_f32 v[34:35], v[72:73], v[148:149], v[34:35]
	s_nop 0
	v_add_f32_e32 v34, v85, v34
	v_add_f32_e32 v85, v34, v35
	v_mul_f32_e32 v34, 0xbfb8aa3b, v85
	v_exp_f32_e32 v34, v34
	v_mul_f32_e32 v35, v87, v82
	v_mul_f32_e32 v79, v35, v79
	v_add_f32_e32 v34, 1.0, v34
	v_rcp_f32_e32 v81, v34
	v_pk_mul_f32 v[34:35], v[22:23], v[162:163]
	v_mul_f32_e32 v81, v85, v81
	v_fma_f32 v35, v2, v202, v35
	v_add_f32_e32 v34, v34, v35
	v_add_f32_e32 v82, 0, v34
	v_pk_mul_f32 v[34:35], v[30:31], v[150:151]
	v_lshlrev_b32_e32 v151, 16, v111
	v_lshlrev_b32_e32 v150, 16, v107
	v_pk_fma_f32 v[34:35], v[42:43], v[178:179], v[34:35]
	v_mul_f32_e32 v80, v81, v80
	v_pk_fma_f32 v[34:35], v[50:51], v[150:151], v[34:35]
	v_cvt_pk_bf16_f32 v78, v79, v80
	s_nop 0
	v_add_f32_e32 v34, v82, v34
	v_add_f32_e32 v82, v34, v35
	v_mul_f32_e32 v34, 0xbfb8aa3b, v82
	v_exp_f32_e32 v86, v34
	v_pk_mul_f32 v[34:35], v[14:15], v[160:161]
	v_add_f32_e32 v85, 1.0, v86
	v_fma_f32 v35, v3, v201, v35
	v_add_f32_e32 v34, v34, v35
	v_add_f32_e32 v87, 0, v34
	v_pk_mul_f32 v[34:35], v[58:59], v[152:153]
	v_and_b32_e32 v153, 0xffff0000, v111
	v_and_b32_e32 v152, 0xffff0000, v107
	v_pk_fma_f32 v[34:35], v[66:67], v[176:177], v[34:35]
	v_rcp_f32_e32 v85, v85
	v_pk_fma_f32 v[34:35], v[74:75], v[152:153], v[34:35]
	v_mul_f32_e32 v81, v82, v85
	v_add_f32_e32 v34, v87, v34
	v_add_f32_e32 v34, v34, v35
	v_mul_f32_e32 v35, 0xbfb8aa3b, v34
	v_exp_f32_e32 v35, v35
	v_mul_f32_e32 v81, v81, v83
	v_add_f32_e32 v35, 1.0, v35
	v_rcp_f32_e32 v35, v35
	s_nop 0
	v_mul_f32_e32 v34, v34, v35
	v_mul_f32_e32 v34, v34, v84
	v_cvt_pk_bf16_f32 v79, v81, v34
	v_add_co_u32_e32 v34, vcc, 0xc402000, v104
	v_mov_b64_e32 v[80:81], v[116:117]
	s_nop 0
	v_addc_co_u32_e32 v35, vcc, 0, v105, vcc
	global_store_dwordx4 v[34:35], v[76:79], off offset:3072
	v_mov_b64_e32 v[84:85], v[124:125]
	s_andn2_b64 vcc, exec, s[16:17]
	v_mov_b64_e32 v[76:77], v[112:113]
	v_mov_b64_e32 v[82:83], v[118:119]
	v_mov_b64_e32 v[78:79], v[114:115]
	v_mov_b64_e32 v[86:87], v[126:127]
	s_cbranch_vccnz .LBB0_1203
	v_add3_u32 v32, v200, s19, 4
	v_mov_b32_e32 v78, v33
	v_mov_b32_e32 v79, v33
	v_cmp_lt_u32_e64 s[0:1], v32, v136
	v_mov_b32_e32 v76, v33
	v_mov_b32_e32 v77, v33
	v_mov_b64_e32 v[82:83], v[78:79]
	s_and_b64 s[16:17], s[10:11], s[0:1]
	v_mov_b64_e32 v[80:81], v[76:77]
	s_and_saveexec_b64 s[2:3], s[16:17]
	s_cbranch_execz .LBB0_1198
	v_lshl_add_u64 v[34:35], v[196:197], 0, s[14:15]
	v_add_co_u32_e32 v34, vcc, 0xc416000, v34
	s_nop 1
	v_addc_co_u32_e32 v35, vcc, 0, v35, vcc
	global_load_dwordx4 v[80:83], v[34:35], off
.LBB0_1198:
	s_or_b64 exec, exec, s[2:3]
	s_and_saveexec_b64 s[2:3], s[0:1]
	s_cbranch_execz .LBB0_1200
	v_add_co_u32_e32 v34, vcc, 0xc416000, v104
	s_nop 1
	v_addc_co_u32_e32 v35, vcc, 0, v105, vcc
	global_load_dwordx4 v[76:79], v[34:35], off
.LBB0_1200:
	s_or_b64 exec, exec, s[2:3]
	v_mov_b32_e32 v34, v33
	v_mov_b32_e32 v35, v33
	v_mov_b32_e32 v32, v33
	v_mov_b64_e32 v[86:87], v[34:35]
	s_and_b64 s[2:3], s[12:13], s[0:1]
	v_mov_b64_e32 v[84:85], v[32:33]
	s_and_saveexec_b64 s[0:1], s[2:3]
	s_cbranch_execz .LBB0_1202
	v_lshl_add_u64 v[34:35], v[194:195], 0, s[14:15]
	v_add_co_u32_e32 v34, vcc, 0xc416000, v34
	s_nop 1
	v_addc_co_u32_e32 v35, vcc, 0, v35, vcc
	global_load_dwordx4 v[84:87], v[34:35], off
.LBB0_1202:
	s_or_b64 exec, exec, s[0:1]
	v_add_co_u32_e32 v34, vcc, 0xc413000, v104
	s_nop 1
	v_addc_co_u32_e32 v35, vcc, 0, v105, vcc
	global_load_dwordx4 v[132:135], v[34:35], off offset:1024
.LBB0_1203:
	v_lshlrev_b32_e32 v34, 16, v96
	v_mov_b32_e32 v35, v174
	v_lshlrev_b32_e32 v128, 16, v99
	v_and_b32_e32 v130, 0xffff0000, v99
	v_lshlrev_b32_e32 v32, 16, v100
	v_and_b32_e32 v99, 0xffff0000, v100
	v_lshlrev_b32_e32 v129, 16, v101
	v_and_b32_e32 v131, 0xffff0000, v101
	v_pk_mul_f32 v[100:101], v[16:17], v[34:35]
	v_lshlrev_b32_e32 v106, 16, v97
	v_fma_f32 v35, v4, v175, v101
	v_add_f32_e32 v35, v100, v35
	v_pk_mul_f32 v[100:101], v[24:25], v[188:189]
	v_lshlrev_b32_e32 v189, 16, v92
	v_lshlrev_b32_e32 v188, 16, v88
	v_pk_fma_f32 v[100:101], v[36:37], v[138:139], v[100:101]
	v_add_f32_e32 v35, 0, v35
	v_pk_fma_f32 v[100:101], v[44:45], v[188:189], v[100:101]
	v_and_b32_e32 v108, 0xffff0000, v97
	v_add_f32_e32 v35, v35, v100
	v_add_f32_e32 v35, v35, v101
	v_mul_f32_e32 v97, 0xbfb8aa3b, v35
	v_and_b32_e32 v96, 0xffff0000, v96
	v_exp_f32_e32 v107, v97
	v_mov_b32_e32 v97, v172
	v_pk_mul_f32 v[100:101], v[8:9], v[96:97]
	v_mov_b32_e32 v109, v168
	v_fma_f32 v97, v5, v173, v101
	v_add_f32_e32 v97, v100, v97
	v_pk_mul_f32 v[100:101], v[52:53], v[190:191]
	v_and_b32_e32 v191, 0xffff0000, v92
	v_and_b32_e32 v190, 0xffff0000, v88
	v_pk_fma_f32 v[100:101], v[60:61], v[140:141], v[100:101]
	v_add_f32_e32 v97, 0, v97
	v_pk_fma_f32 v[100:101], v[68:69], v[190:191], v[100:101]
	v_lshlrev_b32_e32 v110, 16, v98
	v_add_f32_e32 v88, v97, v100
	v_add_f32_e32 v88, v88, v101
	v_mul_f32_e32 v92, 0xbfb8aa3b, v88
	v_exp_f32_e32 v92, v92
	v_add_f32_e32 v100, 1.0, v107
	v_rcp_f32_e32 v100, v100
	v_mov_b32_e32 v107, v170
	v_add_f32_e32 v92, 1.0, v92
	v_rcp_f32_e32 v92, v92
	v_mul_f32_e32 v35, v35, v100
	v_pk_mul_f32 v[100:101], v[18:19], v[106:107]
	v_mul_f32_e32 v32, v35, v32
	v_mul_f32_e32 v35, v88, v92
	v_fma_f32 v88, v6, v171, v101
	v_add_f32_e32 v88, v100, v88
	v_pk_mul_f32 v[100:101], v[26:27], v[184:185]
	v_lshlrev_b32_e32 v185, 16, v93
	v_lshlrev_b32_e32 v184, 16, v89
	v_pk_fma_f32 v[100:101], v[38:39], v[142:143], v[100:101]
	v_add_f32_e32 v88, 0, v88
	v_pk_fma_f32 v[100:101], v[46:47], v[184:185], v[100:101]
	v_mov_b32_e32 v111, v166
	v_add_f32_e32 v88, v88, v100
	v_add_f32_e32 v92, v88, v101
	v_mul_f32_e32 v88, 0xbfb8aa3b, v92
	v_pk_mul_f32 v[100:101], v[10:11], v[108:109]
	v_exp_f32_e32 v107, v88
	v_fma_f32 v88, v7, v169, v101
	v_add_f32_e32 v88, v100, v88
	v_pk_mul_f32 v[100:101], v[54:55], v[186:187]
	v_add_f32_e32 v109, 0, v88
	v_and_b32_e32 v187, 0xffff0000, v93
	v_and_b32_e32 v186, 0xffff0000, v89
	v_pk_fma_f32 v[88:89], v[62:63], v[144:145], v[100:101]
	v_mul_f32_e32 v35, v35, v99
	v_pk_fma_f32 v[88:89], v[70:71], v[186:187], v[88:89]
	v_and_b32_e32 v98, 0xffff0000, v98
	v_add_f32_e32 v88, v109, v88
	v_add_f32_e32 v93, v88, v89
	v_mul_f32_e32 v88, 0xbfb8aa3b, v93
	v_exp_f32_e32 v88, v88
	v_add_f32_e32 v89, 1.0, v107
	v_rcp_f32_e32 v99, v89
	v_lshlrev_b32_e32 v137, 16, v102
	v_add_f32_e32 v88, 1.0, v88
	v_rcp_f32_e32 v100, v88
	v_pk_mul_f32 v[88:89], v[20:21], v[110:111]
	s_add_i32 s19, s19, 2
	v_fma_f32 v89, v0, v167, v89
	v_add_f32_e32 v88, v88, v89
	v_add_f32_e32 v101, 0, v88
	v_pk_mul_f32 v[88:89], v[28:29], v[180:181]
	v_lshlrev_b32_e32 v181, 16, v94
	v_lshlrev_b32_e32 v180, 16, v90
	v_pk_fma_f32 v[88:89], v[40:41], v[146:147], v[88:89]
	v_mul_f32_e32 v93, v93, v100
	v_pk_fma_f32 v[88:89], v[48:49], v[180:181], v[88:89]
	v_mul_f32_e32 v93, v93, v131
	v_add_f32_e32 v88, v101, v88
	v_add_f32_e32 v101, v88, v89
	v_mul_f32_e32 v88, 0xbfb8aa3b, v101
	v_exp_f32_e32 v88, v88
	v_mul_f32_e32 v89, v92, v99
	v_mov_b32_e32 v99, v164
	v_mul_f32_e32 v92, v89, v129
	v_add_f32_e32 v88, 1.0, v88
	v_rcp_f32_e32 v100, v88
	v_pk_mul_f32 v[88:89], v[12:13], v[98:99]
	v_mov_b32_e32 v129, v162
	v_fma_f32 v89, v1, v165, v89
	v_add_f32_e32 v88, v88, v89
	v_add_f32_e32 v99, 0, v88
	v_pk_mul_f32 v[88:89], v[56:57], v[182:183]
	v_and_b32_e32 v183, 0xffff0000, v94
	v_and_b32_e32 v182, 0xffff0000, v90
	v_pk_fma_f32 v[88:89], v[64:65], v[148:149], v[88:89]
	v_mov_b32_e32 v131, v160
	v_pk_fma_f32 v[88:89], v[72:73], v[182:183], v[88:89]
	s_mov_b32 s0, 0xc408000
	v_add_f32_e32 v88, v99, v88
	v_add_f32_e32 v90, v88, v89
	v_mul_f32_e32 v88, 0xbfb8aa3b, v90
	v_exp_f32_e32 v88, v88
	v_mul_f32_e32 v89, v101, v100
	v_mul_f32_e32 v94, v89, v137
	s_add_u32 s14, s14, 0xb000
	v_add_f32_e32 v88, 1.0, v88
	v_rcp_f32_e32 v99, v88
	v_pk_mul_f32 v[88:89], v[22:23], v[128:129]
	v_and_b32_e32 v102, 0xffff0000, v102
	v_fma_f32 v89, v2, v163, v89
	v_add_f32_e32 v88, v88, v89
	v_add_f32_e32 v100, 0, v88
	v_pk_mul_f32 v[88:89], v[30:31], v[178:179]
	v_lshlrev_b32_e32 v179, 16, v95
	v_lshlrev_b32_e32 v178, 16, v91
	v_pk_fma_f32 v[88:89], v[42:43], v[150:151], v[88:89]
	v_lshlrev_b32_e32 v97, 16, v103
	v_pk_fma_f32 v[88:89], v[50:51], v[178:179], v[88:89]
	v_mul_f32_e32 v90, v90, v99
	v_add_f32_e32 v88, v100, v88
	v_add_f32_e32 v100, v88, v89
	v_mul_f32_e32 v88, 0xbfb8aa3b, v100
	v_exp_f32_e32 v101, v88
	v_pk_mul_f32 v[88:89], v[14:15], v[130:131]
	s_addc_u32 s15, s15, 0
	v_fma_f32 v89, v3, v161, v89
	v_add_f32_e32 v88, v88, v89
	v_add_f32_e32 v107, 0, v88
	v_pk_mul_f32 v[88:89], v[58:59], v[176:177]
	v_and_b32_e32 v177, 0xffff0000, v95
	v_and_b32_e32 v176, 0xffff0000, v91
	v_pk_fma_f32 v[88:89], v[66:67], v[152:153], v[88:89]
	v_add_f32_e32 v91, 1.0, v101
	v_pk_fma_f32 v[88:89], v[74:75], v[176:177], v[88:89]
	v_rcp_f32_e32 v91, v91
	v_add_f32_e32 v88, v107, v88
	v_add_f32_e32 v88, v88, v89
	v_mul_f32_e32 v89, 0xbfb8aa3b, v88
	v_exp_f32_e32 v89, v89
	v_mul_f32_e32 v91, v100, v91
	v_and_b32_e32 v103, 0xffff0000, v103
	v_mul_f32_e32 v90, v90, v102
	v_add_f32_e32 v89, 1.0, v89
	v_rcp_f32_e32 v89, v89
	v_mul_f32_e32 v91, v91, v97
	s_cmp_eq_u32 s14, 0x58000
	v_cvt_pk_bf16_f32 v90, v94, v90
	v_mul_f32_e32 v88, v88, v89
	v_cvt_pk_bf16_f32 v89, v92, v93
	v_add_co_u32_e32 v92, vcc, s0, v104
	v_mul_f32_e32 v95, v88, v103
	s_nop 0
	v_addc_co_u32_e32 v93, vcc, 0, v105, vcc
	v_cvt_pk_bf16_f32 v88, v32, v35
	v_cvt_pk_bf16_f32 v91, v91, v95
	global_store_dwordx4 v[92:93], v[88:91], off offset:1024
	s_cbranch_scc1 .LBB0_1155
	s_waitcnt vmcnt(0) lgkmcnt(0)
	v_mov_b64_e32 v[100:101], v[132:133]
	v_mov_b32_e32 v161, v130
	v_mov_b32_e32 v163, v128
	v_mov_b32_e32 v165, v98
	v_mov_b32_e32 v167, v110
	v_mov_b32_e32 v169, v108
	v_mov_b32_e32 v171, v106
	v_mov_b32_e32 v173, v96
	v_mov_b64_e32 v[108:109], v[124:125]
	v_mov_b64_e32 v[104:105], v[112:113]
	v_mov_b64_e32 v[130:131], v[118:119]
	v_mov_b64_e32 v[94:95], v[86:87]
	v_mov_b64_e32 v[90:91], v[78:79]
	v_mov_b64_e32 v[98:99], v[82:83]
	v_mov_b64_e32 v[102:103], v[134:135]
	v_mov_b64_e32 v[134:135], v[122:123]
	v_mov_b32_e32 v175, v34
	v_mov_b64_e32 v[110:111], v[126:127]
	v_mov_b64_e32 v[106:107], v[114:115]
	v_mov_b64_e32 v[128:129], v[116:117]
	v_mov_b64_e32 v[92:93], v[84:85]
	v_mov_b64_e32 v[88:89], v[76:77]
	v_mov_b64_e32 v[96:97], v[80:81]
	v_mov_b32_e32 v208, v174
	v_mov_b32_e32 v207, v172
	v_mov_b32_e32 v206, v170
	v_mov_b32_e32 v205, v168
	v_mov_b32_e32 v204, v166
	v_mov_b32_e32 v203, v164
	v_mov_b32_e32 v202, v162
	v_mov_b32_e32 v201, v160
	v_mov_b64_e32 v[132:133], v[120:121]
	s_branch .LBB0_1187

.LBB0_1253:
	v_lshl_or_b32 v140, s39, 8, v175
	s_lshl_b64 s[14:15], s[14:15], 2
	s_add_u32 s14, s30, s14
	v_ashrrev_i32_e32 v141, 31, v140
	s_addc_u32 s15, s31, s15
	v_lshlrev_b64 v[164:165], 2, v[140:141]
	v_lshl_add_u64 v[160:161], s[14:15], 0, v[164:165]
	v_lshl_add_u64 v[166:167], s[12:13], 0, v[164:165]
	global_load_dwordx4 v[142:145], v[160:161], off
	global_load_dwordx4 v[146:149], v[166:167], off
	v_lshl_add_u32 v162, s46, 8, v155
	v_ashrrev_i32_e32 v163, 31, v162
	v_lshl_add_u64 v[182:183], s[6:7], 0, v[164:165]
	v_lshlrev_b64 v[198:199], 13, v[162:163]
	v_lshl_add_u64 v[178:179], v[182:183], 0, v[198:199]
	v_or_b32_e32 v184, 16, v162
	v_ashrrev_i32_e32 v185, 31, v184
	v_lshlrev_b64 v[214:215], 13, v[184:185]
	v_lshl_add_u64 v[194:195], v[182:183], 0, v[214:215]
	v_lshl_add_u64 v[198:199], s[6:7], 0, v[198:199]
	v_lshl_add_u64 v[216:217], v[198:199], 0, v[164:165]
	v_or_b32_e32 v198, 32, v162
	v_ashrrev_i32_e32 v199, 31, v198
	v_lshlrev_b64 v[198:199], 13, v[198:199]
	v_lshl_add_u64 v[198:199], s[6:7], 0, v[198:199]
	v_lshl_add_u64 v[218:219], v[198:199], 0, v[164:165]
	s_mov_b64 s[14:15], 0x100000
	s_mov_b32 s39, s37
	s_mov_b32 s46, s38
	s_mov_b64 s[16:17], s[4:5]
	s_waitcnt vmcnt(0) lgkmcnt(0)
	v_pk_add_f32 v[140:141], v[144:145], v[148:149]
	v_pk_add_f32 v[142:143], v[142:143], v[146:147]
	global_load_dwordx4 v[146:149], v[160:161], off offset:64
	global_load_dwordx4 v[150:153], v[166:167], off offset:64
	s_waitcnt vmcnt(0) lgkmcnt(0)
	v_pk_add_f32 v[144:145], v[148:149], v[152:153]
	v_pk_add_f32 v[146:147], v[146:147], v[150:151]
	global_load_dwordx4 v[150:153], v[160:161], off offset:512
	global_load_dwordx4 v[156:159], v[166:167], off offset:512
	s_waitcnt vmcnt(0) lgkmcnt(0)
	v_pk_add_f32 v[148:149], v[152:153], v[158:159]
	v_pk_add_f32 v[150:151], v[150:151], v[156:157]
	global_load_dwordx4 v[156:159], v[160:161], off offset:576
	s_nop 0
	global_load_dwordx4 v[166:169], v[166:167], off offset:576
	s_waitcnt vmcnt(0) lgkmcnt(0)
	v_pk_add_f32 v[152:153], v[158:159], v[168:169]
	v_pk_add_f32 v[160:161], v[156:157], v[166:167]
	global_load_dwordx4 v[156:159], v[178:179], off
	global_load_dwordx4 v[166:169], v[178:179], off offset:64
	global_load_dwordx4 v[170:173], v[178:179], off offset:512
	s_nop 0
	global_load_dwordx4 v[178:181], v[178:179], off offset:576
	s_nop 0
	global_load_dwordx4 v[182:185], v[194:195], off
	global_load_dwordx4 v[186:189], v[194:195], off offset:64
	global_load_dwordx4 v[190:193], v[194:195], off offset:512
	s_nop 0
	global_load_dwordx4 v[194:197], v[194:195], off offset:576
	s_nop 0
	global_load_dwordx4 v[198:201], v[218:219], off
	global_load_dwordx4 v[202:205], v[218:219], off offset:64
	global_load_dwordx4 v[206:209], v[218:219], off offset:512
	global_load_dwordx4 v[210:213], v[218:219], off offset:576
	s_waitcnt vmcnt(0) lgkmcnt(0)
	v_pk_fma_f32 v[126:127], v[126:127], v[142:143], v[156:157]
	v_pk_fma_f32 v[128:129], v[128:129], v[140:141], v[158:159]
	v_pk_fma_f32 v[124:125], v[124:125], v[144:145], v[168:169]
	v_pk_fma_f32 v[116:117], v[116:117], v[152:153], v[180:181]
	v_pk_fma_f32 v[114:115], v[114:115], v[160:161], v[178:179]
	global_store_dwordx4 v[216:217], v[114:117], off offset:576
	v_pk_fma_f32 v[122:123], v[122:123], v[146:147], v[166:167]
	v_pk_fma_f32 v[120:121], v[120:121], v[148:149], v[172:173]
	v_lshl_add_u64 v[114:115], s[6:7], 0, v[214:215]
	v_lshl_add_u64 v[156:157], v[114:115], 0, v[164:165]
	v_or_b32_e32 v114, 48, v162
	v_ashrrev_i32_e32 v115, 31, v114
	v_lshlrev_b64 v[114:115], 13, v[114:115]
	v_pk_fma_f32 v[118:119], v[118:119], v[150:151], v[170:171]
	v_lshl_add_u64 v[114:115], s[6:7], 0, v[114:115]
	global_store_dwordx4 v[216:217], v[126:129], off
	global_store_dwordx4 v[216:217], v[122:125], off offset:64
	global_store_dwordx4 v[216:217], v[118:121], off offset:512
	v_lshl_add_u64 v[172:173], v[114:115], 0, v[164:165]
	global_load_dwordx4 v[126:129], v[172:173], off
	global_load_dwordx4 v[122:125], v[172:173], off offset:64
	global_load_dwordx4 v[118:121], v[172:173], off offset:512
	global_load_dwordx4 v[114:117], v[172:173], off offset:576
	v_lshl_add_u64 v[168:169], v[216:217], 0, s[14:15]
	s_mov_b32 s14, 0x100000
	v_pk_fma_f32 v[112:113], v[112:113], v[140:141], v[184:185]
	v_pk_fma_f32 v[110:111], v[110:111], v[142:143], v[182:183]
	v_pk_fma_f32 v[108:109], v[108:109], v[144:145], v[188:189]
	v_pk_fma_f32 v[106:107], v[106:107], v[146:147], v[186:187]
	v_pk_fma_f32 v[96:97], v[96:97], v[148:149], v[192:193]
	v_pk_fma_f32 v[94:95], v[94:95], v[150:151], v[190:191]
	v_pk_fma_f32 v[92:93], v[92:93], v[152:153], v[196:197]
	v_pk_fma_f32 v[90:91], v[90:91], v[160:161], v[194:195]
	v_add_co_u32_e32 v170, vcc, s14, v216
	global_store_dwordx4 v[156:157], v[110:113], off
	global_store_dwordx4 v[156:157], v[106:109], off offset:64
	global_store_dwordx4 v[156:157], v[94:97], off offset:512
	global_store_dwordx4 v[156:157], v[90:93], off offset:576
	v_addc_co_u32_e32 v171, vcc, 0, v217, vcc
	global_load_dwordx4 v[110:113], v[170:171], off
	global_load_dwordx4 v[106:109], v[168:169], off offset:64
	global_load_dwordx4 v[94:97], v[168:169], off offset:512
	global_load_dwordx4 v[90:93], v[168:169], off offset:576
	v_pk_fma_f32 v[84:85], v[84:85], v[152:153], v[212:213]
	v_pk_fma_f32 v[82:83], v[82:83], v[160:161], v[210:211]
	global_store_dwordx4 v[218:219], v[82:85], off offset:576
	v_pk_fma_f32 v[104:105], v[104:105], v[140:141], v[200:201]
	v_pk_fma_f32 v[102:103], v[102:103], v[142:143], v[198:199]
	v_add_u32_e32 v82, 0x90, v162
	v_ashrrev_i32_e32 v83, 31, v82
	v_lshlrev_b64 v[82:83], 13, v[82:83]
	v_pk_fma_f32 v[100:101], v[100:101], v[144:145], v[204:205]
	v_pk_fma_f32 v[98:99], v[98:99], v[146:147], v[202:203]
	v_pk_fma_f32 v[88:89], v[88:89], v[148:149], v[208:209]
	v_pk_fma_f32 v[86:87], v[86:87], v[150:151], v[206:207]
	v_lshl_add_u64 v[82:83], s[6:7], 0, v[82:83]
	global_store_dwordx4 v[218:219], v[102:105], off
	global_store_dwordx4 v[218:219], v[98:101], off offset:64
	global_store_dwordx4 v[218:219], v[86:89], off offset:512
	v_lshl_add_u64 v[166:167], v[82:83], 0, v[164:165]
	global_load_dwordx4 v[86:89], v[166:167], off
	global_load_dwordx4 v[82:85], v[166:167], off offset:64
	global_load_dwordx4 v[102:105], v[166:167], off offset:512
	global_load_dwordx4 v[98:101], v[166:167], off offset:576
	s_and_b64 vcc, exec, s[2:3]
	s_mov_b64 s[14:15], s[0:1]
	s_waitcnt vmcnt(0) lgkmcnt(0)
	v_pk_fma_f32 v[80:81], v[80:81], v[140:141], v[128:129]
	v_pk_fma_f32 v[78:79], v[78:79], v[142:143], v[126:127]
	v_pk_fma_f32 v[76:77], v[76:77], v[144:145], v[124:125]
	v_pk_fma_f32 v[68:69], v[68:69], v[152:153], v[116:117]
	v_pk_fma_f32 v[66:67], v[66:67], v[160:161], v[114:115]
	global_store_dwordx4 v[172:173], v[66:69], off offset:576
	v_pk_fma_f32 v[74:75], v[74:75], v[146:147], v[122:123]
	v_pk_fma_f32 v[72:73], v[72:73], v[148:149], v[120:121]
	v_add_u32_e32 v66, 0xa0, v162
	v_ashrrev_i32_e32 v67, 31, v66
	v_lshlrev_b64 v[66:67], 13, v[66:67]
	v_pk_fma_f32 v[70:71], v[70:71], v[150:151], v[118:119]
	v_lshl_add_u64 v[66:67], s[6:7], 0, v[66:67]
	global_store_dwordx4 v[172:173], v[78:81], off
	global_store_dwordx4 v[172:173], v[74:77], off offset:64
	global_store_dwordx4 v[172:173], v[70:73], off offset:512
	v_lshl_add_u64 v[114:115], v[66:67], 0, v[164:165]
	global_load_dwordx4 v[78:81], v[114:115], off
	global_load_dwordx4 v[74:77], v[114:115], off offset:64
	global_load_dwordx4 v[70:73], v[114:115], off offset:512
	global_load_dwordx4 v[66:69], v[114:115], off offset:576
	v_pk_fma_f32 v[64:65], v[64:65], v[140:141], v[112:113]
	v_pk_fma_f32 v[62:63], v[62:63], v[142:143], v[110:111]
	v_pk_fma_f32 v[60:61], v[60:61], v[144:145], v[108:109]
	v_pk_fma_f32 v[52:53], v[52:53], v[152:153], v[92:93]
	v_pk_fma_f32 v[50:51], v[50:51], v[160:161], v[90:91]
	global_store_dwordx4 v[168:169], v[50:53], off offset:576
	v_pk_fma_f32 v[58:59], v[58:59], v[146:147], v[106:107]
	v_pk_fma_f32 v[56:57], v[56:57], v[148:149], v[96:97]
	v_add_u32_e32 v50, 0xb0, v162
	v_ashrrev_i32_e32 v51, 31, v50
	v_lshlrev_b64 v[50:51], 13, v[50:51]
	v_pk_fma_f32 v[54:55], v[54:55], v[150:151], v[94:95]
	v_lshl_add_u64 v[50:51], s[6:7], 0, v[50:51]
	global_store_dwordx4 v[170:171], v[62:65], off
	global_store_dwordx4 v[168:169], v[58:61], off offset:64
	global_store_dwordx4 v[168:169], v[54:57], off offset:512
	v_lshl_add_u64 v[90:91], v[50:51], 0, v[164:165]
	global_load_dwordx4 v[62:65], v[90:91], off
	global_load_dwordx4 v[58:61], v[90:91], off offset:64
	global_load_dwordx4 v[54:57], v[90:91], off offset:512
	global_load_dwordx4 v[50:53], v[90:91], off offset:576
	v_pk_fma_f32 v[48:49], v[48:49], v[140:141], v[88:89]
	v_pk_fma_f32 v[46:47], v[46:47], v[142:143], v[86:87]
	v_pk_fma_f32 v[44:45], v[44:45], v[144:145], v[84:85]
	v_pk_fma_f32 v[26:27], v[26:27], v[152:153], v[100:101]
	v_pk_fma_f32 v[24:25], v[24:25], v[160:161], v[98:99]
	global_store_dwordx4 v[166:167], v[24:27], off offset:576
	v_pk_fma_f32 v[42:43], v[42:43], v[146:147], v[82:83]
	v_pk_fma_f32 v[36:37], v[36:37], v[148:149], v[104:105]
	v_pk_fma_f32 v[34:35], v[34:35], v[150:151], v[102:103]
	global_store_dwordx4 v[166:167], v[46:49], off
	global_store_dwordx4 v[166:167], v[42:45], off offset:64
	global_store_dwordx4 v[166:167], v[34:37], off offset:512
	s_waitcnt vmcnt(0) lgkmcnt(0)
	v_pk_fma_f32 v[26:27], v[40:41], v[140:141], v[80:81]
	v_pk_fma_f32 v[24:25], v[38:39], v[142:143], v[78:79]
	global_store_dwordx4 v[114:115], v[24:27], off
	v_pk_fma_f32 v[10:11], v[10:11], v[152:153], v[68:69]
	v_pk_fma_f32 v[8:9], v[8:9], v[160:161], v[66:67]
	global_store_dwordx4 v[114:115], v[8:11], off offset:576
	v_pk_fma_f32 v[26:27], v[30:31], v[144:145], v[76:77]
	v_pk_fma_f32 v[24:25], v[28:29], v[146:147], v[74:75]
	v_pk_fma_f32 v[18:19], v[18:19], v[148:149], v[72:73]
	v_pk_fma_f32 v[16:17], v[16:17], v[150:151], v[70:71]
	global_store_dwordx4 v[114:115], v[24:27], off offset:64
	global_store_dwordx4 v[114:115], v[16:19], off offset:512
	v_pk_fma_f32 v[10:11], v[22:23], v[140:141], v[64:65]
	v_pk_fma_f32 v[8:9], v[20:21], v[142:143], v[62:63]
	global_store_dwordx4 v[90:91], v[8:11], off
	v_pk_fma_f32 v[6:7], v[6:7], v[148:149], v[56:57]
	v_pk_fma_f32 v[4:5], v[4:5], v[150:151], v[54:55]
	v_pk_fma_f32 v[10:11], v[14:15], v[144:145], v[60:61]
	v_pk_fma_f32 v[8:9], v[12:13], v[146:147], v[58:59]
	v_pk_fma_f32 v[2:3], v[2:3], v[152:153], v[52:53]
	v_pk_fma_f32 v[0:1], v[0:1], v[160:161], v[50:51]
	global_store_dwordx4 v[90:91], v[8:11], off offset:64
	global_store_dwordx4 v[90:91], v[4:7], off offset:512
	global_store_dwordx4 v[90:91], v[0:3], off offset:576
	s_cbranch_vccnz .LBB0_1264

.LBB0_1312:
	global_load_dwordx4 v[44:47], v[34:35], off
	global_load_dwordx4 v[48:51], v[34:35], off offset:1024
	global_load_dwordx4 v[52:55], v[34:35], off offset:2048
	global_load_dwordx4 v[56:59], v[34:35], off offset:3072
	s_waitcnt vmcnt(0)
	v_add_co_u32_e32 v76, vcc, s6, v34
	v_add_u32_e32 v32, 1, v32
	s_nop 0
	v_addc_co_u32_e32 v77, vcc, 0, v35, vcc
	global_load_dwordx4 v[60:63], v[76:77], off
	global_load_dwordx4 v[64:67], v[76:77], off offset:1024
	global_load_dwordx4 v[68:71], v[76:77], off offset:2048
	global_load_dwordx4 v[72:75], v[76:77], off offset:3072
	v_cmp_ge_i32_e64 s[0:1], v32, v36
	s_or_b64 s[2:3], s[0:1], s[2:3]
	s_waitcnt lgkmcnt(0)
	v_pk_mul_f32 v[78:79], v[44:45], v[44:45]
	v_pk_mul_f32 v[82:83], v[48:49], v[48:49]
	v_pk_mul_f32 v[80:81], v[46:47], v[46:47]
	v_pk_mul_f32 v[84:85], v[50:51], v[50:51]
	v_pk_mul_f32 v[86:87], v[52:53], v[52:53]
	v_add_f32_e32 v43, v82, v83
	v_add_f32_e32 v110, v78, v79
	v_pk_mul_f32 v[88:89], v[54:55], v[54:55]
	v_pk_mul_f32 v[90:91], v[56:57], v[56:57]
	s_waitcnt vmcnt(0)
	v_mov_b32_e32 v96, v61
	v_mov_b32_e32 v97, v65
	v_add_f32_e32 v86, v86, v87
	v_add_f32_e32 v43, v43, v84
	v_add_f32_e32 v80, v110, v80
	v_pk_mul_f32 v[92:93], v[58:59], v[58:59]
	v_mov_b32_e32 v94, v60
	v_mov_b32_e32 v95, v64
	v_add_f32_e32 v87, v90, v91
	v_pk_mul_f32 v[78:79], v[96:97], v[96:97]
	v_add_f32_e32 v84, v86, v88
	v_add_f32_e32 v43, v43, v85
	v_add_f32_e32 v85, v80, v81
	v_mov_b32_e32 v98, v62
	v_mov_b32_e32 v99, v66
	v_mov_b32_e32 v104, v69
	v_mov_b32_e32 v105, v73
	v_add_f32_e32 v86, v87, v92
	v_pk_fma_f32 v[78:79], v[94:95], v[94:95], v[78:79]
	v_add_f32_e32 v84, v84, v89
	v_add_f32_e32 v43, v85, v43
	v_mov_b32_e32 v100, v63
	v_mov_b32_e32 v101, v67
	v_mov_b32_e32 v102, v68
	v_mov_b32_e32 v103, v72
	v_pk_mul_f32 v[82:83], v[104:105], v[104:105]
	v_add_f32_e32 v86, v86, v93
	v_pk_fma_f32 v[78:79], v[98:99], v[98:99], v[78:79]
	v_add_f32_e32 v43, v43, v84
	v_mov_b32_e32 v106, v70
	v_mov_b32_e32 v107, v74
	v_pk_fma_f32 v[82:83], v[102:103], v[102:103], v[82:83]
	v_pk_fma_f32 v[78:79], v[100:101], v[100:101], v[78:79]
	v_add_f32_e32 v43, v43, v86
	v_mov_b32_e32 v108, v71
	v_mov_b32_e32 v109, v75
	v_pk_fma_f32 v[80:81], v[106:107], v[106:107], v[82:83]
	v_add_f32_e32 v43, v43, v78
	v_pk_fma_f32 v[80:81], v[108:109], v[108:109], v[80:81]
	v_add_f32_e32 v43, v43, v79
	v_add_f32_e32 v43, v43, v80
	v_add_f32_e32 v43, v43, v81
	ds_bpermute_b32 v78, v37, v43
	s_waitcnt lgkmcnt(0)
	v_add_f32_e32 v43, v43, v78
	ds_bpermute_b32 v78, v38, v43
	s_waitcnt lgkmcnt(0)
	v_add_f32_e32 v43, v43, v78
	ds_bpermute_b32 v78, v39, v43
	s_waitcnt lgkmcnt(0)
	v_add_f32_e32 v43, v43, v78
	ds_bpermute_b32 v78, v40, v43
	s_waitcnt lgkmcnt(0)
	v_add_f32_e32 v43, v43, v78
	ds_bpermute_b32 v78, v41, v43
	s_waitcnt lgkmcnt(0)
	v_add_f32_e32 v43, v43, v78
	ds_bpermute_b32 v78, v42, v43
	s_waitcnt lgkmcnt(0)
	v_add_f32_e32 v43, v43, v78
	v_fmamk_f32 v43, v43, 0x3a000000, v33
	v_mul_f32_e32 v78, 0x4b800000, v43
	v_cmp_gt_f32_e32 vcc, s7, v43
	s_nop 1
	v_cndmask_b32_e32 v43, v43, v78, vcc
	v_rsq_f32_e32 v43, v43
	s_nop 0
	v_mul_f32_e32 v78, 0x45800000, v43
	v_cndmask_b32_e32 v78, v43, v78, vcc
	v_pk_mul_f32 v[44:45], v[44:45], v[78:79] op_sel_hi:[1,0]
	v_pk_mul_f32 v[46:47], v[46:47], v[78:79] op_sel_hi:[1,0]
	v_pk_mul_f32 v[48:49], v[48:49], v[78:79] op_sel_hi:[1,0]
	v_pk_mul_f32 v[50:51], v[50:51], v[78:79] op_sel_hi:[1,0]
	v_pk_mul_f32 v[52:53], v[52:53], v[78:79] op_sel_hi:[1,0]
	v_pk_mul_f32 v[54:55], v[54:55], v[78:79] op_sel_hi:[1,0]
	v_pk_mul_f32 v[56:57], v[56:57], v[78:79] op_sel_hi:[1,0]
	v_pk_mul_f32 v[58:59], v[58:59], v[78:79] op_sel_hi:[1,0]
	v_pk_mul_f32 v[60:61], v[60:61], v[78:79] op_sel_hi:[1,0]
	v_pk_mul_f32 v[62:63], v[62:63], v[78:79] op_sel_hi:[1,0]
	v_pk_mul_f32 v[64:65], v[64:65], v[78:79] op_sel_hi:[1,0]
	v_pk_mul_f32 v[66:67], v[66:67], v[78:79] op_sel_hi:[1,0]
	v_pk_mul_f32 v[68:69], v[68:69], v[78:79] op_sel_hi:[1,0]
	v_pk_mul_f32 v[70:71], v[70:71], v[78:79] op_sel_hi:[1,0]
	v_pk_mul_f32 v[72:73], v[72:73], v[78:79] op_sel_hi:[1,0]
	v_pk_mul_f32 v[74:75], v[74:75], v[78:79] op_sel_hi:[1,0]
	v_pk_mul_f32 v[44:45], v[0:1], v[44:45]
	v_pk_mul_f32 v[46:47], v[2:3], v[46:47]
	v_pk_mul_f32 v[48:49], v[4:5], v[48:49]
	v_pk_mul_f32 v[50:51], v[6:7], v[50:51]
	v_pk_mul_f32 v[52:53], v[8:9], v[52:53]
	v_pk_mul_f32 v[54:55], v[10:11], v[54:55]
	v_pk_mul_f32 v[56:57], v[12:13], v[56:57]
	v_pk_mul_f32 v[58:59], v[14:15], v[58:59]
	v_pk_mul_f32 v[60:61], v[16:17], v[60:61]
	v_pk_mul_f32 v[62:63], v[18:19], v[62:63]
	v_pk_mul_f32 v[64:65], v[20:21], v[64:65]
	v_pk_mul_f32 v[66:67], v[22:23], v[66:67]
	v_pk_mul_f32 v[68:69], v[24:25], v[68:69]
	v_pk_mul_f32 v[70:71], v[26:27], v[70:71]
	v_pk_mul_f32 v[72:73], v[28:29], v[72:73]
	v_pk_mul_f32 v[74:75], v[30:31], v[74:75]
	global_store_dwordx4 v[34:35], v[44:47], off
	global_store_dwordx4 v[34:35], v[48:51], off offset:1024
	global_store_dwordx4 v[34:35], v[52:55], off offset:2048
	global_store_dwordx4 v[34:35], v[56:59], off offset:3072
	global_store_dwordx4 v[76:77], v[60:63], off
	global_store_dwordx4 v[76:77], v[64:67], off offset:1024
	global_store_dwordx4 v[76:77], v[68:71], off offset:2048
	global_store_dwordx4 v[76:77], v[72:75], off offset:3072
	v_lshl_add_u64 v[34:35], v[34:35], 0, s[4:5]
	s_andn2_b64 exec, exec, s[2:3]
	s_cbranch_execnz .LBB0_1312
